# back-edge rotation: GEMM K-loop control SALU (counter, pointer bumps, compare) hoisted into the last MFMA segment, only the branch after the loop-back barrier (9 loops)
# baseline (speedup 1.0000x reference)
; #define PG8_STAGE(bufoff, gbase, voff) do { _Pragma("unroll") for (int _i = 0; _i < 2; ++_i) \
;         __builtin_amdgcn_global_load_lds((const unsigned*)((const char*)(gbase) + (voff)[_i]), (PG8_LAS unsigned*)(lds + (bufoff) + ldsw + _i * 8192), 16, 0, 0); } while (0)
; #define PG8_LDA(dst, b, h) do { _Pragma("unroll") for (int m = 0; m < 4; ++m) _Pragma("unroll") for (int k = 0; k < 2; ++k) dst[m][k] = *(const PG8_LAS bf16x8*)(lds + PG8_SA(b, h) + aoff + m * 2048 + k * 1024); } while (0)
; #define PG8_LDB(dst, b, h) do { _Pragma("unroll") for (int n = 0; n < 2; ++n) _Pragma("unroll") for (int k = 0; k < 2; ++k) dst[n][k] = *(const PG8_LAS bf16x8*)(lds + PG8_SB(b, h) + boff + n * 2048 + k * 1024); } while (0)
; #define PG8_MMA(ai, bj, At, Bt) do { __builtin_amdgcn_s_setprio(1); _Pragma("unroll") for (int m = 0; m < 4; ++m) _Pragma("unroll") for (int n = 0; n < 2; ++n) _Pragma("unroll") for (int k = 0; k < 2; ++k) \
;         acc[ai][bj][m][n] = __builtin_amdgcn_mfma_f32_16x16x32_bf16(Bt[n][k], At[m][k], acc[ai][bj][m][n], 0, 0, 0); __builtin_amdgcn_s_setprio(0); } while (0)
; #define PG8_WAIT_V(n) asm volatile("s_waitcnt vmcnt(" #n ")" ::: "memory")
; #define PG8_WAIT_L(n) asm volatile("s_waitcnt lgkmcnt(" #n ")" ::: "memory")
; #define PG8_BAR __builtin_amdgcn_s_barrier()
; #define PG8_SCHED __builtin_amdgcn_sched_barrier(0)
; template <class Epi, class Sched, bool ALIGN_EPI = false, bool SP2 = false>
; __device__ __forceinline__ void gemm_phase(PG8_LAS unsigned char* lds, const Gemm g, const Sched& S, const Epi& E) {
;     ...
;             const bool last = (t == nt - 2);
;             const char* a1 = cA + (size_t)(t + 1) * kstep;
;             const char* a2 = last ? nA : cA + (size_t)(t + 2) * kstep; const char* b2 = last ? nB : cB + (size_t)(t + 2) * kstep;
;             const char* a3 = a2 + kstep; const char* b3 = b2 + kstep;
;             if (last && has_next) S.a_ready(nxt);
;             if constexpr (SP2) {
;             PG8_LDB(B0, 0, 0); PG8_LDB(B1, 0, 1); PG8_SCHED; PG8_LDA(At, 0, 0); PG8_STAGE(PG8_SA(1, 1), a1 + hstep, voffA);
;             PG8_WAIT_V(8); PG8_WAIT_L(0); PG8_BAR; PG8_MMA(0, 0, At, B0); PG8_MMA(0, 1, At, B1); PG8_BAR; PG8_SCHED;
;             PG8_LDA(At, 0, 1); PG8_STAGE(PG8_SB(0, 0), b2, voffB); PG8_STAGE(PG8_SB(0, 1), b2 + hstep, voffB); PG8_STAGE(PG8_SA(0, 0), a2, voffA);
.LBB0_210:
	ds_read_b128 v[144:147], v161
	ds_read_b128 v[148:151], v161 offset:1024
	ds_read_b128 v[152:155], v161 offset:2048
	ds_read_b128 v[164:167], v161 offset:3072
	ds_read_b128 v[168:171], v162
	ds_read_b128 v[172:175], v162 offset:1024
	ds_read_b128 v[180:183], v162 offset:2048
	ds_read_b128 v[184:187], v162 offset:3072
	s_add_u32 s3, s8, 0xfffc0080
	s_addc_u32 s33, s9, -1
	s_cmp_eq_u32 s66, 12
	s_cselect_b32 s63, s5, s33
	s_cselect_b32 s62, s7, s3
	s_cselect_b32 s61, s29, s65
	s_cselect_b32 s60, s31, s64
	v_lshl_add_u64 v[156:157], s[8:9], 0, v[136:137]
	s_add_i32 m0, s81, 0xc000
	ds_read_b128 v[188:191], v163
	ds_read_b128 v[192:195], v163 offset:1024
	ds_read_b128 v[196:199], v163 offset:2048
	ds_read_b128 v[200:203], v163 offset:3072
	ds_read_b128 v[204:207], v163 offset:4096
	ds_read_b128 v[208:211], v163 offset:5120
	ds_read_b128 v[212:215], v163 offset:6144
	ds_read_b128 v[216:219], v163 offset:7168
	global_load_lds_dwordx4 v[156:157], off
	v_lshl_add_u64 v[156:157], s[8:9], 0, v[138:139]
	s_add_i32 m0, s81, 0xe000
	s_nop 0
	global_load_lds_dwordx4 v[156:157], off
	s_waitcnt vmcnt(8)
	s_waitcnt lgkmcnt(0)
	s_barrier
	s_setprio 1
	s_waitcnt lgkmcnt(0)
	v_mfma_f32_16x16x32_bf16 v[124:127], v[144:147], v[188:191], v[124:127]
	v_mfma_f32_16x16x32_bf16 v[120:123], v[152:155], v[188:191], v[120:123]
	v_mfma_f32_16x16x32_bf16 v[108:111], v[144:147], v[196:199], v[108:111]
	v_mfma_f32_16x16x32_bf16 v[104:107], v[152:155], v[196:199], v[104:107]
	v_mfma_f32_16x16x32_bf16 v[92:95], v[144:147], v[204:207], v[92:95]
	v_mfma_f32_16x16x32_bf16 v[88:91], v[152:155], v[204:207], v[88:91]
	v_mfma_f32_16x16x32_bf16 v[76:79], v[144:147], v[212:215], v[76:79]
	v_mfma_f32_16x16x32_bf16 v[72:75], v[152:155], v[212:215], v[72:75]
	v_mfma_f32_16x16x32_bf16 v[124:127], v[148:151], v[192:195], v[124:127]
	v_mfma_f32_16x16x32_bf16 v[120:123], v[164:167], v[192:195], v[120:123]
	v_mfma_f32_16x16x32_bf16 v[108:111], v[148:151], v[200:203], v[108:111]
	v_mfma_f32_16x16x32_bf16 v[104:107], v[164:167], v[200:203], v[104:107]
	v_mfma_f32_16x16x32_bf16 v[92:95], v[148:151], v[208:211], v[92:95]
	v_mfma_f32_16x16x32_bf16 v[88:91], v[164:167], v[208:211], v[88:91]
	v_mfma_f32_16x16x32_bf16 v[76:79], v[148:151], v[216:219], v[76:79]
	v_mfma_f32_16x16x32_bf16 v[72:75], v[164:167], v[216:219], v[72:75]
	s_setprio 0
	s_setprio 1
	v_mfma_f32_16x16x32_bf16 v[116:119], v[168:171], v[188:191], v[116:119]
	v_mfma_f32_16x16x32_bf16 v[112:115], v[180:183], v[188:191], v[112:115]
	v_mfma_f32_16x16x32_bf16 v[100:103], v[168:171], v[196:199], v[100:103]
	v_mfma_f32_16x16x32_bf16 v[96:99], v[180:183], v[196:199], v[96:99]
	v_mfma_f32_16x16x32_bf16 v[84:87], v[168:171], v[204:207], v[84:87]
	v_mfma_f32_16x16x32_bf16 v[80:83], v[180:183], v[204:207], v[80:83]
	v_mfma_f32_16x16x32_bf16 v[68:71], v[168:171], v[212:215], v[68:71]
	v_mfma_f32_16x16x32_bf16 v[64:67], v[180:183], v[212:215], v[64:67]
	v_mfma_f32_16x16x32_bf16 v[116:119], v[172:175], v[192:195], v[116:119]
	v_mfma_f32_16x16x32_bf16 v[112:115], v[184:187], v[192:195], v[112:115]
	v_mfma_f32_16x16x32_bf16 v[100:103], v[172:175], v[200:203], v[100:103]
	v_mfma_f32_16x16x32_bf16 v[96:99], v[184:187], v[200:203], v[96:99]
	v_mfma_f32_16x16x32_bf16 v[84:87], v[172:175], v[208:211], v[84:87]
	v_mfma_f32_16x16x32_bf16 v[80:83], v[184:187], v[208:211], v[80:83]
	v_mfma_f32_16x16x32_bf16 v[68:71], v[172:175], v[216:219], v[68:71]
	v_mfma_f32_16x16x32_bf16 v[64:67], v[184:187], v[216:219], v[64:67]
	s_setprio 0
	s_barrier
	s_add_i32 s3, s92, s80
	v_lshl_add_u64 v[156:157], s[60:61], 0, v[130:131]
	s_mov_b32 m0, s3
	ds_read_b128 v[188:191], v163 offset:16384
	ds_read_b128 v[192:195], v163 offset:17408
	ds_read_b128 v[196:199], v163 offset:18432
	ds_read_b128 v[200:203], v163 offset:19456
	ds_read_b128 v[204:207], v163 offset:20480
	ds_read_b128 v[208:211], v163 offset:21504
	ds_read_b128 v[212:215], v163 offset:22528
	ds_read_b128 v[216:219], v163 offset:23552
	global_load_lds_dwordx4 v[156:157], off
	s_add_i32 m0, s3, 0x2000
	s_add_u32 s68, s60, 0x40000
	v_lshl_add_u64 v[220:221], s[60:61], 0, v[134:135]
	s_addc_u32 s69, s61, 0
	s_add_i32 s3, s93, s80
	global_load_lds_dwordx4 v[220:221], off
	v_lshl_add_u64 v[222:223], s[68:69], 0, v[130:131]
	s_mov_b32 m0, s3
	v_lshl_add_u64 v[224:225], s[62:63], 0, v[132:133]
	global_load_lds_dwordx4 v[222:223], off
	v_lshl_add_u64 v[222:223], s[68:69], 0, v[134:135]
	s_add_i32 m0, s3, 0x2000
	s_nop 0
	global_load_lds_dwordx4 v[222:223], off
	v_lshl_add_u64 v[222:223], s[62:63], 0, v[128:129]
	s_mov_b32 m0, s81
	s_nop 0
	global_load_lds_dwordx4 v[222:223], off
	s_mov_b32 m0, s82
	s_nop 0
	global_load_lds_dwordx4 v[224:225], off
	s_waitcnt vmcnt(8)
	s_waitcnt lgkmcnt(0)
	s_barrier
; #define PG8_STAGE(bufoff, gbase, voff) do { _Pragma("unroll") for (int _i = 0; _i < 2; ++_i) \
;         __builtin_amdgcn_global_load_lds((const unsigned*)((const char*)(gbase) + (voff)[_i]), (PG8_LAS unsigned*)(lds + (bufoff) + ldsw + _i * 8192), 16, 0, 0); } while (0)
; #define PG8_LDA(dst, b, h) do { _Pragma("unroll") for (int m = 0; m < 4; ++m) _Pragma("unroll") for (int k = 0; k < 2; ++k) dst[m][k] = *(const PG8_LAS bf16x8*)(lds + PG8_SA(b, h) + aoff + m * 2048 + k * 1024); } while (0)
; #define PG8_LDB(dst, b, h) do { _Pragma("unroll") for (int n = 0; n < 2; ++n) _Pragma("unroll") for (int k = 0; k < 2; ++k) dst[n][k] = *(const PG8_LAS bf16x8*)(lds + PG8_SB(b, h) + boff + n * 2048 + k * 1024); } while (0)
; #define PG8_MMA(ai, bj, At, Bt) do { __builtin_amdgcn_s_setprio(1); _Pragma("unroll") for (int m = 0; m < 4; ++m) _Pragma("unroll") for (int n = 0; n < 2; ++n) _Pragma("unroll") for (int k = 0; k < 2; ++k) \
;         acc[ai][bj][m][n] = __builtin_amdgcn_mfma_f32_16x16x32_bf16(Bt[n][k], At[m][k], acc[ai][bj][m][n], 0, 0, 0); __builtin_amdgcn_s_setprio(0); } while (0)
; #define PG8_WAIT_V(n) asm volatile("s_waitcnt vmcnt(" #n ")" ::: "memory")
; #define PG8_WAIT_L(n) asm volatile("s_waitcnt lgkmcnt(" #n ")" ::: "memory")
; #define PG8_BAR __builtin_amdgcn_s_barrier()
; #define PG8_SCHED __builtin_amdgcn_sched_barrier(0)
; template <class Epi, class Sched, bool ALIGN_EPI = false, bool SP2 = false>
; __device__ __forceinline__ void gemm_phase(PG8_LAS unsigned char* lds, const Gemm g, const Sched& S, const Epi& E) {
;     ...
;             PG8_WAIT_V(8); PG8_WAIT_L(0); PG8_BAR; PG8_MMA(1, 0, At, B0); PG8_MMA(1, 1, At, B1); PG8_BAR; PG8_SCHED;
;             PG8_LDB(B0, 1, 0); PG8_LDB(B1, 1, 1); PG8_SCHED; PG8_LDA(At, 1, 0); PG8_STAGE(PG8_SA(0, 1), a2 + hstep, voffA);
;             PG8_WAIT_V(8); PG8_WAIT_L(0); PG8_BAR; PG8_MMA(0, 0, At, B0); PG8_MMA(0, 1, At, B1); PG8_BAR; PG8_SCHED;
	s_setprio 1
	s_waitcnt lgkmcnt(0)
	v_mfma_f32_16x16x32_bf16 v[60:63], v[144:147], v[188:191], v[60:63]
	v_mfma_f32_16x16x32_bf16 v[56:59], v[152:155], v[188:191], v[56:59]
	v_mfma_f32_16x16x32_bf16 v[44:47], v[144:147], v[196:199], v[44:47]
	v_mfma_f32_16x16x32_bf16 v[40:43], v[152:155], v[196:199], v[40:43]
	v_mfma_f32_16x16x32_bf16 v[28:31], v[144:147], v[204:207], v[28:31]
	v_mfma_f32_16x16x32_bf16 v[24:27], v[152:155], v[204:207], v[24:27]
	v_mfma_f32_16x16x32_bf16 v[12:15], v[144:147], v[212:215], v[12:15]
	v_mfma_f32_16x16x32_bf16 v[8:11], v[152:155], v[212:215], v[8:11]
	v_mfma_f32_16x16x32_bf16 v[60:63], v[148:151], v[192:195], v[60:63]
	v_mfma_f32_16x16x32_bf16 v[56:59], v[164:167], v[192:195], v[56:59]
	v_mfma_f32_16x16x32_bf16 v[44:47], v[148:151], v[200:203], v[44:47]
	v_mfma_f32_16x16x32_bf16 v[40:43], v[164:167], v[200:203], v[40:43]
	v_mfma_f32_16x16x32_bf16 v[28:31], v[148:151], v[208:211], v[28:31]
	v_mfma_f32_16x16x32_bf16 v[24:27], v[164:167], v[208:211], v[24:27]
	v_mfma_f32_16x16x32_bf16 v[12:15], v[148:151], v[216:219], v[12:15]
	v_mfma_f32_16x16x32_bf16 v[8:11], v[164:167], v[216:219], v[8:11]
	s_setprio 0
	s_setprio 1
	v_mfma_f32_16x16x32_bf16 v[52:55], v[168:171], v[188:191], v[52:55]
	v_mfma_f32_16x16x32_bf16 v[48:51], v[180:183], v[188:191], v[48:51]
	v_mfma_f32_16x16x32_bf16 v[36:39], v[168:171], v[196:199], v[36:39]
	v_mfma_f32_16x16x32_bf16 v[32:35], v[180:183], v[196:199], v[32:35]
	v_mfma_f32_16x16x32_bf16 v[20:23], v[168:171], v[204:207], v[20:23]
	v_mfma_f32_16x16x32_bf16 v[16:19], v[180:183], v[204:207], v[16:19]
	v_mfma_f32_16x16x32_bf16 v[4:7], v[168:171], v[212:215], v[4:7]
	v_mfma_f32_16x16x32_bf16 v[0:3], v[180:183], v[212:215], v[0:3]
	v_mfma_f32_16x16x32_bf16 v[52:55], v[172:175], v[192:195], v[52:55]
	v_mfma_f32_16x16x32_bf16 v[48:51], v[184:187], v[192:195], v[48:51]
	v_mfma_f32_16x16x32_bf16 v[36:39], v[172:175], v[200:203], v[36:39]
	v_mfma_f32_16x16x32_bf16 v[32:35], v[184:187], v[200:203], v[32:35]
	v_mfma_f32_16x16x32_bf16 v[20:23], v[172:175], v[208:211], v[20:23]
	v_mfma_f32_16x16x32_bf16 v[16:19], v[184:187], v[208:211], v[16:19]
	v_mfma_f32_16x16x32_bf16 v[4:7], v[172:175], v[216:219], v[4:7]
	v_mfma_f32_16x16x32_bf16 v[0:3], v[184:187], v[216:219], v[0:3]
	s_setprio 0
	s_barrier
	s_add_i32 s3, 0, 0x18000
	s_add_i32 s33, 0, 0x1c000
	v_add_u32_e32 v164, s3, v159
	v_add_u32_e32 v177, s33, v159
	ds_read_b128 v[144:147], v164
	ds_read_b128 v[148:151], v164 offset:1024
	ds_read_b128 v[152:155], v164 offset:2048
	ds_read_b128 v[164:167], v164 offset:3072
	ds_read_b128 v[168:171], v177
	ds_read_b128 v[172:175], v177 offset:1024
	ds_read_b128 v[180:183], v177 offset:2048
	ds_read_b128 v[184:187], v177 offset:3072
	s_add_u32 s62, s62, 0x40000
	s_addc_u32 s63, s63, 0
	s_mov_b32 m0, s83
	v_lshl_add_u64 v[226:227], s[62:63], 0, v[128:129]
	ds_read_b128 v[188:191], v163 offset:32768
	ds_read_b128 v[192:195], v163 offset:33792
	ds_read_b128 v[196:199], v163 offset:34816
	ds_read_b128 v[200:203], v163 offset:35840
	ds_read_b128 v[204:207], v163 offset:36864
	ds_read_b128 v[208:211], v163 offset:37888
	ds_read_b128 v[212:215], v163 offset:38912
	ds_read_b128 v[216:219], v163 offset:39936
	global_load_lds_dwordx4 v[226:227], off
	v_lshl_add_u64 v[226:227], s[62:63], 0, v[132:133]
	s_mov_b32 m0, s84
	s_nop 0
	global_load_lds_dwordx4 v[226:227], off
	s_waitcnt vmcnt(8)
	s_waitcnt lgkmcnt(0)
	s_barrier
	s_setprio 1
	s_waitcnt lgkmcnt(0)
	v_mfma_f32_16x16x32_bf16 v[124:127], v[144:147], v[188:191], v[124:127]
	v_mfma_f32_16x16x32_bf16 v[120:123], v[152:155], v[188:191], v[120:123]
	v_mfma_f32_16x16x32_bf16 v[108:111], v[144:147], v[196:199], v[108:111]
	v_mfma_f32_16x16x32_bf16 v[104:107], v[152:155], v[196:199], v[104:107]
	v_mfma_f32_16x16x32_bf16 v[92:95], v[144:147], v[204:207], v[92:95]
	v_mfma_f32_16x16x32_bf16 v[88:91], v[152:155], v[204:207], v[88:91]
	v_mfma_f32_16x16x32_bf16 v[76:79], v[144:147], v[212:215], v[76:79]
	v_mfma_f32_16x16x32_bf16 v[72:75], v[152:155], v[212:215], v[72:75]
	v_mfma_f32_16x16x32_bf16 v[124:127], v[148:151], v[192:195], v[124:127]
	v_mfma_f32_16x16x32_bf16 v[120:123], v[164:167], v[192:195], v[120:123]
	v_mfma_f32_16x16x32_bf16 v[108:111], v[148:151], v[200:203], v[108:111]
	v_mfma_f32_16x16x32_bf16 v[104:107], v[164:167], v[200:203], v[104:107]
	v_mfma_f32_16x16x32_bf16 v[92:95], v[148:151], v[208:211], v[92:95]
	v_mfma_f32_16x16x32_bf16 v[88:91], v[164:167], v[208:211], v[88:91]
	v_mfma_f32_16x16x32_bf16 v[76:79], v[148:151], v[216:219], v[76:79]
	v_mfma_f32_16x16x32_bf16 v[72:75], v[164:167], v[216:219], v[72:75]
	s_setprio 0
	s_setprio 1
	v_mfma_f32_16x16x32_bf16 v[116:119], v[168:171], v[188:191], v[116:119]
	v_mfma_f32_16x16x32_bf16 v[112:115], v[180:183], v[188:191], v[112:115]
	v_mfma_f32_16x16x32_bf16 v[100:103], v[168:171], v[196:199], v[100:103]
	v_mfma_f32_16x16x32_bf16 v[96:99], v[180:183], v[196:199], v[96:99]
	v_mfma_f32_16x16x32_bf16 v[84:87], v[168:171], v[204:207], v[84:87]
	v_mfma_f32_16x16x32_bf16 v[80:83], v[180:183], v[204:207], v[80:83]
	v_mfma_f32_16x16x32_bf16 v[68:71], v[168:171], v[212:215], v[68:71]
	v_mfma_f32_16x16x32_bf16 v[64:67], v[180:183], v[212:215], v[64:67]
	v_mfma_f32_16x16x32_bf16 v[116:119], v[172:175], v[192:195], v[116:119]
	v_mfma_f32_16x16x32_bf16 v[112:115], v[184:187], v[192:195], v[112:115]
	v_mfma_f32_16x16x32_bf16 v[100:103], v[172:175], v[200:203], v[100:103]
	v_mfma_f32_16x16x32_bf16 v[96:99], v[184:187], v[200:203], v[96:99]
	v_mfma_f32_16x16x32_bf16 v[84:87], v[172:175], v[208:211], v[84:87]
	v_mfma_f32_16x16x32_bf16 v[80:83], v[184:187], v[208:211], v[80:83]
	v_mfma_f32_16x16x32_bf16 v[68:71], v[172:175], v[216:219], v[68:71]
	v_mfma_f32_16x16x32_bf16 v[64:67], v[184:187], v[216:219], v[64:67]
	s_setprio 0
	s_barrier
; #define PG8_STAGE(bufoff, gbase, voff) do { _Pragma("unroll") for (int _i = 0; _i < 2; ++_i) \
;         __builtin_amdgcn_global_load_lds((const unsigned*)((const char*)(gbase) + (voff)[_i]), (PG8_LAS unsigned*)(lds + (bufoff) + ldsw + _i * 8192), 16, 0, 0); } while (0)
; #define PG8_LDA(dst, b, h) do { _Pragma("unroll") for (int m = 0; m < 4; ++m) _Pragma("unroll") for (int k = 0; k < 2; ++k) dst[m][k] = *(const PG8_LAS bf16x8*)(lds + PG8_SA(b, h) + aoff + m * 2048 + k * 1024); } while (0)
; #define PG8_MMA(ai, bj, At, Bt) do { __builtin_amdgcn_s_setprio(1); _Pragma("unroll") for (int m = 0; m < 4; ++m) _Pragma("unroll") for (int n = 0; n < 2; ++n) _Pragma("unroll") for (int k = 0; k < 2; ++k) \
;         acc[ai][bj][m][n] = __builtin_amdgcn_mfma_f32_16x16x32_bf16(Bt[n][k], At[m][k], acc[ai][bj][m][n], 0, 0, 0); __builtin_amdgcn_s_setprio(0); } while (0)
; #define PG8_WAIT_V(n) asm volatile("s_waitcnt vmcnt(" #n ")" ::: "memory")
; #define PG8_WAIT_L(n) asm volatile("s_waitcnt lgkmcnt(" #n ")" ::: "memory")
; #define PG8_BAR __builtin_amdgcn_s_barrier()
; #define PG8_SCHED __builtin_amdgcn_sched_barrier(0)
; template <class Epi, class Sched, bool ALIGN_EPI = false, bool SP2 = false>
; __device__ __forceinline__ void gemm_phase(PG8_LAS unsigned char* lds, const Gemm g, const Sched& S, const Epi& E) {
;     ...
;             PG8_LDA(At, 1, 1); PG8_STAGE(PG8_SB(1, 0), b3, voffB); PG8_STAGE(PG8_SB(1, 1), b3 + hstep, voffB); PG8_STAGE(PG8_SA(1, 0), a3, voffA);
;             PG8_WAIT_V(8); PG8_WAIT_L(0); PG8_BAR; PG8_MMA(1, 0, At, B0); PG8_MMA(1, 1, At, B1); PG8_BAR; PG8_SCHED;
;     ...
;     PG8_WAIT_V(0);
;     if constexpr (!ALIGN_EPI) { if (wr == 0) PG8_BAR; }
	s_add_i32 s3, s3, s80
	v_lshl_add_u64 v[156:157], v[156:157], 0, s[24:25]
	s_mov_b32 m0, s3
	ds_read_b128 v[188:191], v163 offset:49152
	ds_read_b128 v[192:195], v163 offset:50176
	ds_read_b128 v[196:199], v163 offset:51200
	ds_read_b128 v[200:203], v163 offset:52224
	ds_read_b128 v[204:207], v163 offset:53248
	ds_read_b128 v[208:211], v163 offset:54272
	ds_read_b128 v[212:215], v163 offset:55296
	ds_read_b128 v[216:219], v163 offset:56320
	global_load_lds_dwordx4 v[156:157], off
	s_add_i32 m0, s3, 0x2000
	s_add_u32 s60, s60, 0x40080
	v_lshl_add_u64 v[156:157], v[220:221], 0, s[24:25]
	s_addc_u32 s61, s61, 0
	s_add_i32 s3, s33, s80
	global_load_lds_dwordx4 v[156:157], off
	v_lshl_add_u64 v[156:157], s[60:61], 0, v[130:131]
	s_mov_b32 m0, s3
	s_nop 0
	global_load_lds_dwordx4 v[156:157], off
	v_lshl_add_u64 v[156:157], s[60:61], 0, v[134:135]
	s_add_i32 m0, s3, 0x2000
	s_nop 0
	global_load_lds_dwordx4 v[156:157], off
	v_lshl_add_u64 v[156:157], v[222:223], 0, s[24:25]
	s_mov_b32 m0, s86
	s_nop 0
	global_load_lds_dwordx4 v[156:157], off
	v_lshl_add_u64 v[156:157], v[224:225], 0, s[24:25]
	s_mov_b32 m0, s87
	s_nop 0
	global_load_lds_dwordx4 v[156:157], off
	s_waitcnt vmcnt(8)
	s_waitcnt lgkmcnt(0)
	s_barrier
	s_setprio 1
	s_waitcnt lgkmcnt(0)
	v_mfma_f32_16x16x32_bf16 v[60:63], v[144:147], v[188:191], v[60:63]
	v_mfma_f32_16x16x32_bf16 v[56:59], v[152:155], v[188:191], v[56:59]
	v_mfma_f32_16x16x32_bf16 v[44:47], v[144:147], v[196:199], v[44:47]
	v_mfma_f32_16x16x32_bf16 v[40:43], v[152:155], v[196:199], v[40:43]
	v_mfma_f32_16x16x32_bf16 v[28:31], v[144:147], v[204:207], v[28:31]
	v_mfma_f32_16x16x32_bf16 v[24:27], v[152:155], v[204:207], v[24:27]
	v_mfma_f32_16x16x32_bf16 v[12:15], v[144:147], v[212:215], v[12:15]
	v_mfma_f32_16x16x32_bf16 v[8:11], v[152:155], v[212:215], v[8:11]
	v_mfma_f32_16x16x32_bf16 v[60:63], v[148:151], v[192:195], v[60:63]
	v_mfma_f32_16x16x32_bf16 v[56:59], v[164:167], v[192:195], v[56:59]
	v_mfma_f32_16x16x32_bf16 v[44:47], v[148:151], v[200:203], v[44:47]
	v_mfma_f32_16x16x32_bf16 v[40:43], v[164:167], v[200:203], v[40:43]
	v_mfma_f32_16x16x32_bf16 v[28:31], v[148:151], v[208:211], v[28:31]
	v_mfma_f32_16x16x32_bf16 v[24:27], v[164:167], v[208:211], v[24:27]
	v_mfma_f32_16x16x32_bf16 v[12:15], v[148:151], v[216:219], v[12:15]
	v_mfma_f32_16x16x32_bf16 v[8:11], v[164:167], v[216:219], v[8:11]
	s_setprio 0
	s_setprio 1
	v_mfma_f32_16x16x32_bf16 v[52:55], v[168:171], v[188:191], v[52:55]
	v_mfma_f32_16x16x32_bf16 v[48:51], v[180:183], v[188:191], v[48:51]
	v_mfma_f32_16x16x32_bf16 v[36:39], v[168:171], v[196:199], v[36:39]
	v_mfma_f32_16x16x32_bf16 v[32:35], v[180:183], v[196:199], v[32:35]
	v_mfma_f32_16x16x32_bf16 v[20:23], v[168:171], v[204:207], v[20:23]
	s_add_i32 s66, s66, 2
	s_add_u32 s8, s8, 0x100
	s_addc_u32 s9, s9, 0
	s_add_u32 s64, s64, 0x100
	s_addc_u32 s65, s65, 0
	s_cmp_gt_u32 s66, 13
	v_mfma_f32_16x16x32_bf16 v[16:19], v[180:183], v[204:207], v[16:19]
	v_mfma_f32_16x16x32_bf16 v[4:7], v[168:171], v[212:215], v[4:7]
	v_mfma_f32_16x16x32_bf16 v[0:3], v[180:183], v[212:215], v[0:3]
	v_mfma_f32_16x16x32_bf16 v[52:55], v[172:175], v[192:195], v[52:55]
	v_mfma_f32_16x16x32_bf16 v[48:51], v[184:187], v[192:195], v[48:51]
	v_mfma_f32_16x16x32_bf16 v[36:39], v[172:175], v[200:203], v[36:39]
	v_mfma_f32_16x16x32_bf16 v[32:35], v[184:187], v[200:203], v[32:35]
	v_mfma_f32_16x16x32_bf16 v[20:23], v[172:175], v[208:211], v[20:23]
	v_mfma_f32_16x16x32_bf16 v[16:19], v[184:187], v[208:211], v[16:19]
	v_mfma_f32_16x16x32_bf16 v[4:7], v[172:175], v[216:219], v[4:7]
	v_mfma_f32_16x16x32_bf16 v[0:3], v[184:187], v[216:219], v[0:3]
	s_setprio 0
	s_barrier
	s_cbranch_scc0 .LBB0_210
	s_and_b64 vcc, exec, s[26:27]
	s_cbranch_vccz .LBB0_213
	s_barrier

; #define PG8_STAGE(bufoff, gbase, voff) do { _Pragma("unroll") for (int _i = 0; _i < 2; ++_i) \
;         __builtin_amdgcn_global_load_lds((const unsigned*)((const char*)(gbase) + (voff)[_i]), (PG8_LAS unsigned*)(lds + (bufoff) + ldsw + _i * 8192), 16, 0, 0); } while (0)
; #define PG8_LDA(dst, b, h) do { _Pragma("unroll") for (int m = 0; m < 4; ++m) _Pragma("unroll") for (int k = 0; k < 2; ++k) dst[m][k] = *(const PG8_LAS bf16x8*)(lds + PG8_SA(b, h) + aoff + m * 2048 + k * 1024); } while (0)
; #define PG8_LDB(dst, b, h) do { _Pragma("unroll") for (int n = 0; n < 2; ++n) _Pragma("unroll") for (int k = 0; k < 2; ++k) dst[n][k] = *(const PG8_LAS bf16x8*)(lds + PG8_SB(b, h) + boff + n * 2048 + k * 1024); } while (0)
; #define PG8_MMA(ai, bj, At, Bt) do { __builtin_amdgcn_s_setprio(1); _Pragma("unroll") for (int m = 0; m < 4; ++m) _Pragma("unroll") for (int n = 0; n < 2; ++n) _Pragma("unroll") for (int k = 0; k < 2; ++k) \
;         acc[ai][bj][m][n] = __builtin_amdgcn_mfma_f32_16x16x32_bf16(Bt[n][k], At[m][k], acc[ai][bj][m][n], 0, 0, 0); __builtin_amdgcn_s_setprio(0); } while (0)
; #define PG8_WAIT_V(n) asm volatile("s_waitcnt vmcnt(" #n ")" ::: "memory")
; #define PG8_WAIT_L(n) asm volatile("s_waitcnt lgkmcnt(" #n ")" ::: "memory")
; #define PG8_BAR __builtin_amdgcn_s_barrier()
; #define PG8_SCHED __builtin_amdgcn_sched_barrier(0)
; template <class Epi, class Sched, bool ALIGN_EPI = false, bool SP2 = false>
; __device__ __forceinline__ void gemm_phase(PG8_LAS unsigned char* lds, const Gemm g, const Sched& S, const Epi& E) {
;     ...
;             const bool last = (t == nt - 2);
;             const char* a1 = cA + (size_t)(t + 1) * kstep;
;             const char* a2 = last ? nA : cA + (size_t)(t + 2) * kstep; const char* b2 = last ? nB : cB + (size_t)(t + 2) * kstep;
;             const char* a3 = a2 + kstep; const char* b3 = b2 + kstep;
;             if (last && has_next) S.a_ready(nxt);
;             if constexpr (SP2) {
;             PG8_LDB(B0, 0, 0); PG8_LDB(B1, 0, 1); PG8_SCHED; PG8_LDA(At, 0, 0); PG8_STAGE(PG8_SA(1, 1), a1 + hstep, voffA);
;             PG8_WAIT_V(8); PG8_WAIT_L(0); PG8_BAR; PG8_MMA(0, 0, At, B0); PG8_MMA(0, 1, At, B1); PG8_BAR; PG8_SCHED;
;             PG8_LDA(At, 0, 1); PG8_STAGE(PG8_SB(0, 0), b2, voffB); PG8_STAGE(PG8_SB(0, 1), b2 + hstep, voffB); PG8_STAGE(PG8_SA(0, 0), a2, voffA);
.LBB0_647:
	ds_read_b128 v[136:139], v161
	ds_read_b128 v[140:143], v161 offset:1024
	ds_read_b128 v[164:167], v161 offset:2048
	ds_read_b128 v[168:171], v161 offset:3072
	ds_read_b128 v[172:175], v162
	ds_read_b128 v[180:183], v162 offset:1024
	ds_read_b128 v[184:187], v162 offset:2048
	ds_read_b128 v[188:191], v162 offset:3072
	s_add_u32 s3, s46, 0xfffe0080
	s_addc_u32 s33, s47, -1
	s_cmp_eq_u32 s92, 4
	s_cselect_b32 s63, s35, s33
	s_cselect_b32 s62, s88, s3
	s_cselect_b32 s61, s31, s91
	s_cselect_b32 s60, s89, s90
	v_lshl_add_u64 v[144:145], s[46:47], 0, v[132:133]
	s_add_i32 m0, s45, 0xc000
	ds_read_b128 v[192:195], v163
	ds_read_b128 v[196:199], v163 offset:1024
	ds_read_b128 v[200:203], v163 offset:2048
	ds_read_b128 v[204:207], v163 offset:3072
	ds_read_b128 v[208:211], v163 offset:4096
	ds_read_b128 v[212:215], v163 offset:5120
	ds_read_b128 v[216:219], v163 offset:6144
	ds_read_b128 v[220:223], v163 offset:7168
	global_load_lds_dwordx4 v[144:145], off
	v_lshl_add_u64 v[144:145], s[46:47], 0, v[134:135]
	s_add_i32 m0, s45, 0xe000
	s_nop 0
	global_load_lds_dwordx4 v[144:145], off
	s_waitcnt vmcnt(8)
	s_waitcnt lgkmcnt(0)
	s_barrier
	s_setprio 1
	s_waitcnt lgkmcnt(0)
	v_mfma_f32_16x16x32_bf16 v[124:127], v[136:139], v[192:195], v[124:127]
	v_mfma_f32_16x16x32_bf16 v[120:123], v[164:167], v[192:195], v[120:123]
	v_mfma_f32_16x16x32_bf16 v[116:119], v[136:139], v[200:203], v[116:119]
	v_mfma_f32_16x16x32_bf16 v[108:111], v[164:167], v[200:203], v[108:111]
	v_mfma_f32_16x16x32_bf16 v[92:95], v[136:139], v[208:211], v[92:95]
	v_mfma_f32_16x16x32_bf16 v[88:91], v[164:167], v[208:211], v[88:91]
	v_mfma_f32_16x16x32_bf16 v[80:83], v[136:139], v[216:219], v[80:83]
	v_mfma_f32_16x16x32_bf16 v[72:75], v[164:167], v[216:219], v[72:75]
	v_mfma_f32_16x16x32_bf16 v[124:127], v[140:143], v[196:199], v[124:127]
	v_mfma_f32_16x16x32_bf16 v[120:123], v[168:171], v[196:199], v[120:123]
	v_mfma_f32_16x16x32_bf16 v[116:119], v[140:143], v[204:207], v[116:119]
	v_mfma_f32_16x16x32_bf16 v[108:111], v[168:171], v[204:207], v[108:111]
	v_mfma_f32_16x16x32_bf16 v[92:95], v[140:143], v[212:215], v[92:95]
	v_mfma_f32_16x16x32_bf16 v[88:91], v[168:171], v[212:215], v[88:91]
	v_mfma_f32_16x16x32_bf16 v[80:83], v[140:143], v[220:223], v[80:83]
	v_mfma_f32_16x16x32_bf16 v[72:75], v[168:171], v[220:223], v[72:75]
	s_setprio 0
	s_setprio 1
	v_mfma_f32_16x16x32_bf16 v[112:115], v[172:175], v[192:195], v[112:115]
	v_mfma_f32_16x16x32_bf16 v[104:107], v[184:187], v[192:195], v[104:107]
	v_mfma_f32_16x16x32_bf16 v[100:103], v[172:175], v[200:203], v[100:103]
	v_mfma_f32_16x16x32_bf16 v[96:99], v[184:187], v[200:203], v[96:99]
	v_mfma_f32_16x16x32_bf16 v[84:87], v[172:175], v[208:211], v[84:87]
	v_mfma_f32_16x16x32_bf16 v[76:79], v[184:187], v[208:211], v[76:79]
	v_mfma_f32_16x16x32_bf16 v[68:71], v[172:175], v[216:219], v[68:71]
	v_mfma_f32_16x16x32_bf16 v[64:67], v[184:187], v[216:219], v[64:67]
	v_mfma_f32_16x16x32_bf16 v[112:115], v[180:183], v[196:199], v[112:115]
	v_mfma_f32_16x16x32_bf16 v[104:107], v[188:191], v[196:199], v[104:107]
	v_mfma_f32_16x16x32_bf16 v[100:103], v[180:183], v[204:207], v[100:103]
	v_mfma_f32_16x16x32_bf16 v[96:99], v[188:191], v[204:207], v[96:99]
	v_mfma_f32_16x16x32_bf16 v[84:87], v[180:183], v[212:215], v[84:87]
	v_mfma_f32_16x16x32_bf16 v[76:79], v[188:191], v[212:215], v[76:79]
	v_mfma_f32_16x16x32_bf16 v[68:71], v[180:183], v[220:223], v[68:71]
	v_mfma_f32_16x16x32_bf16 v[64:67], v[188:191], v[220:223], v[64:67]
	s_setprio 0
	s_barrier
	s_add_i32 s3, s65, s77
	v_lshl_add_u64 v[144:145], s[60:61], 0, v[128:129]
	s_mov_b32 m0, s3
	ds_read_b128 v[192:195], v163 offset:16384
	ds_read_b128 v[196:199], v163 offset:17408
	ds_read_b128 v[200:203], v163 offset:18432
	ds_read_b128 v[204:207], v163 offset:19456
	ds_read_b128 v[208:211], v163 offset:20480
	ds_read_b128 v[212:215], v163 offset:21504
	ds_read_b128 v[216:219], v163 offset:22528
	ds_read_b128 v[220:223], v163 offset:23552
	global_load_lds_dwordx4 v[144:145], off
	s_add_i32 m0, s3, 0x2000
	s_add_u32 s94, s60, 0x20000
	v_lshl_add_u64 v[224:225], s[60:61], 0, v[130:131]
	s_addc_u32 s95, s61, 0
	s_add_i32 s3, s66, s77
	global_load_lds_dwordx4 v[224:225], off
	v_lshl_add_u64 v[226:227], s[94:95], 0, v[128:129]
	s_mov_b32 m0, s3
	v_lshl_add_u64 v[228:229], s[62:63], 0, v[130:131]
	global_load_lds_dwordx4 v[226:227], off
	v_lshl_add_u64 v[226:227], s[94:95], 0, v[130:131]
	s_add_i32 m0, s3, 0x2000
	s_nop 0
	global_load_lds_dwordx4 v[226:227], off
	v_lshl_add_u64 v[226:227], s[62:63], 0, v[128:129]
	s_mov_b32 m0, s45
	s_nop 0
	global_load_lds_dwordx4 v[226:227], off
	s_mov_b32 m0, s78
	s_nop 0
	global_load_lds_dwordx4 v[228:229], off
	s_waitcnt vmcnt(8)
	s_waitcnt lgkmcnt(0)
	s_barrier
; #define PG8_STAGE(bufoff, gbase, voff) do { _Pragma("unroll") for (int _i = 0; _i < 2; ++_i) \
;         __builtin_amdgcn_global_load_lds((const unsigned*)((const char*)(gbase) + (voff)[_i]), (PG8_LAS unsigned*)(lds + (bufoff) + ldsw + _i * 8192), 16, 0, 0); } while (0)
; #define PG8_LDA(dst, b, h) do { _Pragma("unroll") for (int m = 0; m < 4; ++m) _Pragma("unroll") for (int k = 0; k < 2; ++k) dst[m][k] = *(const PG8_LAS bf16x8*)(lds + PG8_SA(b, h) + aoff + m * 2048 + k * 1024); } while (0)
; #define PG8_LDB(dst, b, h) do { _Pragma("unroll") for (int n = 0; n < 2; ++n) _Pragma("unroll") for (int k = 0; k < 2; ++k) dst[n][k] = *(const PG8_LAS bf16x8*)(lds + PG8_SB(b, h) + boff + n * 2048 + k * 1024); } while (0)
; #define PG8_MMA(ai, bj, At, Bt) do { __builtin_amdgcn_s_setprio(1); _Pragma("unroll") for (int m = 0; m < 4; ++m) _Pragma("unroll") for (int n = 0; n < 2; ++n) _Pragma("unroll") for (int k = 0; k < 2; ++k) \
;         acc[ai][bj][m][n] = __builtin_amdgcn_mfma_f32_16x16x32_bf16(Bt[n][k], At[m][k], acc[ai][bj][m][n], 0, 0, 0); __builtin_amdgcn_s_setprio(0); } while (0)
; #define PG8_WAIT_V(n) asm volatile("s_waitcnt vmcnt(" #n ")" ::: "memory")
; #define PG8_WAIT_L(n) asm volatile("s_waitcnt lgkmcnt(" #n ")" ::: "memory")
; #define PG8_BAR __builtin_amdgcn_s_barrier()
; #define PG8_SCHED __builtin_amdgcn_sched_barrier(0)
; template <class Epi, class Sched, bool ALIGN_EPI = false, bool SP2 = false>
; __device__ __forceinline__ void gemm_phase(PG8_LAS unsigned char* lds, const Gemm g, const Sched& S, const Epi& E) {
;     ...
;             PG8_WAIT_V(8); PG8_WAIT_L(0); PG8_BAR; PG8_MMA(1, 0, At, B0); PG8_MMA(1, 1, At, B1); PG8_BAR; PG8_SCHED;
;             PG8_LDB(B0, 1, 0); PG8_LDB(B1, 1, 1); PG8_SCHED; PG8_LDA(At, 1, 0); PG8_STAGE(PG8_SA(0, 1), a2 + hstep, voffA);
;             PG8_WAIT_V(8); PG8_WAIT_L(0); PG8_BAR; PG8_MMA(0, 0, At, B0); PG8_MMA(0, 1, At, B1); PG8_BAR; PG8_SCHED;
	s_setprio 1
	s_waitcnt lgkmcnt(0)
	v_mfma_f32_16x16x32_bf16 v[60:63], v[136:139], v[192:195], v[60:63]
	v_mfma_f32_16x16x32_bf16 v[56:59], v[164:167], v[192:195], v[56:59]
	v_mfma_f32_16x16x32_bf16 v[44:47], v[136:139], v[200:203], v[44:47]
	v_mfma_f32_16x16x32_bf16 v[40:43], v[164:167], v[200:203], v[40:43]
	v_mfma_f32_16x16x32_bf16 v[36:39], v[136:139], v[208:211], v[36:39]
	v_mfma_f32_16x16x32_bf16 v[28:31], v[164:167], v[208:211], v[28:31]
	v_mfma_f32_16x16x32_bf16 v[20:23], v[136:139], v[216:219], v[20:23]
	v_mfma_f32_16x16x32_bf16 v[12:15], v[164:167], v[216:219], v[12:15]
	v_mfma_f32_16x16x32_bf16 v[60:63], v[140:143], v[196:199], v[60:63]
	v_mfma_f32_16x16x32_bf16 v[56:59], v[168:171], v[196:199], v[56:59]
	v_mfma_f32_16x16x32_bf16 v[44:47], v[140:143], v[204:207], v[44:47]
	v_mfma_f32_16x16x32_bf16 v[40:43], v[168:171], v[204:207], v[40:43]
	v_mfma_f32_16x16x32_bf16 v[36:39], v[140:143], v[212:215], v[36:39]
	v_mfma_f32_16x16x32_bf16 v[28:31], v[168:171], v[212:215], v[28:31]
	v_mfma_f32_16x16x32_bf16 v[20:23], v[140:143], v[220:223], v[20:23]
	v_mfma_f32_16x16x32_bf16 v[12:15], v[168:171], v[220:223], v[12:15]
	s_setprio 0
	s_setprio 1
	v_mfma_f32_16x16x32_bf16 v[52:55], v[172:175], v[192:195], v[52:55]
	v_mfma_f32_16x16x32_bf16 v[48:51], v[184:187], v[192:195], v[48:51]
	v_mfma_f32_16x16x32_bf16 v[32:35], v[172:175], v[200:203], v[32:35]
	v_mfma_f32_16x16x32_bf16 v[24:27], v[184:187], v[200:203], v[24:27]
	v_mfma_f32_16x16x32_bf16 v[16:19], v[172:175], v[208:211], v[16:19]
	v_mfma_f32_16x16x32_bf16 v[8:11], v[184:187], v[208:211], v[8:11]
	v_mfma_f32_16x16x32_bf16 v[4:7], v[172:175], v[216:219], v[4:7]
	v_mfma_f32_16x16x32_bf16 v[0:3], v[184:187], v[216:219], v[0:3]
	v_mfma_f32_16x16x32_bf16 v[52:55], v[180:183], v[196:199], v[52:55]
	v_mfma_f32_16x16x32_bf16 v[48:51], v[188:191], v[196:199], v[48:51]
	v_mfma_f32_16x16x32_bf16 v[32:35], v[180:183], v[204:207], v[32:35]
	v_mfma_f32_16x16x32_bf16 v[24:27], v[188:191], v[204:207], v[24:27]
	v_mfma_f32_16x16x32_bf16 v[16:19], v[180:183], v[212:215], v[16:19]
	v_mfma_f32_16x16x32_bf16 v[8:11], v[188:191], v[212:215], v[8:11]
	v_mfma_f32_16x16x32_bf16 v[4:7], v[180:183], v[220:223], v[4:7]
	v_mfma_f32_16x16x32_bf16 v[0:3], v[188:191], v[220:223], v[0:3]
	s_setprio 0
	s_barrier
	s_add_i32 s67, 0, 0x18000
	s_add_i32 s68, 0, 0x1c000
	v_add_u32_e32 v168, s67, v158
	v_add_u32_e32 v177, s68, v158
	ds_read_b128 v[136:139], v168
	ds_read_b128 v[140:143], v168 offset:1024
	ds_read_b128 v[164:167], v168 offset:2048
	ds_read_b128 v[168:171], v168 offset:3072
	ds_read_b128 v[172:175], v177
	ds_read_b128 v[180:183], v177 offset:1024
	ds_read_b128 v[184:187], v177 offset:2048
	ds_read_b128 v[188:191], v177 offset:3072
	s_add_u32 s62, s62, 0x20000
	s_addc_u32 s63, s63, 0
	s_mov_b32 m0, s79
	v_lshl_add_u64 v[230:231], s[62:63], 0, v[128:129]
	ds_read_b128 v[192:195], v163 offset:32768
	ds_read_b128 v[196:199], v163 offset:33792
	ds_read_b128 v[200:203], v163 offset:34816
	ds_read_b128 v[204:207], v163 offset:35840
	ds_read_b128 v[208:211], v163 offset:36864
	ds_read_b128 v[212:215], v163 offset:37888
	ds_read_b128 v[216:219], v163 offset:38912
	ds_read_b128 v[220:223], v163 offset:39936
	global_load_lds_dwordx4 v[230:231], off
	v_lshl_add_u64 v[230:231], s[62:63], 0, v[130:131]
	s_mov_b32 m0, s80
	s_nop 0
	global_load_lds_dwordx4 v[230:231], off
	s_waitcnt vmcnt(8)
	s_waitcnt lgkmcnt(0)
	s_barrier
	s_setprio 1
	s_waitcnt lgkmcnt(0)
	v_mfma_f32_16x16x32_bf16 v[124:127], v[136:139], v[192:195], v[124:127]
	v_mfma_f32_16x16x32_bf16 v[120:123], v[164:167], v[192:195], v[120:123]
	v_mfma_f32_16x16x32_bf16 v[116:119], v[136:139], v[200:203], v[116:119]
	v_mfma_f32_16x16x32_bf16 v[108:111], v[164:167], v[200:203], v[108:111]
	v_mfma_f32_16x16x32_bf16 v[92:95], v[136:139], v[208:211], v[92:95]
	v_mfma_f32_16x16x32_bf16 v[88:91], v[164:167], v[208:211], v[88:91]
	v_mfma_f32_16x16x32_bf16 v[80:83], v[136:139], v[216:219], v[80:83]
	v_mfma_f32_16x16x32_bf16 v[72:75], v[164:167], v[216:219], v[72:75]
	v_mfma_f32_16x16x32_bf16 v[124:127], v[140:143], v[196:199], v[124:127]
	v_mfma_f32_16x16x32_bf16 v[120:123], v[168:171], v[196:199], v[120:123]
	v_mfma_f32_16x16x32_bf16 v[116:119], v[140:143], v[204:207], v[116:119]
	v_mfma_f32_16x16x32_bf16 v[108:111], v[168:171], v[204:207], v[108:111]
	v_mfma_f32_16x16x32_bf16 v[92:95], v[140:143], v[212:215], v[92:95]
	v_mfma_f32_16x16x32_bf16 v[88:91], v[168:171], v[212:215], v[88:91]
	v_mfma_f32_16x16x32_bf16 v[80:83], v[140:143], v[220:223], v[80:83]
	v_mfma_f32_16x16x32_bf16 v[72:75], v[168:171], v[220:223], v[72:75]
	s_setprio 0
	s_setprio 1
	v_mfma_f32_16x16x32_bf16 v[112:115], v[172:175], v[192:195], v[112:115]
	v_mfma_f32_16x16x32_bf16 v[104:107], v[184:187], v[192:195], v[104:107]
	v_mfma_f32_16x16x32_bf16 v[100:103], v[172:175], v[200:203], v[100:103]
	v_mfma_f32_16x16x32_bf16 v[96:99], v[184:187], v[200:203], v[96:99]
	v_mfma_f32_16x16x32_bf16 v[84:87], v[172:175], v[208:211], v[84:87]
	v_mfma_f32_16x16x32_bf16 v[76:79], v[184:187], v[208:211], v[76:79]
	v_mfma_f32_16x16x32_bf16 v[68:71], v[172:175], v[216:219], v[68:71]
	v_mfma_f32_16x16x32_bf16 v[64:67], v[184:187], v[216:219], v[64:67]
	v_mfma_f32_16x16x32_bf16 v[112:115], v[180:183], v[196:199], v[112:115]
	v_mfma_f32_16x16x32_bf16 v[104:107], v[188:191], v[196:199], v[104:107]
	v_mfma_f32_16x16x32_bf16 v[100:103], v[180:183], v[204:207], v[100:103]
	v_mfma_f32_16x16x32_bf16 v[96:99], v[188:191], v[204:207], v[96:99]
	v_mfma_f32_16x16x32_bf16 v[84:87], v[180:183], v[212:215], v[84:87]
	v_mfma_f32_16x16x32_bf16 v[76:79], v[188:191], v[212:215], v[76:79]
	v_mfma_f32_16x16x32_bf16 v[68:71], v[180:183], v[220:223], v[68:71]
	v_mfma_f32_16x16x32_bf16 v[64:67], v[188:191], v[220:223], v[64:67]
	s_setprio 0
	s_barrier
; #define PG8_STAGE(bufoff, gbase, voff) do { _Pragma("unroll") for (int _i = 0; _i < 2; ++_i) \
;         __builtin_amdgcn_global_load_lds((const unsigned*)((const char*)(gbase) + (voff)[_i]), (PG8_LAS unsigned*)(lds + (bufoff) + ldsw + _i * 8192), 16, 0, 0); } while (0)
; #define PG8_LDA(dst, b, h) do { _Pragma("unroll") for (int m = 0; m < 4; ++m) _Pragma("unroll") for (int k = 0; k < 2; ++k) dst[m][k] = *(const PG8_LAS bf16x8*)(lds + PG8_SA(b, h) + aoff + m * 2048 + k * 1024); } while (0)
; #define PG8_MMA(ai, bj, At, Bt) do { __builtin_amdgcn_s_setprio(1); _Pragma("unroll") for (int m = 0; m < 4; ++m) _Pragma("unroll") for (int n = 0; n < 2; ++n) _Pragma("unroll") for (int k = 0; k < 2; ++k) \
;         acc[ai][bj][m][n] = __builtin_amdgcn_mfma_f32_16x16x32_bf16(Bt[n][k], At[m][k], acc[ai][bj][m][n], 0, 0, 0); __builtin_amdgcn_s_setprio(0); } while (0)
; #define PG8_WAIT_V(n) asm volatile("s_waitcnt vmcnt(" #n ")" ::: "memory")
; #define PG8_WAIT_L(n) asm volatile("s_waitcnt lgkmcnt(" #n ")" ::: "memory")
; #define PG8_BAR __builtin_amdgcn_s_barrier()
; #define PG8_SCHED __builtin_amdgcn_sched_barrier(0)
; template <class Epi, class Sched, bool ALIGN_EPI = false, bool SP2 = false>
; __device__ __forceinline__ void gemm_phase(PG8_LAS unsigned char* lds, const Gemm g, const Sched& S, const Epi& E) {
;     ...
;             PG8_LDA(At, 1, 1); PG8_STAGE(PG8_SB(1, 0), b3, voffB); PG8_STAGE(PG8_SB(1, 1), b3 + hstep, voffB); PG8_STAGE(PG8_SA(1, 0), a3, voffA);
;             PG8_WAIT_V(8); PG8_WAIT_L(0); PG8_BAR; PG8_MMA(1, 0, At, B0); PG8_MMA(1, 1, At, B1); PG8_BAR; PG8_SCHED;
;     __device__ __forceinline__ void operator()(const AccT& acc, const pg8::Unit& u, int wr, int wc, int fr, int fq) const {
;         const int col0 = u.pn * 256 + wc * 32 + 4 * fq, row0 = row_base + u.pm * 256 + wr * 64 + fr;
; #pragma unroll
;         for (int ai = 0; ai < 2; ++ai)
; #pragma unroll
;             for (int m = 0; m < 4; ++m) { const int row = row0 + ai * 128 + m * 16; float ss = 0.f;
; #pragma unroll
;                 for (int bj = 0; bj < 2; ++bj)
; #pragma unroll
;                     for (int n = 0; n < 2; ++n) { f32x4 v = acc[ai][bj][m][n]; const size_t idx = (size_t)row * 1024 + col0 + bj * 128 + n * 16;
;                         if (MODE == 0) v = v * up4(*(const u32x2*)(io + idx));
	s_add_i32 s3, s67, s77
	v_lshl_add_u64 v[144:145], v[144:145], 0, s[10:11]
	s_mov_b32 m0, s3
	ds_read_b128 v[192:195], v163 offset:49152
	ds_read_b128 v[196:199], v163 offset:50176
	ds_read_b128 v[200:203], v163 offset:51200
	ds_read_b128 v[204:207], v163 offset:52224
	ds_read_b128 v[208:211], v163 offset:53248
	ds_read_b128 v[212:215], v163 offset:54272
	ds_read_b128 v[216:219], v163 offset:55296
	ds_read_b128 v[220:223], v163 offset:56320
	global_load_lds_dwordx4 v[144:145], off
	s_add_i32 m0, s3, 0x2000
	s_add_u32 s60, s60, 0x20080
	v_lshl_add_u64 v[144:145], v[224:225], 0, s[10:11]
	s_addc_u32 s61, s61, 0
	s_add_i32 s3, s68, s77
	global_load_lds_dwordx4 v[144:145], off
	v_lshl_add_u64 v[144:145], s[60:61], 0, v[128:129]
	s_mov_b32 m0, s3
	s_nop 0
	global_load_lds_dwordx4 v[144:145], off
	v_lshl_add_u64 v[144:145], s[60:61], 0, v[130:131]
	s_add_i32 m0, s3, 0x2000
	s_nop 0
	global_load_lds_dwordx4 v[144:145], off
	v_lshl_add_u64 v[144:145], v[226:227], 0, s[10:11]
	s_mov_b32 m0, s81
	s_nop 0
	global_load_lds_dwordx4 v[144:145], off
	v_lshl_add_u64 v[144:145], v[228:229], 0, s[10:11]
	s_mov_b32 m0, s82
	s_nop 0
	global_load_lds_dwordx4 v[144:145], off
	s_waitcnt vmcnt(8)
	s_waitcnt lgkmcnt(0)
	s_barrier
	s_setprio 1
	s_waitcnt lgkmcnt(0)
	v_mfma_f32_16x16x32_bf16 v[60:63], v[136:139], v[192:195], v[60:63]
	v_mfma_f32_16x16x32_bf16 v[56:59], v[164:167], v[192:195], v[56:59]
	v_mfma_f32_16x16x32_bf16 v[44:47], v[136:139], v[200:203], v[44:47]
	v_mfma_f32_16x16x32_bf16 v[40:43], v[164:167], v[200:203], v[40:43]
	v_mfma_f32_16x16x32_bf16 v[36:39], v[136:139], v[208:211], v[36:39]
	v_mfma_f32_16x16x32_bf16 v[28:31], v[164:167], v[208:211], v[28:31]
	v_mfma_f32_16x16x32_bf16 v[20:23], v[136:139], v[216:219], v[20:23]
	v_mfma_f32_16x16x32_bf16 v[12:15], v[164:167], v[216:219], v[12:15]
	v_mfma_f32_16x16x32_bf16 v[60:63], v[140:143], v[196:199], v[60:63]
	v_mfma_f32_16x16x32_bf16 v[56:59], v[168:171], v[196:199], v[56:59]
	v_mfma_f32_16x16x32_bf16 v[44:47], v[140:143], v[204:207], v[44:47]
	v_mfma_f32_16x16x32_bf16 v[40:43], v[168:171], v[204:207], v[40:43]
	v_mfma_f32_16x16x32_bf16 v[36:39], v[140:143], v[212:215], v[36:39]
	v_mfma_f32_16x16x32_bf16 v[28:31], v[168:171], v[212:215], v[28:31]
	v_mfma_f32_16x16x32_bf16 v[20:23], v[140:143], v[220:223], v[20:23]
	v_mfma_f32_16x16x32_bf16 v[12:15], v[168:171], v[220:223], v[12:15]
	s_setprio 0
	s_setprio 1
	v_mfma_f32_16x16x32_bf16 v[52:55], v[172:175], v[192:195], v[52:55]
	v_mfma_f32_16x16x32_bf16 v[48:51], v[184:187], v[192:195], v[48:51]
	v_mfma_f32_16x16x32_bf16 v[32:35], v[172:175], v[200:203], v[32:35]
	v_mfma_f32_16x16x32_bf16 v[24:27], v[184:187], v[200:203], v[24:27]
	v_mfma_f32_16x16x32_bf16 v[16:19], v[172:175], v[208:211], v[16:19]
	s_add_i32 s92, s92, 2
	s_add_u32 s46, s46, 0x100
	s_addc_u32 s47, s47, 0
	s_add_u32 s90, s90, 0x100
	s_addc_u32 s91, s91, 0
	s_cmp_gt_u32 s92, 5
	v_mfma_f32_16x16x32_bf16 v[8:11], v[184:187], v[208:211], v[8:11]
	v_mfma_f32_16x16x32_bf16 v[4:7], v[172:175], v[216:219], v[4:7]
	v_mfma_f32_16x16x32_bf16 v[0:3], v[184:187], v[216:219], v[0:3]
	v_mfma_f32_16x16x32_bf16 v[52:55], v[180:183], v[196:199], v[52:55]
	v_mfma_f32_16x16x32_bf16 v[48:51], v[188:191], v[196:199], v[48:51]
	v_mfma_f32_16x16x32_bf16 v[32:35], v[180:183], v[204:207], v[32:35]
	v_mfma_f32_16x16x32_bf16 v[24:27], v[188:191], v[204:207], v[24:27]
	v_mfma_f32_16x16x32_bf16 v[16:19], v[180:183], v[212:215], v[16:19]
	v_mfma_f32_16x16x32_bf16 v[8:11], v[188:191], v[212:215], v[8:11]
	v_mfma_f32_16x16x32_bf16 v[4:7], v[180:183], v[220:223], v[4:7]
	v_mfma_f32_16x16x32_bf16 v[0:3], v[188:191], v[220:223], v[0:3]
	s_setprio 0
	s_barrier
	s_cbranch_scc0 .LBB0_647
	v_lshl_add_u32 v138, s44, 8, v159
	v_lshl_or_b32 v136, s87, 8, v160
	v_ashrrev_i32_e32 v139, 31, v138
	v_ashrrev_i32_e32 v137, 31, v136
	v_lshlrev_b64 v[140:141], 11, v[138:139]
	v_lshl_add_u64 v[140:141], s[4:5], 0, v[140:141]
	v_lshlrev_b64 v[144:145], 1, v[136:137]
	v_lshl_add_u64 v[136:137], v[140:141], 0, v[144:145]
	v_or_b32_e32 v140, 16, v138
	v_ashrrev_i32_e32 v141, 31, v140
	v_lshlrev_b64 v[140:141], 11, v[140:141]
	global_load_dwordx2 v[142:143], v[136:137], off
	global_load_dwordx2 v[164:165], v[136:137], off offset:32
	global_load_dwordx2 v[166:167], v[136:137], off offset:256
	global_load_dwordx2 v[168:169], v[136:137], off offset:288
	v_lshl_add_u64 v[140:141], s[4:5], 0, v[140:141]
	v_lshl_add_u64 v[140:141], v[140:141], 0, v[144:145]
	global_load_dwordx2 v[170:171], v[140:141], off
	global_load_dwordx2 v[172:173], v[140:141], off offset:32
	global_load_dwordx2 v[174:175], v[140:141], off offset:256
	global_load_dwordx2 v[182:183], v[140:141], off offset:288
	v_or_b32_e32 v180, 32, v138
	v_or_b32_e32 v138, 48, v138
	v_ashrrev_i32_e32 v181, 31, v180
	v_ashrrev_i32_e32 v139, 31, v138
	v_lshlrev_b64 v[180:181], 11, v[180:181]
	v_lshlrev_b64 v[138:139], 11, v[138:139]
	v_lshl_add_u64 v[180:181], s[4:5], 0, v[180:181]
	v_lshl_add_u64 v[138:139], s[4:5], 0, v[138:139]
	v_lshl_add_u64 v[180:181], v[180:181], 0, v[144:145]
	v_lshl_add_u64 v[138:139], v[138:139], 0, v[144:145]
	global_load_dwordx2 v[184:185], v[180:181], off
	global_load_dwordx2 v[186:187], v[180:181], off offset:32
	global_load_dwordx2 v[188:189], v[180:181], off offset:256
	global_load_dwordx2 v[190:191], v[180:181], off offset:288
	global_load_dwordx2 v[192:193], v[138:139], off
	global_load_dwordx2 v[144:145], v[138:139], off offset:32
	s_mov_b32 s87, s30
	s_mov_b32 s44, s34
	s_mov_b64 s[60:61], s[42:43]
	s_mov_b64 s[46:47], s[40:41]
	s_waitcnt vmcnt(0)
; __device__ __forceinline__ u32x2 pk4(f32x4 v) { u32x2 w; w.x = cvt_pk_bf16(v[0], v[1]); w.y = cvt_pk_bf16(v[2], v[3]); return w; }
; __device__ __forceinline__ f32x4 up4(u32x2 w) { return (f32x4){bf_lo(w.x), bf_hi(w.x), bf_lo(w.y), bf_hi(w.y)}; }
;     __device__ __forceinline__ void operator()(const AccT& acc, const pg8::Unit& u, int wr, int wc, int fr, int fq) const {
;     ...
;             for (int m = 0; m < 4; ++m) { const int row = row0 + ai * 128 + m * 16; float ss = 0.f;
; #pragma unroll
;                 for (int bj = 0; bj < 2; ++bj)
; #pragma unroll
;                     for (int n = 0; n < 2; ++n) { f32x4 v = acc[ai][bj][m][n]; const size_t idx = (size_t)row * 1024 + col0 + bj * 128 + n * 16;
;                         if (MODE == 0) v = v * up4(*(const u32x2*)(io + idx));
;                         else if (MODE == 1) v = up4(*(const u32x2*)(io + idx)) + up4(*(const u32x2*)(g2 + idx)) * v;
;                         else ss += (v[0] * v[0] + v[1] * v[1]) + (v[2] * v[2] + v[3] * v[3]);
;                         if (!DRYE || v[0] == 123.456f) *(u32x2*)(io + idx) = pk4(v); }
	v_lshlrev_b32_e32 v194, 16, v142
	v_and_b32_e32 v195, 0xffff0000, v142
	v_lshlrev_b32_e32 v142, 16, v143
	v_and_b32_e32 v143, 0xffff0000, v143
	v_lshlrev_b32_e32 v196, 16, v164
	v_and_b32_e32 v197, 0xffff0000, v164
	v_lshlrev_b32_e32 v164, 16, v165
	v_and_b32_e32 v165, 0xffff0000, v165
	v_lshlrev_b32_e32 v198, 16, v166
	v_and_b32_e32 v199, 0xffff0000, v166
	v_lshlrev_b32_e32 v166, 16, v167
	v_and_b32_e32 v167, 0xffff0000, v167
	v_lshlrev_b32_e32 v200, 16, v168
	v_and_b32_e32 v201, 0xffff0000, v168
	v_lshlrev_b32_e32 v168, 16, v169
	v_and_b32_e32 v169, 0xffff0000, v169
	v_pk_mul_f32 v[126:127], v[126:127], v[142:143]
	v_pk_mul_f32 v[124:125], v[124:125], v[194:195]
	v_pk_mul_f32 v[122:123], v[122:123], v[164:165]
	v_pk_mul_f32 v[114:115], v[114:115], v[166:167]
	v_pk_mul_f32 v[112:113], v[112:113], v[198:199]
	v_pk_mul_f32 v[106:107], v[106:107], v[168:169]
	v_pk_mul_f32 v[104:105], v[104:105], v[200:201]
	v_lshlrev_b32_e32 v142, 16, v170
	v_and_b32_e32 v143, 0xffff0000, v170
	v_lshlrev_b32_e32 v164, 16, v171
	v_and_b32_e32 v165, 0xffff0000, v171
	v_lshlrev_b32_e32 v166, 16, v172
	v_and_b32_e32 v167, 0xffff0000, v172
	v_lshlrev_b32_e32 v168, 16, v173
	v_and_b32_e32 v169, 0xffff0000, v173
	v_pk_mul_f32 v[120:121], v[120:121], v[196:197]
	v_cvt_pk_bf16_f32 v124, v124, v125
	v_cvt_pk_bf16_f32 v125, v126, v127
	v_cvt_pk_bf16_f32 v112, v112, v113
	v_cvt_pk_bf16_f32 v113, v114, v115
	v_cvt_pk_bf16_f32 v104, v104, v105
	v_cvt_pk_bf16_f32 v105, v106, v107
	v_pk_mul_f32 v[106:107], v[118:119], v[164:165]
	v_pk_mul_f32 v[114:115], v[116:117], v[142:143]
	v_pk_mul_f32 v[110:111], v[110:111], v[168:169]
	v_pk_mul_f32 v[108:109], v[108:109], v[166:167]
	v_cvt_pk_bf16_f32 v120, v120, v121
	v_cvt_pk_bf16_f32 v121, v122, v123
	global_store_dwordx2 v[136:137], v[124:125], off
	global_store_dwordx2 v[136:137], v[120:121], off offset:32
	global_store_dwordx2 v[136:137], v[112:113], off offset:256
	global_store_dwordx2 v[136:137], v[104:105], off offset:288
	v_cvt_pk_bf16_f32 v104, v114, v115
	v_cvt_pk_bf16_f32 v105, v106, v107
	v_cvt_pk_bf16_f32 v106, v108, v109
	v_cvt_pk_bf16_f32 v107, v110, v111
	global_store_dwordx2 v[140:141], v[104:105], off
	global_store_dwordx2 v[140:141], v[106:107], off offset:32
	v_lshlrev_b32_e32 v104, 16, v174
	v_and_b32_e32 v105, 0xffff0000, v174
	v_lshlrev_b32_e32 v106, 16, v175
	v_and_b32_e32 v107, 0xffff0000, v175
	v_pk_mul_f32 v[102:103], v[102:103], v[106:107]
	v_pk_mul_f32 v[100:101], v[100:101], v[104:105]
	v_lshlrev_b32_e32 v104, 16, v183
	v_cvt_pk_bf16_f32 v100, v100, v101
	v_cvt_pk_bf16_f32 v101, v102, v103
	global_load_dwordx2 v[102:103], v[138:139], off offset:256
	v_and_b32_e32 v105, 0xffff0000, v183
	global_store_dwordx2 v[140:141], v[100:101], off offset:256
	v_lshlrev_b32_e32 v100, 16, v182
	v_and_b32_e32 v101, 0xffff0000, v182
	v_pk_mul_f32 v[98:99], v[98:99], v[104:105]
	v_pk_mul_f32 v[96:97], v[96:97], v[100:101]
	v_lshlrev_b32_e32 v100, 16, v185
	v_cvt_pk_bf16_f32 v96, v96, v97
	v_cvt_pk_bf16_f32 v97, v98, v99
	global_store_dwordx2 v[140:141], v[96:97], off offset:288
	global_load_dwordx2 v[96:97], v[138:139], off offset:288
	v_and_b32_e32 v101, 0xffff0000, v185
	v_pk_mul_f32 v[94:95], v[94:95], v[100:101]
	v_add_co_u32_e32 v100, vcc, s83, v136
	v_lshlrev_b32_e32 v98, 16, v184
	v_and_b32_e32 v99, 0xffff0000, v184
	v_addc_co_u32_e32 v101, vcc, 0, v137, vcc
	global_load_dwordx2 v[104:105], v[100:101], off
	v_pk_mul_f32 v[92:93], v[92:93], v[98:99]
	s_nop 0
	v_cvt_pk_bf16_f32 v92, v92, v93
	v_cvt_pk_bf16_f32 v93, v94, v95
	global_store_dwordx2 v[180:181], v[92:93], off
	v_lshlrev_b32_e32 v92, 16, v186
	v_and_b32_e32 v93, 0xffff0000, v186
	v_lshlrev_b32_e32 v94, 16, v187
	v_and_b32_e32 v95, 0xffff0000, v187
	v_pk_mul_f32 v[90:91], v[90:91], v[94:95]
	v_pk_mul_f32 v[88:89], v[88:89], v[92:93]
	v_lshlrev_b32_e32 v92, 16, v188
	v_cvt_pk_bf16_f32 v88, v88, v89
	v_cvt_pk_bf16_f32 v89, v90, v91
	global_store_dwordx2 v[180:181], v[88:89], off offset:32
	v_lshl_add_u64 v[88:89], v[136:137], 0, s[14:15]
	global_load_dwordx2 v[90:91], v[88:89], off offset:32
	v_and_b32_e32 v93, 0xffff0000, v188
	v_lshlrev_b32_e32 v94, 16, v189
	v_and_b32_e32 v95, 0xffff0000, v189
	v_pk_mul_f32 v[86:87], v[86:87], v[94:95]
	v_pk_mul_f32 v[84:85], v[84:85], v[92:93]
	v_lshlrev_b32_e32 v92, 16, v191
	v_cvt_pk_bf16_f32 v84, v84, v85
	v_cvt_pk_bf16_f32 v85, v86, v87
	global_load_dwordx2 v[86:87], v[88:89], off offset:256
	v_and_b32_e32 v93, 0xffff0000, v191
	global_store_dwordx2 v[180:181], v[84:85], off offset:256
	v_lshlrev_b32_e32 v84, 16, v190
	v_and_b32_e32 v85, 0xffff0000, v190
	v_pk_mul_f32 v[78:79], v[78:79], v[92:93]
	v_pk_mul_f32 v[76:77], v[76:77], v[84:85]
	v_lshlrev_b32_e32 v84, 16, v193
	v_cvt_pk_bf16_f32 v76, v76, v77
	v_cvt_pk_bf16_f32 v77, v78, v79
	global_load_dwordx2 v[78:79], v[88:89], off offset:288
	v_and_b32_e32 v85, 0xffff0000, v193
	global_store_dwordx2 v[180:181], v[76:77], off offset:288
	v_lshlrev_b32_e32 v76, 16, v192
	v_and_b32_e32 v77, 0xffff0000, v192
	v_pk_mul_f32 v[82:83], v[82:83], v[84:85]
	v_pk_mul_f32 v[76:77], v[80:81], v[76:77]
	v_add_co_u32_e32 v80, vcc, s84, v136
	v_cvt_pk_bf16_f32 v76, v76, v77
	v_cvt_pk_bf16_f32 v77, v82, v83
	global_store_dwordx2 v[138:139], v[76:77], off
	v_lshlrev_b32_e32 v76, 16, v144
	v_and_b32_e32 v77, 0xffff0000, v144
	v_addc_co_u32_e32 v81, vcc, 0, v137, vcc
	v_lshlrev_b32_e32 v84, 16, v145
	v_and_b32_e32 v85, 0xffff0000, v145
	global_load_dwordx2 v[82:83], v[80:81], off
	v_pk_mul_f32 v[74:75], v[74:75], v[84:85]
	v_pk_mul_f32 v[72:73], v[72:73], v[76:77]
	s_waitcnt vmcnt(13)
; __device__ __forceinline__ u32x2 pk4(f32x4 v) { u32x2 w; w.x = cvt_pk_bf16(v[0], v[1]); w.y = cvt_pk_bf16(v[2], v[3]); return w; }
; __device__ __forceinline__ f32x4 up4(u32x2 w) { return (f32x4){bf_lo(w.x), bf_hi(w.x), bf_lo(w.y), bf_hi(w.y)}; }
;     __device__ __forceinline__ void operator()(const AccT& acc, const pg8::Unit& u, int wr, int wc, int fr, int fq) const {
;     ...
;             for (int m = 0; m < 4; ++m) { const int row = row0 + ai * 128 + m * 16; float ss = 0.f;
; #pragma unroll
;                 for (int bj = 0; bj < 2; ++bj)
; #pragma unroll
;                     for (int n = 0; n < 2; ++n) { f32x4 v = acc[ai][bj][m][n]; const size_t idx = (size_t)row * 1024 + col0 + bj * 128 + n * 16;
;                         if (MODE == 0) v = v * up4(*(const u32x2*)(io + idx));
;                         else if (MODE == 1) v = up4(*(const u32x2*)(io + idx)) + up4(*(const u32x2*)(g2 + idx)) * v;
;                         else ss += (v[0] * v[0] + v[1] * v[1]) + (v[2] * v[2] + v[3] * v[3]);
;                         if (!DRYE || v[0] == 123.456f) *(u32x2*)(io + idx) = pk4(v); }
	v_lshlrev_b32_e32 v84, 16, v103
	v_cvt_pk_bf16_f32 v72, v72, v73
	v_cvt_pk_bf16_f32 v73, v74, v75
	global_store_dwordx2 v[138:139], v[72:73], off offset:32
	v_lshl_add_u64 v[72:73], v[136:137], 0, s[20:21]
	global_load_dwordx2 v[76:77], v[72:73], off offset:32
	v_lshlrev_b32_e32 v74, 16, v102
	v_and_b32_e32 v75, 0xffff0000, v102
	v_and_b32_e32 v85, 0xffff0000, v103
	v_pk_mul_f32 v[70:71], v[70:71], v[84:85]
	v_pk_mul_f32 v[68:69], v[68:69], v[74:75]
	s_waitcnt vmcnt(12)
	v_lshlrev_b32_e32 v74, 16, v97
	v_cvt_pk_bf16_f32 v68, v68, v69
	v_cvt_pk_bf16_f32 v69, v70, v71
	global_store_dwordx2 v[138:139], v[68:69], off offset:256
	v_lshlrev_b32_e32 v68, 16, v96
	v_and_b32_e32 v69, 0xffff0000, v96
	global_load_dwordx2 v[70:71], v[72:73], off offset:256
	v_and_b32_e32 v75, 0xffff0000, v97
	v_pk_mul_f32 v[66:67], v[66:67], v[74:75]
	v_pk_mul_f32 v[64:65], v[64:65], v[68:69]
	s_waitcnt vmcnt(13)
	v_lshlrev_b32_e32 v68, 16, v105
	v_cvt_pk_bf16_f32 v64, v64, v65
	v_cvt_pk_bf16_f32 v65, v66, v67
	global_store_dwordx2 v[138:139], v[64:65], off offset:288
	v_lshlrev_b32_e32 v64, 16, v104
	v_and_b32_e32 v65, 0xffff0000, v104
	global_load_dwordx2 v[66:67], v[72:73], off offset:288
	v_pk_mul_f32 v[60:61], v[60:61], v[64:65]
	v_add_co_u32_e32 v64, vcc, s85, v136
	v_and_b32_e32 v69, 0xffff0000, v105
	s_nop 0
	v_addc_co_u32_e32 v65, vcc, 0, v137, vcc
	v_pk_mul_f32 v[62:63], v[62:63], v[68:69]
	global_load_dwordx2 v[68:69], v[64:65], off
	v_cvt_pk_bf16_f32 v60, v60, v61
	v_cvt_pk_bf16_f32 v61, v62, v63
	v_lshl_add_u64 v[74:75], v[136:137], 0, s[24:25]
	global_store_dwordx2 v[100:101], v[60:61], off
	s_waitcnt vmcnt(14)
	v_lshlrev_b32_e32 v60, 16, v90
	v_and_b32_e32 v61, 0xffff0000, v90
	v_lshlrev_b32_e32 v62, 16, v91
	v_and_b32_e32 v63, 0xffff0000, v91
	global_load_dwordx2 v[84:85], v[74:75], off offset:32
	v_pk_mul_f32 v[58:59], v[58:59], v[62:63]
	v_pk_mul_f32 v[56:57], v[56:57], v[60:61]
	global_load_dwordx2 v[60:61], v[74:75], off offset:256
	v_cvt_pk_bf16_f32 v56, v56, v57
	v_cvt_pk_bf16_f32 v57, v58, v59
	global_store_dwordx2 v[88:89], v[56:57], off offset:32
	s_waitcnt vmcnt(16)
	v_lshlrev_b32_e32 v56, 16, v86
	v_and_b32_e32 v57, 0xffff0000, v86
	v_lshlrev_b32_e32 v58, 16, v87
	v_and_b32_e32 v59, 0xffff0000, v87
	v_pk_mul_f32 v[54:55], v[54:55], v[58:59]
	v_pk_mul_f32 v[52:53], v[52:53], v[56:57]
	s_waitcnt vmcnt(14)
	v_lshlrev_b32_e32 v56, 16, v79
	v_cvt_pk_bf16_f32 v52, v52, v53
	v_cvt_pk_bf16_f32 v53, v54, v55
	global_store_dwordx2 v[88:89], v[52:53], off offset:256
	v_lshlrev_b32_e32 v52, 16, v78
	v_and_b32_e32 v53, 0xffff0000, v78
	global_load_dwordx2 v[54:55], v[74:75], off offset:288
	v_pk_mul_f32 v[48:49], v[48:49], v[52:53]
	v_add_co_u32_e32 v52, vcc, s86, v136
	v_and_b32_e32 v57, 0xffff0000, v79
	s_nop 0
	v_addc_co_u32_e32 v53, vcc, 0, v137, vcc
	v_pk_mul_f32 v[50:51], v[50:51], v[56:57]
	global_load_dwordx2 v[56:57], v[52:53], off
	v_lshl_add_u64 v[58:59], v[136:137], 0, s[26:27]
	v_cvt_pk_bf16_f32 v48, v48, v49
	v_cvt_pk_bf16_f32 v49, v50, v51
	global_load_dwordx2 v[62:63], v[58:59], off offset:32
	s_waitcnt vmcnt(15)
	v_lshlrev_b32_e32 v50, 16, v83
	global_store_dwordx2 v[88:89], v[48:49], off offset:288
	v_lshlrev_b32_e32 v48, 16, v82
	v_and_b32_e32 v49, 0xffff0000, v82
	v_and_b32_e32 v51, 0xffff0000, v83
	v_pk_mul_f32 v[46:47], v[46:47], v[50:51]
	v_pk_mul_f32 v[44:45], v[44:45], v[48:49]
	global_load_dwordx2 v[48:49], v[58:59], off offset:256
	v_cvt_pk_bf16_f32 v44, v44, v45
	v_cvt_pk_bf16_f32 v45, v46, v47
	global_store_dwordx2 v[80:81], v[44:45], off
	s_waitcnt vmcnt(16)
	v_lshlrev_b32_e32 v44, 16, v76
	v_and_b32_e32 v45, 0xffff0000, v76
	v_lshlrev_b32_e32 v46, 16, v77
	v_and_b32_e32 v47, 0xffff0000, v77
	v_pk_mul_f32 v[42:43], v[42:43], v[46:47]
	v_pk_mul_f32 v[40:41], v[40:41], v[44:45]
	s_and_b64 vcc, exec, s[28:29]
	v_cvt_pk_bf16_f32 v40, v40, v41
	v_cvt_pk_bf16_f32 v41, v42, v43
	global_load_dwordx2 v[42:43], v[58:59], off offset:288
	s_waitcnt vmcnt(15)
; #define PG8_WAIT_V(n) asm volatile("s_waitcnt vmcnt(" #n ")" ::: "memory")
; #define PG8_BAR __builtin_amdgcn_s_barrier()
; __device__ __forceinline__ u32x2 pk4(f32x4 v) { u32x2 w; w.x = cvt_pk_bf16(v[0], v[1]); w.y = cvt_pk_bf16(v[2], v[3]); return w; }
; __device__ __forceinline__ f32x4 up4(u32x2 w) { return (f32x4){bf_lo(w.x), bf_hi(w.x), bf_lo(w.y), bf_hi(w.y)}; }
; template <class Epi, class Sched, bool ALIGN_EPI = false, bool SP2 = false>
; __device__ __forceinline__ void gemm_phase(PG8_LAS unsigned char* lds, const Gemm g, const Sched& S, const Epi& E) {
;     ...
;         if (!has_next) break;
;     ...
;     PG8_WAIT_V(0);
;     if constexpr (!ALIGN_EPI) { if (wr == 0) PG8_BAR; }
;     __device__ __forceinline__ void operator()(const AccT& acc, const pg8::Unit& u, int wr, int wc, int fr, int fq) const {
;     ...
;             for (int m = 0; m < 4; ++m) { const int row = row0 + ai * 128 + m * 16; float ss = 0.f;
; #pragma unroll
;                 for (int bj = 0; bj < 2; ++bj)
; #pragma unroll
;                     for (int n = 0; n < 2; ++n) { f32x4 v = acc[ai][bj][m][n]; const size_t idx = (size_t)row * 1024 + col0 + bj * 128 + n * 16;
;                         if (MODE == 0) v = v * up4(*(const u32x2*)(io + idx));
;                         else if (MODE == 1) v = up4(*(const u32x2*)(io + idx)) + up4(*(const u32x2*)(g2 + idx)) * v;
;                         else ss += (v[0] * v[0] + v[1] * v[1]) + (v[2] * v[2] + v[3] * v[3]);
;                         if (!DRYE || v[0] == 123.456f) *(u32x2*)(io + idx) = pk4(v); }
	v_lshlrev_b32_e32 v44, 16, v71
	global_store_dwordx2 v[72:73], v[40:41], off offset:32
	v_lshlrev_b32_e32 v40, 16, v70
	v_and_b32_e32 v41, 0xffff0000, v70
	v_and_b32_e32 v45, 0xffff0000, v71
	v_pk_mul_f32 v[34:35], v[34:35], v[44:45]
	v_pk_mul_f32 v[32:33], v[32:33], v[40:41]
	s_nop 0
	v_cvt_pk_bf16_f32 v32, v32, v33
	v_cvt_pk_bf16_f32 v33, v34, v35
	global_store_dwordx2 v[72:73], v[32:33], off offset:256
	s_waitcnt vmcnt(15)
	v_lshlrev_b32_e32 v32, 16, v66
	v_and_b32_e32 v33, 0xffff0000, v66
	v_lshlrev_b32_e32 v34, 16, v67
	v_and_b32_e32 v35, 0xffff0000, v67
	v_pk_mul_f32 v[26:27], v[26:27], v[34:35]
	v_pk_mul_f32 v[24:25], v[24:25], v[32:33]
	s_nop 0
	v_cvt_pk_bf16_f32 v24, v24, v25
	v_cvt_pk_bf16_f32 v25, v26, v27
	global_store_dwordx2 v[72:73], v[24:25], off offset:288
	s_waitcnt vmcnt(15)
	v_lshlrev_b32_e32 v24, 16, v68
	v_and_b32_e32 v25, 0xffff0000, v68
	v_lshlrev_b32_e32 v26, 16, v69
	v_and_b32_e32 v27, 0xffff0000, v69
	v_pk_mul_f32 v[26:27], v[38:39], v[26:27]
	v_pk_mul_f32 v[24:25], v[36:37], v[24:25]
	s_nop 0
	v_cvt_pk_bf16_f32 v24, v24, v25
	v_cvt_pk_bf16_f32 v25, v26, v27
	global_store_dwordx2 v[64:65], v[24:25], off
	s_waitcnt vmcnt(14)
	v_lshlrev_b32_e32 v24, 16, v84
	v_and_b32_e32 v25, 0xffff0000, v84
	v_lshlrev_b32_e32 v26, 16, v85
	v_and_b32_e32 v27, 0xffff0000, v85
	v_pk_mul_f32 v[26:27], v[30:31], v[26:27]
	v_pk_mul_f32 v[24:25], v[28:29], v[24:25]
	s_nop 0
	v_cvt_pk_bf16_f32 v24, v24, v25
	v_cvt_pk_bf16_f32 v25, v26, v27
	global_store_dwordx2 v[74:75], v[24:25], off offset:32
	s_waitcnt vmcnt(14)
	v_lshlrev_b32_e32 v24, 16, v60
	v_and_b32_e32 v25, 0xffff0000, v60
	v_lshlrev_b32_e32 v26, 16, v61
	v_and_b32_e32 v27, 0xffff0000, v61
	v_pk_mul_f32 v[18:19], v[18:19], v[26:27]
	v_pk_mul_f32 v[16:17], v[16:17], v[24:25]
	s_nop 0
	v_cvt_pk_bf16_f32 v16, v16, v17
	v_cvt_pk_bf16_f32 v17, v18, v19
	global_store_dwordx2 v[74:75], v[16:17], off offset:256
	s_waitcnt vmcnt(12)
	v_lshlrev_b32_e32 v16, 16, v54
	v_and_b32_e32 v17, 0xffff0000, v54
	v_lshlrev_b32_e32 v18, 16, v55
	v_and_b32_e32 v19, 0xffff0000, v55
	v_pk_mul_f32 v[10:11], v[10:11], v[18:19]
	v_pk_mul_f32 v[8:9], v[8:9], v[16:17]
	s_nop 0
	v_cvt_pk_bf16_f32 v8, v8, v9
	v_cvt_pk_bf16_f32 v9, v10, v11
	global_store_dwordx2 v[74:75], v[8:9], off offset:288
	s_waitcnt vmcnt(12)
	v_lshlrev_b32_e32 v8, 16, v56
	v_and_b32_e32 v9, 0xffff0000, v56
	v_lshlrev_b32_e32 v10, 16, v57
	v_and_b32_e32 v11, 0xffff0000, v57
	v_pk_mul_f32 v[10:11], v[22:23], v[10:11]
	v_pk_mul_f32 v[8:9], v[20:21], v[8:9]
	s_nop 0
	v_cvt_pk_bf16_f32 v8, v8, v9
	v_cvt_pk_bf16_f32 v9, v10, v11
	global_store_dwordx2 v[52:53], v[8:9], off
	s_waitcnt vmcnt(12)
	v_lshlrev_b32_e32 v8, 16, v62
	v_and_b32_e32 v9, 0xffff0000, v62
	v_lshlrev_b32_e32 v10, 16, v63
	v_and_b32_e32 v11, 0xffff0000, v63
	v_pk_mul_f32 v[10:11], v[14:15], v[10:11]
	v_pk_mul_f32 v[8:9], v[12:13], v[8:9]
	s_nop 0
	v_cvt_pk_bf16_f32 v8, v8, v9
	v_cvt_pk_bf16_f32 v9, v10, v11
	global_store_dwordx2 v[58:59], v[8:9], off offset:32
	s_waitcnt vmcnt(11)
	v_lshlrev_b32_e32 v8, 16, v48
	v_and_b32_e32 v9, 0xffff0000, v48
	v_lshlrev_b32_e32 v10, 16, v49
	v_and_b32_e32 v11, 0xffff0000, v49
	v_pk_mul_f32 v[6:7], v[6:7], v[10:11]
	v_pk_mul_f32 v[4:5], v[4:5], v[8:9]
	s_nop 0
	v_cvt_pk_bf16_f32 v4, v4, v5
	v_cvt_pk_bf16_f32 v5, v6, v7
	global_store_dwordx2 v[58:59], v[4:5], off offset:256
	s_waitcnt vmcnt(10)
	v_lshlrev_b32_e32 v4, 16, v42
	v_and_b32_e32 v5, 0xffff0000, v42
	v_lshlrev_b32_e32 v6, 16, v43
	v_and_b32_e32 v7, 0xffff0000, v43
	v_pk_mul_f32 v[2:3], v[2:3], v[6:7]
	v_pk_mul_f32 v[0:1], v[0:1], v[4:5]
	s_nop 0
	v_cvt_pk_bf16_f32 v0, v0, v1
	v_cvt_pk_bf16_f32 v1, v2, v3
	global_store_dwordx2 v[58:59], v[0:1], off offset:288
	s_cbranch_vccz .LBB0_640
	s_waitcnt vmcnt(0)
	s_cmpk_gt_u32 s71, 0xff
	s_cbranch_scc1 .LBB0_651
	s_barrier

; #define PG8_STAGE(bufoff, gbase, voff) do { _Pragma("unroll") for (int _i = 0; _i < 2; ++_i) \
;         __builtin_amdgcn_global_load_lds((const unsigned*)((const char*)(gbase) + (voff)[_i]), (PG8_LAS unsigned*)(lds + (bufoff) + ldsw + _i * 8192), 16, 0, 0); } while (0)
; #define PG8_LDA(dst, b, h) do { _Pragma("unroll") for (int m = 0; m < 4; ++m) _Pragma("unroll") for (int k = 0; k < 2; ++k) dst[m][k] = *(const PG8_LAS bf16x8*)(lds + PG8_SA(b, h) + aoff + m * 2048 + k * 1024); } while (0)
; #define PG8_LDB(dst, b, h) do { _Pragma("unroll") for (int n = 0; n < 2; ++n) _Pragma("unroll") for (int k = 0; k < 2; ++k) dst[n][k] = *(const PG8_LAS bf16x8*)(lds + PG8_SB(b, h) + boff + n * 2048 + k * 1024); } while (0)
; #define PG8_MMA(ai, bj, At, Bt) do { __builtin_amdgcn_s_setprio(1); _Pragma("unroll") for (int m = 0; m < 4; ++m) _Pragma("unroll") for (int n = 0; n < 2; ++n) _Pragma("unroll") for (int k = 0; k < 2; ++k) \
;         acc[ai][bj][m][n] = __builtin_amdgcn_mfma_f32_16x16x32_bf16(Bt[n][k], At[m][k], acc[ai][bj][m][n], 0, 0, 0); __builtin_amdgcn_s_setprio(0); } while (0)
; #define PG8_BAR __builtin_amdgcn_s_barrier()
; template <class Epi, class Sched, bool ALIGN_EPI = false, bool SP2 = false>
; __device__ __forceinline__ void gemm_phase(PG8_LAS unsigned char* lds, const Gemm g, const Sched& S, const Epi& E) {
;     ...
;         const bool has_next = S.next(ui + 1, nxt);
;         const char* nA = has_next ? (const char*)g.A + (size_t)nxt.pm * tstep : cA; const char* nB = has_next ? (const char*)g.Bt + (size_t)nxt.pn * tstep : cB;
;         for (int t = 0; t < nt; t += 2) {
;             const bool last = (t == nt - 2);
;             const char* a1 = cA + (size_t)(t + 1) * kstep;
;             const char* a2 = last ? nA : cA + (size_t)(t + 2) * kstep; const char* b2 = last ? nB : cB + (size_t)(t + 2) * kstep;
;             const char* a3 = a2 + kstep; const char* b3 = b2 + kstep;
;             if (last && has_next) S.a_ready(nxt);
;             if constexpr (SP2) {
;             PG8_LDB(B0, 0, 0); PG8_LDB(B1, 0, 1); PG8_SCHED; PG8_LDA(At, 0, 0); PG8_STAGE(PG8_SA(1, 1), a1 + hstep, voffA);
;             PG8_WAIT_V(8); PG8_WAIT_L(0); PG8_BAR; PG8_MMA(0, 0, At, B0); PG8_MMA(0, 1, At, B1); PG8_BAR; PG8_SCHED;
;             PG8_LDA(At, 0, 1); PG8_STAGE(PG8_SB(0, 0), b2, voffB); PG8_STAGE(PG8_SB(0, 1), b2 + hstep, voffB); PG8_STAGE(PG8_SA(0, 0), a2, voffA);
.LBB0_665:
	ds_read_b128 v[144:147], v141
	ds_read_b128 v[148:151], v141 offset:1024
	ds_read_b128 v[152:155], v141 offset:2048
	ds_read_b128 v[156:159], v141 offset:3072
	ds_read_b128 v[160:163], v142
	ds_read_b128 v[164:167], v142 offset:1024
	ds_read_b128 v[168:171], v142 offset:2048
	ds_read_b128 v[172:175], v142 offset:3072
	s_add_u32 s3, s40, 0xfffc0080
	s_addc_u32 s33, s41, -1
	s_cmp_eq_u32 s77, 12
	s_cselect_b32 s45, s21, s33
	s_cselect_b32 s44, s73, s3
	s_cselect_b32 s43, s15, s76
	s_cselect_b32 s42, s74, s75
	v_lshl_add_u64 v[136:137], s[40:41], 0, v[132:133]
	s_add_i32 m0, s31, 0xc000
	ds_read_b128 v[180:183], v143
	ds_read_b128 v[184:187], v143 offset:1024
	ds_read_b128 v[188:191], v143 offset:2048
	ds_read_b128 v[192:195], v143 offset:3072
	ds_read_b128 v[196:199], v143 offset:4096
	ds_read_b128 v[200:203], v143 offset:5120
	ds_read_b128 v[204:207], v143 offset:6144
	ds_read_b128 v[208:211], v143 offset:7168
	global_load_lds_dwordx4 v[136:137], off
	v_lshl_add_u64 v[136:137], s[40:41], 0, v[134:135]
	s_add_i32 m0, s31, 0xe000
	s_nop 0
	global_load_lds_dwordx4 v[136:137], off
	s_waitcnt vmcnt(8)
	s_waitcnt lgkmcnt(0)
	s_barrier
	s_setprio 1
	s_waitcnt lgkmcnt(0)
	v_mfma_f32_16x16x32_bf16 v[124:127], v[144:147], v[180:183], v[124:127]
	v_mfma_f32_16x16x32_bf16 v[120:123], v[152:155], v[180:183], v[120:123]
	v_mfma_f32_16x16x32_bf16 v[108:111], v[144:147], v[188:191], v[108:111]
	v_mfma_f32_16x16x32_bf16 v[104:107], v[152:155], v[188:191], v[104:107]
	v_mfma_f32_16x16x32_bf16 v[92:95], v[144:147], v[196:199], v[92:95]
	v_mfma_f32_16x16x32_bf16 v[88:91], v[152:155], v[196:199], v[88:91]
	v_mfma_f32_16x16x32_bf16 v[76:79], v[144:147], v[204:207], v[76:79]
	v_mfma_f32_16x16x32_bf16 v[72:75], v[152:155], v[204:207], v[72:75]
	v_mfma_f32_16x16x32_bf16 v[124:127], v[148:151], v[184:187], v[124:127]
	v_mfma_f32_16x16x32_bf16 v[120:123], v[156:159], v[184:187], v[120:123]
	v_mfma_f32_16x16x32_bf16 v[108:111], v[148:151], v[192:195], v[108:111]
	v_mfma_f32_16x16x32_bf16 v[104:107], v[156:159], v[192:195], v[104:107]
	v_mfma_f32_16x16x32_bf16 v[92:95], v[148:151], v[200:203], v[92:95]
	v_mfma_f32_16x16x32_bf16 v[88:91], v[156:159], v[200:203], v[88:91]
	v_mfma_f32_16x16x32_bf16 v[76:79], v[148:151], v[208:211], v[76:79]
	v_mfma_f32_16x16x32_bf16 v[72:75], v[156:159], v[208:211], v[72:75]
	s_setprio 0
	s_setprio 1
	v_mfma_f32_16x16x32_bf16 v[116:119], v[160:163], v[180:183], v[116:119]
	v_mfma_f32_16x16x32_bf16 v[112:115], v[168:171], v[180:183], v[112:115]
	v_mfma_f32_16x16x32_bf16 v[100:103], v[160:163], v[188:191], v[100:103]
	v_mfma_f32_16x16x32_bf16 v[96:99], v[168:171], v[188:191], v[96:99]
	v_mfma_f32_16x16x32_bf16 v[84:87], v[160:163], v[196:199], v[84:87]
	v_mfma_f32_16x16x32_bf16 v[80:83], v[168:171], v[196:199], v[80:83]
	v_mfma_f32_16x16x32_bf16 v[68:71], v[160:163], v[204:207], v[68:71]
	v_mfma_f32_16x16x32_bf16 v[64:67], v[168:171], v[204:207], v[64:67]
	v_mfma_f32_16x16x32_bf16 v[116:119], v[164:167], v[184:187], v[116:119]
	v_mfma_f32_16x16x32_bf16 v[112:115], v[172:175], v[184:187], v[112:115]
	v_mfma_f32_16x16x32_bf16 v[100:103], v[164:167], v[192:195], v[100:103]
	v_mfma_f32_16x16x32_bf16 v[96:99], v[172:175], v[192:195], v[96:99]
	v_mfma_f32_16x16x32_bf16 v[84:87], v[164:167], v[200:203], v[84:87]
	v_mfma_f32_16x16x32_bf16 v[80:83], v[172:175], v[200:203], v[80:83]
	v_mfma_f32_16x16x32_bf16 v[68:71], v[164:167], v[208:211], v[68:71]
	v_mfma_f32_16x16x32_bf16 v[64:67], v[172:175], v[208:211], v[64:67]
	s_setprio 0
	s_barrier
	s_add_i32 s3, s65, s63
	v_lshl_add_u64 v[136:137], s[42:43], 0, v[128:129]
	s_mov_b32 m0, s3
	ds_read_b128 v[180:183], v143 offset:16384
	ds_read_b128 v[184:187], v143 offset:17408
	ds_read_b128 v[188:191], v143 offset:18432
	ds_read_b128 v[192:195], v143 offset:19456
	ds_read_b128 v[196:199], v143 offset:20480
	ds_read_b128 v[200:203], v143 offset:21504
	ds_read_b128 v[204:207], v143 offset:22528
	ds_read_b128 v[208:211], v143 offset:23552
	global_load_lds_dwordx4 v[136:137], off
	s_add_i32 m0, s3, 0x2000
	s_add_u32 s78, s42, 0x40000
	v_lshl_add_u64 v[212:213], s[42:43], 0, v[130:131]
	s_addc_u32 s79, s43, 0
	s_add_i32 s3, s66, s63
	global_load_lds_dwordx4 v[212:213], off
	v_lshl_add_u64 v[214:215], s[78:79], 0, v[128:129]
	s_mov_b32 m0, s3
	v_lshl_add_u64 v[216:217], s[44:45], 0, v[130:131]
	global_load_lds_dwordx4 v[214:215], off
	v_lshl_add_u64 v[214:215], s[78:79], 0, v[130:131]
	s_add_i32 m0, s3, 0x2000
	s_nop 0
	global_load_lds_dwordx4 v[214:215], off
	v_lshl_add_u64 v[214:215], s[44:45], 0, v[128:129]
	s_mov_b32 m0, s31
	s_nop 0
	global_load_lds_dwordx4 v[214:215], off
	s_mov_b32 m0, s35
	s_nop 0
	global_load_lds_dwordx4 v[216:217], off
	s_waitcnt vmcnt(8)
	s_waitcnt lgkmcnt(0)
	s_barrier
; #define PG8_STAGE(bufoff, gbase, voff) do { _Pragma("unroll") for (int _i = 0; _i < 2; ++_i) \
;         __builtin_amdgcn_global_load_lds((const unsigned*)((const char*)(gbase) + (voff)[_i]), (PG8_LAS unsigned*)(lds + (bufoff) + ldsw + _i * 8192), 16, 0, 0); } while (0)
; #define PG8_LDA(dst, b, h) do { _Pragma("unroll") for (int m = 0; m < 4; ++m) _Pragma("unroll") for (int k = 0; k < 2; ++k) dst[m][k] = *(const PG8_LAS bf16x8*)(lds + PG8_SA(b, h) + aoff + m * 2048 + k * 1024); } while (0)
; #define PG8_LDB(dst, b, h) do { _Pragma("unroll") for (int n = 0; n < 2; ++n) _Pragma("unroll") for (int k = 0; k < 2; ++k) dst[n][k] = *(const PG8_LAS bf16x8*)(lds + PG8_SB(b, h) + boff + n * 2048 + k * 1024); } while (0)
; #define PG8_MMA(ai, bj, At, Bt) do { __builtin_amdgcn_s_setprio(1); _Pragma("unroll") for (int m = 0; m < 4; ++m) _Pragma("unroll") for (int n = 0; n < 2; ++n) _Pragma("unroll") for (int k = 0; k < 2; ++k) \
;         acc[ai][bj][m][n] = __builtin_amdgcn_mfma_f32_16x16x32_bf16(Bt[n][k], At[m][k], acc[ai][bj][m][n], 0, 0, 0); __builtin_amdgcn_s_setprio(0); } while (0)
; #define PG8_WAIT_V(n) asm volatile("s_waitcnt vmcnt(" #n ")" ::: "memory")
; #define PG8_WAIT_L(n) asm volatile("s_waitcnt lgkmcnt(" #n ")" ::: "memory")
; #define PG8_BAR __builtin_amdgcn_s_barrier()
; #define PG8_SCHED __builtin_amdgcn_sched_barrier(0)
; template <class Epi, class Sched, bool ALIGN_EPI = false, bool SP2 = false>
; __device__ __forceinline__ void gemm_phase(PG8_LAS unsigned char* lds, const Gemm g, const Sched& S, const Epi& E) {
;     ...
;             PG8_WAIT_V(8); PG8_WAIT_L(0); PG8_BAR; PG8_MMA(1, 0, At, B0); PG8_MMA(1, 1, At, B1); PG8_BAR; PG8_SCHED;
;             PG8_LDB(B0, 1, 0); PG8_LDB(B1, 1, 1); PG8_SCHED; PG8_LDA(At, 1, 0); PG8_STAGE(PG8_SA(0, 1), a2 + hstep, voffA);
;             PG8_WAIT_V(8); PG8_WAIT_L(0); PG8_BAR; PG8_MMA(0, 0, At, B0); PG8_MMA(0, 1, At, B1); PG8_BAR; PG8_SCHED;
	s_setprio 1
	s_waitcnt lgkmcnt(0)
	v_mfma_f32_16x16x32_bf16 v[60:63], v[144:147], v[180:183], v[60:63]
	v_mfma_f32_16x16x32_bf16 v[56:59], v[152:155], v[180:183], v[56:59]
	v_mfma_f32_16x16x32_bf16 v[44:47], v[144:147], v[188:191], v[44:47]
	v_mfma_f32_16x16x32_bf16 v[40:43], v[152:155], v[188:191], v[40:43]
	v_mfma_f32_16x16x32_bf16 v[28:31], v[144:147], v[196:199], v[28:31]
	v_mfma_f32_16x16x32_bf16 v[24:27], v[152:155], v[196:199], v[24:27]
	v_mfma_f32_16x16x32_bf16 v[12:15], v[144:147], v[204:207], v[12:15]
	v_mfma_f32_16x16x32_bf16 v[8:11], v[152:155], v[204:207], v[8:11]
	v_mfma_f32_16x16x32_bf16 v[60:63], v[148:151], v[184:187], v[60:63]
	v_mfma_f32_16x16x32_bf16 v[56:59], v[156:159], v[184:187], v[56:59]
	v_mfma_f32_16x16x32_bf16 v[44:47], v[148:151], v[192:195], v[44:47]
	v_mfma_f32_16x16x32_bf16 v[40:43], v[156:159], v[192:195], v[40:43]
	v_mfma_f32_16x16x32_bf16 v[28:31], v[148:151], v[200:203], v[28:31]
	v_mfma_f32_16x16x32_bf16 v[24:27], v[156:159], v[200:203], v[24:27]
	v_mfma_f32_16x16x32_bf16 v[12:15], v[148:151], v[208:211], v[12:15]
	v_mfma_f32_16x16x32_bf16 v[8:11], v[156:159], v[208:211], v[8:11]
	s_setprio 0
	s_setprio 1
	v_mfma_f32_16x16x32_bf16 v[52:55], v[160:163], v[180:183], v[52:55]
	v_mfma_f32_16x16x32_bf16 v[48:51], v[168:171], v[180:183], v[48:51]
	v_mfma_f32_16x16x32_bf16 v[36:39], v[160:163], v[188:191], v[36:39]
	v_mfma_f32_16x16x32_bf16 v[32:35], v[168:171], v[188:191], v[32:35]
	v_mfma_f32_16x16x32_bf16 v[20:23], v[160:163], v[196:199], v[20:23]
	v_mfma_f32_16x16x32_bf16 v[16:19], v[168:171], v[196:199], v[16:19]
	v_mfma_f32_16x16x32_bf16 v[4:7], v[160:163], v[204:207], v[4:7]
	v_mfma_f32_16x16x32_bf16 v[0:3], v[168:171], v[204:207], v[0:3]
	v_mfma_f32_16x16x32_bf16 v[52:55], v[164:167], v[184:187], v[52:55]
	v_mfma_f32_16x16x32_bf16 v[48:51], v[172:175], v[184:187], v[48:51]
	v_mfma_f32_16x16x32_bf16 v[36:39], v[164:167], v[192:195], v[36:39]
	v_mfma_f32_16x16x32_bf16 v[32:35], v[172:175], v[192:195], v[32:35]
	v_mfma_f32_16x16x32_bf16 v[20:23], v[164:167], v[200:203], v[20:23]
	v_mfma_f32_16x16x32_bf16 v[16:19], v[172:175], v[200:203], v[16:19]
	v_mfma_f32_16x16x32_bf16 v[4:7], v[164:167], v[208:211], v[4:7]
	v_mfma_f32_16x16x32_bf16 v[0:3], v[172:175], v[208:211], v[0:3]
	s_setprio 0
	s_barrier
	v_add_u32_e32 v156, s67, v139
	v_add_u32_e32 v172, s68, v139
	ds_read_b128 v[144:147], v156
	ds_read_b128 v[148:151], v156 offset:1024
	ds_read_b128 v[152:155], v156 offset:2048
	ds_read_b128 v[156:159], v156 offset:3072
	ds_read_b128 v[160:163], v172
	ds_read_b128 v[164:167], v172 offset:1024
	ds_read_b128 v[168:171], v172 offset:2048
	ds_read_b128 v[172:175], v172 offset:3072
	s_add_u32 s44, s44, 0x40000
	s_addc_u32 s45, s45, 0
	s_mov_b32 m0, s69
	v_lshl_add_u64 v[218:219], s[44:45], 0, v[128:129]
	ds_read_b128 v[180:183], v143 offset:32768
	ds_read_b128 v[184:187], v143 offset:33792
	ds_read_b128 v[188:191], v143 offset:34816
	ds_read_b128 v[192:195], v143 offset:35840
	ds_read_b128 v[196:199], v143 offset:36864
	ds_read_b128 v[200:203], v143 offset:37888
	ds_read_b128 v[204:207], v143 offset:38912
	ds_read_b128 v[208:211], v143 offset:39936
	global_load_lds_dwordx4 v[218:219], off
	v_lshl_add_u64 v[218:219], s[44:45], 0, v[130:131]
	s_mov_b32 m0, s70
	s_nop 0
	global_load_lds_dwordx4 v[218:219], off
	s_waitcnt vmcnt(8)
	s_waitcnt lgkmcnt(0)
	s_barrier
	s_setprio 1
	s_waitcnt lgkmcnt(0)
	v_mfma_f32_16x16x32_bf16 v[124:127], v[144:147], v[180:183], v[124:127]
	v_mfma_f32_16x16x32_bf16 v[120:123], v[152:155], v[180:183], v[120:123]
	v_mfma_f32_16x16x32_bf16 v[108:111], v[144:147], v[188:191], v[108:111]
	v_mfma_f32_16x16x32_bf16 v[104:107], v[152:155], v[188:191], v[104:107]
	v_mfma_f32_16x16x32_bf16 v[92:95], v[144:147], v[196:199], v[92:95]
	v_mfma_f32_16x16x32_bf16 v[88:91], v[152:155], v[196:199], v[88:91]
	v_mfma_f32_16x16x32_bf16 v[76:79], v[144:147], v[204:207], v[76:79]
	v_mfma_f32_16x16x32_bf16 v[72:75], v[152:155], v[204:207], v[72:75]
	v_mfma_f32_16x16x32_bf16 v[124:127], v[148:151], v[184:187], v[124:127]
	v_mfma_f32_16x16x32_bf16 v[120:123], v[156:159], v[184:187], v[120:123]
	v_mfma_f32_16x16x32_bf16 v[108:111], v[148:151], v[192:195], v[108:111]
	v_mfma_f32_16x16x32_bf16 v[104:107], v[156:159], v[192:195], v[104:107]
	v_mfma_f32_16x16x32_bf16 v[92:95], v[148:151], v[200:203], v[92:95]
	v_mfma_f32_16x16x32_bf16 v[88:91], v[156:159], v[200:203], v[88:91]
	v_mfma_f32_16x16x32_bf16 v[76:79], v[148:151], v[208:211], v[76:79]
	v_mfma_f32_16x16x32_bf16 v[72:75], v[156:159], v[208:211], v[72:75]
	s_setprio 0
	s_setprio 1
	v_mfma_f32_16x16x32_bf16 v[116:119], v[160:163], v[180:183], v[116:119]
	v_mfma_f32_16x16x32_bf16 v[112:115], v[168:171], v[180:183], v[112:115]
	v_mfma_f32_16x16x32_bf16 v[100:103], v[160:163], v[188:191], v[100:103]
	v_mfma_f32_16x16x32_bf16 v[96:99], v[168:171], v[188:191], v[96:99]
	v_mfma_f32_16x16x32_bf16 v[84:87], v[160:163], v[196:199], v[84:87]
	v_mfma_f32_16x16x32_bf16 v[80:83], v[168:171], v[196:199], v[80:83]
	v_mfma_f32_16x16x32_bf16 v[68:71], v[160:163], v[204:207], v[68:71]
	v_mfma_f32_16x16x32_bf16 v[64:67], v[168:171], v[204:207], v[64:67]
	v_mfma_f32_16x16x32_bf16 v[116:119], v[164:167], v[184:187], v[116:119]
	v_mfma_f32_16x16x32_bf16 v[112:115], v[172:175], v[184:187], v[112:115]
	v_mfma_f32_16x16x32_bf16 v[100:103], v[164:167], v[192:195], v[100:103]
	v_mfma_f32_16x16x32_bf16 v[96:99], v[172:175], v[192:195], v[96:99]
	v_mfma_f32_16x16x32_bf16 v[84:87], v[164:167], v[200:203], v[84:87]
	v_mfma_f32_16x16x32_bf16 v[80:83], v[172:175], v[200:203], v[80:83]
	v_mfma_f32_16x16x32_bf16 v[68:71], v[164:167], v[208:211], v[68:71]
	v_mfma_f32_16x16x32_bf16 v[64:67], v[172:175], v[208:211], v[64:67]
	s_setprio 0
	s_barrier
; #define PG8_STAGE(bufoff, gbase, voff) do { _Pragma("unroll") for (int _i = 0; _i < 2; ++_i) \
;         __builtin_amdgcn_global_load_lds((const unsigned*)((const char*)(gbase) + (voff)[_i]), (PG8_LAS unsigned*)(lds + (bufoff) + ldsw + _i * 8192), 16, 0, 0); } while (0)
; #define PG8_LDA(dst, b, h) do { _Pragma("unroll") for (int m = 0; m < 4; ++m) _Pragma("unroll") for (int k = 0; k < 2; ++k) dst[m][k] = *(const PG8_LAS bf16x8*)(lds + PG8_SA(b, h) + aoff + m * 2048 + k * 1024); } while (0)
; #define PG8_WAIT_V(n) asm volatile("s_waitcnt vmcnt(" #n ")" ::: "memory")
; #define PG8_WAIT_L(n) asm volatile("s_waitcnt lgkmcnt(" #n ")" ::: "memory")
; #define PG8_BAR __builtin_amdgcn_s_barrier()
; template <class Epi, class Sched, bool ALIGN_EPI = false, bool SP2 = false>
; __device__ __forceinline__ void gemm_phase(PG8_LAS unsigned char* lds, const Gemm g, const Sched& S, const Epi& E) {
;     ...
;         for (int t = 0; t < nt; t += 2) {
;             const bool last = (t == nt - 2);
;             const char* a1 = cA + (size_t)(t + 1) * kstep;
;             const char* a2 = last ? nA : cA + (size_t)(t + 2) * kstep; const char* b2 = last ? nB : cB + (size_t)(t + 2) * kstep;
;             const char* a3 = a2 + kstep; const char* b3 = b2 + kstep;
;     ...
;             PG8_LDA(At, 1, 1); PG8_STAGE(PG8_SB(1, 0), b3, voffB); PG8_STAGE(PG8_SB(1, 1), b3 + hstep, voffB); PG8_STAGE(PG8_SA(1, 0), a3, voffA);
;             PG8_WAIT_V(8); PG8_WAIT_L(0); PG8_BAR; PG8_MMA(1, 0, At, B0); PG8_MMA(1, 1, At, B1); PG8_BAR; PG8_SCHED;
;     __device__ __forceinline__ void operator()(const AccT& acc, const pg8::Unit& u, int wr, int wc, int fr, int fq) const {
;         const int col0 = u.pn * 256 + wc * 32 + 4 * fq, row0 = row_base + u.pm * 256 + wr * 64 + fr;
; #pragma unroll
;         for (int ai = 0; ai < 2; ++ai)
; #pragma unroll
;             for (int m = 0; m < 4; ++m) { const int row = row0 + ai * 128 + m * 16; float ss = 0.f;
; #pragma unroll
;                 for (int bj = 0; bj < 2; ++bj)
; #pragma unroll
;                     for (int n = 0; n < 2; ++n) { f32x4 v = acc[ai][bj][m][n]; const size_t idx = (size_t)row * 1024 + col0 + bj * 128 + n * 16;
;                         if (MODE == 0) v = v * up4(*(const u32x2*)(io + idx));
;                         else if (MODE == 1) v = up4(*(const u32x2*)(io + idx)) + up4(*(const u32x2*)(g2 + idx)) * v;
	s_add_i32 s3, s67, s63
	v_lshl_add_u64 v[136:137], v[136:137], 0, s[10:11]
	s_mov_b32 m0, s3
	ds_read_b128 v[180:183], v143 offset:49152
	ds_read_b128 v[184:187], v143 offset:50176
	ds_read_b128 v[188:191], v143 offset:51200
	ds_read_b128 v[192:195], v143 offset:52224
	ds_read_b128 v[196:199], v143 offset:53248
	ds_read_b128 v[200:203], v143 offset:54272
	ds_read_b128 v[204:207], v143 offset:55296
	ds_read_b128 v[208:211], v143 offset:56320
	global_load_lds_dwordx4 v[136:137], off
	s_add_i32 m0, s3, 0x2000
	s_add_u32 s42, s42, 0x40080
	v_lshl_add_u64 v[136:137], v[212:213], 0, s[10:11]
	s_addc_u32 s43, s43, 0
	s_add_i32 s3, s68, s63
	global_load_lds_dwordx4 v[136:137], off
	v_lshl_add_u64 v[136:137], s[42:43], 0, v[128:129]
	s_mov_b32 m0, s3
	s_nop 0
	global_load_lds_dwordx4 v[136:137], off
	v_lshl_add_u64 v[136:137], s[42:43], 0, v[130:131]
	s_add_i32 m0, s3, 0x2000
	s_nop 0
	global_load_lds_dwordx4 v[136:137], off
	v_lshl_add_u64 v[136:137], v[214:215], 0, s[10:11]
	s_mov_b32 m0, s71
	s_nop 0
	global_load_lds_dwordx4 v[136:137], off
	v_lshl_add_u64 v[136:137], v[216:217], 0, s[10:11]
	s_mov_b32 m0, s72
	s_nop 0
	global_load_lds_dwordx4 v[136:137], off
	s_waitcnt vmcnt(8)
	s_waitcnt lgkmcnt(0)
	s_barrier
	s_setprio 1
	s_waitcnt lgkmcnt(0)
	v_mfma_f32_16x16x32_bf16 v[60:63], v[144:147], v[180:183], v[60:63]
	v_mfma_f32_16x16x32_bf16 v[56:59], v[152:155], v[180:183], v[56:59]
	v_mfma_f32_16x16x32_bf16 v[44:47], v[144:147], v[188:191], v[44:47]
	v_mfma_f32_16x16x32_bf16 v[40:43], v[152:155], v[188:191], v[40:43]
	v_mfma_f32_16x16x32_bf16 v[28:31], v[144:147], v[196:199], v[28:31]
	v_mfma_f32_16x16x32_bf16 v[24:27], v[152:155], v[196:199], v[24:27]
	v_mfma_f32_16x16x32_bf16 v[12:15], v[144:147], v[204:207], v[12:15]
	v_mfma_f32_16x16x32_bf16 v[8:11], v[152:155], v[204:207], v[8:11]
	v_mfma_f32_16x16x32_bf16 v[60:63], v[148:151], v[184:187], v[60:63]
	v_mfma_f32_16x16x32_bf16 v[56:59], v[156:159], v[184:187], v[56:59]
	v_mfma_f32_16x16x32_bf16 v[44:47], v[148:151], v[192:195], v[44:47]
	v_mfma_f32_16x16x32_bf16 v[40:43], v[156:159], v[192:195], v[40:43]
	v_mfma_f32_16x16x32_bf16 v[28:31], v[148:151], v[200:203], v[28:31]
	v_mfma_f32_16x16x32_bf16 v[24:27], v[156:159], v[200:203], v[24:27]
	v_mfma_f32_16x16x32_bf16 v[12:15], v[148:151], v[208:211], v[12:15]
	v_mfma_f32_16x16x32_bf16 v[8:11], v[156:159], v[208:211], v[8:11]
	s_setprio 0
	s_setprio 1
	v_mfma_f32_16x16x32_bf16 v[52:55], v[160:163], v[180:183], v[52:55]
	v_mfma_f32_16x16x32_bf16 v[48:51], v[168:171], v[180:183], v[48:51]
	v_mfma_f32_16x16x32_bf16 v[36:39], v[160:163], v[188:191], v[36:39]
	v_mfma_f32_16x16x32_bf16 v[32:35], v[168:171], v[188:191], v[32:35]
	v_mfma_f32_16x16x32_bf16 v[20:23], v[160:163], v[196:199], v[20:23]
	s_add_i32 s77, s77, 2
	s_add_u32 s40, s40, 0x100
	s_addc_u32 s41, s41, 0
	s_add_u32 s75, s75, 0x100
	s_addc_u32 s76, s76, 0
	s_cmp_gt_u32 s77, 13
	v_mfma_f32_16x16x32_bf16 v[16:19], v[168:171], v[196:199], v[16:19]
	v_mfma_f32_16x16x32_bf16 v[4:7], v[160:163], v[204:207], v[4:7]
	v_mfma_f32_16x16x32_bf16 v[0:3], v[168:171], v[204:207], v[0:3]
	v_mfma_f32_16x16x32_bf16 v[52:55], v[164:167], v[184:187], v[52:55]
	v_mfma_f32_16x16x32_bf16 v[48:51], v[172:175], v[184:187], v[48:51]
	v_mfma_f32_16x16x32_bf16 v[36:39], v[164:167], v[192:195], v[36:39]
	v_mfma_f32_16x16x32_bf16 v[32:35], v[172:175], v[192:195], v[32:35]
	v_mfma_f32_16x16x32_bf16 v[20:23], v[164:167], v[200:203], v[20:23]
	v_mfma_f32_16x16x32_bf16 v[16:19], v[172:175], v[200:203], v[16:19]
	v_mfma_f32_16x16x32_bf16 v[4:7], v[164:167], v[208:211], v[4:7]
	v_mfma_f32_16x16x32_bf16 v[0:3], v[172:175], v[208:211], v[0:3]
	s_setprio 0
	s_barrier
	s_cbranch_scc0 .LBB0_665
	v_lshl_add_u32 v144, s34, 8, v138
	v_add_u32_e32 v146, 0x4000, v144
	v_lshl_or_b32 v136, s30, 8, v140
	v_ashrrev_i32_e32 v147, 31, v146
	v_ashrrev_i32_e32 v137, 31, v136
	v_lshlrev_b64 v[146:147], 10, v[146:147]
	v_lshl_add_u64 v[146:147], v[146:147], 0, v[136:137]
	v_lshlrev_b64 v[146:147], 1, v[146:147]
	v_lshl_add_u64 v[148:149], s[4:5], 0, v[146:147]
	v_lshl_add_u64 v[152:153], s[8:9], 0, v[146:147]
	v_or_b32_e32 v154, 32, v146
	v_mov_b32_e32 v155, v147
	v_or_b32_e32 v160, 0x100, v146
	v_mov_b32_e32 v161, v147
	v_or_b32_e32 v146, 0x120, v146
	global_load_dwordx2 v[150:151], v[148:149], off
	v_lshl_add_u64 v[156:157], s[4:5], 0, v[154:155]
	global_load_dwordx2 v[152:153], v[152:153], off
	v_lshl_add_u64 v[154:155], s[8:9], 0, v[154:155]
	v_lshl_add_u64 v[162:163], s[4:5], 0, v[160:161]
	v_lshl_add_u64 v[160:161], s[8:9], 0, v[160:161]
	v_lshl_add_u64 v[166:167], s[4:5], 0, v[146:147]
	global_load_dwordx2 v[158:159], v[156:157], off
	global_load_dwordx2 v[164:165], v[162:163], off
	global_load_dwordx2 v[168:169], v[166:167], off
	v_lshl_add_u64 v[146:147], s[8:9], 0, v[146:147]
	global_load_dwordx2 v[154:155], v[154:155], off
	v_add_u32_e32 v170, 0x4010, v144
	global_load_dwordx2 v[160:161], v[160:161], off
	v_ashrrev_i32_e32 v171, 31, v170
	global_load_dwordx2 v[146:147], v[146:147], off
	v_lshlrev_b64 v[170:171], 10, v[170:171]
	v_lshl_add_u64 v[170:171], v[170:171], 0, v[136:137]
	v_lshlrev_b64 v[170:171], 1, v[170:171]
	v_lshl_add_u64 v[172:173], s[4:5], 0, v[170:171]
	s_and_b64 vcc, exec, s[24:25]
	s_mov_b32 s30, s14
	s_mov_b32 s34, s20
	s_mov_b64 s[42:43], s[28:29]
	s_mov_b64 s[40:41], s[26:27]
	s_waitcnt vmcnt(0)
; __device__ __forceinline__ u32x2 pk4(f32x4 v) { u32x2 w; w.x = cvt_pk_bf16(v[0], v[1]); w.y = cvt_pk_bf16(v[2], v[3]); return w; }
; __device__ __forceinline__ f32x4 up4(u32x2 w) { return (f32x4){bf_lo(w.x), bf_hi(w.x), bf_lo(w.y), bf_hi(w.y)}; }
;     __device__ __forceinline__ void operator()(const AccT& acc, const pg8::Unit& u, int wr, int wc, int fr, int fq) const {
;     ...
;                     for (int n = 0; n < 2; ++n) { f32x4 v = acc[ai][bj][m][n]; const size_t idx = (size_t)row * 1024 + col0 + bj * 128 + n * 16;
;                         if (MODE == 0) v = v * up4(*(const u32x2*)(io + idx));
;                         else if (MODE == 1) v = up4(*(const u32x2*)(io + idx)) + up4(*(const u32x2*)(g2 + idx)) * v;
;                         else ss += (v[0] * v[0] + v[1] * v[1]) + (v[2] * v[2] + v[3] * v[3]);
;                         if (!DRYE || v[0] == 123.456f) *(u32x2*)(io + idx) = pk4(v); }
	v_lshlrev_b32_e32 v174, 16, v150
	v_and_b32_e32 v175, 0xffff0000, v150
	v_lshlrev_b32_e32 v150, 16, v151
	v_and_b32_e32 v151, 0xffff0000, v151
	v_lshlrev_b32_e32 v180, 16, v152
	v_and_b32_e32 v181, 0xffff0000, v152
	v_lshlrev_b32_e32 v152, 16, v153
	v_and_b32_e32 v153, 0xffff0000, v153
	v_pk_fma_f32 v[126:127], v[126:127], v[152:153], v[150:151]
	v_pk_fma_f32 v[124:125], v[124:125], v[180:181], v[174:175]
	v_lshlrev_b32_e32 v150, 16, v158
	v_and_b32_e32 v151, 0xffff0000, v158
	v_lshlrev_b32_e32 v152, 16, v159
	v_and_b32_e32 v153, 0xffff0000, v159
	v_lshlrev_b32_e32 v158, 16, v154
	v_and_b32_e32 v159, 0xffff0000, v154
	v_lshlrev_b32_e32 v154, 16, v155
	v_and_b32_e32 v155, 0xffff0000, v155
	v_lshlrev_b32_e32 v174, 16, v164
	v_and_b32_e32 v175, 0xffff0000, v164
	v_lshlrev_b32_e32 v164, 16, v165
	v_and_b32_e32 v165, 0xffff0000, v165
	v_lshlrev_b32_e32 v180, 16, v160
	v_and_b32_e32 v181, 0xffff0000, v160
	v_lshlrev_b32_e32 v160, 16, v161
	v_and_b32_e32 v161, 0xffff0000, v161
	v_lshlrev_b32_e32 v182, 16, v168
	v_and_b32_e32 v183, 0xffff0000, v168
	v_lshlrev_b32_e32 v168, 16, v169
	v_and_b32_e32 v169, 0xffff0000, v169
	v_lshlrev_b32_e32 v184, 16, v146
	v_and_b32_e32 v185, 0xffff0000, v146
	v_lshlrev_b32_e32 v146, 16, v147
	v_and_b32_e32 v147, 0xffff0000, v147
	v_pk_fma_f32 v[122:123], v[122:123], v[154:155], v[152:153]
	v_pk_fma_f32 v[120:121], v[120:121], v[158:159], v[150:151]
	v_pk_fma_f32 v[118:119], v[118:119], v[160:161], v[164:165]
	v_pk_fma_f32 v[116:117], v[116:117], v[180:181], v[174:175]
	v_cvt_pk_bf16_f32 v124, v124, v125
	v_cvt_pk_bf16_f32 v125, v126, v127
	v_pk_fma_f32 v[114:115], v[114:115], v[146:147], v[168:169]
	v_pk_fma_f32 v[112:113], v[112:113], v[184:185], v[182:183]
	v_cvt_pk_bf16_f32 v120, v120, v121
	v_cvt_pk_bf16_f32 v121, v122, v123
	v_cvt_pk_bf16_f32 v116, v116, v117
	v_cvt_pk_bf16_f32 v117, v118, v119
	global_store_dwordx2 v[148:149], v[124:125], off
	v_cvt_pk_bf16_f32 v112, v112, v113
	v_cvt_pk_bf16_f32 v113, v114, v115
	global_store_dwordx2 v[156:157], v[120:121], off
	global_store_dwordx2 v[162:163], v[116:117], off
	global_store_dwordx2 v[166:167], v[112:113], off
	v_or_b32_e32 v116, 32, v170
	v_mov_b32_e32 v117, v171
	v_or_b32_e32 v122, 0x100, v170
	v_mov_b32_e32 v123, v171
	v_lshl_add_u64 v[114:115], s[8:9], 0, v[170:171]
	v_lshl_add_u64 v[118:119], s[4:5], 0, v[116:117]
	v_lshl_add_u64 v[124:125], s[4:5], 0, v[122:123]
	v_lshl_add_u64 v[122:123], s[8:9], 0, v[122:123]
	v_or_b32_e32 v170, 0x120, v170
	global_load_dwordx2 v[112:113], v[172:173], off
	global_load_dwordx2 v[126:127], v[124:125], off
	global_load_dwordx2 v[120:121], v[118:119], off
	v_lshl_add_u64 v[116:117], s[8:9], 0, v[116:117]
	global_load_dwordx2 v[114:115], v[114:115], off
	v_lshl_add_u64 v[146:147], s[4:5], 0, v[170:171]
	global_load_dwordx2 v[122:123], v[122:123], off
	v_lshl_add_u64 v[150:151], s[8:9], 0, v[170:171]
	global_load_dwordx2 v[116:117], v[116:117], off
	v_add_u32_e32 v152, 0x4020, v144
	global_load_dwordx2 v[148:149], v[146:147], off
	v_ashrrev_i32_e32 v153, 31, v152
	global_load_dwordx2 v[150:151], v[150:151], off
	v_lshlrev_b64 v[152:153], 10, v[152:153]
	v_lshl_add_u64 v[152:153], v[152:153], 0, v[136:137]
	v_lshlrev_b64 v[152:153], 1, v[152:153]
	v_lshl_add_u64 v[154:155], s[4:5], 0, v[152:153]
	s_waitcnt vmcnt(7)
	v_lshlrev_b32_e32 v156, 16, v112
	v_and_b32_e32 v157, 0xffff0000, v112
	v_lshlrev_b32_e32 v112, 16, v113
	v_and_b32_e32 v113, 0xffff0000, v113
	s_waitcnt vmcnt(4)
	v_lshlrev_b32_e32 v158, 16, v114
	v_and_b32_e32 v159, 0xffff0000, v114
	v_lshlrev_b32_e32 v114, 16, v115
	v_and_b32_e32 v115, 0xffff0000, v115
	v_lshlrev_b32_e32 v164, 16, v126
	v_and_b32_e32 v165, 0xffff0000, v126
	v_lshlrev_b32_e32 v126, 16, v127
	v_and_b32_e32 v127, 0xffff0000, v127
	s_waitcnt vmcnt(3)
	v_lshlrev_b32_e32 v166, 16, v122
	v_and_b32_e32 v167, 0xffff0000, v122
	v_lshlrev_b32_e32 v122, 16, v123
	v_and_b32_e32 v123, 0xffff0000, v123
	v_lshlrev_b32_e32 v160, 16, v120
	v_and_b32_e32 v161, 0xffff0000, v120
	v_lshlrev_b32_e32 v120, 16, v121
	v_and_b32_e32 v121, 0xffff0000, v121
	s_waitcnt vmcnt(2)
	v_lshlrev_b32_e32 v162, 16, v116
	v_and_b32_e32 v163, 0xffff0000, v116
	v_lshlrev_b32_e32 v116, 16, v117
	v_and_b32_e32 v117, 0xffff0000, v117
	s_waitcnt vmcnt(1)
	v_lshlrev_b32_e32 v168, 16, v148
	v_and_b32_e32 v169, 0xffff0000, v148
	v_lshlrev_b32_e32 v148, 16, v149
	v_and_b32_e32 v149, 0xffff0000, v149
	s_waitcnt vmcnt(0)
	v_lshlrev_b32_e32 v170, 16, v150
	v_and_b32_e32 v171, 0xffff0000, v150
	v_lshlrev_b32_e32 v150, 16, v151
	v_and_b32_e32 v151, 0xffff0000, v151
	v_pk_fma_f32 v[110:111], v[110:111], v[114:115], v[112:113]
	v_pk_fma_f32 v[108:109], v[108:109], v[158:159], v[156:157]
	v_pk_fma_f32 v[102:103], v[102:103], v[122:123], v[126:127]
	v_pk_fma_f32 v[100:101], v[100:101], v[166:167], v[164:165]
	v_pk_fma_f32 v[106:107], v[106:107], v[116:117], v[120:121]
	v_pk_fma_f32 v[104:105], v[104:105], v[162:163], v[160:161]
	v_pk_fma_f32 v[98:99], v[98:99], v[150:151], v[148:149]
	v_pk_fma_f32 v[96:97], v[96:97], v[170:171], v[168:169]
	v_cvt_pk_bf16_f32 v108, v108, v109
	v_cvt_pk_bf16_f32 v109, v110, v111
	v_cvt_pk_bf16_f32 v100, v100, v101
	v_cvt_pk_bf16_f32 v101, v102, v103
	v_cvt_pk_bf16_f32 v104, v104, v105
	v_cvt_pk_bf16_f32 v105, v106, v107
	v_cvt_pk_bf16_f32 v96, v96, v97
	v_cvt_pk_bf16_f32 v97, v98, v99
	global_store_dwordx2 v[172:173], v[108:109], off
	global_store_dwordx2 v[118:119], v[104:105], off
	global_store_dwordx2 v[124:125], v[100:101], off
	global_store_dwordx2 v[146:147], v[96:97], off
	v_or_b32_e32 v100, 32, v152
	v_mov_b32_e32 v101, v153
	v_or_b32_e32 v106, 0x100, v152
	v_mov_b32_e32 v107, v153
	v_lshl_add_u64 v[98:99], s[8:9], 0, v[152:153]
	v_lshl_add_u64 v[102:103], s[4:5], 0, v[100:101]
	v_lshl_add_u64 v[108:109], s[4:5], 0, v[106:107]
	v_lshl_add_u64 v[106:107], s[8:9], 0, v[106:107]
	v_or_b32_e32 v152, 0x120, v152
	global_load_dwordx2 v[96:97], v[154:155], off
	global_load_dwordx2 v[110:111], v[108:109], off
	global_load_dwordx2 v[104:105], v[102:103], off
	v_lshl_add_u64 v[100:101], s[8:9], 0, v[100:101]
	global_load_dwordx2 v[98:99], v[98:99], off
	v_lshl_add_u64 v[112:113], s[4:5], 0, v[152:153]
	global_load_dwordx2 v[106:107], v[106:107], off
	v_lshl_add_u64 v[116:117], s[8:9], 0, v[152:153]
	global_load_dwordx2 v[100:101], v[100:101], off
	v_add_u32_e32 v118, 0x4030, v144
	global_load_dwordx2 v[114:115], v[112:113], off
	v_ashrrev_i32_e32 v119, 31, v118
	global_load_dwordx2 v[116:117], v[116:117], off
	v_lshlrev_b64 v[118:119], 10, v[118:119]
	v_lshl_add_u64 v[118:119], v[118:119], 0, v[136:137]
	v_lshlrev_b64 v[118:119], 1, v[118:119]
	v_lshl_add_u64 v[120:121], s[4:5], 0, v[118:119]
	s_waitcnt vmcnt(7)
; __device__ __forceinline__ u32x2 pk4(f32x4 v) { u32x2 w; w.x = cvt_pk_bf16(v[0], v[1]); w.y = cvt_pk_bf16(v[2], v[3]); return w; }
; __device__ __forceinline__ f32x4 up4(u32x2 w) { return (f32x4){bf_lo(w.x), bf_hi(w.x), bf_lo(w.y), bf_hi(w.y)}; }
;     __device__ __forceinline__ void operator()(const AccT& acc, const pg8::Unit& u, int wr, int wc, int fr, int fq) const {
;     ...
;                     for (int n = 0; n < 2; ++n) { f32x4 v = acc[ai][bj][m][n]; const size_t idx = (size_t)row * 1024 + col0 + bj * 128 + n * 16;
;                         if (MODE == 0) v = v * up4(*(const u32x2*)(io + idx));
;                         else if (MODE == 1) v = up4(*(const u32x2*)(io + idx)) + up4(*(const u32x2*)(g2 + idx)) * v;
;                         else ss += (v[0] * v[0] + v[1] * v[1]) + (v[2] * v[2] + v[3] * v[3]);
;                         if (!DRYE || v[0] == 123.456f) *(u32x2*)(io + idx) = pk4(v); }
	v_lshlrev_b32_e32 v122, 16, v96
	v_and_b32_e32 v123, 0xffff0000, v96
	v_lshlrev_b32_e32 v96, 16, v97
	v_and_b32_e32 v97, 0xffff0000, v97
	s_waitcnt vmcnt(4)
	v_lshlrev_b32_e32 v124, 16, v98
	v_and_b32_e32 v125, 0xffff0000, v98
	v_lshlrev_b32_e32 v98, 16, v99
	v_and_b32_e32 v99, 0xffff0000, v99
	v_lshlrev_b32_e32 v148, 16, v110
	v_and_b32_e32 v149, 0xffff0000, v110
	v_lshlrev_b32_e32 v110, 16, v111
	v_and_b32_e32 v111, 0xffff0000, v111
	s_waitcnt vmcnt(3)
	v_lshlrev_b32_e32 v150, 16, v106
	v_and_b32_e32 v151, 0xffff0000, v106
	v_lshlrev_b32_e32 v106, 16, v107
	v_and_b32_e32 v107, 0xffff0000, v107
	v_lshlrev_b32_e32 v126, 16, v104
	v_and_b32_e32 v127, 0xffff0000, v104
	v_lshlrev_b32_e32 v104, 16, v105
	v_and_b32_e32 v105, 0xffff0000, v105
	s_waitcnt vmcnt(2)
	v_lshlrev_b32_e32 v146, 16, v100
	v_and_b32_e32 v147, 0xffff0000, v100
	v_lshlrev_b32_e32 v100, 16, v101
	v_and_b32_e32 v101, 0xffff0000, v101
	s_waitcnt vmcnt(1)
	v_lshlrev_b32_e32 v152, 16, v114
	v_and_b32_e32 v153, 0xffff0000, v114
	v_lshlrev_b32_e32 v114, 16, v115
	v_and_b32_e32 v115, 0xffff0000, v115
	s_waitcnt vmcnt(0)
	v_lshlrev_b32_e32 v156, 16, v116
	v_and_b32_e32 v157, 0xffff0000, v116
	v_lshlrev_b32_e32 v116, 16, v117
	v_and_b32_e32 v117, 0xffff0000, v117
	v_pk_fma_f32 v[94:95], v[94:95], v[98:99], v[96:97]
	v_pk_fma_f32 v[92:93], v[92:93], v[124:125], v[122:123]
	v_pk_fma_f32 v[86:87], v[86:87], v[106:107], v[110:111]
	v_pk_fma_f32 v[84:85], v[84:85], v[150:151], v[148:149]
	v_pk_fma_f32 v[90:91], v[90:91], v[100:101], v[104:105]
	v_pk_fma_f32 v[88:89], v[88:89], v[146:147], v[126:127]
	v_pk_fma_f32 v[82:83], v[82:83], v[116:117], v[114:115]
	v_pk_fma_f32 v[80:81], v[80:81], v[156:157], v[152:153]
	v_cvt_pk_bf16_f32 v92, v92, v93
	v_cvt_pk_bf16_f32 v93, v94, v95
	v_cvt_pk_bf16_f32 v84, v84, v85
	v_cvt_pk_bf16_f32 v85, v86, v87
	v_cvt_pk_bf16_f32 v88, v88, v89
	v_cvt_pk_bf16_f32 v89, v90, v91
	v_cvt_pk_bf16_f32 v80, v80, v81
	v_cvt_pk_bf16_f32 v81, v82, v83
	global_store_dwordx2 v[154:155], v[92:93], off
	global_store_dwordx2 v[102:103], v[88:89], off
	global_store_dwordx2 v[108:109], v[84:85], off
	global_store_dwordx2 v[112:113], v[80:81], off
	v_or_b32_e32 v84, 32, v118
	v_mov_b32_e32 v85, v119
	v_or_b32_e32 v90, 0x100, v118
	v_mov_b32_e32 v91, v119
	v_lshl_add_u64 v[82:83], s[8:9], 0, v[118:119]
	v_lshl_add_u64 v[86:87], s[4:5], 0, v[84:85]
	v_lshl_add_u64 v[92:93], s[4:5], 0, v[90:91]
	v_lshl_add_u64 v[90:91], s[8:9], 0, v[90:91]
	v_or_b32_e32 v118, 0x120, v118
	global_load_dwordx2 v[80:81], v[120:121], off
	global_load_dwordx2 v[94:95], v[92:93], off
	global_load_dwordx2 v[88:89], v[86:87], off
	v_lshl_add_u64 v[84:85], s[8:9], 0, v[84:85]
	global_load_dwordx2 v[82:83], v[82:83], off
	v_lshl_add_u64 v[96:97], s[4:5], 0, v[118:119]
	global_load_dwordx2 v[90:91], v[90:91], off
	v_lshl_add_u64 v[100:101], s[8:9], 0, v[118:119]
	global_load_dwordx2 v[84:85], v[84:85], off
	v_add_u32_e32 v102, 0x4080, v144
	global_load_dwordx2 v[98:99], v[96:97], off
	v_ashrrev_i32_e32 v103, 31, v102
	global_load_dwordx2 v[100:101], v[100:101], off
	v_lshlrev_b64 v[102:103], 10, v[102:103]
	v_lshl_add_u64 v[102:103], v[102:103], 0, v[136:137]
	v_lshlrev_b64 v[102:103], 1, v[102:103]
	v_lshl_add_u64 v[104:105], s[4:5], 0, v[102:103]
	s_waitcnt vmcnt(7)
	v_lshlrev_b32_e32 v106, 16, v80
	v_and_b32_e32 v107, 0xffff0000, v80
	v_lshlrev_b32_e32 v80, 16, v81
	v_and_b32_e32 v81, 0xffff0000, v81
	s_waitcnt vmcnt(4)
	v_lshlrev_b32_e32 v108, 16, v82
	v_and_b32_e32 v109, 0xffff0000, v82
	v_lshlrev_b32_e32 v82, 16, v83
	v_and_b32_e32 v83, 0xffff0000, v83
	v_lshlrev_b32_e32 v114, 16, v94
	v_and_b32_e32 v115, 0xffff0000, v94
	v_lshlrev_b32_e32 v94, 16, v95
	v_and_b32_e32 v95, 0xffff0000, v95
	s_waitcnt vmcnt(3)
	v_lshlrev_b32_e32 v116, 16, v90
	v_and_b32_e32 v117, 0xffff0000, v90
	v_lshlrev_b32_e32 v90, 16, v91
	v_and_b32_e32 v91, 0xffff0000, v91
	v_lshlrev_b32_e32 v110, 16, v88
	v_and_b32_e32 v111, 0xffff0000, v88
	v_lshlrev_b32_e32 v88, 16, v89
	v_and_b32_e32 v89, 0xffff0000, v89
	s_waitcnt vmcnt(2)
	v_lshlrev_b32_e32 v112, 16, v84
	v_and_b32_e32 v113, 0xffff0000, v84
	v_lshlrev_b32_e32 v84, 16, v85
	v_and_b32_e32 v85, 0xffff0000, v85
	s_waitcnt vmcnt(1)
	v_lshlrev_b32_e32 v118, 16, v98
	v_and_b32_e32 v119, 0xffff0000, v98
	v_lshlrev_b32_e32 v98, 16, v99
	v_and_b32_e32 v99, 0xffff0000, v99
	s_waitcnt vmcnt(0)
	v_lshlrev_b32_e32 v122, 16, v100
	v_and_b32_e32 v123, 0xffff0000, v100
	v_lshlrev_b32_e32 v100, 16, v101
	v_and_b32_e32 v101, 0xffff0000, v101
	v_pk_fma_f32 v[78:79], v[78:79], v[82:83], v[80:81]
	v_pk_fma_f32 v[76:77], v[76:77], v[108:109], v[106:107]
	v_pk_fma_f32 v[70:71], v[70:71], v[90:91], v[94:95]
	v_pk_fma_f32 v[68:69], v[68:69], v[116:117], v[114:115]
	v_pk_fma_f32 v[74:75], v[74:75], v[84:85], v[88:89]
	v_pk_fma_f32 v[72:73], v[72:73], v[112:113], v[110:111]
	v_pk_fma_f32 v[66:67], v[66:67], v[100:101], v[98:99]
	v_pk_fma_f32 v[64:65], v[64:65], v[122:123], v[118:119]
	v_cvt_pk_bf16_f32 v76, v76, v77
	v_cvt_pk_bf16_f32 v77, v78, v79
	v_cvt_pk_bf16_f32 v68, v68, v69
	v_cvt_pk_bf16_f32 v69, v70, v71
	v_cvt_pk_bf16_f32 v72, v72, v73
	v_cvt_pk_bf16_f32 v73, v74, v75
	v_cvt_pk_bf16_f32 v64, v64, v65
	v_cvt_pk_bf16_f32 v65, v66, v67
	global_store_dwordx2 v[120:121], v[76:77], off
	global_store_dwordx2 v[86:87], v[72:73], off
	global_store_dwordx2 v[92:93], v[68:69], off
	global_store_dwordx2 v[96:97], v[64:65], off
	v_or_b32_e32 v68, 32, v102
	v_mov_b32_e32 v69, v103
	v_or_b32_e32 v74, 0x100, v102
	v_mov_b32_e32 v75, v103
	v_lshl_add_u64 v[66:67], s[8:9], 0, v[102:103]
	v_lshl_add_u64 v[70:71], s[4:5], 0, v[68:69]
	v_lshl_add_u64 v[76:77], s[4:5], 0, v[74:75]
	v_lshl_add_u64 v[74:75], s[8:9], 0, v[74:75]
	v_or_b32_e32 v102, 0x120, v102
	global_load_dwordx2 v[64:65], v[104:105], off
	global_load_dwordx2 v[78:79], v[76:77], off
	global_load_dwordx2 v[72:73], v[70:71], off
	v_lshl_add_u64 v[68:69], s[8:9], 0, v[68:69]
	global_load_dwordx2 v[66:67], v[66:67], off
	v_lshl_add_u64 v[80:81], s[4:5], 0, v[102:103]
	global_load_dwordx2 v[74:75], v[74:75], off
	v_lshl_add_u64 v[84:85], s[8:9], 0, v[102:103]
	global_load_dwordx2 v[68:69], v[68:69], off
	v_add_u32_e32 v86, 0x4090, v144
	global_load_dwordx2 v[82:83], v[80:81], off
	v_ashrrev_i32_e32 v87, 31, v86
	global_load_dwordx2 v[84:85], v[84:85], off
	v_lshlrev_b64 v[86:87], 10, v[86:87]
	v_lshl_add_u64 v[86:87], v[86:87], 0, v[136:137]
	v_lshlrev_b64 v[86:87], 1, v[86:87]
	v_lshl_add_u64 v[88:89], s[4:5], 0, v[86:87]
	s_waitcnt vmcnt(7)
; __device__ __forceinline__ u32x2 pk4(f32x4 v) { u32x2 w; w.x = cvt_pk_bf16(v[0], v[1]); w.y = cvt_pk_bf16(v[2], v[3]); return w; }
; __device__ __forceinline__ f32x4 up4(u32x2 w) { return (f32x4){bf_lo(w.x), bf_hi(w.x), bf_lo(w.y), bf_hi(w.y)}; }
;     __device__ __forceinline__ void operator()(const AccT& acc, const pg8::Unit& u, int wr, int wc, int fr, int fq) const {
;     ...
;                     for (int n = 0; n < 2; ++n) { f32x4 v = acc[ai][bj][m][n]; const size_t idx = (size_t)row * 1024 + col0 + bj * 128 + n * 16;
;                         if (MODE == 0) v = v * up4(*(const u32x2*)(io + idx));
;                         else if (MODE == 1) v = up4(*(const u32x2*)(io + idx)) + up4(*(const u32x2*)(g2 + idx)) * v;
;                         else ss += (v[0] * v[0] + v[1] * v[1]) + (v[2] * v[2] + v[3] * v[3]);
;                         if (!DRYE || v[0] == 123.456f) *(u32x2*)(io + idx) = pk4(v); }
	v_lshlrev_b32_e32 v90, 16, v64
	v_and_b32_e32 v91, 0xffff0000, v64
	v_lshlrev_b32_e32 v64, 16, v65
	v_and_b32_e32 v65, 0xffff0000, v65
	s_waitcnt vmcnt(4)
	v_lshlrev_b32_e32 v92, 16, v66
	v_and_b32_e32 v93, 0xffff0000, v66
	v_lshlrev_b32_e32 v66, 16, v67
	v_and_b32_e32 v67, 0xffff0000, v67
	v_lshlrev_b32_e32 v98, 16, v78
	v_and_b32_e32 v99, 0xffff0000, v78
	v_lshlrev_b32_e32 v78, 16, v79
	v_and_b32_e32 v79, 0xffff0000, v79
	s_waitcnt vmcnt(3)
	v_lshlrev_b32_e32 v100, 16, v74
	v_and_b32_e32 v101, 0xffff0000, v74
	v_lshlrev_b32_e32 v74, 16, v75
	v_and_b32_e32 v75, 0xffff0000, v75
	v_lshlrev_b32_e32 v94, 16, v72
	v_and_b32_e32 v95, 0xffff0000, v72
	v_lshlrev_b32_e32 v72, 16, v73
	v_and_b32_e32 v73, 0xffff0000, v73
	s_waitcnt vmcnt(2)
	v_lshlrev_b32_e32 v96, 16, v68
	v_and_b32_e32 v97, 0xffff0000, v68
	v_lshlrev_b32_e32 v68, 16, v69
	v_and_b32_e32 v69, 0xffff0000, v69
	s_waitcnt vmcnt(1)
	v_lshlrev_b32_e32 v102, 16, v82
	v_and_b32_e32 v103, 0xffff0000, v82
	v_lshlrev_b32_e32 v82, 16, v83
	v_and_b32_e32 v83, 0xffff0000, v83
	s_waitcnt vmcnt(0)
	v_lshlrev_b32_e32 v106, 16, v84
	v_and_b32_e32 v107, 0xffff0000, v84
	v_lshlrev_b32_e32 v84, 16, v85
	v_and_b32_e32 v85, 0xffff0000, v85
	v_pk_fma_f32 v[62:63], v[62:63], v[66:67], v[64:65]
	v_pk_fma_f32 v[60:61], v[60:61], v[92:93], v[90:91]
	v_pk_fma_f32 v[54:55], v[54:55], v[74:75], v[78:79]
	v_pk_fma_f32 v[52:53], v[52:53], v[100:101], v[98:99]
	v_pk_fma_f32 v[58:59], v[58:59], v[68:69], v[72:73]
	v_pk_fma_f32 v[56:57], v[56:57], v[96:97], v[94:95]
	v_pk_fma_f32 v[50:51], v[50:51], v[84:85], v[82:83]
	v_pk_fma_f32 v[48:49], v[48:49], v[106:107], v[102:103]
	v_cvt_pk_bf16_f32 v60, v60, v61
	v_cvt_pk_bf16_f32 v61, v62, v63
	v_cvt_pk_bf16_f32 v52, v52, v53
	v_cvt_pk_bf16_f32 v53, v54, v55
	v_cvt_pk_bf16_f32 v56, v56, v57
	v_cvt_pk_bf16_f32 v57, v58, v59
	v_cvt_pk_bf16_f32 v48, v48, v49
	v_cvt_pk_bf16_f32 v49, v50, v51
	global_store_dwordx2 v[104:105], v[60:61], off
	global_store_dwordx2 v[70:71], v[56:57], off
	global_store_dwordx2 v[76:77], v[52:53], off
	global_store_dwordx2 v[80:81], v[48:49], off
	v_or_b32_e32 v52, 32, v86
	v_mov_b32_e32 v53, v87
	v_or_b32_e32 v58, 0x100, v86
	v_mov_b32_e32 v59, v87
	v_lshl_add_u64 v[50:51], s[8:9], 0, v[86:87]
	v_lshl_add_u64 v[54:55], s[4:5], 0, v[52:53]
	v_lshl_add_u64 v[60:61], s[4:5], 0, v[58:59]
	v_lshl_add_u64 v[58:59], s[8:9], 0, v[58:59]
	v_or_b32_e32 v86, 0x120, v86
	global_load_dwordx2 v[48:49], v[88:89], off
	global_load_dwordx2 v[62:63], v[60:61], off
	global_load_dwordx2 v[56:57], v[54:55], off
	v_lshl_add_u64 v[52:53], s[8:9], 0, v[52:53]
	global_load_dwordx2 v[50:51], v[50:51], off
	v_lshl_add_u64 v[64:65], s[4:5], 0, v[86:87]
	global_load_dwordx2 v[58:59], v[58:59], off
	v_lshl_add_u64 v[68:69], s[8:9], 0, v[86:87]
	global_load_dwordx2 v[52:53], v[52:53], off
	v_add_u32_e32 v70, 0x40a0, v144
	global_load_dwordx2 v[66:67], v[64:65], off
	v_ashrrev_i32_e32 v71, 31, v70
	global_load_dwordx2 v[68:69], v[68:69], off
	v_lshlrev_b64 v[70:71], 10, v[70:71]
	v_lshl_add_u64 v[70:71], v[70:71], 0, v[136:137]
	v_lshlrev_b64 v[70:71], 1, v[70:71]
	v_lshl_add_u64 v[72:73], s[4:5], 0, v[70:71]
	s_waitcnt vmcnt(7)
	v_lshlrev_b32_e32 v74, 16, v48
	v_and_b32_e32 v75, 0xffff0000, v48
	v_lshlrev_b32_e32 v48, 16, v49
	v_and_b32_e32 v49, 0xffff0000, v49
	s_waitcnt vmcnt(4)
	v_lshlrev_b32_e32 v76, 16, v50
	v_and_b32_e32 v77, 0xffff0000, v50
	v_lshlrev_b32_e32 v50, 16, v51
	v_and_b32_e32 v51, 0xffff0000, v51
	v_lshlrev_b32_e32 v82, 16, v62
	v_and_b32_e32 v83, 0xffff0000, v62
	v_lshlrev_b32_e32 v62, 16, v63
	v_and_b32_e32 v63, 0xffff0000, v63
	s_waitcnt vmcnt(3)
	v_lshlrev_b32_e32 v84, 16, v58
	v_and_b32_e32 v85, 0xffff0000, v58
	v_lshlrev_b32_e32 v58, 16, v59
	v_and_b32_e32 v59, 0xffff0000, v59
	v_lshlrev_b32_e32 v78, 16, v56
	v_and_b32_e32 v79, 0xffff0000, v56
	v_lshlrev_b32_e32 v56, 16, v57
	v_and_b32_e32 v57, 0xffff0000, v57
	s_waitcnt vmcnt(2)
	v_lshlrev_b32_e32 v80, 16, v52
	v_and_b32_e32 v81, 0xffff0000, v52
	v_lshlrev_b32_e32 v52, 16, v53
	v_and_b32_e32 v53, 0xffff0000, v53
	s_waitcnt vmcnt(1)
	v_lshlrev_b32_e32 v86, 16, v66
	v_and_b32_e32 v87, 0xffff0000, v66
	v_lshlrev_b32_e32 v66, 16, v67
	v_and_b32_e32 v67, 0xffff0000, v67
	s_waitcnt vmcnt(0)
	v_lshlrev_b32_e32 v90, 16, v68
	v_and_b32_e32 v91, 0xffff0000, v68
	v_lshlrev_b32_e32 v68, 16, v69
	v_and_b32_e32 v69, 0xffff0000, v69
	v_pk_fma_f32 v[46:47], v[46:47], v[50:51], v[48:49]
	v_pk_fma_f32 v[44:45], v[44:45], v[76:77], v[74:75]
	v_pk_fma_f32 v[38:39], v[38:39], v[58:59], v[62:63]
	v_pk_fma_f32 v[36:37], v[36:37], v[84:85], v[82:83]
	v_pk_fma_f32 v[42:43], v[42:43], v[52:53], v[56:57]
	v_pk_fma_f32 v[40:41], v[40:41], v[80:81], v[78:79]
	v_pk_fma_f32 v[34:35], v[34:35], v[68:69], v[66:67]
	v_pk_fma_f32 v[32:33], v[32:33], v[90:91], v[86:87]
	v_cvt_pk_bf16_f32 v44, v44, v45
	v_cvt_pk_bf16_f32 v45, v46, v47
	v_cvt_pk_bf16_f32 v36, v36, v37
	v_cvt_pk_bf16_f32 v37, v38, v39
	v_cvt_pk_bf16_f32 v40, v40, v41
	v_cvt_pk_bf16_f32 v41, v42, v43
	v_cvt_pk_bf16_f32 v32, v32, v33
	v_cvt_pk_bf16_f32 v33, v34, v35
	global_store_dwordx2 v[88:89], v[44:45], off
	global_store_dwordx2 v[54:55], v[40:41], off
	global_store_dwordx2 v[60:61], v[36:37], off
	global_store_dwordx2 v[64:65], v[32:33], off
	v_or_b32_e32 v36, 32, v70
	v_mov_b32_e32 v37, v71
	v_or_b32_e32 v42, 0x100, v70
	v_mov_b32_e32 v43, v71
	v_lshl_add_u64 v[34:35], s[8:9], 0, v[70:71]
	v_lshl_add_u64 v[38:39], s[4:5], 0, v[36:37]
	v_lshl_add_u64 v[44:45], s[4:5], 0, v[42:43]
	v_lshl_add_u64 v[42:43], s[8:9], 0, v[42:43]
	v_or_b32_e32 v70, 0x120, v70
	global_load_dwordx2 v[32:33], v[72:73], off
	global_load_dwordx2 v[46:47], v[44:45], off
	global_load_dwordx2 v[40:41], v[38:39], off
	v_lshl_add_u64 v[36:37], s[8:9], 0, v[36:37]
	global_load_dwordx2 v[34:35], v[34:35], off
	v_lshl_add_u64 v[48:49], s[4:5], 0, v[70:71]
	global_load_dwordx2 v[42:43], v[42:43], off
	v_lshl_add_u64 v[52:53], s[8:9], 0, v[70:71]
	global_load_dwordx2 v[36:37], v[36:37], off
	v_add_u32_e32 v54, 0x40b0, v144
	global_load_dwordx2 v[50:51], v[48:49], off
	v_ashrrev_i32_e32 v55, 31, v54
	global_load_dwordx2 v[52:53], v[52:53], off
	v_lshlrev_b64 v[54:55], 10, v[54:55]
	v_lshl_add_u64 v[54:55], v[54:55], 0, v[136:137]
	v_lshlrev_b64 v[54:55], 1, v[54:55]
	v_lshl_add_u64 v[56:57], s[4:5], 0, v[54:55]
	s_waitcnt vmcnt(7)
; #define PG8_WAIT_V(n) asm volatile("s_waitcnt vmcnt(" #n ")" ::: "memory")
; #define PG8_BAR __builtin_amdgcn_s_barrier()
; __device__ __forceinline__ u32x2 pk4(f32x4 v) { u32x2 w; w.x = cvt_pk_bf16(v[0], v[1]); w.y = cvt_pk_bf16(v[2], v[3]); return w; }
; __device__ __forceinline__ f32x4 up4(u32x2 w) { return (f32x4){bf_lo(w.x), bf_hi(w.x), bf_lo(w.y), bf_hi(w.y)}; }
; template <class Epi, class Sched, bool ALIGN_EPI = false, bool SP2 = false>
; __device__ __forceinline__ void gemm_phase(PG8_LAS unsigned char* lds, const Gemm g, const Sched& S, const Epi& E) {
;     ...
;         if (!has_next) break;
;     ...
;     PG8_WAIT_V(0);
;     if constexpr (!ALIGN_EPI) { if (wr == 0) PG8_BAR; }
;     __device__ __forceinline__ void operator()(const AccT& acc, const pg8::Unit& u, int wr, int wc, int fr, int fq) const {
;     ...
;                     for (int n = 0; n < 2; ++n) { f32x4 v = acc[ai][bj][m][n]; const size_t idx = (size_t)row * 1024 + col0 + bj * 128 + n * 16;
;                         if (MODE == 0) v = v * up4(*(const u32x2*)(io + idx));
;                         else if (MODE == 1) v = up4(*(const u32x2*)(io + idx)) + up4(*(const u32x2*)(g2 + idx)) * v;
;                         else ss += (v[0] * v[0] + v[1] * v[1]) + (v[2] * v[2] + v[3] * v[3]);
;                         if (!DRYE || v[0] == 123.456f) *(u32x2*)(io + idx) = pk4(v); }
	v_lshlrev_b32_e32 v58, 16, v32
	v_and_b32_e32 v59, 0xffff0000, v32
	v_lshlrev_b32_e32 v32, 16, v33
	v_and_b32_e32 v33, 0xffff0000, v33
	s_waitcnt vmcnt(4)
	v_lshlrev_b32_e32 v60, 16, v34
	v_and_b32_e32 v61, 0xffff0000, v34
	v_lshlrev_b32_e32 v34, 16, v35
	v_and_b32_e32 v35, 0xffff0000, v35
	v_lshlrev_b32_e32 v66, 16, v46
	v_and_b32_e32 v67, 0xffff0000, v46
	v_lshlrev_b32_e32 v46, 16, v47
	v_and_b32_e32 v47, 0xffff0000, v47
	s_waitcnt vmcnt(3)
	v_lshlrev_b32_e32 v68, 16, v42
	v_and_b32_e32 v69, 0xffff0000, v42
	v_lshlrev_b32_e32 v42, 16, v43
	v_and_b32_e32 v43, 0xffff0000, v43
	v_lshlrev_b32_e32 v62, 16, v40
	v_and_b32_e32 v63, 0xffff0000, v40
	v_lshlrev_b32_e32 v40, 16, v41
	v_and_b32_e32 v41, 0xffff0000, v41
	s_waitcnt vmcnt(2)
	v_lshlrev_b32_e32 v64, 16, v36
	v_and_b32_e32 v65, 0xffff0000, v36
	v_lshlrev_b32_e32 v36, 16, v37
	v_and_b32_e32 v37, 0xffff0000, v37
	s_waitcnt vmcnt(1)
	v_lshlrev_b32_e32 v70, 16, v50
	v_and_b32_e32 v71, 0xffff0000, v50
	v_lshlrev_b32_e32 v50, 16, v51
	v_and_b32_e32 v51, 0xffff0000, v51
	s_waitcnt vmcnt(0)
	v_lshlrev_b32_e32 v74, 16, v52
	v_and_b32_e32 v75, 0xffff0000, v52
	v_lshlrev_b32_e32 v52, 16, v53
	v_and_b32_e32 v53, 0xffff0000, v53
	v_pk_fma_f32 v[30:31], v[30:31], v[34:35], v[32:33]
	v_pk_fma_f32 v[28:29], v[28:29], v[60:61], v[58:59]
	v_pk_fma_f32 v[22:23], v[22:23], v[42:43], v[46:47]
	v_pk_fma_f32 v[20:21], v[20:21], v[68:69], v[66:67]
	v_pk_fma_f32 v[26:27], v[26:27], v[36:37], v[40:41]
	v_pk_fma_f32 v[24:25], v[24:25], v[64:65], v[62:63]
	v_pk_fma_f32 v[18:19], v[18:19], v[52:53], v[50:51]
	v_pk_fma_f32 v[16:17], v[16:17], v[74:75], v[70:71]
	v_cvt_pk_bf16_f32 v28, v28, v29
	v_cvt_pk_bf16_f32 v29, v30, v31
	v_cvt_pk_bf16_f32 v20, v20, v21
	v_cvt_pk_bf16_f32 v21, v22, v23
	v_cvt_pk_bf16_f32 v24, v24, v25
	v_cvt_pk_bf16_f32 v25, v26, v27
	v_cvt_pk_bf16_f32 v16, v16, v17
	v_cvt_pk_bf16_f32 v17, v18, v19
	global_store_dwordx2 v[72:73], v[28:29], off
	global_store_dwordx2 v[38:39], v[24:25], off
	global_store_dwordx2 v[44:45], v[20:21], off
	global_store_dwordx2 v[48:49], v[16:17], off
	v_lshl_add_u64 v[18:19], s[8:9], 0, v[54:55]
	v_or_b32_e32 v20, 32, v54
	v_mov_b32_e32 v21, v55
	v_or_b32_e32 v26, 0x100, v54
	v_mov_b32_e32 v27, v55
	v_or_b32_e32 v54, 0x120, v54
	global_load_dwordx2 v[16:17], v[56:57], off
	v_lshl_add_u64 v[22:23], s[4:5], 0, v[20:21]
	global_load_dwordx2 v[18:19], v[18:19], off
	v_lshl_add_u64 v[20:21], s[8:9], 0, v[20:21]
	v_lshl_add_u64 v[28:29], s[4:5], 0, v[26:27]
	v_lshl_add_u64 v[26:27], s[8:9], 0, v[26:27]
	v_lshl_add_u64 v[32:33], s[4:5], 0, v[54:55]
	v_lshl_add_u64 v[36:37], s[8:9], 0, v[54:55]
	global_load_dwordx2 v[24:25], v[22:23], off
	global_load_dwordx2 v[30:31], v[28:29], off
	global_load_dwordx2 v[34:35], v[32:33], off
	s_nop 0
	global_load_dwordx2 v[36:37], v[36:37], off
	s_waitcnt vmcnt(5)
	v_lshlrev_b32_e32 v38, 16, v16
	global_load_dwordx2 v[26:27], v[26:27], off
	v_and_b32_e32 v39, 0xffff0000, v16
	global_load_dwordx2 v[20:21], v[20:21], off
	v_lshlrev_b32_e32 v16, 16, v17
	v_and_b32_e32 v17, 0xffff0000, v17
	s_waitcnt vmcnt(6)
	v_lshlrev_b32_e32 v40, 16, v18
	v_and_b32_e32 v41, 0xffff0000, v18
	v_lshlrev_b32_e32 v18, 16, v19
	v_and_b32_e32 v19, 0xffff0000, v19
	s_waitcnt vmcnt(5)
	v_lshlrev_b32_e32 v42, 16, v24
	v_and_b32_e32 v43, 0xffff0000, v24
	v_lshlrev_b32_e32 v24, 16, v25
	v_and_b32_e32 v25, 0xffff0000, v25
	s_waitcnt vmcnt(4)
	v_lshlrev_b32_e32 v46, 16, v30
	v_and_b32_e32 v47, 0xffff0000, v30
	v_lshlrev_b32_e32 v30, 16, v31
	v_and_b32_e32 v31, 0xffff0000, v31
	s_waitcnt vmcnt(3)
	v_lshlrev_b32_e32 v50, 16, v34
	v_and_b32_e32 v51, 0xffff0000, v34
	v_lshlrev_b32_e32 v34, 16, v35
	v_and_b32_e32 v35, 0xffff0000, v35
	s_waitcnt vmcnt(2)
	v_lshlrev_b32_e32 v52, 16, v36
	v_and_b32_e32 v53, 0xffff0000, v36
	v_lshlrev_b32_e32 v36, 16, v37
	v_and_b32_e32 v37, 0xffff0000, v37
	v_pk_fma_f32 v[14:15], v[14:15], v[18:19], v[16:17]
	v_pk_fma_f32 v[12:13], v[12:13], v[40:41], v[38:39]
	v_pk_fma_f32 v[2:3], v[2:3], v[36:37], v[34:35]
	v_pk_fma_f32 v[0:1], v[0:1], v[52:53], v[50:51]
	v_cvt_pk_bf16_f32 v12, v12, v13
	v_cvt_pk_bf16_f32 v13, v14, v15
	v_cvt_pk_bf16_f32 v0, v0, v1
	v_cvt_pk_bf16_f32 v1, v2, v3
	s_waitcnt vmcnt(1)
	v_lshlrev_b32_e32 v48, 16, v26
	v_and_b32_e32 v49, 0xffff0000, v26
	s_waitcnt vmcnt(0)
	v_lshlrev_b32_e32 v44, 16, v20
	v_and_b32_e32 v45, 0xffff0000, v20
	v_lshlrev_b32_e32 v20, 16, v21
	v_and_b32_e32 v21, 0xffff0000, v21
	v_lshlrev_b32_e32 v26, 16, v27
	v_and_b32_e32 v27, 0xffff0000, v27
	v_pk_fma_f32 v[10:11], v[10:11], v[20:21], v[24:25]
	v_pk_fma_f32 v[8:9], v[8:9], v[44:45], v[42:43]
	v_pk_fma_f32 v[6:7], v[6:7], v[26:27], v[30:31]
	v_pk_fma_f32 v[4:5], v[4:5], v[48:49], v[46:47]
	v_cvt_pk_bf16_f32 v8, v8, v9
	v_cvt_pk_bf16_f32 v9, v10, v11
	v_cvt_pk_bf16_f32 v4, v4, v5
	v_cvt_pk_bf16_f32 v5, v6, v7
	global_store_dwordx2 v[56:57], v[12:13], off
	global_store_dwordx2 v[22:23], v[8:9], off
	global_store_dwordx2 v[28:29], v[4:5], off
	global_store_dwordx2 v[32:33], v[0:1], off
	s_cbranch_vccz .LBB0_658
	s_waitcnt vmcnt(0)
	s_cmpk_gt_u32 s46, 0xff
	s_cbranch_scc1 .LBB0_669
	s_barrier

; #define PG8_STAGE(bufoff, gbase, voff) do { _Pragma("unroll") for (int _i = 0; _i < 2; ++_i) \
;         __builtin_amdgcn_global_load_lds((const unsigned*)((const char*)(gbase) + (voff)[_i]), (PG8_LAS unsigned*)(lds + (bufoff) + ldsw + _i * 8192), 16, 0, 0); } while (0)
; #define PG8_LDA(dst, b, h) do { _Pragma("unroll") for (int m = 0; m < 4; ++m) _Pragma("unroll") for (int k = 0; k < 2; ++k) dst[m][k] = *(const PG8_LAS bf16x8*)(lds + PG8_SA(b, h) + aoff + m * 2048 + k * 1024); } while (0)
; #define PG8_LDB(dst, b, h) do { _Pragma("unroll") for (int n = 0; n < 2; ++n) _Pragma("unroll") for (int k = 0; k < 2; ++k) dst[n][k] = *(const PG8_LAS bf16x8*)(lds + PG8_SB(b, h) + boff + n * 2048 + k * 1024); } while (0)
; #define PG8_MMA(ai, bj, At, Bt) do { __builtin_amdgcn_s_setprio(1); _Pragma("unroll") for (int m = 0; m < 4; ++m) _Pragma("unroll") for (int n = 0; n < 2; ++n) _Pragma("unroll") for (int k = 0; k < 2; ++k) \
;         acc[ai][bj][m][n] = __builtin_amdgcn_mfma_f32_16x16x32_bf16(Bt[n][k], At[m][k], acc[ai][bj][m][n], 0, 0, 0); __builtin_amdgcn_s_setprio(0); } while (0)
; #define PG8_BAR __builtin_amdgcn_s_barrier()
; template <class Epi, class Sched, bool ALIGN_EPI = false, bool SP2 = false>
; __device__ __forceinline__ void gemm_phase(PG8_LAS unsigned char* lds, const Gemm g, const Sched& S, const Epi& E) {
;     ...
;         const bool has_next = S.next(ui + 1, nxt);
;         const char* nA = has_next ? (const char*)g.A + (size_t)nxt.pm * tstep : cA; const char* nB = has_next ? (const char*)g.Bt + (size_t)nxt.pn * tstep : cB;
;         for (int t = 0; t < nt; t += 2) {
;             const bool last = (t == nt - 2);
;             const char* a1 = cA + (size_t)(t + 1) * kstep;
;             const char* a2 = last ? nA : cA + (size_t)(t + 2) * kstep; const char* b2 = last ? nB : cB + (size_t)(t + 2) * kstep;
;             const char* a3 = a2 + kstep; const char* b3 = b2 + kstep;
;             if (last && has_next) S.a_ready(nxt);
;             if constexpr (SP2) {
;             PG8_LDB(B0, 0, 0); PG8_LDB(B1, 0, 1); PG8_SCHED; PG8_LDA(At, 0, 0); PG8_STAGE(PG8_SA(1, 1), a1 + hstep, voffA);
;             PG8_WAIT_V(8); PG8_WAIT_L(0); PG8_BAR; PG8_MMA(0, 0, At, B0); PG8_MMA(0, 1, At, B1); PG8_BAR; PG8_SCHED;
;             PG8_LDA(At, 0, 1); PG8_STAGE(PG8_SB(0, 0), b2, voffB); PG8_STAGE(PG8_SB(0, 1), b2 + hstep, voffB); PG8_STAGE(PG8_SA(0, 0), a2, voffA);
.LBB0_815:
	ds_read_b128 v[140:143], v164
	ds_read_b128 v[144:147], v164 offset:1024
	ds_read_b128 v[168:171], v164 offset:2048
	ds_read_b128 v[172:175], v164 offset:3072
	ds_read_b128 v[180:183], v165
	ds_read_b128 v[184:187], v165 offset:1024
	ds_read_b128 v[188:191], v165 offset:2048
	ds_read_b128 v[192:195], v165 offset:3072
	s_add_u32 s3, s30, 0xfffe0080
	s_addc_u32 s33, s31, -1
	s_cmp_eq_u32 s80, 4
	s_cselect_b32 s41, s23, s33
	s_cselect_b32 s40, s76, s3
	s_cselect_b32 s35, s21, s79
	s_cselect_b32 s34, s77, s78
	v_lshl_add_u64 v[148:149], s[30:31], 0, v[132:133]
	s_add_i32 m0, s29, 0xc000
	ds_read_b128 v[196:199], v166
	ds_read_b128 v[200:203], v166 offset:1024
	ds_read_b128 v[204:207], v166 offset:2048
	ds_read_b128 v[208:211], v166 offset:3072
	ds_read_b128 v[212:215], v166 offset:4096
	ds_read_b128 v[216:219], v166 offset:5120
	ds_read_b128 v[220:223], v166 offset:6144
	ds_read_b128 v[224:227], v166 offset:7168
	global_load_lds_dwordx4 v[148:149], off
	v_lshl_add_u64 v[148:149], s[30:31], 0, v[134:135]
	s_add_i32 m0, s29, 0xe000
	s_nop 0
	global_load_lds_dwordx4 v[148:149], off
	s_waitcnt vmcnt(8)
	s_waitcnt lgkmcnt(0)
	s_barrier
	s_setprio 1
	s_waitcnt lgkmcnt(0)
	v_mfma_f32_16x16x32_bf16 v[124:127], v[140:143], v[196:199], v[124:127]
	v_mfma_f32_16x16x32_bf16 v[120:123], v[168:171], v[196:199], v[120:123]
	v_mfma_f32_16x16x32_bf16 v[116:119], v[140:143], v[204:207], v[116:119]
	v_mfma_f32_16x16x32_bf16 v[108:111], v[168:171], v[204:207], v[108:111]
	v_mfma_f32_16x16x32_bf16 v[92:95], v[140:143], v[212:215], v[92:95]
	v_mfma_f32_16x16x32_bf16 v[88:91], v[168:171], v[212:215], v[88:91]
	v_mfma_f32_16x16x32_bf16 v[80:83], v[140:143], v[220:223], v[80:83]
	v_mfma_f32_16x16x32_bf16 v[72:75], v[168:171], v[220:223], v[72:75]
	v_mfma_f32_16x16x32_bf16 v[124:127], v[144:147], v[200:203], v[124:127]
	v_mfma_f32_16x16x32_bf16 v[120:123], v[172:175], v[200:203], v[120:123]
	v_mfma_f32_16x16x32_bf16 v[116:119], v[144:147], v[208:211], v[116:119]
	v_mfma_f32_16x16x32_bf16 v[108:111], v[172:175], v[208:211], v[108:111]
	v_mfma_f32_16x16x32_bf16 v[92:95], v[144:147], v[216:219], v[92:95]
	v_mfma_f32_16x16x32_bf16 v[88:91], v[172:175], v[216:219], v[88:91]
	v_mfma_f32_16x16x32_bf16 v[80:83], v[144:147], v[224:227], v[80:83]
	v_mfma_f32_16x16x32_bf16 v[72:75], v[172:175], v[224:227], v[72:75]
	s_setprio 0
	s_setprio 1
	v_mfma_f32_16x16x32_bf16 v[112:115], v[180:183], v[196:199], v[112:115]
	v_mfma_f32_16x16x32_bf16 v[104:107], v[188:191], v[196:199], v[104:107]
	v_mfma_f32_16x16x32_bf16 v[100:103], v[180:183], v[204:207], v[100:103]
	v_mfma_f32_16x16x32_bf16 v[96:99], v[188:191], v[204:207], v[96:99]
	v_mfma_f32_16x16x32_bf16 v[84:87], v[180:183], v[212:215], v[84:87]
	v_mfma_f32_16x16x32_bf16 v[76:79], v[188:191], v[212:215], v[76:79]
	v_mfma_f32_16x16x32_bf16 v[68:71], v[180:183], v[220:223], v[68:71]
	v_mfma_f32_16x16x32_bf16 v[64:67], v[188:191], v[220:223], v[64:67]
	v_mfma_f32_16x16x32_bf16 v[112:115], v[184:187], v[200:203], v[112:115]
	v_mfma_f32_16x16x32_bf16 v[104:107], v[192:195], v[200:203], v[104:107]
	v_mfma_f32_16x16x32_bf16 v[100:103], v[184:187], v[208:211], v[100:103]
	v_mfma_f32_16x16x32_bf16 v[96:99], v[192:195], v[208:211], v[96:99]
	v_mfma_f32_16x16x32_bf16 v[84:87], v[184:187], v[216:219], v[84:87]
	v_mfma_f32_16x16x32_bf16 v[76:79], v[192:195], v[216:219], v[76:79]
	v_mfma_f32_16x16x32_bf16 v[68:71], v[184:187], v[224:227], v[68:71]
	v_mfma_f32_16x16x32_bf16 v[64:67], v[192:195], v[224:227], v[64:67]
	s_setprio 0
	s_barrier
	s_add_i32 s3, s69, s60
	v_lshl_add_u64 v[148:149], s[34:35], 0, v[128:129]
	s_mov_b32 m0, s3
	ds_read_b128 v[196:199], v166 offset:16384
	ds_read_b128 v[200:203], v166 offset:17408
	ds_read_b128 v[204:207], v166 offset:18432
	ds_read_b128 v[208:211], v166 offset:19456
	ds_read_b128 v[212:215], v166 offset:20480
	ds_read_b128 v[216:219], v166 offset:21504
	ds_read_b128 v[220:223], v166 offset:22528
	ds_read_b128 v[224:227], v166 offset:23552
	global_load_lds_dwordx4 v[148:149], off
	s_add_i32 m0, s3, 0x2000
	s_add_u32 s82, s34, 0x20000
	v_lshl_add_u64 v[228:229], s[34:35], 0, v[130:131]
	s_addc_u32 s83, s35, 0
	s_add_i32 s3, s70, s60
	global_load_lds_dwordx4 v[228:229], off
	v_lshl_add_u64 v[230:231], s[82:83], 0, v[128:129]
	s_mov_b32 m0, s3
	v_lshl_add_u64 v[232:233], s[40:41], 0, v[130:131]
	global_load_lds_dwordx4 v[230:231], off
	v_lshl_add_u64 v[230:231], s[82:83], 0, v[130:131]
	s_add_i32 m0, s3, 0x2000
	s_nop 0
	global_load_lds_dwordx4 v[230:231], off
	v_lshl_add_u64 v[230:231], s[40:41], 0, v[128:129]
	s_mov_b32 m0, s29
	s_nop 0
	global_load_lds_dwordx4 v[230:231], off
	s_mov_b32 m0, s61
	s_nop 0
	global_load_lds_dwordx4 v[232:233], off
	s_waitcnt vmcnt(8)
	s_waitcnt lgkmcnt(0)
	s_barrier
; #define PG8_STAGE(bufoff, gbase, voff) do { _Pragma("unroll") for (int _i = 0; _i < 2; ++_i) \
;         __builtin_amdgcn_global_load_lds((const unsigned*)((const char*)(gbase) + (voff)[_i]), (PG8_LAS unsigned*)(lds + (bufoff) + ldsw + _i * 8192), 16, 0, 0); } while (0)
; #define PG8_LDA(dst, b, h) do { _Pragma("unroll") for (int m = 0; m < 4; ++m) _Pragma("unroll") for (int k = 0; k < 2; ++k) dst[m][k] = *(const PG8_LAS bf16x8*)(lds + PG8_SA(b, h) + aoff + m * 2048 + k * 1024); } while (0)
; #define PG8_LDB(dst, b, h) do { _Pragma("unroll") for (int n = 0; n < 2; ++n) _Pragma("unroll") for (int k = 0; k < 2; ++k) dst[n][k] = *(const PG8_LAS bf16x8*)(lds + PG8_SB(b, h) + boff + n * 2048 + k * 1024); } while (0)
; #define PG8_MMA(ai, bj, At, Bt) do { __builtin_amdgcn_s_setprio(1); _Pragma("unroll") for (int m = 0; m < 4; ++m) _Pragma("unroll") for (int n = 0; n < 2; ++n) _Pragma("unroll") for (int k = 0; k < 2; ++k) \
;         acc[ai][bj][m][n] = __builtin_amdgcn_mfma_f32_16x16x32_bf16(Bt[n][k], At[m][k], acc[ai][bj][m][n], 0, 0, 0); __builtin_amdgcn_s_setprio(0); } while (0)
; #define PG8_WAIT_V(n) asm volatile("s_waitcnt vmcnt(" #n ")" ::: "memory")
; #define PG8_WAIT_L(n) asm volatile("s_waitcnt lgkmcnt(" #n ")" ::: "memory")
; #define PG8_BAR __builtin_amdgcn_s_barrier()
; #define PG8_SCHED __builtin_amdgcn_sched_barrier(0)
; template <class Epi, class Sched, bool ALIGN_EPI = false, bool SP2 = false>
; __device__ __forceinline__ void gemm_phase(PG8_LAS unsigned char* lds, const Gemm g, const Sched& S, const Epi& E) {
;     ...
;             PG8_WAIT_V(8); PG8_WAIT_L(0); PG8_BAR; PG8_MMA(1, 0, At, B0); PG8_MMA(1, 1, At, B1); PG8_BAR; PG8_SCHED;
;             PG8_LDB(B0, 1, 0); PG8_LDB(B1, 1, 1); PG8_SCHED; PG8_LDA(At, 1, 0); PG8_STAGE(PG8_SA(0, 1), a2 + hstep, voffA);
;             PG8_WAIT_V(8); PG8_WAIT_L(0); PG8_BAR; PG8_MMA(0, 0, At, B0); PG8_MMA(0, 1, At, B1); PG8_BAR; PG8_SCHED;
	s_setprio 1
	s_waitcnt lgkmcnt(0)
	v_mfma_f32_16x16x32_bf16 v[60:63], v[140:143], v[196:199], v[60:63]
	v_mfma_f32_16x16x32_bf16 v[56:59], v[168:171], v[196:199], v[56:59]
	v_mfma_f32_16x16x32_bf16 v[44:47], v[140:143], v[204:207], v[44:47]
	v_mfma_f32_16x16x32_bf16 v[40:43], v[168:171], v[204:207], v[40:43]
	v_mfma_f32_16x16x32_bf16 v[36:39], v[140:143], v[212:215], v[36:39]
	v_mfma_f32_16x16x32_bf16 v[28:31], v[168:171], v[212:215], v[28:31]
	v_mfma_f32_16x16x32_bf16 v[20:23], v[140:143], v[220:223], v[20:23]
	v_mfma_f32_16x16x32_bf16 v[12:15], v[168:171], v[220:223], v[12:15]
	v_mfma_f32_16x16x32_bf16 v[60:63], v[144:147], v[200:203], v[60:63]
	v_mfma_f32_16x16x32_bf16 v[56:59], v[172:175], v[200:203], v[56:59]
	v_mfma_f32_16x16x32_bf16 v[44:47], v[144:147], v[208:211], v[44:47]
	v_mfma_f32_16x16x32_bf16 v[40:43], v[172:175], v[208:211], v[40:43]
	v_mfma_f32_16x16x32_bf16 v[36:39], v[144:147], v[216:219], v[36:39]
	v_mfma_f32_16x16x32_bf16 v[28:31], v[172:175], v[216:219], v[28:31]
	v_mfma_f32_16x16x32_bf16 v[20:23], v[144:147], v[224:227], v[20:23]
	v_mfma_f32_16x16x32_bf16 v[12:15], v[172:175], v[224:227], v[12:15]
	s_setprio 0
	s_setprio 1
	v_mfma_f32_16x16x32_bf16 v[52:55], v[180:183], v[196:199], v[52:55]
	v_mfma_f32_16x16x32_bf16 v[48:51], v[188:191], v[196:199], v[48:51]
	v_mfma_f32_16x16x32_bf16 v[32:35], v[180:183], v[204:207], v[32:35]
	v_mfma_f32_16x16x32_bf16 v[24:27], v[188:191], v[204:207], v[24:27]
	v_mfma_f32_16x16x32_bf16 v[16:19], v[180:183], v[212:215], v[16:19]
	v_mfma_f32_16x16x32_bf16 v[8:11], v[188:191], v[212:215], v[8:11]
	v_mfma_f32_16x16x32_bf16 v[4:7], v[180:183], v[220:223], v[4:7]
	v_mfma_f32_16x16x32_bf16 v[0:3], v[188:191], v[220:223], v[0:3]
	v_mfma_f32_16x16x32_bf16 v[52:55], v[184:187], v[200:203], v[52:55]
	v_mfma_f32_16x16x32_bf16 v[48:51], v[192:195], v[200:203], v[48:51]
	v_mfma_f32_16x16x32_bf16 v[32:35], v[184:187], v[208:211], v[32:35]
	v_mfma_f32_16x16x32_bf16 v[24:27], v[192:195], v[208:211], v[24:27]
	v_mfma_f32_16x16x32_bf16 v[16:19], v[184:187], v[216:219], v[16:19]
	v_mfma_f32_16x16x32_bf16 v[8:11], v[192:195], v[216:219], v[8:11]
	v_mfma_f32_16x16x32_bf16 v[4:7], v[184:187], v[224:227], v[4:7]
	v_mfma_f32_16x16x32_bf16 v[0:3], v[192:195], v[224:227], v[0:3]
	s_setprio 0
	s_barrier
	s_add_i32 s3, 0, 0x18000
	v_add_u32_e32 v167, s3, v162
	s_add_i32 s33, 0, 0x1c000
	ds_read_b128 v[140:143], v167
	ds_read_b128 v[144:147], v167 offset:1024
	ds_read_b128 v[168:171], v167 offset:2048
	ds_read_b128 v[172:175], v167 offset:3072
	v_add_u32_e32 v167, s33, v162
	ds_read_b128 v[180:183], v167
	ds_read_b128 v[184:187], v167 offset:1024
	ds_read_b128 v[188:191], v167 offset:2048
	ds_read_b128 v[192:195], v167 offset:3072
	s_add_u32 s40, s40, 0x20000
	s_addc_u32 s41, s41, 0
	s_mov_b32 m0, s62
	v_lshl_add_u64 v[234:235], s[40:41], 0, v[128:129]
	ds_read_b128 v[196:199], v166 offset:32768
	ds_read_b128 v[200:203], v166 offset:33792
	ds_read_b128 v[204:207], v166 offset:34816
	ds_read_b128 v[208:211], v166 offset:35840
	ds_read_b128 v[212:215], v166 offset:36864
	ds_read_b128 v[216:219], v166 offset:37888
	ds_read_b128 v[220:223], v166 offset:38912
	ds_read_b128 v[224:227], v166 offset:39936
	global_load_lds_dwordx4 v[234:235], off
	v_lshl_add_u64 v[234:235], s[40:41], 0, v[130:131]
	s_mov_b32 m0, s63
	s_nop 0
	global_load_lds_dwordx4 v[234:235], off
	s_waitcnt vmcnt(8)
	s_waitcnt lgkmcnt(0)
	s_barrier
	s_setprio 1
	s_waitcnt lgkmcnt(0)
	v_mfma_f32_16x16x32_bf16 v[124:127], v[140:143], v[196:199], v[124:127]
	v_mfma_f32_16x16x32_bf16 v[120:123], v[168:171], v[196:199], v[120:123]
	v_mfma_f32_16x16x32_bf16 v[116:119], v[140:143], v[204:207], v[116:119]
	v_mfma_f32_16x16x32_bf16 v[108:111], v[168:171], v[204:207], v[108:111]
	v_mfma_f32_16x16x32_bf16 v[92:95], v[140:143], v[212:215], v[92:95]
	v_mfma_f32_16x16x32_bf16 v[88:91], v[168:171], v[212:215], v[88:91]
	v_mfma_f32_16x16x32_bf16 v[80:83], v[140:143], v[220:223], v[80:83]
	v_mfma_f32_16x16x32_bf16 v[72:75], v[168:171], v[220:223], v[72:75]
	v_mfma_f32_16x16x32_bf16 v[124:127], v[144:147], v[200:203], v[124:127]
	v_mfma_f32_16x16x32_bf16 v[120:123], v[172:175], v[200:203], v[120:123]
	v_mfma_f32_16x16x32_bf16 v[116:119], v[144:147], v[208:211], v[116:119]
	v_mfma_f32_16x16x32_bf16 v[108:111], v[172:175], v[208:211], v[108:111]
	v_mfma_f32_16x16x32_bf16 v[92:95], v[144:147], v[216:219], v[92:95]
	v_mfma_f32_16x16x32_bf16 v[88:91], v[172:175], v[216:219], v[88:91]
	v_mfma_f32_16x16x32_bf16 v[80:83], v[144:147], v[224:227], v[80:83]
	v_mfma_f32_16x16x32_bf16 v[72:75], v[172:175], v[224:227], v[72:75]
	s_setprio 0
	s_setprio 1
	v_mfma_f32_16x16x32_bf16 v[112:115], v[180:183], v[196:199], v[112:115]
	v_mfma_f32_16x16x32_bf16 v[104:107], v[188:191], v[196:199], v[104:107]
	v_mfma_f32_16x16x32_bf16 v[100:103], v[180:183], v[204:207], v[100:103]
	v_mfma_f32_16x16x32_bf16 v[96:99], v[188:191], v[204:207], v[96:99]
	v_mfma_f32_16x16x32_bf16 v[84:87], v[180:183], v[212:215], v[84:87]
	v_mfma_f32_16x16x32_bf16 v[76:79], v[188:191], v[212:215], v[76:79]
	v_mfma_f32_16x16x32_bf16 v[68:71], v[180:183], v[220:223], v[68:71]
	v_mfma_f32_16x16x32_bf16 v[64:67], v[188:191], v[220:223], v[64:67]
	v_mfma_f32_16x16x32_bf16 v[112:115], v[184:187], v[200:203], v[112:115]
	v_mfma_f32_16x16x32_bf16 v[104:107], v[192:195], v[200:203], v[104:107]
	v_mfma_f32_16x16x32_bf16 v[100:103], v[184:187], v[208:211], v[100:103]
	v_mfma_f32_16x16x32_bf16 v[96:99], v[192:195], v[208:211], v[96:99]
	v_mfma_f32_16x16x32_bf16 v[84:87], v[184:187], v[216:219], v[84:87]
	v_mfma_f32_16x16x32_bf16 v[76:79], v[192:195], v[216:219], v[76:79]
	v_mfma_f32_16x16x32_bf16 v[68:71], v[184:187], v[224:227], v[68:71]
	v_mfma_f32_16x16x32_bf16 v[64:67], v[192:195], v[224:227], v[64:67]
	s_setprio 0
	s_barrier
; #define PG8_STAGE(bufoff, gbase, voff) do { _Pragma("unroll") for (int _i = 0; _i < 2; ++_i) \
;         __builtin_amdgcn_global_load_lds((const unsigned*)((const char*)(gbase) + (voff)[_i]), (PG8_LAS unsigned*)(lds + (bufoff) + ldsw + _i * 8192), 16, 0, 0); } while (0)
; #define PG8_LDA(dst, b, h) do { _Pragma("unroll") for (int m = 0; m < 4; ++m) _Pragma("unroll") for (int k = 0; k < 2; ++k) dst[m][k] = *(const PG8_LAS bf16x8*)(lds + PG8_SA(b, h) + aoff + m * 2048 + k * 1024); } while (0)
; #define PG8_MMA(ai, bj, At, Bt) do { __builtin_amdgcn_s_setprio(1); _Pragma("unroll") for (int m = 0; m < 4; ++m) _Pragma("unroll") for (int n = 0; n < 2; ++n) _Pragma("unroll") for (int k = 0; k < 2; ++k) \
;         acc[ai][bj][m][n] = __builtin_amdgcn_mfma_f32_16x16x32_bf16(Bt[n][k], At[m][k], acc[ai][bj][m][n], 0, 0, 0); __builtin_amdgcn_s_setprio(0); } while (0)
; #define PG8_WAIT_V(n) asm volatile("s_waitcnt vmcnt(" #n ")" ::: "memory")
; #define PG8_WAIT_L(n) asm volatile("s_waitcnt lgkmcnt(" #n ")" ::: "memory")
; #define PG8_BAR __builtin_amdgcn_s_barrier()
; #define PG8_SCHED __builtin_amdgcn_sched_barrier(0)
; template <class Epi, class Sched, bool ALIGN_EPI = false, bool SP2 = false>
; __device__ __forceinline__ void gemm_phase(PG8_LAS unsigned char* lds, const Gemm g, const Sched& S, const Epi& E) {
;     ...
;             PG8_LDA(At, 1, 1); PG8_STAGE(PG8_SB(1, 0), b3, voffB); PG8_STAGE(PG8_SB(1, 1), b3 + hstep, voffB); PG8_STAGE(PG8_SA(1, 0), a3, voffA);
;             PG8_WAIT_V(8); PG8_WAIT_L(0); PG8_BAR; PG8_MMA(1, 0, At, B0); PG8_MMA(1, 1, At, B1); PG8_BAR; PG8_SCHED;
;     __device__ __forceinline__ void operator()(const AccT& acc, const pg8::Unit& u, int wr, int wc, int fr, int fq) const {
;         const int col0 = u.pn * 256 + wc * 32 + 4 * fq, row0 = row_base + u.pm * 256 + wr * 64 + fr;
; #pragma unroll
;         for (int ai = 0; ai < 2; ++ai)
; #pragma unroll
;             for (int m = 0; m < 4; ++m) { const int row = row0 + ai * 128 + m * 16; float ss = 0.f;
; #pragma unroll
;                 for (int bj = 0; bj < 2; ++bj)
; #pragma unroll
;                     for (int n = 0; n < 2; ++n) { f32x4 v = acc[ai][bj][m][n]; const size_t idx = (size_t)row * 1024 + col0 + bj * 128 + n * 16;
;                         if (MODE == 0) v = v * up4(*(const u32x2*)(io + idx));
	s_add_i32 s3, s3, s60
	v_lshl_add_u64 v[148:149], v[148:149], 0, s[8:9]
	s_mov_b32 m0, s3
	ds_read_b128 v[196:199], v166 offset:49152
	ds_read_b128 v[200:203], v166 offset:50176
	ds_read_b128 v[204:207], v166 offset:51200
	ds_read_b128 v[208:211], v166 offset:52224
	ds_read_b128 v[212:215], v166 offset:53248
	ds_read_b128 v[216:219], v166 offset:54272
	ds_read_b128 v[220:223], v166 offset:55296
	ds_read_b128 v[224:227], v166 offset:56320
	global_load_lds_dwordx4 v[148:149], off
	s_add_i32 m0, s3, 0x2000
	s_add_u32 s34, s34, 0x20080
	v_lshl_add_u64 v[148:149], v[228:229], 0, s[8:9]
	s_addc_u32 s35, s35, 0
	s_add_i32 s3, s33, s60
	global_load_lds_dwordx4 v[148:149], off
	v_lshl_add_u64 v[148:149], s[34:35], 0, v[128:129]
	s_mov_b32 m0, s3
	s_nop 0
	global_load_lds_dwordx4 v[148:149], off
	v_lshl_add_u64 v[148:149], s[34:35], 0, v[130:131]
	s_add_i32 m0, s3, 0x2000
	s_nop 0
	global_load_lds_dwordx4 v[148:149], off
	v_lshl_add_u64 v[148:149], v[230:231], 0, s[8:9]
	s_mov_b32 m0, s65
	s_nop 0
	global_load_lds_dwordx4 v[148:149], off
	v_lshl_add_u64 v[148:149], v[232:233], 0, s[8:9]
	s_mov_b32 m0, s66
	s_nop 0
	global_load_lds_dwordx4 v[148:149], off
	s_waitcnt vmcnt(8)
	s_waitcnt lgkmcnt(0)
	s_barrier
	s_setprio 1
	s_waitcnt lgkmcnt(0)
	v_mfma_f32_16x16x32_bf16 v[60:63], v[140:143], v[196:199], v[60:63]
	v_mfma_f32_16x16x32_bf16 v[56:59], v[168:171], v[196:199], v[56:59]
	v_mfma_f32_16x16x32_bf16 v[44:47], v[140:143], v[204:207], v[44:47]
	v_mfma_f32_16x16x32_bf16 v[40:43], v[168:171], v[204:207], v[40:43]
	v_mfma_f32_16x16x32_bf16 v[36:39], v[140:143], v[212:215], v[36:39]
	v_mfma_f32_16x16x32_bf16 v[28:31], v[168:171], v[212:215], v[28:31]
	v_mfma_f32_16x16x32_bf16 v[20:23], v[140:143], v[220:223], v[20:23]
	v_mfma_f32_16x16x32_bf16 v[12:15], v[168:171], v[220:223], v[12:15]
	v_mfma_f32_16x16x32_bf16 v[60:63], v[144:147], v[200:203], v[60:63]
	v_mfma_f32_16x16x32_bf16 v[56:59], v[172:175], v[200:203], v[56:59]
	v_mfma_f32_16x16x32_bf16 v[44:47], v[144:147], v[208:211], v[44:47]
	v_mfma_f32_16x16x32_bf16 v[40:43], v[172:175], v[208:211], v[40:43]
	v_mfma_f32_16x16x32_bf16 v[36:39], v[144:147], v[216:219], v[36:39]
	v_mfma_f32_16x16x32_bf16 v[28:31], v[172:175], v[216:219], v[28:31]
	v_mfma_f32_16x16x32_bf16 v[20:23], v[144:147], v[224:227], v[20:23]
	v_mfma_f32_16x16x32_bf16 v[12:15], v[172:175], v[224:227], v[12:15]
	s_setprio 0
	s_setprio 1
	v_mfma_f32_16x16x32_bf16 v[52:55], v[180:183], v[196:199], v[52:55]
	v_mfma_f32_16x16x32_bf16 v[48:51], v[188:191], v[196:199], v[48:51]
	v_mfma_f32_16x16x32_bf16 v[32:35], v[180:183], v[204:207], v[32:35]
	v_mfma_f32_16x16x32_bf16 v[24:27], v[188:191], v[204:207], v[24:27]
	v_mfma_f32_16x16x32_bf16 v[16:19], v[180:183], v[212:215], v[16:19]
	s_add_i32 s80, s80, 2
	s_add_u32 s30, s30, 0x100
	s_addc_u32 s31, s31, 0
	s_add_u32 s78, s78, 0x100
	s_addc_u32 s79, s79, 0
	s_cmp_gt_u32 s80, 5
	v_mfma_f32_16x16x32_bf16 v[8:11], v[188:191], v[212:215], v[8:11]
	v_mfma_f32_16x16x32_bf16 v[4:7], v[180:183], v[220:223], v[4:7]
	v_mfma_f32_16x16x32_bf16 v[0:3], v[188:191], v[220:223], v[0:3]
	v_mfma_f32_16x16x32_bf16 v[52:55], v[184:187], v[200:203], v[52:55]
	v_mfma_f32_16x16x32_bf16 v[48:51], v[192:195], v[200:203], v[48:51]
	v_mfma_f32_16x16x32_bf16 v[32:35], v[184:187], v[208:211], v[32:35]
	v_mfma_f32_16x16x32_bf16 v[24:27], v[192:195], v[208:211], v[24:27]
	v_mfma_f32_16x16x32_bf16 v[16:19], v[184:187], v[216:219], v[16:19]
	v_mfma_f32_16x16x32_bf16 v[8:11], v[192:195], v[216:219], v[8:11]
	v_mfma_f32_16x16x32_bf16 v[4:7], v[184:187], v[224:227], v[4:7]
	v_mfma_f32_16x16x32_bf16 v[0:3], v[192:195], v[224:227], v[0:3]
	s_setprio 0
	s_barrier
	s_cbranch_scc0 .LBB0_815
	v_lshl_add_u32 v142, s28, 8, v161
	v_lshl_or_b32 v140, s75, 8, v163
	v_ashrrev_i32_e32 v143, 31, v142
	v_ashrrev_i32_e32 v141, 31, v140
	v_lshlrev_b64 v[144:145], 11, v[142:143]
	v_lshl_add_u64 v[144:145], s[4:5], 0, v[144:145]
	v_lshlrev_b64 v[148:149], 1, v[140:141]
	v_lshl_add_u64 v[140:141], v[144:145], 0, v[148:149]
	v_or_b32_e32 v144, 16, v142
	v_ashrrev_i32_e32 v145, 31, v144
	v_lshlrev_b64 v[144:145], 11, v[144:145]
	global_load_dwordx2 v[146:147], v[140:141], off
	global_load_dwordx2 v[168:169], v[140:141], off offset:32
	global_load_dwordx2 v[170:171], v[140:141], off offset:256
	global_load_dwordx2 v[172:173], v[140:141], off offset:288
	v_lshl_add_u64 v[144:145], s[4:5], 0, v[144:145]
	v_lshl_add_u64 v[144:145], v[144:145], 0, v[148:149]
	global_load_dwordx2 v[174:175], v[144:145], off
	global_load_dwordx2 v[180:181], v[144:145], off offset:32
	global_load_dwordx2 v[182:183], v[144:145], off offset:256
	global_load_dwordx2 v[186:187], v[144:145], off offset:288
	v_or_b32_e32 v184, 32, v142
	v_or_b32_e32 v142, 48, v142
	v_ashrrev_i32_e32 v185, 31, v184
	v_ashrrev_i32_e32 v143, 31, v142
	v_lshlrev_b64 v[184:185], 11, v[184:185]
	v_lshlrev_b64 v[142:143], 11, v[142:143]
	v_lshl_add_u64 v[184:185], s[4:5], 0, v[184:185]
	v_lshl_add_u64 v[142:143], s[4:5], 0, v[142:143]
	v_lshl_add_u64 v[184:185], v[184:185], 0, v[148:149]
	v_lshl_add_u64 v[142:143], v[142:143], 0, v[148:149]
	global_load_dwordx2 v[188:189], v[184:185], off
	global_load_dwordx2 v[190:191], v[184:185], off offset:32
	global_load_dwordx2 v[192:193], v[184:185], off offset:256
	global_load_dwordx2 v[194:195], v[184:185], off offset:288
	global_load_dwordx2 v[196:197], v[142:143], off
	global_load_dwordx2 v[148:149], v[142:143], off offset:32
	s_mov_b32 s75, s20
	s_mov_b32 s28, s22
	s_mov_b64 s[34:35], s[26:27]
	s_mov_b64 s[30:31], s[24:25]
	s_waitcnt vmcnt(0)
; __device__ __forceinline__ u32x2 pk4(f32x4 v) { u32x2 w; w.x = cvt_pk_bf16(v[0], v[1]); w.y = cvt_pk_bf16(v[2], v[3]); return w; }
; __device__ __forceinline__ f32x4 up4(u32x2 w) { return (f32x4){bf_lo(w.x), bf_hi(w.x), bf_lo(w.y), bf_hi(w.y)}; }
;     __device__ __forceinline__ void operator()(const AccT& acc, const pg8::Unit& u, int wr, int wc, int fr, int fq) const {
;     ...
;             for (int m = 0; m < 4; ++m) { const int row = row0 + ai * 128 + m * 16; float ss = 0.f;
; #pragma unroll
;                 for (int bj = 0; bj < 2; ++bj)
; #pragma unroll
;                     for (int n = 0; n < 2; ++n) { f32x4 v = acc[ai][bj][m][n]; const size_t idx = (size_t)row * 1024 + col0 + bj * 128 + n * 16;
;                         if (MODE == 0) v = v * up4(*(const u32x2*)(io + idx));
;                         else if (MODE == 1) v = up4(*(const u32x2*)(io + idx)) + up4(*(const u32x2*)(g2 + idx)) * v;
;                         else ss += (v[0] * v[0] + v[1] * v[1]) + (v[2] * v[2] + v[3] * v[3]);
;                         if (!DRYE || v[0] == 123.456f) *(u32x2*)(io + idx) = pk4(v); }
	v_lshlrev_b32_e32 v198, 16, v146
	v_and_b32_e32 v199, 0xffff0000, v146
	v_lshlrev_b32_e32 v146, 16, v147
	v_and_b32_e32 v147, 0xffff0000, v147
	v_lshlrev_b32_e32 v200, 16, v168
	v_and_b32_e32 v201, 0xffff0000, v168
	v_lshlrev_b32_e32 v168, 16, v169
	v_and_b32_e32 v169, 0xffff0000, v169
	v_lshlrev_b32_e32 v202, 16, v170
	v_and_b32_e32 v203, 0xffff0000, v170
	v_lshlrev_b32_e32 v170, 16, v171
	v_and_b32_e32 v171, 0xffff0000, v171
	v_lshlrev_b32_e32 v204, 16, v172
	v_and_b32_e32 v205, 0xffff0000, v172
	v_lshlrev_b32_e32 v172, 16, v173
	v_and_b32_e32 v173, 0xffff0000, v173
	v_pk_mul_f32 v[126:127], v[126:127], v[146:147]
	v_pk_mul_f32 v[124:125], v[124:125], v[198:199]
	v_pk_mul_f32 v[122:123], v[122:123], v[168:169]
	v_pk_mul_f32 v[114:115], v[114:115], v[170:171]
	v_pk_mul_f32 v[112:113], v[112:113], v[202:203]
	v_pk_mul_f32 v[106:107], v[106:107], v[172:173]
	v_pk_mul_f32 v[104:105], v[104:105], v[204:205]
	v_lshlrev_b32_e32 v146, 16, v174
	v_and_b32_e32 v147, 0xffff0000, v174
	v_lshlrev_b32_e32 v168, 16, v175
	v_and_b32_e32 v169, 0xffff0000, v175
	v_lshlrev_b32_e32 v170, 16, v180
	v_and_b32_e32 v171, 0xffff0000, v180
	v_lshlrev_b32_e32 v172, 16, v181
	v_and_b32_e32 v173, 0xffff0000, v181
	v_pk_mul_f32 v[120:121], v[120:121], v[200:201]
	v_cvt_pk_bf16_f32 v124, v124, v125
	v_cvt_pk_bf16_f32 v125, v126, v127
	v_cvt_pk_bf16_f32 v112, v112, v113
	v_cvt_pk_bf16_f32 v113, v114, v115
	v_cvt_pk_bf16_f32 v104, v104, v105
	v_cvt_pk_bf16_f32 v105, v106, v107
	v_pk_mul_f32 v[106:107], v[118:119], v[168:169]
	v_pk_mul_f32 v[114:115], v[116:117], v[146:147]
	v_pk_mul_f32 v[110:111], v[110:111], v[172:173]
	v_pk_mul_f32 v[108:109], v[108:109], v[170:171]
	v_cvt_pk_bf16_f32 v120, v120, v121
	v_cvt_pk_bf16_f32 v121, v122, v123
	global_store_dwordx2 v[140:141], v[124:125], off
	global_store_dwordx2 v[140:141], v[120:121], off offset:32
	global_store_dwordx2 v[140:141], v[112:113], off offset:256
	global_store_dwordx2 v[140:141], v[104:105], off offset:288
	v_cvt_pk_bf16_f32 v104, v114, v115
	v_cvt_pk_bf16_f32 v105, v106, v107
	v_cvt_pk_bf16_f32 v106, v108, v109
	v_cvt_pk_bf16_f32 v107, v110, v111
	global_store_dwordx2 v[144:145], v[104:105], off
	global_store_dwordx2 v[144:145], v[106:107], off offset:32
	v_lshlrev_b32_e32 v104, 16, v182
	v_and_b32_e32 v105, 0xffff0000, v182
	v_lshlrev_b32_e32 v106, 16, v183
	v_and_b32_e32 v107, 0xffff0000, v183
	v_pk_mul_f32 v[102:103], v[102:103], v[106:107]
	v_pk_mul_f32 v[100:101], v[100:101], v[104:105]
	v_lshlrev_b32_e32 v104, 16, v187
	v_cvt_pk_bf16_f32 v100, v100, v101
	v_cvt_pk_bf16_f32 v101, v102, v103
	global_load_dwordx2 v[102:103], v[142:143], off offset:256
	v_and_b32_e32 v105, 0xffff0000, v187
	global_store_dwordx2 v[144:145], v[100:101], off offset:256
	v_lshlrev_b32_e32 v100, 16, v186
	v_and_b32_e32 v101, 0xffff0000, v186
	v_pk_mul_f32 v[98:99], v[98:99], v[104:105]
	v_pk_mul_f32 v[96:97], v[96:97], v[100:101]
	v_lshlrev_b32_e32 v100, 16, v189
	v_cvt_pk_bf16_f32 v96, v96, v97
	v_cvt_pk_bf16_f32 v97, v98, v99
	global_store_dwordx2 v[144:145], v[96:97], off offset:288
	global_load_dwordx2 v[96:97], v[142:143], off offset:288
	v_and_b32_e32 v101, 0xffff0000, v189
	v_pk_mul_f32 v[94:95], v[94:95], v[100:101]
	v_add_co_u32_e32 v100, vcc, s71, v140
	v_lshlrev_b32_e32 v98, 16, v188
	v_and_b32_e32 v99, 0xffff0000, v188
	v_addc_co_u32_e32 v101, vcc, 0, v141, vcc
	global_load_dwordx2 v[104:105], v[100:101], off
	v_pk_mul_f32 v[92:93], v[92:93], v[98:99]
	s_nop 0
	v_cvt_pk_bf16_f32 v92, v92, v93
	v_cvt_pk_bf16_f32 v93, v94, v95
	global_store_dwordx2 v[184:185], v[92:93], off
	v_lshlrev_b32_e32 v92, 16, v190
	v_and_b32_e32 v93, 0xffff0000, v190
	v_lshlrev_b32_e32 v94, 16, v191
	v_and_b32_e32 v95, 0xffff0000, v191
	v_pk_mul_f32 v[90:91], v[90:91], v[94:95]
	v_pk_mul_f32 v[88:89], v[88:89], v[92:93]
	v_lshlrev_b32_e32 v92, 16, v192
	v_cvt_pk_bf16_f32 v88, v88, v89
	v_cvt_pk_bf16_f32 v89, v90, v91
	global_store_dwordx2 v[184:185], v[88:89], off offset:32
	v_lshl_add_u64 v[88:89], v[140:141], 0, s[10:11]
	global_load_dwordx2 v[90:91], v[88:89], off offset:32
	v_and_b32_e32 v93, 0xffff0000, v192
	v_lshlrev_b32_e32 v94, 16, v193
	v_and_b32_e32 v95, 0xffff0000, v193
	v_pk_mul_f32 v[86:87], v[86:87], v[94:95]
	v_pk_mul_f32 v[84:85], v[84:85], v[92:93]
	v_lshlrev_b32_e32 v92, 16, v195
	v_cvt_pk_bf16_f32 v84, v84, v85
	v_cvt_pk_bf16_f32 v85, v86, v87
	global_load_dwordx2 v[86:87], v[88:89], off offset:256
	v_and_b32_e32 v93, 0xffff0000, v195
	global_store_dwordx2 v[184:185], v[84:85], off offset:256
	v_lshlrev_b32_e32 v84, 16, v194
	v_and_b32_e32 v85, 0xffff0000, v194
	v_pk_mul_f32 v[78:79], v[78:79], v[92:93]
	v_pk_mul_f32 v[76:77], v[76:77], v[84:85]
	v_lshlrev_b32_e32 v84, 16, v197
	v_cvt_pk_bf16_f32 v76, v76, v77
	v_cvt_pk_bf16_f32 v77, v78, v79
	global_load_dwordx2 v[78:79], v[88:89], off offset:288
	v_and_b32_e32 v85, 0xffff0000, v197
	global_store_dwordx2 v[184:185], v[76:77], off offset:288
	v_lshlrev_b32_e32 v76, 16, v196
	v_and_b32_e32 v77, 0xffff0000, v196
	v_pk_mul_f32 v[82:83], v[82:83], v[84:85]
	v_pk_mul_f32 v[76:77], v[80:81], v[76:77]
	v_add_co_u32_e32 v80, vcc, s72, v140
	v_cvt_pk_bf16_f32 v76, v76, v77
	v_cvt_pk_bf16_f32 v77, v82, v83
	global_store_dwordx2 v[142:143], v[76:77], off
	v_lshlrev_b32_e32 v76, 16, v148
	v_and_b32_e32 v77, 0xffff0000, v148
	v_addc_co_u32_e32 v81, vcc, 0, v141, vcc
	v_lshlrev_b32_e32 v84, 16, v149
	v_and_b32_e32 v85, 0xffff0000, v149
	global_load_dwordx2 v[82:83], v[80:81], off
	v_pk_mul_f32 v[74:75], v[74:75], v[84:85]
	v_pk_mul_f32 v[72:73], v[72:73], v[76:77]
	s_waitcnt vmcnt(13)
; __device__ __forceinline__ u32x2 pk4(f32x4 v) { u32x2 w; w.x = cvt_pk_bf16(v[0], v[1]); w.y = cvt_pk_bf16(v[2], v[3]); return w; }
; __device__ __forceinline__ f32x4 up4(u32x2 w) { return (f32x4){bf_lo(w.x), bf_hi(w.x), bf_lo(w.y), bf_hi(w.y)}; }
;     __device__ __forceinline__ void operator()(const AccT& acc, const pg8::Unit& u, int wr, int wc, int fr, int fq) const {
;     ...
;             for (int m = 0; m < 4; ++m) { const int row = row0 + ai * 128 + m * 16; float ss = 0.f;
; #pragma unroll
;                 for (int bj = 0; bj < 2; ++bj)
; #pragma unroll
;                     for (int n = 0; n < 2; ++n) { f32x4 v = acc[ai][bj][m][n]; const size_t idx = (size_t)row * 1024 + col0 + bj * 128 + n * 16;
;                         if (MODE == 0) v = v * up4(*(const u32x2*)(io + idx));
;                         else if (MODE == 1) v = up4(*(const u32x2*)(io + idx)) + up4(*(const u32x2*)(g2 + idx)) * v;
;                         else ss += (v[0] * v[0] + v[1] * v[1]) + (v[2] * v[2] + v[3] * v[3]);
;                         if (!DRYE || v[0] == 123.456f) *(u32x2*)(io + idx) = pk4(v); }
	v_lshlrev_b32_e32 v84, 16, v103
	v_cvt_pk_bf16_f32 v72, v72, v73
	v_cvt_pk_bf16_f32 v73, v74, v75
	global_store_dwordx2 v[142:143], v[72:73], off offset:32
	v_lshl_add_u64 v[72:73], v[140:141], 0, s[14:15]
	global_load_dwordx2 v[76:77], v[72:73], off offset:32
	v_lshlrev_b32_e32 v74, 16, v102
	v_and_b32_e32 v75, 0xffff0000, v102
	v_and_b32_e32 v85, 0xffff0000, v103
	v_pk_mul_f32 v[70:71], v[70:71], v[84:85]
	v_pk_mul_f32 v[68:69], v[68:69], v[74:75]
	s_waitcnt vmcnt(12)
	v_lshlrev_b32_e32 v74, 16, v97
	v_cvt_pk_bf16_f32 v68, v68, v69
	v_cvt_pk_bf16_f32 v69, v70, v71
	global_store_dwordx2 v[142:143], v[68:69], off offset:256
	v_lshlrev_b32_e32 v68, 16, v96
	v_and_b32_e32 v69, 0xffff0000, v96
	global_load_dwordx2 v[70:71], v[72:73], off offset:256
	v_and_b32_e32 v75, 0xffff0000, v97
	v_pk_mul_f32 v[66:67], v[66:67], v[74:75]
	v_pk_mul_f32 v[64:65], v[64:65], v[68:69]
	s_waitcnt vmcnt(13)
	v_lshlrev_b32_e32 v68, 16, v105
	v_cvt_pk_bf16_f32 v64, v64, v65
	v_cvt_pk_bf16_f32 v65, v66, v67
	global_store_dwordx2 v[142:143], v[64:65], off offset:288
	v_lshlrev_b32_e32 v64, 16, v104
	v_and_b32_e32 v65, 0xffff0000, v104
	global_load_dwordx2 v[66:67], v[72:73], off offset:288
	v_pk_mul_f32 v[60:61], v[60:61], v[64:65]
	v_add_co_u32_e32 v64, vcc, s73, v140
	v_and_b32_e32 v69, 0xffff0000, v105
	s_nop 0
	v_addc_co_u32_e32 v65, vcc, 0, v141, vcc
	v_pk_mul_f32 v[62:63], v[62:63], v[68:69]
	global_load_dwordx2 v[68:69], v[64:65], off
	v_cvt_pk_bf16_f32 v60, v60, v61
	v_cvt_pk_bf16_f32 v61, v62, v63
	v_lshl_add_u64 v[74:75], v[140:141], 0, s[16:17]
	global_store_dwordx2 v[100:101], v[60:61], off
	s_waitcnt vmcnt(14)
	v_lshlrev_b32_e32 v60, 16, v90
	v_and_b32_e32 v61, 0xffff0000, v90
	v_lshlrev_b32_e32 v62, 16, v91
	v_and_b32_e32 v63, 0xffff0000, v91
	global_load_dwordx2 v[84:85], v[74:75], off offset:32
	v_pk_mul_f32 v[58:59], v[58:59], v[62:63]
	v_pk_mul_f32 v[56:57], v[56:57], v[60:61]
	global_load_dwordx2 v[60:61], v[74:75], off offset:256
	v_cvt_pk_bf16_f32 v56, v56, v57
	v_cvt_pk_bf16_f32 v57, v58, v59
	global_store_dwordx2 v[88:89], v[56:57], off offset:32
	s_waitcnt vmcnt(16)
	v_lshlrev_b32_e32 v56, 16, v86
	v_and_b32_e32 v57, 0xffff0000, v86
	v_lshlrev_b32_e32 v58, 16, v87
	v_and_b32_e32 v59, 0xffff0000, v87
	v_pk_mul_f32 v[54:55], v[54:55], v[58:59]
	v_pk_mul_f32 v[52:53], v[52:53], v[56:57]
	s_waitcnt vmcnt(14)
	v_lshlrev_b32_e32 v56, 16, v79
	v_cvt_pk_bf16_f32 v52, v52, v53
	v_cvt_pk_bf16_f32 v53, v54, v55
	global_store_dwordx2 v[88:89], v[52:53], off offset:256
	v_lshlrev_b32_e32 v52, 16, v78
	v_and_b32_e32 v53, 0xffff0000, v78
	global_load_dwordx2 v[54:55], v[74:75], off offset:288
	v_pk_mul_f32 v[48:49], v[48:49], v[52:53]
	v_add_co_u32_e32 v52, vcc, s74, v140
	v_and_b32_e32 v57, 0xffff0000, v79
	s_nop 0
	v_addc_co_u32_e32 v53, vcc, 0, v141, vcc
	v_pk_mul_f32 v[50:51], v[50:51], v[56:57]
	global_load_dwordx2 v[56:57], v[52:53], off
	v_lshl_add_u64 v[58:59], v[140:141], 0, s[18:19]
	v_cvt_pk_bf16_f32 v48, v48, v49
	v_cvt_pk_bf16_f32 v49, v50, v51
	global_load_dwordx2 v[62:63], v[58:59], off offset:32
	s_waitcnt vmcnt(15)
	v_lshlrev_b32_e32 v50, 16, v83
	global_store_dwordx2 v[88:89], v[48:49], off offset:288
	v_lshlrev_b32_e32 v48, 16, v82
	v_and_b32_e32 v49, 0xffff0000, v82
	v_and_b32_e32 v51, 0xffff0000, v83
	v_pk_mul_f32 v[46:47], v[46:47], v[50:51]
	v_pk_mul_f32 v[44:45], v[44:45], v[48:49]
	global_load_dwordx2 v[48:49], v[58:59], off offset:256
	v_cvt_pk_bf16_f32 v44, v44, v45
	v_cvt_pk_bf16_f32 v45, v46, v47
	global_store_dwordx2 v[80:81], v[44:45], off
	s_waitcnt vmcnt(16)
	v_lshlrev_b32_e32 v44, 16, v76
	v_and_b32_e32 v45, 0xffff0000, v76
	v_lshlrev_b32_e32 v46, 16, v77
	v_and_b32_e32 v47, 0xffff0000, v77
	v_pk_mul_f32 v[42:43], v[42:43], v[46:47]
	v_pk_mul_f32 v[40:41], v[40:41], v[44:45]
	s_and_b64 vcc, exec, s[0:1]
	v_cvt_pk_bf16_f32 v40, v40, v41
	v_cvt_pk_bf16_f32 v41, v42, v43
	global_load_dwordx2 v[42:43], v[58:59], off offset:288
	s_waitcnt vmcnt(15)
; #define PG8_WAIT_V(n) asm volatile("s_waitcnt vmcnt(" #n ")" ::: "memory")
; #define PG8_BAR __builtin_amdgcn_s_barrier()
; __device__ __forceinline__ u32x2 pk4(f32x4 v) { u32x2 w; w.x = cvt_pk_bf16(v[0], v[1]); w.y = cvt_pk_bf16(v[2], v[3]); return w; }
; __device__ __forceinline__ f32x4 up4(u32x2 w) { return (f32x4){bf_lo(w.x), bf_hi(w.x), bf_lo(w.y), bf_hi(w.y)}; }
; template <class Epi, class Sched, bool ALIGN_EPI = false, bool SP2 = false>
; __device__ __forceinline__ void gemm_phase(PG8_LAS unsigned char* lds, const Gemm g, const Sched& S, const Epi& E) {
;     ...
;         if (!has_next) break;
;     ...
;     PG8_WAIT_V(0);
;     if constexpr (!ALIGN_EPI) { if (wr == 0) PG8_BAR; }
;     __device__ __forceinline__ void operator()(const AccT& acc, const pg8::Unit& u, int wr, int wc, int fr, int fq) const {
;     ...
;             for (int m = 0; m < 4; ++m) { const int row = row0 + ai * 128 + m * 16; float ss = 0.f;
; #pragma unroll
;                 for (int bj = 0; bj < 2; ++bj)
; #pragma unroll
;                     for (int n = 0; n < 2; ++n) { f32x4 v = acc[ai][bj][m][n]; const size_t idx = (size_t)row * 1024 + col0 + bj * 128 + n * 16;
;                         if (MODE == 0) v = v * up4(*(const u32x2*)(io + idx));
;                         else if (MODE == 1) v = up4(*(const u32x2*)(io + idx)) + up4(*(const u32x2*)(g2 + idx)) * v;
;                         else ss += (v[0] * v[0] + v[1] * v[1]) + (v[2] * v[2] + v[3] * v[3]);
;                         if (!DRYE || v[0] == 123.456f) *(u32x2*)(io + idx) = pk4(v); }
	v_lshlrev_b32_e32 v44, 16, v71
	global_store_dwordx2 v[72:73], v[40:41], off offset:32
	v_lshlrev_b32_e32 v40, 16, v70
	v_and_b32_e32 v41, 0xffff0000, v70
	v_and_b32_e32 v45, 0xffff0000, v71
	v_pk_mul_f32 v[34:35], v[34:35], v[44:45]
	v_pk_mul_f32 v[32:33], v[32:33], v[40:41]
	s_nop 0
	v_cvt_pk_bf16_f32 v32, v32, v33
	v_cvt_pk_bf16_f32 v33, v34, v35
	global_store_dwordx2 v[72:73], v[32:33], off offset:256
	s_waitcnt vmcnt(15)
	v_lshlrev_b32_e32 v32, 16, v66
	v_and_b32_e32 v33, 0xffff0000, v66
	v_lshlrev_b32_e32 v34, 16, v67
	v_and_b32_e32 v35, 0xffff0000, v67
	v_pk_mul_f32 v[26:27], v[26:27], v[34:35]
	v_pk_mul_f32 v[24:25], v[24:25], v[32:33]
	s_nop 0
	v_cvt_pk_bf16_f32 v24, v24, v25
	v_cvt_pk_bf16_f32 v25, v26, v27
	global_store_dwordx2 v[72:73], v[24:25], off offset:288
	s_waitcnt vmcnt(15)
	v_lshlrev_b32_e32 v24, 16, v68
	v_and_b32_e32 v25, 0xffff0000, v68
	v_lshlrev_b32_e32 v26, 16, v69
	v_and_b32_e32 v27, 0xffff0000, v69
	v_pk_mul_f32 v[26:27], v[38:39], v[26:27]
	v_pk_mul_f32 v[24:25], v[36:37], v[24:25]
	s_nop 0
	v_cvt_pk_bf16_f32 v24, v24, v25
	v_cvt_pk_bf16_f32 v25, v26, v27
	global_store_dwordx2 v[64:65], v[24:25], off
	s_waitcnt vmcnt(14)
	v_lshlrev_b32_e32 v24, 16, v84
	v_and_b32_e32 v25, 0xffff0000, v84
	v_lshlrev_b32_e32 v26, 16, v85
	v_and_b32_e32 v27, 0xffff0000, v85
	v_pk_mul_f32 v[26:27], v[30:31], v[26:27]
	v_pk_mul_f32 v[24:25], v[28:29], v[24:25]
	s_nop 0
	v_cvt_pk_bf16_f32 v24, v24, v25
	v_cvt_pk_bf16_f32 v25, v26, v27
	global_store_dwordx2 v[74:75], v[24:25], off offset:32
	s_waitcnt vmcnt(14)
	v_lshlrev_b32_e32 v24, 16, v60
	v_and_b32_e32 v25, 0xffff0000, v60
	v_lshlrev_b32_e32 v26, 16, v61
	v_and_b32_e32 v27, 0xffff0000, v61
	v_pk_mul_f32 v[18:19], v[18:19], v[26:27]
	v_pk_mul_f32 v[16:17], v[16:17], v[24:25]
	s_nop 0
	v_cvt_pk_bf16_f32 v16, v16, v17
	v_cvt_pk_bf16_f32 v17, v18, v19
	global_store_dwordx2 v[74:75], v[16:17], off offset:256
	s_waitcnt vmcnt(12)
	v_lshlrev_b32_e32 v16, 16, v54
	v_and_b32_e32 v17, 0xffff0000, v54
	v_lshlrev_b32_e32 v18, 16, v55
	v_and_b32_e32 v19, 0xffff0000, v55
	v_pk_mul_f32 v[10:11], v[10:11], v[18:19]
	v_pk_mul_f32 v[8:9], v[8:9], v[16:17]
	s_nop 0
	v_cvt_pk_bf16_f32 v8, v8, v9
	v_cvt_pk_bf16_f32 v9, v10, v11
	global_store_dwordx2 v[74:75], v[8:9], off offset:288
	s_waitcnt vmcnt(12)
	v_lshlrev_b32_e32 v8, 16, v56
	v_and_b32_e32 v9, 0xffff0000, v56
	v_lshlrev_b32_e32 v10, 16, v57
	v_and_b32_e32 v11, 0xffff0000, v57
	v_pk_mul_f32 v[10:11], v[22:23], v[10:11]
	v_pk_mul_f32 v[8:9], v[20:21], v[8:9]
	s_nop 0
	v_cvt_pk_bf16_f32 v8, v8, v9
	v_cvt_pk_bf16_f32 v9, v10, v11
	global_store_dwordx2 v[52:53], v[8:9], off
	s_waitcnt vmcnt(12)
	v_lshlrev_b32_e32 v8, 16, v62
	v_and_b32_e32 v9, 0xffff0000, v62
	v_lshlrev_b32_e32 v10, 16, v63
	v_and_b32_e32 v11, 0xffff0000, v63
	v_pk_mul_f32 v[10:11], v[14:15], v[10:11]
	v_pk_mul_f32 v[8:9], v[12:13], v[8:9]
	s_nop 0
	v_cvt_pk_bf16_f32 v8, v8, v9
	v_cvt_pk_bf16_f32 v9, v10, v11
	global_store_dwordx2 v[58:59], v[8:9], off offset:32
	s_waitcnt vmcnt(11)
	v_lshlrev_b32_e32 v8, 16, v48
	v_and_b32_e32 v9, 0xffff0000, v48
	v_lshlrev_b32_e32 v10, 16, v49
	v_and_b32_e32 v11, 0xffff0000, v49
	v_pk_mul_f32 v[6:7], v[6:7], v[10:11]
	v_pk_mul_f32 v[4:5], v[4:5], v[8:9]
	s_nop 0
	v_cvt_pk_bf16_f32 v4, v4, v5
	v_cvt_pk_bf16_f32 v5, v6, v7
	global_store_dwordx2 v[58:59], v[4:5], off offset:256
	s_waitcnt vmcnt(10)
	v_lshlrev_b32_e32 v4, 16, v42
	v_and_b32_e32 v5, 0xffff0000, v42
	v_lshlrev_b32_e32 v6, 16, v43
	v_and_b32_e32 v7, 0xffff0000, v43
	v_pk_mul_f32 v[2:3], v[2:3], v[6:7]
	v_pk_mul_f32 v[0:1], v[0:1], v[4:5]
	s_nop 0
	v_cvt_pk_bf16_f32 v0, v0, v1
	v_cvt_pk_bf16_f32 v1, v2, v3
	global_store_dwordx2 v[58:59], v[0:1], off offset:288
	s_cbranch_vccz .LBB0_808
	s_waitcnt vmcnt(0)
	s_cmpk_gt_u32 s42, 0xff
	s_cbranch_scc1 .LBB0_819
	s_barrier

; #define PG8_STAGE(bufoff, gbase, voff) do { _Pragma("unroll") for (int _i = 0; _i < 2; ++_i) \
;         __builtin_amdgcn_global_load_lds((const unsigned*)((const char*)(gbase) + (voff)[_i]), (PG8_LAS unsigned*)(lds + (bufoff) + ldsw + _i * 8192), 16, 0, 0); } while (0)
; #define PG8_LDA(dst, b, h) do { _Pragma("unroll") for (int m = 0; m < 4; ++m) _Pragma("unroll") for (int k = 0; k < 2; ++k) dst[m][k] = *(const PG8_LAS bf16x8*)(lds + PG8_SA(b, h) + aoff + m * 2048 + k * 1024); } while (0)
; #define PG8_LDB(dst, b, h) do { _Pragma("unroll") for (int n = 0; n < 2; ++n) _Pragma("unroll") for (int k = 0; k < 2; ++k) dst[n][k] = *(const PG8_LAS bf16x8*)(lds + PG8_SB(b, h) + boff + n * 2048 + k * 1024); } while (0)
; #define PG8_MMA(ai, bj, At, Bt) do { __builtin_amdgcn_s_setprio(1); _Pragma("unroll") for (int m = 0; m < 4; ++m) _Pragma("unroll") for (int n = 0; n < 2; ++n) _Pragma("unroll") for (int k = 0; k < 2; ++k) \
;         acc[ai][bj][m][n] = __builtin_amdgcn_mfma_f32_16x16x32_bf16(Bt[n][k], At[m][k], acc[ai][bj][m][n], 0, 0, 0); __builtin_amdgcn_s_setprio(0); } while (0)
; #define PG8_BAR __builtin_amdgcn_s_barrier()
; template <class Epi, class Sched, bool ALIGN_EPI = false, bool SP2 = false>
; __device__ __forceinline__ void gemm_phase(PG8_LAS unsigned char* lds, const Gemm g, const Sched& S, const Epi& E) {
;     ...
;         const bool has_next = S.next(ui + 1, nxt);
;         const char* nA = has_next ? (const char*)g.A + (size_t)nxt.pm * tstep : cA; const char* nB = has_next ? (const char*)g.Bt + (size_t)nxt.pn * tstep : cB;
;         for (int t = 0; t < nt; t += 2) {
;             const bool last = (t == nt - 2);
;             const char* a1 = cA + (size_t)(t + 1) * kstep;
;             const char* a2 = last ? nA : cA + (size_t)(t + 2) * kstep; const char* b2 = last ? nB : cB + (size_t)(t + 2) * kstep;
;             const char* a3 = a2 + kstep; const char* b3 = b2 + kstep;
;             if (last && has_next) S.a_ready(nxt);
;             if constexpr (SP2) {
;             PG8_LDB(B0, 0, 0); PG8_LDB(B1, 0, 1); PG8_SCHED; PG8_LDA(At, 0, 0); PG8_STAGE(PG8_SA(1, 1), a1 + hstep, voffA);
;             PG8_WAIT_V(8); PG8_WAIT_L(0); PG8_BAR; PG8_MMA(0, 0, At, B0); PG8_MMA(0, 1, At, B1); PG8_BAR; PG8_SCHED;
;             PG8_LDA(At, 0, 1); PG8_STAGE(PG8_SB(0, 0), b2, voffB); PG8_STAGE(PG8_SB(0, 1), b2 + hstep, voffB); PG8_STAGE(PG8_SA(0, 0), a2, voffA);
.LBB0_836:
	ds_read_b128 v[140:143], v149
	ds_read_b128 v[152:155], v149 offset:1024
	ds_read_b128 v[156:159], v149 offset:2048
	ds_read_b128 v[160:163], v149 offset:3072
	ds_read_b128 v[164:167], v150
	ds_read_b128 v[168:171], v150 offset:1024
	ds_read_b128 v[172:175], v150 offset:2048
	ds_read_b128 v[180:183], v150 offset:3072
	s_add_u32 s3, s70, 0xfffc0080
	s_addc_u32 s33, s71, -1
	s_cmp_eq_u32 vcc_lo, 12
	s_cselect_b32 s75, s63, s33
	s_cselect_b32 s74, s94, s3
	s_cselect_b32 s73, s61, s97
	s_cselect_b32 s72, s95, s96
	v_lshl_add_u64 v[144:145], s[70:71], 0, v[132:133]
	s_add_i32 m0, s69, 0xc000
	ds_read_b128 v[184:187], v151
	ds_read_b128 v[188:191], v151 offset:1024
	ds_read_b128 v[192:195], v151 offset:2048
	ds_read_b128 v[196:199], v151 offset:3072
	ds_read_b128 v[200:203], v151 offset:4096
	ds_read_b128 v[204:207], v151 offset:5120
	ds_read_b128 v[208:211], v151 offset:6144
	ds_read_b128 v[212:215], v151 offset:7168
	global_load_lds_dwordx4 v[144:145], off
	v_lshl_add_u64 v[144:145], s[70:71], 0, v[134:135]
	s_add_i32 m0, s69, 0xe000
	s_nop 0
	global_load_lds_dwordx4 v[144:145], off
	s_waitcnt vmcnt(8)
	s_waitcnt lgkmcnt(0)
	s_barrier
	s_setprio 1
	s_waitcnt lgkmcnt(0)
	v_mfma_f32_16x16x32_bf16 v[124:127], v[140:143], v[184:187], v[124:127]
	v_mfma_f32_16x16x32_bf16 v[120:123], v[156:159], v[184:187], v[120:123]
	v_mfma_f32_16x16x32_bf16 v[108:111], v[140:143], v[192:195], v[108:111]
	v_mfma_f32_16x16x32_bf16 v[104:107], v[156:159], v[192:195], v[104:107]
	v_mfma_f32_16x16x32_bf16 v[92:95], v[140:143], v[200:203], v[92:95]
	v_mfma_f32_16x16x32_bf16 v[88:91], v[156:159], v[200:203], v[88:91]
	v_mfma_f32_16x16x32_bf16 v[76:79], v[140:143], v[208:211], v[76:79]
	v_mfma_f32_16x16x32_bf16 v[72:75], v[156:159], v[208:211], v[72:75]
	v_mfma_f32_16x16x32_bf16 v[124:127], v[152:155], v[188:191], v[124:127]
	v_mfma_f32_16x16x32_bf16 v[120:123], v[160:163], v[188:191], v[120:123]
	v_mfma_f32_16x16x32_bf16 v[108:111], v[152:155], v[196:199], v[108:111]
	v_mfma_f32_16x16x32_bf16 v[104:107], v[160:163], v[196:199], v[104:107]
	v_mfma_f32_16x16x32_bf16 v[92:95], v[152:155], v[204:207], v[92:95]
	v_mfma_f32_16x16x32_bf16 v[88:91], v[160:163], v[204:207], v[88:91]
	v_mfma_f32_16x16x32_bf16 v[76:79], v[152:155], v[212:215], v[76:79]
	v_mfma_f32_16x16x32_bf16 v[72:75], v[160:163], v[212:215], v[72:75]
	s_setprio 0
	s_setprio 1
	v_mfma_f32_16x16x32_bf16 v[116:119], v[164:167], v[184:187], v[116:119]
	v_mfma_f32_16x16x32_bf16 v[112:115], v[172:175], v[184:187], v[112:115]
	v_mfma_f32_16x16x32_bf16 v[100:103], v[164:167], v[192:195], v[100:103]
	v_mfma_f32_16x16x32_bf16 v[96:99], v[172:175], v[192:195], v[96:99]
	v_mfma_f32_16x16x32_bf16 v[84:87], v[164:167], v[200:203], v[84:87]
	v_mfma_f32_16x16x32_bf16 v[80:83], v[172:175], v[200:203], v[80:83]
	v_mfma_f32_16x16x32_bf16 v[68:71], v[164:167], v[208:211], v[68:71]
	v_mfma_f32_16x16x32_bf16 v[64:67], v[172:175], v[208:211], v[64:67]
	v_mfma_f32_16x16x32_bf16 v[116:119], v[168:171], v[188:191], v[116:119]
	v_mfma_f32_16x16x32_bf16 v[112:115], v[180:183], v[188:191], v[112:115]
	v_mfma_f32_16x16x32_bf16 v[100:103], v[168:171], v[196:199], v[100:103]
	v_mfma_f32_16x16x32_bf16 v[96:99], v[180:183], v[196:199], v[96:99]
	v_mfma_f32_16x16x32_bf16 v[84:87], v[168:171], v[204:207], v[84:87]
	v_mfma_f32_16x16x32_bf16 v[80:83], v[180:183], v[204:207], v[80:83]
	v_mfma_f32_16x16x32_bf16 v[68:71], v[168:171], v[212:215], v[68:71]
	v_mfma_f32_16x16x32_bf16 v[64:67], v[180:183], v[212:215], v[64:67]
	s_setprio 0
	s_barrier
	s_add_i32 s3, s91, s82
	v_lshl_add_u64 v[144:145], s[72:73], 0, v[128:129]
	s_mov_b32 m0, s3
	ds_read_b128 v[184:187], v151 offset:16384
	ds_read_b128 v[188:191], v151 offset:17408
	ds_read_b128 v[192:195], v151 offset:18432
	ds_read_b128 v[196:199], v151 offset:19456
	ds_read_b128 v[200:203], v151 offset:20480
	ds_read_b128 v[204:207], v151 offset:21504
	ds_read_b128 v[208:211], v151 offset:22528
	ds_read_b128 v[212:215], v151 offset:23552
	global_load_lds_dwordx4 v[144:145], off
	s_add_i32 m0, s3, 0x2000
	s_add_u32 s36, s72, 0x40000
	v_lshl_add_u64 v[216:217], s[72:73], 0, v[130:131]
	s_addc_u32 s37, s73, 0
	s_add_i32 s3, s92, s82
	global_load_lds_dwordx4 v[216:217], off
	v_lshl_add_u64 v[218:219], s[36:37], 0, v[128:129]
	s_mov_b32 m0, s3
	v_lshl_add_u64 v[220:221], s[74:75], 0, v[130:131]
	global_load_lds_dwordx4 v[218:219], off
	v_lshl_add_u64 v[218:219], s[36:37], 0, v[130:131]
	s_add_i32 m0, s3, 0x2000
	s_nop 0
	global_load_lds_dwordx4 v[218:219], off
	v_lshl_add_u64 v[218:219], s[74:75], 0, v[128:129]
	s_mov_b32 m0, s69
	s_nop 0
	global_load_lds_dwordx4 v[218:219], off
	s_mov_b32 m0, s83
	s_nop 0
	global_load_lds_dwordx4 v[220:221], off
	s_waitcnt vmcnt(8)
	s_waitcnt lgkmcnt(0)
	s_barrier
; #define PG8_STAGE(bufoff, gbase, voff) do { _Pragma("unroll") for (int _i = 0; _i < 2; ++_i) \
;         __builtin_amdgcn_global_load_lds((const unsigned*)((const char*)(gbase) + (voff)[_i]), (PG8_LAS unsigned*)(lds + (bufoff) + ldsw + _i * 8192), 16, 0, 0); } while (0)
; #define PG8_LDA(dst, b, h) do { _Pragma("unroll") for (int m = 0; m < 4; ++m) _Pragma("unroll") for (int k = 0; k < 2; ++k) dst[m][k] = *(const PG8_LAS bf16x8*)(lds + PG8_SA(b, h) + aoff + m * 2048 + k * 1024); } while (0)
; #define PG8_LDB(dst, b, h) do { _Pragma("unroll") for (int n = 0; n < 2; ++n) _Pragma("unroll") for (int k = 0; k < 2; ++k) dst[n][k] = *(const PG8_LAS bf16x8*)(lds + PG8_SB(b, h) + boff + n * 2048 + k * 1024); } while (0)
; #define PG8_MMA(ai, bj, At, Bt) do { __builtin_amdgcn_s_setprio(1); _Pragma("unroll") for (int m = 0; m < 4; ++m) _Pragma("unroll") for (int n = 0; n < 2; ++n) _Pragma("unroll") for (int k = 0; k < 2; ++k) \
;         acc[ai][bj][m][n] = __builtin_amdgcn_mfma_f32_16x16x32_bf16(Bt[n][k], At[m][k], acc[ai][bj][m][n], 0, 0, 0); __builtin_amdgcn_s_setprio(0); } while (0)
; #define PG8_WAIT_V(n) asm volatile("s_waitcnt vmcnt(" #n ")" ::: "memory")
; #define PG8_WAIT_L(n) asm volatile("s_waitcnt lgkmcnt(" #n ")" ::: "memory")
; #define PG8_BAR __builtin_amdgcn_s_barrier()
; #define PG8_SCHED __builtin_amdgcn_sched_barrier(0)
; template <class Epi, class Sched, bool ALIGN_EPI = false, bool SP2 = false>
; __device__ __forceinline__ void gemm_phase(PG8_LAS unsigned char* lds, const Gemm g, const Sched& S, const Epi& E) {
;     ...
;             PG8_WAIT_V(8); PG8_WAIT_L(0); PG8_BAR; PG8_MMA(1, 0, At, B0); PG8_MMA(1, 1, At, B1); PG8_BAR; PG8_SCHED;
;             PG8_LDB(B0, 1, 0); PG8_LDB(B1, 1, 1); PG8_SCHED; PG8_LDA(At, 1, 0); PG8_STAGE(PG8_SA(0, 1), a2 + hstep, voffA);
;             PG8_WAIT_V(8); PG8_WAIT_L(0); PG8_BAR; PG8_MMA(0, 0, At, B0); PG8_MMA(0, 1, At, B1); PG8_BAR; PG8_SCHED;
	s_setprio 1
	s_waitcnt lgkmcnt(0)
	v_mfma_f32_16x16x32_bf16 v[60:63], v[140:143], v[184:187], v[60:63]
	v_mfma_f32_16x16x32_bf16 v[56:59], v[156:159], v[184:187], v[56:59]
	v_mfma_f32_16x16x32_bf16 v[44:47], v[140:143], v[192:195], v[44:47]
	v_mfma_f32_16x16x32_bf16 v[40:43], v[156:159], v[192:195], v[40:43]
	v_mfma_f32_16x16x32_bf16 v[28:31], v[140:143], v[200:203], v[28:31]
	v_mfma_f32_16x16x32_bf16 v[24:27], v[156:159], v[200:203], v[24:27]
	v_mfma_f32_16x16x32_bf16 v[12:15], v[140:143], v[208:211], v[12:15]
	v_mfma_f32_16x16x32_bf16 v[8:11], v[156:159], v[208:211], v[8:11]
	v_mfma_f32_16x16x32_bf16 v[60:63], v[152:155], v[188:191], v[60:63]
	v_mfma_f32_16x16x32_bf16 v[56:59], v[160:163], v[188:191], v[56:59]
	v_mfma_f32_16x16x32_bf16 v[44:47], v[152:155], v[196:199], v[44:47]
	v_mfma_f32_16x16x32_bf16 v[40:43], v[160:163], v[196:199], v[40:43]
	v_mfma_f32_16x16x32_bf16 v[28:31], v[152:155], v[204:207], v[28:31]
	v_mfma_f32_16x16x32_bf16 v[24:27], v[160:163], v[204:207], v[24:27]
	v_mfma_f32_16x16x32_bf16 v[12:15], v[152:155], v[212:215], v[12:15]
	v_mfma_f32_16x16x32_bf16 v[8:11], v[160:163], v[212:215], v[8:11]
	s_setprio 0
	s_setprio 1
	v_mfma_f32_16x16x32_bf16 v[52:55], v[164:167], v[184:187], v[52:55]
	v_mfma_f32_16x16x32_bf16 v[48:51], v[172:175], v[184:187], v[48:51]
	v_mfma_f32_16x16x32_bf16 v[36:39], v[164:167], v[192:195], v[36:39]
	v_mfma_f32_16x16x32_bf16 v[32:35], v[172:175], v[192:195], v[32:35]
	v_mfma_f32_16x16x32_bf16 v[20:23], v[164:167], v[200:203], v[20:23]
	v_mfma_f32_16x16x32_bf16 v[16:19], v[172:175], v[200:203], v[16:19]
	v_mfma_f32_16x16x32_bf16 v[4:7], v[164:167], v[208:211], v[4:7]
	v_mfma_f32_16x16x32_bf16 v[0:3], v[172:175], v[208:211], v[0:3]
	v_mfma_f32_16x16x32_bf16 v[52:55], v[168:171], v[188:191], v[52:55]
	v_mfma_f32_16x16x32_bf16 v[48:51], v[180:183], v[188:191], v[48:51]
	v_mfma_f32_16x16x32_bf16 v[36:39], v[168:171], v[196:199], v[36:39]
	v_mfma_f32_16x16x32_bf16 v[32:35], v[180:183], v[196:199], v[32:35]
	v_mfma_f32_16x16x32_bf16 v[20:23], v[168:171], v[204:207], v[20:23]
	v_mfma_f32_16x16x32_bf16 v[16:19], v[180:183], v[204:207], v[16:19]
	v_mfma_f32_16x16x32_bf16 v[4:7], v[168:171], v[212:215], v[4:7]
	v_mfma_f32_16x16x32_bf16 v[0:3], v[180:183], v[212:215], v[0:3]
	s_setprio 0
	s_barrier
	s_add_i32 s3, 0, 0x18000
	s_add_i32 s33, 0, 0x1c000
	v_add_u32_e32 v160, s3, v147
	v_add_u32_e32 v177, s33, v147
	ds_read_b128 v[140:143], v160
	ds_read_b128 v[152:155], v160 offset:1024
	ds_read_b128 v[156:159], v160 offset:2048
	ds_read_b128 v[160:163], v160 offset:3072
	ds_read_b128 v[164:167], v177
	ds_read_b128 v[168:171], v177 offset:1024
	ds_read_b128 v[172:175], v177 offset:2048
	ds_read_b128 v[180:183], v177 offset:3072
	s_add_u32 s36, s74, 0x40000
	s_addc_u32 s37, s75, 0
	s_mov_b32 m0, s84
	v_lshl_add_u64 v[222:223], s[36:37], 0, v[128:129]
	ds_read_b128 v[184:187], v151 offset:32768
	ds_read_b128 v[188:191], v151 offset:33792
	ds_read_b128 v[192:195], v151 offset:34816
	ds_read_b128 v[196:199], v151 offset:35840
	ds_read_b128 v[200:203], v151 offset:36864
	ds_read_b128 v[204:207], v151 offset:37888
	ds_read_b128 v[208:211], v151 offset:38912
	ds_read_b128 v[212:215], v151 offset:39936
	global_load_lds_dwordx4 v[222:223], off
	v_lshl_add_u64 v[222:223], s[36:37], 0, v[130:131]
	s_mov_b32 m0, s85
	s_nop 0
	global_load_lds_dwordx4 v[222:223], off
	s_waitcnt vmcnt(8)
	s_waitcnt lgkmcnt(0)
	s_barrier
	s_setprio 1
	s_waitcnt lgkmcnt(0)
	v_mfma_f32_16x16x32_bf16 v[124:127], v[140:143], v[184:187], v[124:127]
	v_mfma_f32_16x16x32_bf16 v[120:123], v[156:159], v[184:187], v[120:123]
	v_mfma_f32_16x16x32_bf16 v[108:111], v[140:143], v[192:195], v[108:111]
	v_mfma_f32_16x16x32_bf16 v[104:107], v[156:159], v[192:195], v[104:107]
	v_mfma_f32_16x16x32_bf16 v[92:95], v[140:143], v[200:203], v[92:95]
	v_mfma_f32_16x16x32_bf16 v[88:91], v[156:159], v[200:203], v[88:91]
	v_mfma_f32_16x16x32_bf16 v[76:79], v[140:143], v[208:211], v[76:79]
	v_mfma_f32_16x16x32_bf16 v[72:75], v[156:159], v[208:211], v[72:75]
	v_mfma_f32_16x16x32_bf16 v[124:127], v[152:155], v[188:191], v[124:127]
	v_mfma_f32_16x16x32_bf16 v[120:123], v[160:163], v[188:191], v[120:123]
	v_mfma_f32_16x16x32_bf16 v[108:111], v[152:155], v[196:199], v[108:111]
	v_mfma_f32_16x16x32_bf16 v[104:107], v[160:163], v[196:199], v[104:107]
	v_mfma_f32_16x16x32_bf16 v[92:95], v[152:155], v[204:207], v[92:95]
	v_mfma_f32_16x16x32_bf16 v[88:91], v[160:163], v[204:207], v[88:91]
	v_mfma_f32_16x16x32_bf16 v[76:79], v[152:155], v[212:215], v[76:79]
	v_mfma_f32_16x16x32_bf16 v[72:75], v[160:163], v[212:215], v[72:75]
	s_setprio 0
	s_setprio 1
	v_mfma_f32_16x16x32_bf16 v[116:119], v[164:167], v[184:187], v[116:119]
	v_mfma_f32_16x16x32_bf16 v[112:115], v[172:175], v[184:187], v[112:115]
	v_mfma_f32_16x16x32_bf16 v[100:103], v[164:167], v[192:195], v[100:103]
	v_mfma_f32_16x16x32_bf16 v[96:99], v[172:175], v[192:195], v[96:99]
	v_mfma_f32_16x16x32_bf16 v[84:87], v[164:167], v[200:203], v[84:87]
	v_mfma_f32_16x16x32_bf16 v[80:83], v[172:175], v[200:203], v[80:83]
	v_mfma_f32_16x16x32_bf16 v[68:71], v[164:167], v[208:211], v[68:71]
	v_mfma_f32_16x16x32_bf16 v[64:67], v[172:175], v[208:211], v[64:67]
	v_mfma_f32_16x16x32_bf16 v[116:119], v[168:171], v[188:191], v[116:119]
	v_mfma_f32_16x16x32_bf16 v[112:115], v[180:183], v[188:191], v[112:115]
	v_mfma_f32_16x16x32_bf16 v[100:103], v[168:171], v[196:199], v[100:103]
	v_mfma_f32_16x16x32_bf16 v[96:99], v[180:183], v[196:199], v[96:99]
	v_mfma_f32_16x16x32_bf16 v[84:87], v[168:171], v[204:207], v[84:87]
	v_mfma_f32_16x16x32_bf16 v[80:83], v[180:183], v[204:207], v[80:83]
	v_mfma_f32_16x16x32_bf16 v[68:71], v[168:171], v[212:215], v[68:71]
	v_mfma_f32_16x16x32_bf16 v[64:67], v[180:183], v[212:215], v[64:67]
	s_setprio 0
	s_barrier
; #define PG8_STAGE(bufoff, gbase, voff) do { _Pragma("unroll") for (int _i = 0; _i < 2; ++_i) \
;         __builtin_amdgcn_global_load_lds((const unsigned*)((const char*)(gbase) + (voff)[_i]), (PG8_LAS unsigned*)(lds + (bufoff) + ldsw + _i * 8192), 16, 0, 0); } while (0)
; #define PG8_LDA(dst, b, h) do { _Pragma("unroll") for (int m = 0; m < 4; ++m) _Pragma("unroll") for (int k = 0; k < 2; ++k) dst[m][k] = *(const PG8_LAS bf16x8*)(lds + PG8_SA(b, h) + aoff + m * 2048 + k * 1024); } while (0)
; #define PG8_MMA(ai, bj, At, Bt) do { __builtin_amdgcn_s_setprio(1); _Pragma("unroll") for (int m = 0; m < 4; ++m) _Pragma("unroll") for (int n = 0; n < 2; ++n) _Pragma("unroll") for (int k = 0; k < 2; ++k) \
;         acc[ai][bj][m][n] = __builtin_amdgcn_mfma_f32_16x16x32_bf16(Bt[n][k], At[m][k], acc[ai][bj][m][n], 0, 0, 0); __builtin_amdgcn_s_setprio(0); } while (0)
; #define PG8_WAIT_V(n) asm volatile("s_waitcnt vmcnt(" #n ")" ::: "memory")
; #define PG8_WAIT_L(n) asm volatile("s_waitcnt lgkmcnt(" #n ")" ::: "memory")
; #define PG8_BAR __builtin_amdgcn_s_barrier()
; #define PG8_SCHED __builtin_amdgcn_sched_barrier(0)
; template <class Epi, class Sched, bool ALIGN_EPI = false, bool SP2 = false>
; __device__ __forceinline__ void gemm_phase(PG8_LAS unsigned char* lds, const Gemm g, const Sched& S, const Epi& E) {
;     ...
;             PG8_LDA(At, 1, 1); PG8_STAGE(PG8_SB(1, 0), b3, voffB); PG8_STAGE(PG8_SB(1, 1), b3 + hstep, voffB); PG8_STAGE(PG8_SA(1, 0), a3, voffA);
;             PG8_WAIT_V(8); PG8_WAIT_L(0); PG8_BAR; PG8_MMA(1, 0, At, B0); PG8_MMA(1, 1, At, B1); PG8_BAR; PG8_SCHED;
;     __device__ __forceinline__ void operator()(const AccT& acc, const pg8::Unit& u, int wr, int wc, int fr, int fq) const {
;         const int col0 = u.pn * 256 + wc * 32 + 4 * fq, row0 = row_base + u.pm * 256 + wr * 64 + fr;
; #pragma unroll
;         for (int ai = 0; ai < 2; ++ai)
; #pragma unroll
;             for (int m = 0; m < 4; ++m) { const int row = row0 + ai * 128 + m * 16; float ss = 0.f;
; #pragma unroll
;                 for (int bj = 0; bj < 2; ++bj)
; #pragma unroll
;                     for (int n = 0; n < 2; ++n) { f32x4 v = acc[ai][bj][m][n]; const size_t idx = (size_t)row * 1024 + col0 + bj * 128 + n * 16;
;                         if (MODE == 0) v = v * up4(*(const u32x2*)(io + idx));
	s_add_i32 s3, s3, s82
	v_lshl_add_u64 v[144:145], v[144:145], 0, s[8:9]
	s_mov_b32 m0, s3
	ds_read_b128 v[184:187], v151 offset:49152
	ds_read_b128 v[188:191], v151 offset:50176
	ds_read_b128 v[192:195], v151 offset:51200
	ds_read_b128 v[196:199], v151 offset:52224
	ds_read_b128 v[200:203], v151 offset:53248
	ds_read_b128 v[204:207], v151 offset:54272
	ds_read_b128 v[208:211], v151 offset:55296
	ds_read_b128 v[212:215], v151 offset:56320
	global_load_lds_dwordx4 v[144:145], off
	s_add_i32 m0, s3, 0x2000
	s_add_u32 s36, s72, 0x40080
	v_lshl_add_u64 v[144:145], v[216:217], 0, s[8:9]
	s_addc_u32 s37, s73, 0
	s_add_i32 s3, s33, s82
	global_load_lds_dwordx4 v[144:145], off
	v_lshl_add_u64 v[144:145], s[36:37], 0, v[128:129]
	s_mov_b32 m0, s3
	s_nop 0
	global_load_lds_dwordx4 v[144:145], off
	v_lshl_add_u64 v[144:145], s[36:37], 0, v[130:131]
	s_add_i32 m0, s3, 0x2000
	s_nop 0
	global_load_lds_dwordx4 v[144:145], off
	v_lshl_add_u64 v[144:145], v[218:219], 0, s[8:9]
	s_mov_b32 m0, s87
	s_nop 0
	global_load_lds_dwordx4 v[144:145], off
	v_lshl_add_u64 v[144:145], v[220:221], 0, s[8:9]
	s_mov_b32 m0, s88
	s_nop 0
	global_load_lds_dwordx4 v[144:145], off
	s_waitcnt vmcnt(8)
	s_waitcnt lgkmcnt(0)
	s_barrier
	s_setprio 1
	s_waitcnt lgkmcnt(0)
	v_mfma_f32_16x16x32_bf16 v[60:63], v[140:143], v[184:187], v[60:63]
	v_mfma_f32_16x16x32_bf16 v[56:59], v[156:159], v[184:187], v[56:59]
	v_mfma_f32_16x16x32_bf16 v[44:47], v[140:143], v[192:195], v[44:47]
	v_mfma_f32_16x16x32_bf16 v[40:43], v[156:159], v[192:195], v[40:43]
	v_mfma_f32_16x16x32_bf16 v[28:31], v[140:143], v[200:203], v[28:31]
	v_mfma_f32_16x16x32_bf16 v[24:27], v[156:159], v[200:203], v[24:27]
	v_mfma_f32_16x16x32_bf16 v[12:15], v[140:143], v[208:211], v[12:15]
	v_mfma_f32_16x16x32_bf16 v[8:11], v[156:159], v[208:211], v[8:11]
	v_mfma_f32_16x16x32_bf16 v[60:63], v[152:155], v[188:191], v[60:63]
	v_mfma_f32_16x16x32_bf16 v[56:59], v[160:163], v[188:191], v[56:59]
	v_mfma_f32_16x16x32_bf16 v[44:47], v[152:155], v[196:199], v[44:47]
	v_mfma_f32_16x16x32_bf16 v[40:43], v[160:163], v[196:199], v[40:43]
	v_mfma_f32_16x16x32_bf16 v[28:31], v[152:155], v[204:207], v[28:31]
	v_mfma_f32_16x16x32_bf16 v[24:27], v[160:163], v[204:207], v[24:27]
	v_mfma_f32_16x16x32_bf16 v[12:15], v[152:155], v[212:215], v[12:15]
	v_mfma_f32_16x16x32_bf16 v[8:11], v[160:163], v[212:215], v[8:11]
	s_setprio 0
	s_setprio 1
	v_mfma_f32_16x16x32_bf16 v[52:55], v[164:167], v[184:187], v[52:55]
	v_mfma_f32_16x16x32_bf16 v[48:51], v[172:175], v[184:187], v[48:51]
	v_mfma_f32_16x16x32_bf16 v[36:39], v[164:167], v[192:195], v[36:39]
	v_mfma_f32_16x16x32_bf16 v[32:35], v[172:175], v[192:195], v[32:35]
	v_mfma_f32_16x16x32_bf16 v[20:23], v[164:167], v[200:203], v[20:23]
	s_add_i32 vcc_lo, vcc_lo, 2
	s_add_u32 s70, s70, 0x100
	s_addc_u32 s71, s71, 0
	s_add_u32 s96, s96, 0x100
	s_addc_u32 s97, s97, 0
	s_cmp_gt_u32 vcc_lo, 13
	v_mfma_f32_16x16x32_bf16 v[16:19], v[172:175], v[200:203], v[16:19]
	v_mfma_f32_16x16x32_bf16 v[4:7], v[164:167], v[208:211], v[4:7]
	v_mfma_f32_16x16x32_bf16 v[0:3], v[172:175], v[208:211], v[0:3]
	v_mfma_f32_16x16x32_bf16 v[52:55], v[168:171], v[188:191], v[52:55]
	v_mfma_f32_16x16x32_bf16 v[48:51], v[180:183], v[188:191], v[48:51]
	v_mfma_f32_16x16x32_bf16 v[36:39], v[168:171], v[196:199], v[36:39]
	v_mfma_f32_16x16x32_bf16 v[32:35], v[180:183], v[196:199], v[32:35]
	v_mfma_f32_16x16x32_bf16 v[20:23], v[168:171], v[204:207], v[20:23]
	v_mfma_f32_16x16x32_bf16 v[16:19], v[180:183], v[204:207], v[16:19]
	v_mfma_f32_16x16x32_bf16 v[4:7], v[168:171], v[212:215], v[4:7]
	v_mfma_f32_16x16x32_bf16 v[0:3], v[180:183], v[212:215], v[0:3]
	s_setprio 0
	s_barrier
	s_cbranch_scc0 .LBB0_836
	v_lshl_add_u32 v144, s68, 8, v146
	v_lshl_or_b32 v142, s93, 8, v148
	v_ashrrev_i32_e32 v145, 31, v144
	v_ashrrev_i32_e32 v143, 31, v142
	v_lshlrev_b64 v[140:141], 10, v[144:145]
	v_lshl_add_u64 v[140:141], v[140:141], 0, v[142:143]
	v_lshlrev_b64 v[140:141], 1, v[140:141]
	v_lshl_add_u64 v[152:153], s[4:5], 0, v[140:141]
	v_lshl_add_u64 v[156:157], s[6:7], 0, v[140:141]
	v_or_b32_e32 v158, 32, v140
	v_mov_b32_e32 v159, v141
	v_or_b32_e32 v164, 0x100, v140
	v_mov_b32_e32 v165, v141
	v_or_b32_e32 v170, 0x120, v140
	v_mov_b32_e32 v171, v141
	global_load_dwordx2 v[154:155], v[152:153], off
	v_lshl_add_u64 v[160:161], s[4:5], 0, v[158:159]
	global_load_dwordx2 v[156:157], v[156:157], off
	v_lshl_add_u64 v[158:159], s[6:7], 0, v[158:159]
	v_lshl_add_u64 v[166:167], s[4:5], 0, v[164:165]
	v_lshl_add_u64 v[164:165], s[6:7], 0, v[164:165]
	v_lshl_add_u64 v[172:173], s[4:5], 0, v[170:171]
	v_lshl_add_u64 v[170:171], s[6:7], 0, v[170:171]
	global_load_dwordx2 v[162:163], v[160:161], off
	global_load_dwordx2 v[168:169], v[166:167], off
	global_load_dwordx2 v[174:175], v[172:173], off
	v_or_b32_e32 v180, 16, v144
	global_load_dwordx2 v[158:159], v[158:159], off
	v_ashrrev_i32_e32 v181, 31, v180
	global_load_dwordx2 v[170:171], v[170:171], off
	v_lshlrev_b64 v[180:181], 10, v[180:181]
	global_load_dwordx2 v[164:165], v[164:165], off
	v_lshl_add_u64 v[180:181], v[180:181], 0, v[142:143]
	v_lshlrev_b64 v[180:181], 1, v[180:181]
	v_lshl_add_u64 v[182:183], s[4:5], 0, v[180:181]
	s_mov_b64 s[70:71], 0x40000
	s_and_b64 vcc, exec, s[0:1]
	s_mov_b32 s93, s60
	s_mov_b32 s68, s62
	s_mov_b64 s[72:73], s[66:67]
	s_waitcnt vmcnt(0)
; __device__ __forceinline__ u32x2 pk4(f32x4 v) { u32x2 w; w.x = cvt_pk_bf16(v[0], v[1]); w.y = cvt_pk_bf16(v[2], v[3]); return w; }
; __device__ __forceinline__ f32x4 up4(u32x2 w) { return (f32x4){bf_lo(w.x), bf_hi(w.x), bf_lo(w.y), bf_hi(w.y)}; }
;     __device__ __forceinline__ void operator()(const AccT& acc, const pg8::Unit& u, int wr, int wc, int fr, int fq) const {
;     ...
;                     for (int n = 0; n < 2; ++n) { f32x4 v = acc[ai][bj][m][n]; const size_t idx = (size_t)row * 1024 + col0 + bj * 128 + n * 16;
;                         if (MODE == 0) v = v * up4(*(const u32x2*)(io + idx));
;                         else if (MODE == 1) v = up4(*(const u32x2*)(io + idx)) + up4(*(const u32x2*)(g2 + idx)) * v;
;                         else ss += (v[0] * v[0] + v[1] * v[1]) + (v[2] * v[2] + v[3] * v[3]);
;                         if (!DRYE || v[0] == 123.456f) *(u32x2*)(io + idx) = pk4(v); }
	v_lshlrev_b32_e32 v184, 16, v154
	v_and_b32_e32 v185, 0xffff0000, v154
	v_lshlrev_b32_e32 v154, 16, v155
	v_and_b32_e32 v155, 0xffff0000, v155
	v_lshlrev_b32_e32 v186, 16, v156
	v_and_b32_e32 v187, 0xffff0000, v156
	v_lshlrev_b32_e32 v156, 16, v157
	v_and_b32_e32 v157, 0xffff0000, v157
	v_pk_fma_f32 v[126:127], v[126:127], v[156:157], v[154:155]
	v_pk_fma_f32 v[124:125], v[124:125], v[186:187], v[184:185]
	v_lshlrev_b32_e32 v154, 16, v162
	v_and_b32_e32 v155, 0xffff0000, v162
	v_lshlrev_b32_e32 v156, 16, v163
	v_and_b32_e32 v157, 0xffff0000, v163
	v_lshlrev_b32_e32 v162, 16, v158
	v_and_b32_e32 v163, 0xffff0000, v158
	v_lshlrev_b32_e32 v158, 16, v159
	v_and_b32_e32 v159, 0xffff0000, v159
	v_lshlrev_b32_e32 v184, 16, v168
	v_and_b32_e32 v185, 0xffff0000, v168
	v_lshlrev_b32_e32 v168, 16, v169
	v_and_b32_e32 v169, 0xffff0000, v169
	v_lshlrev_b32_e32 v186, 16, v164
	v_and_b32_e32 v187, 0xffff0000, v164
	v_lshlrev_b32_e32 v164, 16, v165
	v_and_b32_e32 v165, 0xffff0000, v165
	v_lshlrev_b32_e32 v188, 16, v174
	v_and_b32_e32 v189, 0xffff0000, v174
	v_lshlrev_b32_e32 v174, 16, v175
	v_and_b32_e32 v175, 0xffff0000, v175
	v_lshlrev_b32_e32 v190, 16, v170
	v_and_b32_e32 v191, 0xffff0000, v170
	v_lshlrev_b32_e32 v170, 16, v171
	v_and_b32_e32 v171, 0xffff0000, v171
	v_pk_fma_f32 v[122:123], v[122:123], v[158:159], v[156:157]
	v_pk_fma_f32 v[120:121], v[120:121], v[162:163], v[154:155]
	v_pk_fma_f32 v[118:119], v[118:119], v[164:165], v[168:169]
	v_pk_fma_f32 v[116:117], v[116:117], v[186:187], v[184:185]
	v_cvt_pk_bf16_f32 v124, v124, v125
	v_cvt_pk_bf16_f32 v125, v126, v127
	v_pk_fma_f32 v[114:115], v[114:115], v[170:171], v[174:175]
	v_pk_fma_f32 v[112:113], v[112:113], v[190:191], v[188:189]
	v_cvt_pk_bf16_f32 v120, v120, v121
	v_cvt_pk_bf16_f32 v121, v122, v123
	v_cvt_pk_bf16_f32 v116, v116, v117
	v_cvt_pk_bf16_f32 v117, v118, v119
	global_store_dwordx2 v[152:153], v[124:125], off
	v_cvt_pk_bf16_f32 v112, v112, v113
	v_cvt_pk_bf16_f32 v113, v114, v115
	global_store_dwordx2 v[160:161], v[120:121], off
	global_store_dwordx2 v[166:167], v[116:117], off
	global_store_dwordx2 v[172:173], v[112:113], off
	v_or_b32_e32 v116, 32, v180
	v_mov_b32_e32 v117, v181
	v_or_b32_e32 v122, 0x100, v180
	v_mov_b32_e32 v123, v181
	v_lshl_add_u64 v[114:115], s[6:7], 0, v[180:181]
	v_lshl_add_u64 v[118:119], s[4:5], 0, v[116:117]
	v_lshl_add_u64 v[124:125], s[4:5], 0, v[122:123]
	v_lshl_add_u64 v[122:123], s[6:7], 0, v[122:123]
	v_or_b32_e32 v180, 0x120, v180
	global_load_dwordx2 v[112:113], v[182:183], off
	global_load_dwordx2 v[126:127], v[124:125], off
	global_load_dwordx2 v[120:121], v[118:119], off
	v_lshl_add_u64 v[116:117], s[6:7], 0, v[116:117]
	global_load_dwordx2 v[114:115], v[114:115], off
	v_lshl_add_u64 v[152:153], s[4:5], 0, v[180:181]
	global_load_dwordx2 v[122:123], v[122:123], off
	v_lshl_add_u64 v[156:157], s[6:7], 0, v[180:181]
	global_load_dwordx2 v[116:117], v[116:117], off
	v_or_b32_e32 v158, 32, v144
	global_load_dwordx2 v[154:155], v[152:153], off
	v_ashrrev_i32_e32 v159, 31, v158
	global_load_dwordx2 v[156:157], v[156:157], off
	v_lshlrev_b64 v[158:159], 10, v[158:159]
	v_lshl_add_u64 v[158:159], v[158:159], 0, v[142:143]
	v_lshlrev_b64 v[158:159], 1, v[158:159]
	v_lshl_add_u64 v[160:161], s[4:5], 0, v[158:159]
	s_waitcnt vmcnt(7)
	v_lshlrev_b32_e32 v162, 16, v112
	v_and_b32_e32 v163, 0xffff0000, v112
	v_lshlrev_b32_e32 v112, 16, v113
	v_and_b32_e32 v113, 0xffff0000, v113
	s_waitcnt vmcnt(4)
	v_lshlrev_b32_e32 v164, 16, v114
	v_and_b32_e32 v165, 0xffff0000, v114
	v_lshlrev_b32_e32 v114, 16, v115
	v_and_b32_e32 v115, 0xffff0000, v115
	v_lshlrev_b32_e32 v170, 16, v126
	v_and_b32_e32 v171, 0xffff0000, v126
	v_lshlrev_b32_e32 v126, 16, v127
	v_and_b32_e32 v127, 0xffff0000, v127
	s_waitcnt vmcnt(3)
	v_lshlrev_b32_e32 v172, 16, v122
	v_and_b32_e32 v173, 0xffff0000, v122
	v_lshlrev_b32_e32 v122, 16, v123
	v_and_b32_e32 v123, 0xffff0000, v123
	v_lshlrev_b32_e32 v166, 16, v120
	v_and_b32_e32 v167, 0xffff0000, v120
	v_lshlrev_b32_e32 v120, 16, v121
	v_and_b32_e32 v121, 0xffff0000, v121
	s_waitcnt vmcnt(2)
	v_lshlrev_b32_e32 v168, 16, v116
	v_and_b32_e32 v169, 0xffff0000, v116
	v_lshlrev_b32_e32 v116, 16, v117
	v_and_b32_e32 v117, 0xffff0000, v117
	s_waitcnt vmcnt(1)
	v_lshlrev_b32_e32 v174, 16, v154
	v_and_b32_e32 v175, 0xffff0000, v154
	v_lshlrev_b32_e32 v154, 16, v155
	v_and_b32_e32 v155, 0xffff0000, v155
	s_waitcnt vmcnt(0)
	v_lshlrev_b32_e32 v180, 16, v156
	v_and_b32_e32 v181, 0xffff0000, v156
	v_lshlrev_b32_e32 v156, 16, v157
	v_and_b32_e32 v157, 0xffff0000, v157
	v_pk_fma_f32 v[110:111], v[110:111], v[114:115], v[112:113]
	v_pk_fma_f32 v[108:109], v[108:109], v[164:165], v[162:163]
	v_pk_fma_f32 v[102:103], v[102:103], v[122:123], v[126:127]
	v_pk_fma_f32 v[100:101], v[100:101], v[172:173], v[170:171]
	v_pk_fma_f32 v[106:107], v[106:107], v[116:117], v[120:121]
	v_pk_fma_f32 v[104:105], v[104:105], v[168:169], v[166:167]
	v_pk_fma_f32 v[98:99], v[98:99], v[156:157], v[154:155]
	v_pk_fma_f32 v[96:97], v[96:97], v[180:181], v[174:175]
	v_cvt_pk_bf16_f32 v108, v108, v109
	v_cvt_pk_bf16_f32 v109, v110, v111
	v_cvt_pk_bf16_f32 v100, v100, v101
	v_cvt_pk_bf16_f32 v101, v102, v103
	v_cvt_pk_bf16_f32 v104, v104, v105
	v_cvt_pk_bf16_f32 v105, v106, v107
	v_cvt_pk_bf16_f32 v96, v96, v97
	v_cvt_pk_bf16_f32 v97, v98, v99
	global_store_dwordx2 v[182:183], v[108:109], off
	global_store_dwordx2 v[118:119], v[104:105], off
	global_store_dwordx2 v[124:125], v[100:101], off
	global_store_dwordx2 v[152:153], v[96:97], off
	v_or_b32_e32 v100, 32, v158
	v_mov_b32_e32 v101, v159
	v_or_b32_e32 v106, 0x100, v158
	v_mov_b32_e32 v107, v159
	v_lshl_add_u64 v[98:99], s[6:7], 0, v[158:159]
	v_lshl_add_u64 v[102:103], s[4:5], 0, v[100:101]
	v_lshl_add_u64 v[108:109], s[4:5], 0, v[106:107]
	v_lshl_add_u64 v[106:107], s[6:7], 0, v[106:107]
	v_or_b32_e32 v158, 0x120, v158
	global_load_dwordx2 v[96:97], v[160:161], off
	global_load_dwordx2 v[110:111], v[108:109], off
	global_load_dwordx2 v[104:105], v[102:103], off
	v_lshl_add_u64 v[100:101], s[6:7], 0, v[100:101]
	global_load_dwordx2 v[98:99], v[98:99], off
	v_lshl_add_u64 v[112:113], s[4:5], 0, v[158:159]
	global_load_dwordx2 v[106:107], v[106:107], off
	v_lshl_add_u64 v[116:117], s[6:7], 0, v[158:159]
	global_load_dwordx2 v[100:101], v[100:101], off
	v_or_b32_e32 v118, 48, v144
	global_load_dwordx2 v[114:115], v[112:113], off
	v_ashrrev_i32_e32 v119, 31, v118
	global_load_dwordx2 v[116:117], v[116:117], off
	v_lshlrev_b64 v[118:119], 10, v[118:119]
	v_lshl_add_u64 v[118:119], v[118:119], 0, v[142:143]
	v_lshlrev_b64 v[118:119], 1, v[118:119]
	v_lshl_add_u64 v[120:121], s[4:5], 0, v[118:119]
	s_waitcnt vmcnt(7)
; __device__ __forceinline__ u32x2 pk4(f32x4 v) { u32x2 w; w.x = cvt_pk_bf16(v[0], v[1]); w.y = cvt_pk_bf16(v[2], v[3]); return w; }
; __device__ __forceinline__ f32x4 up4(u32x2 w) { return (f32x4){bf_lo(w.x), bf_hi(w.x), bf_lo(w.y), bf_hi(w.y)}; }
;     __device__ __forceinline__ void operator()(const AccT& acc, const pg8::Unit& u, int wr, int wc, int fr, int fq) const {
;     ...
;                     for (int n = 0; n < 2; ++n) { f32x4 v = acc[ai][bj][m][n]; const size_t idx = (size_t)row * 1024 + col0 + bj * 128 + n * 16;
;                         if (MODE == 0) v = v * up4(*(const u32x2*)(io + idx));
;                         else if (MODE == 1) v = up4(*(const u32x2*)(io + idx)) + up4(*(const u32x2*)(g2 + idx)) * v;
;                         else ss += (v[0] * v[0] + v[1] * v[1]) + (v[2] * v[2] + v[3] * v[3]);
;                         if (!DRYE || v[0] == 123.456f) *(u32x2*)(io + idx) = pk4(v); }
	v_lshlrev_b32_e32 v122, 16, v96
	v_and_b32_e32 v123, 0xffff0000, v96
	v_lshlrev_b32_e32 v96, 16, v97
	v_and_b32_e32 v97, 0xffff0000, v97
	s_waitcnt vmcnt(4)
	v_lshlrev_b32_e32 v124, 16, v98
	v_and_b32_e32 v125, 0xffff0000, v98
	v_lshlrev_b32_e32 v98, 16, v99
	v_and_b32_e32 v99, 0xffff0000, v99
	v_lshlrev_b32_e32 v144, 16, v110
	v_and_b32_e32 v145, 0xffff0000, v110
	v_lshlrev_b32_e32 v110, 16, v111
	v_and_b32_e32 v111, 0xffff0000, v111
	s_waitcnt vmcnt(3)
	v_lshlrev_b32_e32 v152, 16, v106
	v_and_b32_e32 v153, 0xffff0000, v106
	v_lshlrev_b32_e32 v106, 16, v107
	v_and_b32_e32 v107, 0xffff0000, v107
	v_lshlrev_b32_e32 v126, 16, v104
	v_and_b32_e32 v127, 0xffff0000, v104
	v_lshlrev_b32_e32 v104, 16, v105
	v_and_b32_e32 v105, 0xffff0000, v105
	s_waitcnt vmcnt(2)
	v_lshlrev_b32_e32 v142, 16, v100
	v_and_b32_e32 v143, 0xffff0000, v100
	v_lshlrev_b32_e32 v100, 16, v101
	v_and_b32_e32 v101, 0xffff0000, v101
	s_waitcnt vmcnt(1)
	v_lshlrev_b32_e32 v154, 16, v114
	v_and_b32_e32 v155, 0xffff0000, v114
	v_lshlrev_b32_e32 v114, 16, v115
	v_and_b32_e32 v115, 0xffff0000, v115
	s_waitcnt vmcnt(0)
	v_lshlrev_b32_e32 v156, 16, v116
	v_and_b32_e32 v157, 0xffff0000, v116
	v_lshlrev_b32_e32 v116, 16, v117
	v_and_b32_e32 v117, 0xffff0000, v117
	v_pk_fma_f32 v[94:95], v[94:95], v[98:99], v[96:97]
	v_pk_fma_f32 v[92:93], v[92:93], v[124:125], v[122:123]
	v_pk_fma_f32 v[86:87], v[86:87], v[106:107], v[110:111]
	v_pk_fma_f32 v[84:85], v[84:85], v[152:153], v[144:145]
	v_pk_fma_f32 v[90:91], v[90:91], v[100:101], v[104:105]
	v_pk_fma_f32 v[88:89], v[88:89], v[142:143], v[126:127]
	v_pk_fma_f32 v[82:83], v[82:83], v[116:117], v[114:115]
	v_pk_fma_f32 v[80:81], v[80:81], v[156:157], v[154:155]
	v_cvt_pk_bf16_f32 v92, v92, v93
	v_cvt_pk_bf16_f32 v93, v94, v95
	v_cvt_pk_bf16_f32 v84, v84, v85
	v_cvt_pk_bf16_f32 v85, v86, v87
	v_cvt_pk_bf16_f32 v88, v88, v89
	v_cvt_pk_bf16_f32 v89, v90, v91
	v_cvt_pk_bf16_f32 v80, v80, v81
	v_cvt_pk_bf16_f32 v81, v82, v83
	global_store_dwordx2 v[160:161], v[92:93], off
	global_store_dwordx2 v[102:103], v[88:89], off
	global_store_dwordx2 v[108:109], v[84:85], off
	global_store_dwordx2 v[112:113], v[80:81], off
	v_or_b32_e32 v84, 32, v118
	v_mov_b32_e32 v85, v119
	v_or_b32_e32 v90, 0x100, v118
	v_mov_b32_e32 v91, v119
	v_lshl_add_u64 v[82:83], s[6:7], 0, v[118:119]
	v_lshl_add_u64 v[86:87], s[4:5], 0, v[84:85]
	v_lshl_add_u64 v[92:93], s[4:5], 0, v[90:91]
	v_lshl_add_u64 v[90:91], s[6:7], 0, v[90:91]
	v_or_b32_e32 v118, 0x120, v118
	global_load_dwordx2 v[80:81], v[120:121], off
	global_load_dwordx2 v[94:95], v[92:93], off
	global_load_dwordx2 v[88:89], v[86:87], off
	v_lshl_add_u64 v[84:85], s[6:7], 0, v[84:85]
	global_load_dwordx2 v[82:83], v[82:83], off
	v_lshl_add_u64 v[96:97], s[4:5], 0, v[118:119]
	global_load_dwordx2 v[90:91], v[90:91], off
	v_lshl_add_u64 v[100:101], s[6:7], 0, v[118:119]
	global_load_dwordx2 v[84:85], v[84:85], off
	v_lshl_add_u64 v[102:103], v[140:141], 0, s[70:71]
	global_load_dwordx2 v[98:99], v[96:97], off
	v_lshl_add_u64 v[104:105], s[4:5], 0, v[102:103]
	global_load_dwordx2 v[100:101], v[100:101], off
	s_mov_b64 s[70:71], s[64:65]
	s_waitcnt vmcnt(7)
	v_lshlrev_b32_e32 v106, 16, v80
	v_and_b32_e32 v107, 0xffff0000, v80
	v_lshlrev_b32_e32 v80, 16, v81
	v_and_b32_e32 v81, 0xffff0000, v81
	s_waitcnt vmcnt(4)
	v_lshlrev_b32_e32 v108, 16, v82
	v_and_b32_e32 v109, 0xffff0000, v82
	v_lshlrev_b32_e32 v82, 16, v83
	v_and_b32_e32 v83, 0xffff0000, v83
	v_lshlrev_b32_e32 v114, 16, v94
	v_and_b32_e32 v115, 0xffff0000, v94
	v_lshlrev_b32_e32 v94, 16, v95
	v_and_b32_e32 v95, 0xffff0000, v95
	s_waitcnt vmcnt(3)
	v_lshlrev_b32_e32 v116, 16, v90
	v_and_b32_e32 v117, 0xffff0000, v90
	v_lshlrev_b32_e32 v90, 16, v91
	v_and_b32_e32 v91, 0xffff0000, v91
	v_lshlrev_b32_e32 v110, 16, v88
	v_and_b32_e32 v111, 0xffff0000, v88
	v_lshlrev_b32_e32 v88, 16, v89
	v_and_b32_e32 v89, 0xffff0000, v89
	s_waitcnt vmcnt(2)
	v_lshlrev_b32_e32 v112, 16, v84
	v_and_b32_e32 v113, 0xffff0000, v84
	v_lshlrev_b32_e32 v84, 16, v85
	v_and_b32_e32 v85, 0xffff0000, v85
	s_waitcnt vmcnt(1)
	v_lshlrev_b32_e32 v118, 16, v98
	v_and_b32_e32 v119, 0xffff0000, v98
	v_lshlrev_b32_e32 v98, 16, v99
	v_and_b32_e32 v99, 0xffff0000, v99
	s_waitcnt vmcnt(0)
	v_lshlrev_b32_e32 v122, 16, v100
	v_and_b32_e32 v123, 0xffff0000, v100
	v_lshlrev_b32_e32 v100, 16, v101
	v_and_b32_e32 v101, 0xffff0000, v101
	v_pk_fma_f32 v[78:79], v[78:79], v[82:83], v[80:81]
	v_pk_fma_f32 v[76:77], v[76:77], v[108:109], v[106:107]
	v_pk_fma_f32 v[70:71], v[70:71], v[90:91], v[94:95]
	v_pk_fma_f32 v[68:69], v[68:69], v[116:117], v[114:115]
	v_pk_fma_f32 v[74:75], v[74:75], v[84:85], v[88:89]
	v_pk_fma_f32 v[72:73], v[72:73], v[112:113], v[110:111]
	v_pk_fma_f32 v[66:67], v[66:67], v[100:101], v[98:99]
	v_pk_fma_f32 v[64:65], v[64:65], v[122:123], v[118:119]
	v_cvt_pk_bf16_f32 v76, v76, v77
	v_cvt_pk_bf16_f32 v77, v78, v79
	v_cvt_pk_bf16_f32 v68, v68, v69
	v_cvt_pk_bf16_f32 v69, v70, v71
	v_cvt_pk_bf16_f32 v72, v72, v73
	v_cvt_pk_bf16_f32 v73, v74, v75
	v_cvt_pk_bf16_f32 v64, v64, v65
	v_cvt_pk_bf16_f32 v65, v66, v67
	global_store_dwordx2 v[120:121], v[76:77], off
	global_store_dwordx2 v[86:87], v[72:73], off
	global_store_dwordx2 v[92:93], v[68:69], off
	global_store_dwordx2 v[96:97], v[64:65], off
	v_lshl_add_u64 v[68:69], v[140:141], 0, s[10:11]
	v_lshl_add_u64 v[74:75], v[140:141], 0, s[14:15]
	v_lshl_add_u64 v[66:67], s[6:7], 0, v[102:103]
	v_lshl_add_u64 v[70:71], s[4:5], 0, v[68:69]
	v_lshl_add_u64 v[76:77], s[4:5], 0, v[74:75]
	v_lshl_add_u64 v[74:75], s[6:7], 0, v[74:75]
	v_lshl_add_u64 v[80:81], v[140:141], 0, s[16:17]
	global_load_dwordx2 v[64:65], v[104:105], off
	global_load_dwordx2 v[78:79], v[76:77], off
	global_load_dwordx2 v[72:73], v[70:71], off
	v_lshl_add_u64 v[68:69], s[6:7], 0, v[68:69]
	global_load_dwordx2 v[66:67], v[66:67], off
	v_lshl_add_u64 v[82:83], s[4:5], 0, v[80:81]
	global_load_dwordx2 v[74:75], v[74:75], off
	v_lshl_add_u64 v[80:81], s[6:7], 0, v[80:81]
	global_load_dwordx2 v[68:69], v[68:69], off
	v_lshl_add_u64 v[86:87], v[140:141], 0, s[18:19]
	global_load_dwordx2 v[84:85], v[82:83], off
	v_lshl_add_u64 v[88:89], s[4:5], 0, v[86:87]
	global_load_dwordx2 v[80:81], v[80:81], off
	s_waitcnt vmcnt(7)
; __device__ __forceinline__ u32x2 pk4(f32x4 v) { u32x2 w; w.x = cvt_pk_bf16(v[0], v[1]); w.y = cvt_pk_bf16(v[2], v[3]); return w; }
; __device__ __forceinline__ f32x4 up4(u32x2 w) { return (f32x4){bf_lo(w.x), bf_hi(w.x), bf_lo(w.y), bf_hi(w.y)}; }
;     __device__ __forceinline__ void operator()(const AccT& acc, const pg8::Unit& u, int wr, int wc, int fr, int fq) const {
;     ...
;                     for (int n = 0; n < 2; ++n) { f32x4 v = acc[ai][bj][m][n]; const size_t idx = (size_t)row * 1024 + col0 + bj * 128 + n * 16;
;                         if (MODE == 0) v = v * up4(*(const u32x2*)(io + idx));
;                         else if (MODE == 1) v = up4(*(const u32x2*)(io + idx)) + up4(*(const u32x2*)(g2 + idx)) * v;
;                         else ss += (v[0] * v[0] + v[1] * v[1]) + (v[2] * v[2] + v[3] * v[3]);
;                         if (!DRYE || v[0] == 123.456f) *(u32x2*)(io + idx) = pk4(v); }
	v_lshlrev_b32_e32 v90, 16, v64
	v_and_b32_e32 v91, 0xffff0000, v64
	v_lshlrev_b32_e32 v64, 16, v65
	v_and_b32_e32 v65, 0xffff0000, v65
	s_waitcnt vmcnt(4)
	v_lshlrev_b32_e32 v92, 16, v66
	v_and_b32_e32 v93, 0xffff0000, v66
	v_lshlrev_b32_e32 v66, 16, v67
	v_and_b32_e32 v67, 0xffff0000, v67
	v_lshlrev_b32_e32 v98, 16, v78
	v_and_b32_e32 v99, 0xffff0000, v78
	v_lshlrev_b32_e32 v78, 16, v79
	v_and_b32_e32 v79, 0xffff0000, v79
	s_waitcnt vmcnt(3)
	v_lshlrev_b32_e32 v100, 16, v74
	v_and_b32_e32 v101, 0xffff0000, v74
	v_lshlrev_b32_e32 v74, 16, v75
	v_and_b32_e32 v75, 0xffff0000, v75
	v_lshlrev_b32_e32 v94, 16, v72
	v_and_b32_e32 v95, 0xffff0000, v72
	v_lshlrev_b32_e32 v72, 16, v73
	v_and_b32_e32 v73, 0xffff0000, v73
	s_waitcnt vmcnt(2)
	v_lshlrev_b32_e32 v96, 16, v68
	v_and_b32_e32 v97, 0xffff0000, v68
	v_lshlrev_b32_e32 v68, 16, v69
	v_and_b32_e32 v69, 0xffff0000, v69
	s_waitcnt vmcnt(1)
	v_lshlrev_b32_e32 v102, 16, v84
	v_and_b32_e32 v103, 0xffff0000, v84
	v_lshlrev_b32_e32 v84, 16, v85
	v_and_b32_e32 v85, 0xffff0000, v85
	s_waitcnt vmcnt(0)
	v_lshlrev_b32_e32 v106, 16, v80
	v_and_b32_e32 v107, 0xffff0000, v80
	v_lshlrev_b32_e32 v80, 16, v81
	v_and_b32_e32 v81, 0xffff0000, v81
	v_pk_fma_f32 v[62:63], v[62:63], v[66:67], v[64:65]
	v_pk_fma_f32 v[60:61], v[60:61], v[92:93], v[90:91]
	v_pk_fma_f32 v[54:55], v[54:55], v[74:75], v[78:79]
	v_pk_fma_f32 v[52:53], v[52:53], v[100:101], v[98:99]
	v_pk_fma_f32 v[58:59], v[58:59], v[68:69], v[72:73]
	v_pk_fma_f32 v[56:57], v[56:57], v[96:97], v[94:95]
	v_pk_fma_f32 v[50:51], v[50:51], v[80:81], v[84:85]
	v_pk_fma_f32 v[48:49], v[48:49], v[106:107], v[102:103]
	v_cvt_pk_bf16_f32 v60, v60, v61
	v_cvt_pk_bf16_f32 v61, v62, v63
	v_cvt_pk_bf16_f32 v52, v52, v53
	v_cvt_pk_bf16_f32 v53, v54, v55
	v_cvt_pk_bf16_f32 v56, v56, v57
	v_cvt_pk_bf16_f32 v57, v58, v59
	v_cvt_pk_bf16_f32 v48, v48, v49
	v_cvt_pk_bf16_f32 v49, v50, v51
	global_store_dwordx2 v[104:105], v[60:61], off
	global_store_dwordx2 v[70:71], v[56:57], off
	global_store_dwordx2 v[76:77], v[52:53], off
	global_store_dwordx2 v[82:83], v[48:49], off
	v_lshl_add_u64 v[52:53], v[140:141], 0, s[20:21]
	v_lshl_add_u64 v[58:59], v[140:141], 0, s[22:23]
	v_lshl_add_u64 v[50:51], s[6:7], 0, v[86:87]
	v_lshl_add_u64 v[54:55], s[4:5], 0, v[52:53]
	v_lshl_add_u64 v[60:61], s[4:5], 0, v[58:59]
	v_lshl_add_u64 v[58:59], s[6:7], 0, v[58:59]
	v_lshl_add_u64 v[64:65], v[140:141], 0, s[24:25]
	global_load_dwordx2 v[48:49], v[88:89], off
	global_load_dwordx2 v[62:63], v[60:61], off
	global_load_dwordx2 v[56:57], v[54:55], off
	v_lshl_add_u64 v[52:53], s[6:7], 0, v[52:53]
	global_load_dwordx2 v[50:51], v[50:51], off
	v_lshl_add_u64 v[66:67], s[4:5], 0, v[64:65]
	global_load_dwordx2 v[58:59], v[58:59], off
	v_lshl_add_u64 v[64:65], s[6:7], 0, v[64:65]
	global_load_dwordx2 v[52:53], v[52:53], off
	v_lshl_add_u64 v[70:71], v[140:141], 0, s[26:27]
	global_load_dwordx2 v[68:69], v[66:67], off
	v_lshl_add_u64 v[72:73], s[4:5], 0, v[70:71]
	global_load_dwordx2 v[64:65], v[64:65], off
	s_waitcnt vmcnt(7)
	v_lshlrev_b32_e32 v74, 16, v48
	v_and_b32_e32 v75, 0xffff0000, v48
	v_lshlrev_b32_e32 v48, 16, v49
	v_and_b32_e32 v49, 0xffff0000, v49
	s_waitcnt vmcnt(4)
	v_lshlrev_b32_e32 v76, 16, v50
	v_and_b32_e32 v77, 0xffff0000, v50
	v_lshlrev_b32_e32 v50, 16, v51
	v_and_b32_e32 v51, 0xffff0000, v51
	v_lshlrev_b32_e32 v82, 16, v62
	v_and_b32_e32 v83, 0xffff0000, v62
	v_lshlrev_b32_e32 v62, 16, v63
	v_and_b32_e32 v63, 0xffff0000, v63
	s_waitcnt vmcnt(3)
	v_lshlrev_b32_e32 v84, 16, v58
	v_and_b32_e32 v85, 0xffff0000, v58
	v_lshlrev_b32_e32 v58, 16, v59
	v_and_b32_e32 v59, 0xffff0000, v59
	v_lshlrev_b32_e32 v78, 16, v56
	v_and_b32_e32 v79, 0xffff0000, v56
	v_lshlrev_b32_e32 v56, 16, v57
	v_and_b32_e32 v57, 0xffff0000, v57
	s_waitcnt vmcnt(2)
	v_lshlrev_b32_e32 v80, 16, v52
	v_and_b32_e32 v81, 0xffff0000, v52
	v_lshlrev_b32_e32 v52, 16, v53
	v_and_b32_e32 v53, 0xffff0000, v53
	s_waitcnt vmcnt(1)
	v_lshlrev_b32_e32 v86, 16, v68
	v_and_b32_e32 v87, 0xffff0000, v68
	v_lshlrev_b32_e32 v68, 16, v69
	v_and_b32_e32 v69, 0xffff0000, v69
	s_waitcnt vmcnt(0)
	v_lshlrev_b32_e32 v90, 16, v64
	v_and_b32_e32 v91, 0xffff0000, v64
	v_lshlrev_b32_e32 v64, 16, v65
	v_and_b32_e32 v65, 0xffff0000, v65
	v_pk_fma_f32 v[46:47], v[46:47], v[50:51], v[48:49]
	v_pk_fma_f32 v[44:45], v[44:45], v[76:77], v[74:75]
	v_pk_fma_f32 v[38:39], v[38:39], v[58:59], v[62:63]
	v_pk_fma_f32 v[36:37], v[36:37], v[84:85], v[82:83]
	v_pk_fma_f32 v[42:43], v[42:43], v[52:53], v[56:57]
	v_pk_fma_f32 v[40:41], v[40:41], v[80:81], v[78:79]
	v_pk_fma_f32 v[34:35], v[34:35], v[64:65], v[68:69]
	v_pk_fma_f32 v[32:33], v[32:33], v[90:91], v[86:87]
	v_cvt_pk_bf16_f32 v44, v44, v45
	v_cvt_pk_bf16_f32 v45, v46, v47
	v_cvt_pk_bf16_f32 v36, v36, v37
	v_cvt_pk_bf16_f32 v37, v38, v39
	v_cvt_pk_bf16_f32 v40, v40, v41
	v_cvt_pk_bf16_f32 v41, v42, v43
	v_cvt_pk_bf16_f32 v32, v32, v33
	v_cvt_pk_bf16_f32 v33, v34, v35
	global_store_dwordx2 v[88:89], v[44:45], off
	global_store_dwordx2 v[54:55], v[40:41], off
	global_store_dwordx2 v[60:61], v[36:37], off
	global_store_dwordx2 v[66:67], v[32:33], off
	v_lshl_add_u64 v[36:37], v[140:141], 0, s[28:29]
	v_lshl_add_u64 v[42:43], v[140:141], 0, s[30:31]
	v_lshl_add_u64 v[34:35], s[6:7], 0, v[70:71]
	v_lshl_add_u64 v[38:39], s[4:5], 0, v[36:37]
	v_lshl_add_u64 v[44:45], s[4:5], 0, v[42:43]
	v_lshl_add_u64 v[42:43], s[6:7], 0, v[42:43]
	v_lshl_add_u64 v[48:49], v[140:141], 0, s[34:35]
	global_load_dwordx2 v[32:33], v[72:73], off
	global_load_dwordx2 v[46:47], v[44:45], off
	global_load_dwordx2 v[40:41], v[38:39], off
	v_lshl_add_u64 v[36:37], s[6:7], 0, v[36:37]
	global_load_dwordx2 v[34:35], v[34:35], off
	v_lshl_add_u64 v[50:51], s[4:5], 0, v[48:49]
	global_load_dwordx2 v[42:43], v[42:43], off
	v_lshl_add_u64 v[48:49], s[6:7], 0, v[48:49]
	global_load_dwordx2 v[36:37], v[36:37], off
	v_lshl_add_u64 v[54:55], v[140:141], 0, s[40:41]
	global_load_dwordx2 v[52:53], v[50:51], off
	v_lshl_add_u64 v[56:57], s[4:5], 0, v[54:55]
	global_load_dwordx2 v[48:49], v[48:49], off
	s_waitcnt vmcnt(7)
; #define PG8_WAIT_V(n) asm volatile("s_waitcnt vmcnt(" #n ")" ::: "memory")
; #define PG8_BAR __builtin_amdgcn_s_barrier()
; __device__ __forceinline__ u32x2 pk4(f32x4 v) { u32x2 w; w.x = cvt_pk_bf16(v[0], v[1]); w.y = cvt_pk_bf16(v[2], v[3]); return w; }
; __device__ __forceinline__ f32x4 up4(u32x2 w) { return (f32x4){bf_lo(w.x), bf_hi(w.x), bf_lo(w.y), bf_hi(w.y)}; }
; template <class Epi, class Sched, bool ALIGN_EPI = false, bool SP2 = false>
; __device__ __forceinline__ void gemm_phase(PG8_LAS unsigned char* lds, const Gemm g, const Sched& S, const Epi& E) {
;     ...
;         if (!has_next) break;
;     ...
;     PG8_WAIT_V(0);
;     if constexpr (!ALIGN_EPI) { if (wr == 0) PG8_BAR; }
;     __device__ __forceinline__ void operator()(const AccT& acc, const pg8::Unit& u, int wr, int wc, int fr, int fq) const {
;     ...
;                     for (int n = 0; n < 2; ++n) { f32x4 v = acc[ai][bj][m][n]; const size_t idx = (size_t)row * 1024 + col0 + bj * 128 + n * 16;
;                         if (MODE == 0) v = v * up4(*(const u32x2*)(io + idx));
;                         else if (MODE == 1) v = up4(*(const u32x2*)(io + idx)) + up4(*(const u32x2*)(g2 + idx)) * v;
;                         else ss += (v[0] * v[0] + v[1] * v[1]) + (v[2] * v[2] + v[3] * v[3]);
;                         if (!DRYE || v[0] == 123.456f) *(u32x2*)(io + idx) = pk4(v); }
	v_lshlrev_b32_e32 v58, 16, v32
	v_and_b32_e32 v59, 0xffff0000, v32
	v_lshlrev_b32_e32 v32, 16, v33
	v_and_b32_e32 v33, 0xffff0000, v33
	s_waitcnt vmcnt(4)
	v_lshlrev_b32_e32 v60, 16, v34
	v_and_b32_e32 v61, 0xffff0000, v34
	v_lshlrev_b32_e32 v34, 16, v35
	v_and_b32_e32 v35, 0xffff0000, v35
	v_lshlrev_b32_e32 v66, 16, v46
	v_and_b32_e32 v67, 0xffff0000, v46
	v_lshlrev_b32_e32 v46, 16, v47
	v_and_b32_e32 v47, 0xffff0000, v47
	s_waitcnt vmcnt(3)
	v_lshlrev_b32_e32 v68, 16, v42
	v_and_b32_e32 v69, 0xffff0000, v42
	v_lshlrev_b32_e32 v42, 16, v43
	v_and_b32_e32 v43, 0xffff0000, v43
	v_lshlrev_b32_e32 v62, 16, v40
	v_and_b32_e32 v63, 0xffff0000, v40
	v_lshlrev_b32_e32 v40, 16, v41
	v_and_b32_e32 v41, 0xffff0000, v41
	s_waitcnt vmcnt(2)
	v_lshlrev_b32_e32 v64, 16, v36
	v_and_b32_e32 v65, 0xffff0000, v36
	v_lshlrev_b32_e32 v36, 16, v37
	v_and_b32_e32 v37, 0xffff0000, v37
	s_waitcnt vmcnt(1)
	v_lshlrev_b32_e32 v70, 16, v52
	v_and_b32_e32 v71, 0xffff0000, v52
	v_lshlrev_b32_e32 v52, 16, v53
	v_and_b32_e32 v53, 0xffff0000, v53
	s_waitcnt vmcnt(0)
	v_lshlrev_b32_e32 v74, 16, v48
	v_and_b32_e32 v75, 0xffff0000, v48
	v_lshlrev_b32_e32 v48, 16, v49
	v_and_b32_e32 v49, 0xffff0000, v49
	v_pk_fma_f32 v[30:31], v[30:31], v[34:35], v[32:33]
	v_pk_fma_f32 v[28:29], v[28:29], v[60:61], v[58:59]
	v_pk_fma_f32 v[22:23], v[22:23], v[42:43], v[46:47]
	v_pk_fma_f32 v[20:21], v[20:21], v[68:69], v[66:67]
	v_pk_fma_f32 v[26:27], v[26:27], v[36:37], v[40:41]
	v_pk_fma_f32 v[24:25], v[24:25], v[64:65], v[62:63]
	v_pk_fma_f32 v[18:19], v[18:19], v[48:49], v[52:53]
	v_pk_fma_f32 v[16:17], v[16:17], v[74:75], v[70:71]
	v_cvt_pk_bf16_f32 v28, v28, v29
	v_cvt_pk_bf16_f32 v29, v30, v31
	v_cvt_pk_bf16_f32 v20, v20, v21
	v_cvt_pk_bf16_f32 v21, v22, v23
	v_cvt_pk_bf16_f32 v24, v24, v25
	v_cvt_pk_bf16_f32 v25, v26, v27
	v_cvt_pk_bf16_f32 v16, v16, v17
	v_cvt_pk_bf16_f32 v17, v18, v19
	global_store_dwordx2 v[72:73], v[28:29], off
	global_store_dwordx2 v[38:39], v[24:25], off
	global_store_dwordx2 v[44:45], v[20:21], off
	global_store_dwordx2 v[50:51], v[16:17], off
	v_lshl_add_u64 v[18:19], s[6:7], 0, v[54:55]
	v_lshl_add_u64 v[20:21], v[140:141], 0, s[42:43]
	v_lshl_add_u64 v[26:27], v[140:141], 0, s[44:45]
	v_lshl_add_u64 v[32:33], v[140:141], 0, s[46:47]
	global_load_dwordx2 v[16:17], v[56:57], off
	v_lshl_add_u64 v[22:23], s[4:5], 0, v[20:21]
	global_load_dwordx2 v[18:19], v[18:19], off
	v_lshl_add_u64 v[20:21], s[6:7], 0, v[20:21]
	v_lshl_add_u64 v[28:29], s[4:5], 0, v[26:27]
	v_lshl_add_u64 v[26:27], s[6:7], 0, v[26:27]
	v_lshl_add_u64 v[34:35], s[4:5], 0, v[32:33]
	v_lshl_add_u64 v[32:33], s[6:7], 0, v[32:33]
	global_load_dwordx2 v[24:25], v[22:23], off
	global_load_dwordx2 v[30:31], v[28:29], off
	global_load_dwordx2 v[36:37], v[34:35], off
	s_waitcnt vmcnt(4)
	v_lshlrev_b32_e32 v38, 16, v16
	global_load_dwordx2 v[26:27], v[26:27], off
	v_and_b32_e32 v39, 0xffff0000, v16
	global_load_dwordx2 v[20:21], v[20:21], off
	v_lshlrev_b32_e32 v16, 16, v17
	global_load_dwordx2 v[32:33], v[32:33], off
	v_and_b32_e32 v17, 0xffff0000, v17
	s_waitcnt vmcnt(6)
	v_lshlrev_b32_e32 v40, 16, v18
	v_and_b32_e32 v41, 0xffff0000, v18
	v_lshlrev_b32_e32 v18, 16, v19
	v_and_b32_e32 v19, 0xffff0000, v19
	s_waitcnt vmcnt(5)
	v_lshlrev_b32_e32 v42, 16, v24
	v_and_b32_e32 v43, 0xffff0000, v24
	v_lshlrev_b32_e32 v24, 16, v25
	v_and_b32_e32 v25, 0xffff0000, v25
	s_waitcnt vmcnt(4)
	v_lshlrev_b32_e32 v46, 16, v30
	v_and_b32_e32 v47, 0xffff0000, v30
	v_lshlrev_b32_e32 v30, 16, v31
	v_and_b32_e32 v31, 0xffff0000, v31
	s_waitcnt vmcnt(3)
	v_lshlrev_b32_e32 v50, 16, v36
	v_and_b32_e32 v51, 0xffff0000, v36
	v_lshlrev_b32_e32 v36, 16, v37
	v_and_b32_e32 v37, 0xffff0000, v37
	v_pk_fma_f32 v[14:15], v[14:15], v[18:19], v[16:17]
	v_pk_fma_f32 v[12:13], v[12:13], v[40:41], v[38:39]
	s_waitcnt vmcnt(2)
	v_lshlrev_b32_e32 v48, 16, v26
	v_and_b32_e32 v49, 0xffff0000, v26
	s_waitcnt vmcnt(1)
	v_lshlrev_b32_e32 v44, 16, v20
	v_and_b32_e32 v45, 0xffff0000, v20
	v_lshlrev_b32_e32 v20, 16, v21
	v_and_b32_e32 v21, 0xffff0000, v21
	v_lshlrev_b32_e32 v26, 16, v27
	v_and_b32_e32 v27, 0xffff0000, v27
	s_waitcnt vmcnt(0)
	v_lshlrev_b32_e32 v52, 16, v32
	v_and_b32_e32 v53, 0xffff0000, v32
	v_lshlrev_b32_e32 v32, 16, v33
	v_and_b32_e32 v33, 0xffff0000, v33
	v_pk_fma_f32 v[10:11], v[10:11], v[20:21], v[24:25]
	v_pk_fma_f32 v[8:9], v[8:9], v[44:45], v[42:43]
	v_pk_fma_f32 v[6:7], v[6:7], v[26:27], v[30:31]
	v_pk_fma_f32 v[4:5], v[4:5], v[48:49], v[46:47]
	v_pk_fma_f32 v[2:3], v[2:3], v[32:33], v[36:37]
	v_pk_fma_f32 v[0:1], v[0:1], v[52:53], v[50:51]
	v_cvt_pk_bf16_f32 v12, v12, v13
	v_cvt_pk_bf16_f32 v13, v14, v15
	v_cvt_pk_bf16_f32 v8, v8, v9
	v_cvt_pk_bf16_f32 v9, v10, v11
	v_cvt_pk_bf16_f32 v4, v4, v5
	v_cvt_pk_bf16_f32 v5, v6, v7
	v_cvt_pk_bf16_f32 v0, v0, v1
	v_cvt_pk_bf16_f32 v1, v2, v3
	global_store_dwordx2 v[56:57], v[12:13], off
	global_store_dwordx2 v[22:23], v[8:9], off
	global_store_dwordx2 v[28:29], v[4:5], off
	global_store_dwordx2 v[34:35], v[0:1], off
	s_cbranch_vccz .LBB0_829
	s_waitcnt vmcnt(0)
	s_cmpk_gt_u32 s76, 0xff
	s_cbranch_scc1 .LBB0_840
	s_barrier

; #define PG8_STAGE(bufoff, gbase, voff) do { _Pragma("unroll") for (int _i = 0; _i < 2; ++_i) \
;         __builtin_amdgcn_global_load_lds((const unsigned*)((const char*)(gbase) + (voff)[_i]), (PG8_LAS unsigned*)(lds + (bufoff) + ldsw + _i * 8192), 16, 0, 0); } while (0)
; #define PG8_LDA(dst, b, h) do { _Pragma("unroll") for (int m = 0; m < 4; ++m) _Pragma("unroll") for (int k = 0; k < 2; ++k) dst[m][k] = *(const PG8_LAS bf16x8*)(lds + PG8_SA(b, h) + aoff + m * 2048 + k * 1024); } while (0)
; #define PG8_LDB(dst, b, h) do { _Pragma("unroll") for (int n = 0; n < 2; ++n) _Pragma("unroll") for (int k = 0; k < 2; ++k) dst[n][k] = *(const PG8_LAS bf16x8*)(lds + PG8_SB(b, h) + boff + n * 2048 + k * 1024); } while (0)
; #define PG8_WAIT_V(n) asm volatile("s_waitcnt vmcnt(" #n ")" ::: "memory")
; #define PG8_WAIT_L(n) asm volatile("s_waitcnt lgkmcnt(" #n ")" ::: "memory")
; #define PG8_BAR __builtin_amdgcn_s_barrier()
; #define PG8_SCHED __builtin_amdgcn_sched_barrier(0)
; template <class Epi, class Sched, bool ALIGN_EPI = false, bool SP2 = false>
; __device__ __forceinline__ void gemm_phase(PG8_LAS unsigned char* lds, const Gemm g, const Sched& S, const Epi& E) {
;     ...
;         const bool has_next = S.next(ui + 1, nxt);
;         const char* nA = has_next ? (const char*)g.A + (size_t)nxt.pm * tstep : cA; const char* nB = has_next ? (const char*)g.Bt + (size_t)nxt.pn * tstep : cB;
;         for (int t = 0; t < nt; t += 2) {
;             const bool last = (t == nt - 2);
;             const char* a1 = cA + (size_t)(t + 1) * kstep;
;             const char* a2 = last ? nA : cA + (size_t)(t + 2) * kstep; const char* b2 = last ? nB : cB + (size_t)(t + 2) * kstep;
;             const char* a3 = a2 + kstep; const char* b3 = b2 + kstep;
;             if (last && has_next) S.a_ready(nxt);
;             if constexpr (SP2) {
;             PG8_LDB(B0, 0, 0); PG8_LDB(B1, 0, 1); PG8_SCHED; PG8_LDA(At, 0, 0); PG8_STAGE(PG8_SA(1, 1), a1 + hstep, voffA);
;             PG8_WAIT_V(8); PG8_WAIT_L(0); PG8_BAR; PG8_MMA(0, 0, At, B0); PG8_MMA(0, 1, At, B1); PG8_BAR; PG8_SCHED;
;             PG8_LDA(At, 0, 1); PG8_STAGE(PG8_SB(0, 0), b2, voffB); PG8_STAGE(PG8_SB(0, 1), b2 + hstep, voffB); PG8_STAGE(PG8_SA(0, 0), a2, voffA);
;             PG8_WAIT_V(8); PG8_WAIT_L(0); PG8_BAR; PG8_MMA(1, 0, At, B0); PG8_MMA(1, 1, At, B1); PG8_BAR; PG8_SCHED;
.LBB0_914:
	ds_read_b128 v[140:143], v147
	ds_read_b128 v[152:155], v147 offset:1024
	ds_read_b128 v[156:159], v147 offset:2048
	ds_read_b128 v[160:163], v147 offset:3072
	ds_read_b128 v[164:167], v148
	ds_read_b128 v[168:171], v148 offset:1024
	ds_read_b128 v[172:175], v148 offset:2048
	ds_read_b128 v[180:183], v148 offset:3072
	s_add_u32 s3, s28, 0xfffc0080
	s_addc_u32 s30, s29, -1
	s_cmp_eq_u32 s72, 12
	s_cselect_b32 s35, s19, s30
	s_cselect_b32 s34, s25, s3
	s_cselect_b32 s31, s17, s71
	s_cselect_b32 s30, s69, s70
	v_lshl_add_u64 v[216:217], s[28:29], 0, v[132:133]
	s_add_i32 m0, s27, 0xc000
	ds_read_b128 v[184:187], v149
	ds_read_b128 v[188:191], v149 offset:1024
	ds_read_b128 v[192:195], v149 offset:2048
	ds_read_b128 v[196:199], v149 offset:3072
	ds_read_b128 v[200:203], v149 offset:4096
	ds_read_b128 v[204:207], v149 offset:5120
	ds_read_b128 v[208:211], v149 offset:6144
	ds_read_b128 v[212:215], v149 offset:7168
	global_load_lds_dwordx4 v[216:217], off
	v_lshl_add_u64 v[216:217], s[28:29], 0, v[134:135]
	s_add_i32 m0, s27, 0xe000
	s_nop 0
	global_load_lds_dwordx4 v[216:217], off
	s_waitcnt vmcnt(8)
	s_waitcnt lgkmcnt(0)
	s_barrier
	s_setprio 1
	s_waitcnt lgkmcnt(0)
	v_mfma_f32_16x16x32_bf16 v[124:127], v[140:143], v[184:187], v[124:127]
	v_mfma_f32_16x16x32_bf16 v[120:123], v[156:159], v[184:187], v[120:123]
	v_mfma_f32_16x16x32_bf16 v[112:115], v[140:143], v[192:195], v[112:115]
	v_mfma_f32_16x16x32_bf16 v[104:107], v[156:159], v[192:195], v[104:107]
	v_mfma_f32_16x16x32_bf16 v[96:99], v[140:143], v[200:203], v[96:99]
	v_mfma_f32_16x16x32_bf16 v[88:91], v[156:159], v[200:203], v[88:91]
	v_mfma_f32_16x16x32_bf16 v[80:83], v[140:143], v[208:211], v[80:83]
	v_mfma_f32_16x16x32_bf16 v[72:75], v[156:159], v[208:211], v[72:75]
	v_mfma_f32_16x16x32_bf16 v[124:127], v[152:155], v[188:191], v[124:127]
	v_mfma_f32_16x16x32_bf16 v[120:123], v[160:163], v[188:191], v[120:123]
	v_mfma_f32_16x16x32_bf16 v[112:115], v[152:155], v[196:199], v[112:115]
	v_mfma_f32_16x16x32_bf16 v[104:107], v[160:163], v[196:199], v[104:107]
	v_mfma_f32_16x16x32_bf16 v[96:99], v[152:155], v[204:207], v[96:99]
	v_mfma_f32_16x16x32_bf16 v[88:91], v[160:163], v[204:207], v[88:91]
	v_mfma_f32_16x16x32_bf16 v[80:83], v[152:155], v[212:215], v[80:83]
	v_mfma_f32_16x16x32_bf16 v[72:75], v[160:163], v[212:215], v[72:75]
	s_setprio 0
	s_setprio 1
	v_mfma_f32_16x16x32_bf16 v[116:119], v[164:167], v[184:187], v[116:119]
	v_mfma_f32_16x16x32_bf16 v[108:111], v[172:175], v[184:187], v[108:111]
	v_mfma_f32_16x16x32_bf16 v[100:103], v[164:167], v[192:195], v[100:103]
	v_mfma_f32_16x16x32_bf16 v[92:95], v[172:175], v[192:195], v[92:95]
	v_mfma_f32_16x16x32_bf16 v[84:87], v[164:167], v[200:203], v[84:87]
	v_mfma_f32_16x16x32_bf16 v[76:79], v[172:175], v[200:203], v[76:79]
	v_mfma_f32_16x16x32_bf16 v[68:71], v[164:167], v[208:211], v[68:71]
	v_mfma_f32_16x16x32_bf16 v[64:67], v[172:175], v[208:211], v[64:67]
	v_mfma_f32_16x16x32_bf16 v[116:119], v[168:171], v[188:191], v[116:119]
	v_mfma_f32_16x16x32_bf16 v[108:111], v[180:183], v[188:191], v[108:111]
	v_mfma_f32_16x16x32_bf16 v[100:103], v[168:171], v[196:199], v[100:103]
	v_mfma_f32_16x16x32_bf16 v[92:95], v[180:183], v[196:199], v[92:95]
	v_mfma_f32_16x16x32_bf16 v[84:87], v[168:171], v[204:207], v[84:87]
	v_mfma_f32_16x16x32_bf16 v[76:79], v[180:183], v[204:207], v[76:79]
	v_mfma_f32_16x16x32_bf16 v[68:71], v[168:171], v[212:215], v[68:71]
	v_mfma_f32_16x16x32_bf16 v[64:67], v[180:183], v[212:215], v[64:67]
	s_setprio 0
	s_barrier
	s_add_i32 s3, s67, s45
	v_lshl_add_u64 v[216:217], s[30:31], 0, v[128:129]
	s_mov_b32 m0, s3
	ds_read_b128 v[184:187], v149 offset:16384
	ds_read_b128 v[188:191], v149 offset:17408
	ds_read_b128 v[192:195], v149 offset:18432
	ds_read_b128 v[196:199], v149 offset:19456
	ds_read_b128 v[200:203], v149 offset:20480
	ds_read_b128 v[204:207], v149 offset:21504
	ds_read_b128 v[208:211], v149 offset:22528
	ds_read_b128 v[212:215], v149 offset:23552
	global_load_lds_dwordx4 v[216:217], off
	s_add_i32 m0, s3, 0x2000
	s_add_u32 s36, s30, 0x40000
	v_lshl_add_u64 v[218:219], s[30:31], 0, v[130:131]
	s_addc_u32 s37, s31, 0
	s_add_i32 s3, s68, s45
	global_load_lds_dwordx4 v[218:219], off
	v_lshl_add_u64 v[220:221], s[36:37], 0, v[128:129]
	s_mov_b32 m0, s3
	v_lshl_add_u64 v[222:223], s[34:35], 0, v[130:131]
	global_load_lds_dwordx4 v[220:221], off
	v_lshl_add_u64 v[220:221], s[36:37], 0, v[130:131]
	s_add_i32 m0, s3, 0x2000
	s_nop 0
	global_load_lds_dwordx4 v[220:221], off
	v_lshl_add_u64 v[220:221], s[34:35], 0, v[128:129]
	s_mov_b32 m0, s27
	s_nop 0
	global_load_lds_dwordx4 v[220:221], off
	s_mov_b32 m0, s46
	s_nop 0
	global_load_lds_dwordx4 v[222:223], off
	s_waitcnt vmcnt(8)
	s_waitcnt lgkmcnt(0)
	s_barrier
; #define PG8_STAGE(bufoff, gbase, voff) do { _Pragma("unroll") for (int _i = 0; _i < 2; ++_i) \
;         __builtin_amdgcn_global_load_lds((const unsigned*)((const char*)(gbase) + (voff)[_i]), (PG8_LAS unsigned*)(lds + (bufoff) + ldsw + _i * 8192), 16, 0, 0); } while (0)
; #define PG8_LDA(dst, b, h) do { _Pragma("unroll") for (int m = 0; m < 4; ++m) _Pragma("unroll") for (int k = 0; k < 2; ++k) dst[m][k] = *(const PG8_LAS bf16x8*)(lds + PG8_SA(b, h) + aoff + m * 2048 + k * 1024); } while (0)
; #define PG8_LDB(dst, b, h) do { _Pragma("unroll") for (int n = 0; n < 2; ++n) _Pragma("unroll") for (int k = 0; k < 2; ++k) dst[n][k] = *(const PG8_LAS bf16x8*)(lds + PG8_SB(b, h) + boff + n * 2048 + k * 1024); } while (0)
; #define PG8_MMA(ai, bj, At, Bt) do { __builtin_amdgcn_s_setprio(1); _Pragma("unroll") for (int m = 0; m < 4; ++m) _Pragma("unroll") for (int n = 0; n < 2; ++n) _Pragma("unroll") for (int k = 0; k < 2; ++k) \
;         acc[ai][bj][m][n] = __builtin_amdgcn_mfma_f32_16x16x32_bf16(Bt[n][k], At[m][k], acc[ai][bj][m][n], 0, 0, 0); __builtin_amdgcn_s_setprio(0); } while (0)
; #define PG8_WAIT_V(n) asm volatile("s_waitcnt vmcnt(" #n ")" ::: "memory")
; #define PG8_WAIT_L(n) asm volatile("s_waitcnt lgkmcnt(" #n ")" ::: "memory")
; #define PG8_BAR __builtin_amdgcn_s_barrier()
; #define PG8_SCHED __builtin_amdgcn_sched_barrier(0)
; template <class Epi, class Sched, bool ALIGN_EPI = false, bool SP2 = false>
; __device__ __forceinline__ void gemm_phase(PG8_LAS unsigned char* lds, const Gemm g, const Sched& S, const Epi& E) {
;     ...
;             PG8_WAIT_V(8); PG8_WAIT_L(0); PG8_BAR; PG8_MMA(1, 0, At, B0); PG8_MMA(1, 1, At, B1); PG8_BAR; PG8_SCHED;
;             PG8_LDB(B0, 1, 0); PG8_LDB(B1, 1, 1); PG8_SCHED; PG8_LDA(At, 1, 0); PG8_STAGE(PG8_SA(0, 1), a2 + hstep, voffA);
;             PG8_WAIT_V(8); PG8_WAIT_L(0); PG8_BAR; PG8_MMA(0, 0, At, B0); PG8_MMA(0, 1, At, B1); PG8_BAR; PG8_SCHED;
	s_setprio 1
	s_waitcnt lgkmcnt(0)
	v_mfma_f32_16x16x32_bf16 v[60:63], v[140:143], v[184:187], v[60:63]
	v_mfma_f32_16x16x32_bf16 v[56:59], v[156:159], v[184:187], v[56:59]
	v_mfma_f32_16x16x32_bf16 v[48:51], v[140:143], v[192:195], v[48:51]
	v_mfma_f32_16x16x32_bf16 v[40:43], v[156:159], v[192:195], v[40:43]
	v_mfma_f32_16x16x32_bf16 v[32:35], v[140:143], v[200:203], v[32:35]
	v_mfma_f32_16x16x32_bf16 v[24:27], v[156:159], v[200:203], v[24:27]
	v_mfma_f32_16x16x32_bf16 v[16:19], v[140:143], v[208:211], v[16:19]
	v_mfma_f32_16x16x32_bf16 v[8:11], v[156:159], v[208:211], v[8:11]
	v_mfma_f32_16x16x32_bf16 v[60:63], v[152:155], v[188:191], v[60:63]
	v_mfma_f32_16x16x32_bf16 v[56:59], v[160:163], v[188:191], v[56:59]
	v_mfma_f32_16x16x32_bf16 v[48:51], v[152:155], v[196:199], v[48:51]
	v_mfma_f32_16x16x32_bf16 v[40:43], v[160:163], v[196:199], v[40:43]
	v_mfma_f32_16x16x32_bf16 v[32:35], v[152:155], v[204:207], v[32:35]
	v_mfma_f32_16x16x32_bf16 v[24:27], v[160:163], v[204:207], v[24:27]
	v_mfma_f32_16x16x32_bf16 v[16:19], v[152:155], v[212:215], v[16:19]
	v_mfma_f32_16x16x32_bf16 v[8:11], v[160:163], v[212:215], v[8:11]
	s_setprio 0
	s_setprio 1
	v_mfma_f32_16x16x32_bf16 v[52:55], v[164:167], v[184:187], v[52:55]
	v_mfma_f32_16x16x32_bf16 v[44:47], v[172:175], v[184:187], v[44:47]
	v_mfma_f32_16x16x32_bf16 v[36:39], v[164:167], v[192:195], v[36:39]
	v_mfma_f32_16x16x32_bf16 v[28:31], v[172:175], v[192:195], v[28:31]
	v_mfma_f32_16x16x32_bf16 v[20:23], v[164:167], v[200:203], v[20:23]
	v_mfma_f32_16x16x32_bf16 v[12:15], v[172:175], v[200:203], v[12:15]
	v_mfma_f32_16x16x32_bf16 v[4:7], v[164:167], v[208:211], v[4:7]
	v_mfma_f32_16x16x32_bf16 v[0:3], v[172:175], v[208:211], v[0:3]
	v_mfma_f32_16x16x32_bf16 v[52:55], v[168:171], v[188:191], v[52:55]
	v_mfma_f32_16x16x32_bf16 v[44:47], v[180:183], v[188:191], v[44:47]
	v_mfma_f32_16x16x32_bf16 v[36:39], v[168:171], v[196:199], v[36:39]
	v_mfma_f32_16x16x32_bf16 v[28:31], v[180:183], v[196:199], v[28:31]
	v_mfma_f32_16x16x32_bf16 v[20:23], v[168:171], v[204:207], v[20:23]
	v_mfma_f32_16x16x32_bf16 v[12:15], v[180:183], v[204:207], v[12:15]
	v_mfma_f32_16x16x32_bf16 v[4:7], v[168:171], v[212:215], v[4:7]
	v_mfma_f32_16x16x32_bf16 v[0:3], v[180:183], v[212:215], v[0:3]
	s_setprio 0
	s_barrier
	s_add_i32 s3, 0, 0x18000
	v_add_u32_e32 v151, s3, v145
	s_add_i32 s33, 0, 0x1c000
	ds_read_b128 v[140:143], v151
	ds_read_b128 v[152:155], v151 offset:1024
	ds_read_b128 v[156:159], v151 offset:2048
	ds_read_b128 v[160:163], v151 offset:3072
	v_add_u32_e32 v151, s33, v145
	ds_read_b128 v[164:167], v151
	ds_read_b128 v[168:171], v151 offset:1024
	ds_read_b128 v[172:175], v151 offset:2048
	ds_read_b128 v[180:183], v151 offset:3072
	s_add_u32 s34, s34, 0x40000
	s_addc_u32 s35, s35, 0
	s_mov_b32 m0, s47
	v_lshl_add_u64 v[224:225], s[34:35], 0, v[128:129]
	ds_read_b128 v[184:187], v149 offset:32768
	ds_read_b128 v[188:191], v149 offset:33792
	ds_read_b128 v[192:195], v149 offset:34816
	ds_read_b128 v[196:199], v149 offset:35840
	ds_read_b128 v[200:203], v149 offset:36864
	ds_read_b128 v[204:207], v149 offset:37888
	ds_read_b128 v[208:211], v149 offset:38912
	ds_read_b128 v[212:215], v149 offset:39936
	global_load_lds_dwordx4 v[224:225], off
	v_lshl_add_u64 v[224:225], s[34:35], 0, v[130:131]
	s_mov_b32 m0, s60
	s_nop 0
	global_load_lds_dwordx4 v[224:225], off
	s_waitcnt vmcnt(8)
	s_waitcnt lgkmcnt(0)
	s_barrier
	s_setprio 1
	s_waitcnt lgkmcnt(0)
	v_mfma_f32_16x16x32_bf16 v[124:127], v[140:143], v[184:187], v[124:127]
	v_mfma_f32_16x16x32_bf16 v[120:123], v[156:159], v[184:187], v[120:123]
	v_mfma_f32_16x16x32_bf16 v[112:115], v[140:143], v[192:195], v[112:115]
	v_mfma_f32_16x16x32_bf16 v[104:107], v[156:159], v[192:195], v[104:107]
	v_mfma_f32_16x16x32_bf16 v[96:99], v[140:143], v[200:203], v[96:99]
	v_mfma_f32_16x16x32_bf16 v[88:91], v[156:159], v[200:203], v[88:91]
	v_mfma_f32_16x16x32_bf16 v[80:83], v[140:143], v[208:211], v[80:83]
	v_mfma_f32_16x16x32_bf16 v[72:75], v[156:159], v[208:211], v[72:75]
	v_mfma_f32_16x16x32_bf16 v[124:127], v[152:155], v[188:191], v[124:127]
	v_mfma_f32_16x16x32_bf16 v[120:123], v[160:163], v[188:191], v[120:123]
	v_mfma_f32_16x16x32_bf16 v[112:115], v[152:155], v[196:199], v[112:115]
	v_mfma_f32_16x16x32_bf16 v[104:107], v[160:163], v[196:199], v[104:107]
	v_mfma_f32_16x16x32_bf16 v[96:99], v[152:155], v[204:207], v[96:99]
	v_mfma_f32_16x16x32_bf16 v[88:91], v[160:163], v[204:207], v[88:91]
	v_mfma_f32_16x16x32_bf16 v[80:83], v[152:155], v[212:215], v[80:83]
	v_mfma_f32_16x16x32_bf16 v[72:75], v[160:163], v[212:215], v[72:75]
	s_setprio 0
	s_setprio 1
	v_mfma_f32_16x16x32_bf16 v[116:119], v[164:167], v[184:187], v[116:119]
	v_mfma_f32_16x16x32_bf16 v[108:111], v[172:175], v[184:187], v[108:111]
	v_mfma_f32_16x16x32_bf16 v[100:103], v[164:167], v[192:195], v[100:103]
	v_mfma_f32_16x16x32_bf16 v[92:95], v[172:175], v[192:195], v[92:95]
	v_mfma_f32_16x16x32_bf16 v[84:87], v[164:167], v[200:203], v[84:87]
	v_mfma_f32_16x16x32_bf16 v[76:79], v[172:175], v[200:203], v[76:79]
	v_mfma_f32_16x16x32_bf16 v[68:71], v[164:167], v[208:211], v[68:71]
	v_mfma_f32_16x16x32_bf16 v[64:67], v[172:175], v[208:211], v[64:67]
	v_mfma_f32_16x16x32_bf16 v[116:119], v[168:171], v[188:191], v[116:119]
	v_mfma_f32_16x16x32_bf16 v[108:111], v[180:183], v[188:191], v[108:111]
	v_mfma_f32_16x16x32_bf16 v[100:103], v[168:171], v[196:199], v[100:103]
	v_mfma_f32_16x16x32_bf16 v[92:95], v[180:183], v[196:199], v[92:95]
	v_mfma_f32_16x16x32_bf16 v[84:87], v[168:171], v[204:207], v[84:87]
	v_mfma_f32_16x16x32_bf16 v[76:79], v[180:183], v[204:207], v[76:79]
	v_mfma_f32_16x16x32_bf16 v[68:71], v[168:171], v[212:215], v[68:71]
	v_mfma_f32_16x16x32_bf16 v[64:67], v[180:183], v[212:215], v[64:67]
	s_setprio 0
	s_barrier
; #define PG8_STAGE(bufoff, gbase, voff) do { _Pragma("unroll") for (int _i = 0; _i < 2; ++_i) \
;         __builtin_amdgcn_global_load_lds((const unsigned*)((const char*)(gbase) + (voff)[_i]), (PG8_LAS unsigned*)(lds + (bufoff) + ldsw + _i * 8192), 16, 0, 0); } while (0)
; #define PG8_LDA(dst, b, h) do { _Pragma("unroll") for (int m = 0; m < 4; ++m) _Pragma("unroll") for (int k = 0; k < 2; ++k) dst[m][k] = *(const PG8_LAS bf16x8*)(lds + PG8_SA(b, h) + aoff + m * 2048 + k * 1024); } while (0)
; #define PG8_MMA(ai, bj, At, Bt) do { __builtin_amdgcn_s_setprio(1); _Pragma("unroll") for (int m = 0; m < 4; ++m) _Pragma("unroll") for (int n = 0; n < 2; ++n) _Pragma("unroll") for (int k = 0; k < 2; ++k) \
;         acc[ai][bj][m][n] = __builtin_amdgcn_mfma_f32_16x16x32_bf16(Bt[n][k], At[m][k], acc[ai][bj][m][n], 0, 0, 0); __builtin_amdgcn_s_setprio(0); } while (0)
; #define PG8_WAIT_V(n) asm volatile("s_waitcnt vmcnt(" #n ")" ::: "memory")
; template <class Epi, class Sched, bool ALIGN_EPI = false, bool SP2 = false>
; __device__ __forceinline__ void gemm_phase(PG8_LAS unsigned char* lds, const Gemm g, const Sched& S, const Epi& E) {
;     ...
;             PG8_LDA(At, 1, 1); PG8_STAGE(PG8_SB(1, 0), b3, voffB); PG8_STAGE(PG8_SB(1, 1), b3 + hstep, voffB); PG8_STAGE(PG8_SA(1, 0), a3, voffA);
;             PG8_WAIT_V(8); PG8_WAIT_L(0); PG8_BAR; PG8_MMA(1, 0, At, B0); PG8_MMA(1, 1, At, B1); PG8_BAR; PG8_SCHED;
;     __device__ __forceinline__ void operator()(const AccT& acc, const pg8::Unit& u, int wr, int wc, int fr, int fq) const {
;     ...
;             for (int m = 0; m < 4; ++m) { const int row = row0 + ai * 128 + m * 16; float ss = 0.f;
; #pragma unroll
;                 for (int bj = 0; bj < 2; ++bj)
; #pragma unroll
;                     for (int n = 0; n < 2; ++n) { f32x4 v = acc[ai][bj][m][n]; const size_t idx = (size_t)row * 1024 + col0 + bj * 128 + n * 16;
;                         if (MODE == 0) v = v * up4(*(const u32x2*)(io + idx));
;                         else if (MODE == 1) v = up4(*(const u32x2*)(io + idx)) + up4(*(const u32x2*)(g2 + idx)) * v;
;                         else ss += (v[0] * v[0] + v[1] * v[1]) + (v[2] * v[2] + v[3] * v[3]);
;                         if (!DRYE || v[0] == 123.456f) *(u32x2*)(io + idx) = pk4(v); }
;                 if (MODE == 2 && !DRYE) { ss += __shfl_xor(ss, 16); ss += __shfl_xor(ss, 32); if (fq == 0) atomicAdd(rowss + row, ss); } }
	s_add_i32 s3, s3, s45
	v_lshl_add_u64 v[216:217], v[216:217], 0, s[14:15]
	s_mov_b32 m0, s3
	ds_read_b128 v[184:187], v149 offset:49152
	ds_read_b128 v[188:191], v149 offset:50176
	ds_read_b128 v[192:195], v149 offset:51200
	ds_read_b128 v[196:199], v149 offset:52224
	ds_read_b128 v[200:203], v149 offset:53248
	ds_read_b128 v[204:207], v149 offset:54272
	ds_read_b128 v[208:211], v149 offset:55296
	ds_read_b128 v[212:215], v149 offset:56320
	global_load_lds_dwordx4 v[216:217], off
	s_add_i32 m0, s3, 0x2000
	s_add_u32 s30, s30, 0x40080
	v_lshl_add_u64 v[216:217], v[218:219], 0, s[14:15]
	s_addc_u32 s31, s31, 0
	s_add_i32 s3, s33, s45
	global_load_lds_dwordx4 v[216:217], off
	v_lshl_add_u64 v[216:217], s[30:31], 0, v[128:129]
	s_mov_b32 m0, s3
	s_nop 0
	global_load_lds_dwordx4 v[216:217], off
	v_lshl_add_u64 v[216:217], s[30:31], 0, v[130:131]
	s_add_i32 m0, s3, 0x2000
	s_nop 0
	global_load_lds_dwordx4 v[216:217], off
	v_lshl_add_u64 v[216:217], v[220:221], 0, s[14:15]
	s_mov_b32 m0, s62
	s_nop 0
	global_load_lds_dwordx4 v[216:217], off
	v_lshl_add_u64 v[216:217], v[222:223], 0, s[14:15]
	s_mov_b32 m0, s63
	s_nop 0
	global_load_lds_dwordx4 v[216:217], off
	s_waitcnt vmcnt(8)
	s_waitcnt lgkmcnt(0)
	s_barrier
	s_setprio 1
	s_waitcnt lgkmcnt(0)
	v_mfma_f32_16x16x32_bf16 v[60:63], v[140:143], v[184:187], v[60:63]
	v_mfma_f32_16x16x32_bf16 v[56:59], v[156:159], v[184:187], v[56:59]
	v_mfma_f32_16x16x32_bf16 v[48:51], v[140:143], v[192:195], v[48:51]
	v_mfma_f32_16x16x32_bf16 v[40:43], v[156:159], v[192:195], v[40:43]
	v_mfma_f32_16x16x32_bf16 v[32:35], v[140:143], v[200:203], v[32:35]
	v_mfma_f32_16x16x32_bf16 v[24:27], v[156:159], v[200:203], v[24:27]
	v_mfma_f32_16x16x32_bf16 v[16:19], v[140:143], v[208:211], v[16:19]
	v_mfma_f32_16x16x32_bf16 v[8:11], v[156:159], v[208:211], v[8:11]
	v_mfma_f32_16x16x32_bf16 v[60:63], v[152:155], v[188:191], v[60:63]
	v_mfma_f32_16x16x32_bf16 v[56:59], v[160:163], v[188:191], v[56:59]
	v_mfma_f32_16x16x32_bf16 v[48:51], v[152:155], v[196:199], v[48:51]
	v_mfma_f32_16x16x32_bf16 v[40:43], v[160:163], v[196:199], v[40:43]
	v_mfma_f32_16x16x32_bf16 v[32:35], v[152:155], v[204:207], v[32:35]
	v_mfma_f32_16x16x32_bf16 v[24:27], v[160:163], v[204:207], v[24:27]
	v_mfma_f32_16x16x32_bf16 v[16:19], v[152:155], v[212:215], v[16:19]
	v_mfma_f32_16x16x32_bf16 v[8:11], v[160:163], v[212:215], v[8:11]
	s_setprio 0
	s_setprio 1
	v_mfma_f32_16x16x32_bf16 v[52:55], v[164:167], v[184:187], v[52:55]
	v_mfma_f32_16x16x32_bf16 v[44:47], v[172:175], v[184:187], v[44:47]
	v_mfma_f32_16x16x32_bf16 v[36:39], v[164:167], v[192:195], v[36:39]
	v_mfma_f32_16x16x32_bf16 v[28:31], v[172:175], v[192:195], v[28:31]
	v_mfma_f32_16x16x32_bf16 v[20:23], v[164:167], v[200:203], v[20:23]
	s_add_i32 s72, s72, 2
	s_add_u32 s28, s28, 0x100
	s_addc_u32 s29, s29, 0
	s_add_u32 s70, s70, 0x100
	s_addc_u32 s71, s71, 0
	s_cmp_gt_u32 s72, 13
	v_mfma_f32_16x16x32_bf16 v[12:15], v[172:175], v[200:203], v[12:15]
	v_mfma_f32_16x16x32_bf16 v[4:7], v[164:167], v[208:211], v[4:7]
	v_mfma_f32_16x16x32_bf16 v[0:3], v[172:175], v[208:211], v[0:3]
	v_mfma_f32_16x16x32_bf16 v[52:55], v[168:171], v[188:191], v[52:55]
	v_mfma_f32_16x16x32_bf16 v[44:47], v[180:183], v[188:191], v[44:47]
	v_mfma_f32_16x16x32_bf16 v[36:39], v[168:171], v[196:199], v[36:39]
	v_mfma_f32_16x16x32_bf16 v[28:31], v[180:183], v[196:199], v[28:31]
	v_mfma_f32_16x16x32_bf16 v[20:23], v[168:171], v[204:207], v[20:23]
	v_mfma_f32_16x16x32_bf16 v[12:15], v[180:183], v[204:207], v[12:15]
	v_mfma_f32_16x16x32_bf16 v[4:7], v[168:171], v[212:215], v[4:7]
	v_mfma_f32_16x16x32_bf16 v[0:3], v[180:183], v[212:215], v[0:3]
	s_setprio 0
	s_barrier
	s_cbranch_scc0 .LBB0_914
	v_and_b32_e32 v151, 64, v150
	v_xor_b32_e32 v143, 16, v150
	v_add_u32_e32 v151, 64, v151
	v_cmp_lt_i32_e32 vcc, v143, v151
	v_lshl_add_u32 v142, s24, 8, v144
	v_lshl_or_b32 v140, s26, 8, v146
	v_cndmask_b32_e32 v143, v150, v143, vcc
	v_lshlrev_b32_e32 v152, 2, v143
	v_xor_b32_e32 v143, 32, v150
	v_cmp_lt_i32_e32 vcc, v143, v151
	v_mul_f32_e32 v153, v125, v125
	v_mul_f32_e32 v156, v127, v127
	v_cndmask_b32_e32 v143, v150, v143, vcc
	v_lshlrev_b32_e32 v151, 2, v143
	v_ashrrev_i32_e32 v143, 31, v142
	v_lshlrev_b64 v[154:155], 11, v[142:143]
	v_ashrrev_i32_e32 v141, 31, v140
	v_fmac_f32_e32 v153, v124, v124
	v_fmac_f32_e32 v156, v126, v126
	v_cvt_pk_bf16_f32 v124, v124, v125
	v_cvt_pk_bf16_f32 v125, v126, v127
	v_lshl_add_u64 v[126:127], s[8:9], 0, v[154:155]
	v_lshl_add_u64 v[126:127], v[140:141], 1, v[126:127]
	global_store_dwordx2 v[126:127], v[124:125], off
	v_mul_f32_e32 v124, v121, v121
	v_mul_f32_e32 v125, v123, v123
	v_fmac_f32_e32 v124, v120, v120
	v_fmac_f32_e32 v125, v122, v122
	v_add_f32_e32 v124, v124, v125
	v_cvt_pk_bf16_f32 v120, v120, v121
	v_mul_f32_e32 v121, v117, v117
	v_mul_f32_e32 v125, v119, v119
	v_add_f32_e32 v153, v153, v156
	v_fmac_f32_e32 v121, v116, v116
	v_fmac_f32_e32 v125, v118, v118
	v_add_f32_e32 v124, v153, v124
	v_add_f32_e32 v121, v121, v125
	v_add_f32_e32 v121, v124, v121
	v_mul_f32_e32 v124, v109, v109
	v_mul_f32_e32 v125, v111, v111
	v_fmac_f32_e32 v124, v108, v108
	v_fmac_f32_e32 v125, v110, v110
	v_add_f32_e32 v124, v124, v125
	v_add_f32_e32 v124, v121, v124
	ds_bpermute_b32 v125, v152, v124
	v_cvt_pk_bf16_f32 v121, v122, v123
	global_store_dwordx2 v[126:127], v[120:121], off offset:32
	v_cvt_pk_bf16_f32 v120, v116, v117
	v_cvt_pk_bf16_f32 v121, v118, v119
	s_waitcnt lgkmcnt(0)
	v_add_f32_e32 v116, v124, v125
	ds_bpermute_b32 v117, v151, v116
	v_cvt_pk_bf16_f32 v108, v108, v109
	v_cvt_pk_bf16_f32 v109, v110, v111
	global_store_dwordx2 v[126:127], v[120:121], off offset:256
	global_store_dwordx2 v[126:127], v[108:109], off offset:288
	s_and_saveexec_b64 s[24:25], s[0:1]
	s_cbranch_execz .LBB0_917
	v_lshl_add_u64 v[108:109], v[142:143], 2, s[10:11]
	s_waitcnt lgkmcnt(0)
	v_add_f32_e32 v110, v116, v117
	global_atomic_add_f32 v[108:109], v110, off

; #define PG8_STAGE(bufoff, gbase, voff) do { _Pragma("unroll") for (int _i = 0; _i < 2; ++_i) \
;         __builtin_amdgcn_global_load_lds((const unsigned*)((const char*)(gbase) + (voff)[_i]), (PG8_LAS unsigned*)(lds + (bufoff) + ldsw + _i * 8192), 16, 0, 0); } while (0)
; #define PG8_LDA(dst, b, h) do { _Pragma("unroll") for (int m = 0; m < 4; ++m) _Pragma("unroll") for (int k = 0; k < 2; ++k) dst[m][k] = *(const PG8_LAS bf16x8*)(lds + PG8_SA(b, h) + aoff + m * 2048 + k * 1024); } while (0)
; #define PG8_LDB(dst, b, h) do { _Pragma("unroll") for (int n = 0; n < 2; ++n) _Pragma("unroll") for (int k = 0; k < 2; ++k) dst[n][k] = *(const PG8_LAS bf16x8*)(lds + PG8_SB(b, h) + boff + n * 2048 + k * 1024); } while (0)
; #define PG8_WAIT_V(n) asm volatile("s_waitcnt vmcnt(" #n ")" ::: "memory")
; #define PG8_WAIT_L(n) asm volatile("s_waitcnt lgkmcnt(" #n ")" ::: "memory")
; #define PG8_BAR __builtin_amdgcn_s_barrier()
; #define PG8_SCHED __builtin_amdgcn_sched_barrier(0)
; template <class Epi, class Sched, bool ALIGN_EPI = false, bool SP2 = false>
; __device__ __forceinline__ void gemm_phase(PG8_LAS unsigned char* lds, const Gemm g, const Sched& S, const Epi& E) {
;     ...
;         const bool has_next = S.next(ui + 1, nxt);
;         const char* nA = has_next ? (const char*)g.A + (size_t)nxt.pm * tstep : cA; const char* nB = has_next ? (const char*)g.Bt + (size_t)nxt.pn * tstep : cB;
;         for (int t = 0; t < nt; t += 2) {
;             const bool last = (t == nt - 2);
;             const char* a1 = cA + (size_t)(t + 1) * kstep;
;             const char* a2 = last ? nA : cA + (size_t)(t + 2) * kstep; const char* b2 = last ? nB : cB + (size_t)(t + 2) * kstep;
;             const char* a3 = a2 + kstep; const char* b3 = b2 + kstep;
;             if (last && has_next) S.a_ready(nxt);
;             if constexpr (SP2) {
;             PG8_LDB(B0, 0, 0); PG8_LDB(B1, 0, 1); PG8_SCHED; PG8_LDA(At, 0, 0); PG8_STAGE(PG8_SA(1, 1), a1 + hstep, voffA);
;             PG8_WAIT_V(8); PG8_WAIT_L(0); PG8_BAR; PG8_MMA(0, 0, At, B0); PG8_MMA(0, 1, At, B1); PG8_BAR; PG8_SCHED;
;             PG8_LDA(At, 0, 1); PG8_STAGE(PG8_SB(0, 0), b2, voffB); PG8_STAGE(PG8_SB(0, 1), b2 + hstep, voffB); PG8_STAGE(PG8_SA(0, 0), a2, voffA);
;             PG8_WAIT_V(8); PG8_WAIT_L(0); PG8_BAR; PG8_MMA(1, 0, At, B0); PG8_MMA(1, 1, At, B1); PG8_BAR; PG8_SCHED;
.LBB0_1059:
	ds_read_b128 v[136:139], v143
	ds_read_b128 v[148:151], v143 offset:1024
	ds_read_b128 v[152:155], v143 offset:2048
	ds_read_b128 v[156:159], v143 offset:3072
	ds_read_b128 v[160:163], v144
	ds_read_b128 v[164:167], v144 offset:1024
	ds_read_b128 v[168:171], v144 offset:2048
	ds_read_b128 v[172:175], v144 offset:3072
	s_add_u32 s3, s28, 0xfffc0080
	s_addc_u32 s30, s29, -1
	s_cmp_eq_u32 s71, 12
	s_cselect_b32 s35, s21, s30
	s_cselect_b32 s34, s67, s3
	s_cselect_b32 s31, s19, s70
	s_cselect_b32 s30, s68, s69
	v_lshl_add_u64 v[212:213], s[28:29], 0, v[132:133]
	s_add_i32 m0, s47, 0xc000
	ds_read_b128 v[180:183], v145
	ds_read_b128 v[184:187], v145 offset:1024
	ds_read_b128 v[188:191], v145 offset:2048
	ds_read_b128 v[192:195], v145 offset:3072
	ds_read_b128 v[196:199], v145 offset:4096
	ds_read_b128 v[200:203], v145 offset:5120
	ds_read_b128 v[204:207], v145 offset:6144
	ds_read_b128 v[208:211], v145 offset:7168
	global_load_lds_dwordx4 v[212:213], off
	v_lshl_add_u64 v[212:213], s[28:29], 0, v[134:135]
	s_add_i32 m0, s47, 0xe000
	s_nop 0
	global_load_lds_dwordx4 v[212:213], off
	s_waitcnt vmcnt(8)
	s_waitcnt lgkmcnt(0)
	s_barrier
	s_setprio 1
	s_waitcnt lgkmcnt(0)
	v_mfma_f32_16x16x32_bf16 v[124:127], v[136:139], v[180:183], v[124:127]
	v_mfma_f32_16x16x32_bf16 v[120:123], v[152:155], v[180:183], v[120:123]
	v_mfma_f32_16x16x32_bf16 v[112:115], v[136:139], v[188:191], v[112:115]
	v_mfma_f32_16x16x32_bf16 v[104:107], v[152:155], v[188:191], v[104:107]
	v_mfma_f32_16x16x32_bf16 v[96:99], v[136:139], v[196:199], v[96:99]
	v_mfma_f32_16x16x32_bf16 v[88:91], v[152:155], v[196:199], v[88:91]
	v_mfma_f32_16x16x32_bf16 v[80:83], v[136:139], v[204:207], v[80:83]
	v_mfma_f32_16x16x32_bf16 v[72:75], v[152:155], v[204:207], v[72:75]
	v_mfma_f32_16x16x32_bf16 v[124:127], v[148:151], v[184:187], v[124:127]
	v_mfma_f32_16x16x32_bf16 v[120:123], v[156:159], v[184:187], v[120:123]
	v_mfma_f32_16x16x32_bf16 v[112:115], v[148:151], v[192:195], v[112:115]
	v_mfma_f32_16x16x32_bf16 v[104:107], v[156:159], v[192:195], v[104:107]
	v_mfma_f32_16x16x32_bf16 v[96:99], v[148:151], v[200:203], v[96:99]
	v_mfma_f32_16x16x32_bf16 v[88:91], v[156:159], v[200:203], v[88:91]
	v_mfma_f32_16x16x32_bf16 v[80:83], v[148:151], v[208:211], v[80:83]
	v_mfma_f32_16x16x32_bf16 v[72:75], v[156:159], v[208:211], v[72:75]
	s_setprio 0
	s_setprio 1
	v_mfma_f32_16x16x32_bf16 v[116:119], v[160:163], v[180:183], v[116:119]
	v_mfma_f32_16x16x32_bf16 v[108:111], v[168:171], v[180:183], v[108:111]
	v_mfma_f32_16x16x32_bf16 v[100:103], v[160:163], v[188:191], v[100:103]
	v_mfma_f32_16x16x32_bf16 v[92:95], v[168:171], v[188:191], v[92:95]
	v_mfma_f32_16x16x32_bf16 v[84:87], v[160:163], v[196:199], v[84:87]
	v_mfma_f32_16x16x32_bf16 v[76:79], v[168:171], v[196:199], v[76:79]
	v_mfma_f32_16x16x32_bf16 v[68:71], v[160:163], v[204:207], v[68:71]
	v_mfma_f32_16x16x32_bf16 v[64:67], v[168:171], v[204:207], v[64:67]
	v_mfma_f32_16x16x32_bf16 v[116:119], v[164:167], v[184:187], v[116:119]
	v_mfma_f32_16x16x32_bf16 v[108:111], v[172:175], v[184:187], v[108:111]
	v_mfma_f32_16x16x32_bf16 v[100:103], v[164:167], v[192:195], v[100:103]
	v_mfma_f32_16x16x32_bf16 v[92:95], v[172:175], v[192:195], v[92:95]
	v_mfma_f32_16x16x32_bf16 v[84:87], v[164:167], v[200:203], v[84:87]
	v_mfma_f32_16x16x32_bf16 v[76:79], v[172:175], v[200:203], v[76:79]
	v_mfma_f32_16x16x32_bf16 v[68:71], v[164:167], v[208:211], v[68:71]
	v_mfma_f32_16x16x32_bf16 v[64:67], v[172:175], v[208:211], v[64:67]
	s_setprio 0
	s_barrier
	s_add_i32 s3, s65, s46
	v_lshl_add_u64 v[212:213], s[30:31], 0, v[128:129]
	s_mov_b32 m0, s3
	ds_read_b128 v[180:183], v145 offset:16384
	ds_read_b128 v[184:187], v145 offset:17408
	ds_read_b128 v[188:191], v145 offset:18432
	ds_read_b128 v[192:195], v145 offset:19456
	ds_read_b128 v[196:199], v145 offset:20480
	ds_read_b128 v[200:203], v145 offset:21504
	ds_read_b128 v[204:207], v145 offset:22528
	ds_read_b128 v[208:211], v145 offset:23552
	global_load_lds_dwordx4 v[212:213], off
	s_add_i32 m0, s3, 0x2000
	s_add_u32 s36, s30, 0x40000
	v_lshl_add_u64 v[214:215], s[30:31], 0, v[130:131]
	s_addc_u32 s37, s31, 0
	s_add_i32 s3, s66, s46
	global_load_lds_dwordx4 v[214:215], off
	v_lshl_add_u64 v[216:217], s[36:37], 0, v[128:129]
	s_mov_b32 m0, s3
	v_lshl_add_u64 v[218:219], s[34:35], 0, v[130:131]
	global_load_lds_dwordx4 v[216:217], off
	v_lshl_add_u64 v[216:217], s[36:37], 0, v[130:131]
	s_add_i32 m0, s3, 0x2000
	s_nop 0
	global_load_lds_dwordx4 v[216:217], off
	v_lshl_add_u64 v[216:217], s[34:35], 0, v[128:129]
	s_mov_b32 m0, s47
	s_nop 0
	global_load_lds_dwordx4 v[216:217], off
	s_mov_b32 m0, s60
	s_nop 0
	global_load_lds_dwordx4 v[218:219], off
	s_waitcnt vmcnt(8)
	s_waitcnt lgkmcnt(0)
	s_barrier
; #define PG8_STAGE(bufoff, gbase, voff) do { _Pragma("unroll") for (int _i = 0; _i < 2; ++_i) \
;         __builtin_amdgcn_global_load_lds((const unsigned*)((const char*)(gbase) + (voff)[_i]), (PG8_LAS unsigned*)(lds + (bufoff) + ldsw + _i * 8192), 16, 0, 0); } while (0)
; #define PG8_LDA(dst, b, h) do { _Pragma("unroll") for (int m = 0; m < 4; ++m) _Pragma("unroll") for (int k = 0; k < 2; ++k) dst[m][k] = *(const PG8_LAS bf16x8*)(lds + PG8_SA(b, h) + aoff + m * 2048 + k * 1024); } while (0)
; #define PG8_LDB(dst, b, h) do { _Pragma("unroll") for (int n = 0; n < 2; ++n) _Pragma("unroll") for (int k = 0; k < 2; ++k) dst[n][k] = *(const PG8_LAS bf16x8*)(lds + PG8_SB(b, h) + boff + n * 2048 + k * 1024); } while (0)
; #define PG8_MMA(ai, bj, At, Bt) do { __builtin_amdgcn_s_setprio(1); _Pragma("unroll") for (int m = 0; m < 4; ++m) _Pragma("unroll") for (int n = 0; n < 2; ++n) _Pragma("unroll") for (int k = 0; k < 2; ++k) \
;         acc[ai][bj][m][n] = __builtin_amdgcn_mfma_f32_16x16x32_bf16(Bt[n][k], At[m][k], acc[ai][bj][m][n], 0, 0, 0); __builtin_amdgcn_s_setprio(0); } while (0)
; #define PG8_WAIT_V(n) asm volatile("s_waitcnt vmcnt(" #n ")" ::: "memory")
; #define PG8_WAIT_L(n) asm volatile("s_waitcnt lgkmcnt(" #n ")" ::: "memory")
; #define PG8_BAR __builtin_amdgcn_s_barrier()
; #define PG8_SCHED __builtin_amdgcn_sched_barrier(0)
; template <class Epi, class Sched, bool ALIGN_EPI = false, bool SP2 = false>
; __device__ __forceinline__ void gemm_phase(PG8_LAS unsigned char* lds, const Gemm g, const Sched& S, const Epi& E) {
;     ...
;             PG8_WAIT_V(8); PG8_WAIT_L(0); PG8_BAR; PG8_MMA(1, 0, At, B0); PG8_MMA(1, 1, At, B1); PG8_BAR; PG8_SCHED;
;             PG8_LDB(B0, 1, 0); PG8_LDB(B1, 1, 1); PG8_SCHED; PG8_LDA(At, 1, 0); PG8_STAGE(PG8_SA(0, 1), a2 + hstep, voffA);
;             PG8_WAIT_V(8); PG8_WAIT_L(0); PG8_BAR; PG8_MMA(0, 0, At, B0); PG8_MMA(0, 1, At, B1); PG8_BAR; PG8_SCHED;
	s_setprio 1
	s_waitcnt lgkmcnt(0)
	v_mfma_f32_16x16x32_bf16 v[60:63], v[136:139], v[180:183], v[60:63]
	v_mfma_f32_16x16x32_bf16 v[56:59], v[152:155], v[180:183], v[56:59]
	v_mfma_f32_16x16x32_bf16 v[48:51], v[136:139], v[188:191], v[48:51]
	v_mfma_f32_16x16x32_bf16 v[40:43], v[152:155], v[188:191], v[40:43]
	v_mfma_f32_16x16x32_bf16 v[32:35], v[136:139], v[196:199], v[32:35]
	v_mfma_f32_16x16x32_bf16 v[24:27], v[152:155], v[196:199], v[24:27]
	v_mfma_f32_16x16x32_bf16 v[16:19], v[136:139], v[204:207], v[16:19]
	v_mfma_f32_16x16x32_bf16 v[8:11], v[152:155], v[204:207], v[8:11]
	v_mfma_f32_16x16x32_bf16 v[60:63], v[148:151], v[184:187], v[60:63]
	v_mfma_f32_16x16x32_bf16 v[56:59], v[156:159], v[184:187], v[56:59]
	v_mfma_f32_16x16x32_bf16 v[48:51], v[148:151], v[192:195], v[48:51]
	v_mfma_f32_16x16x32_bf16 v[40:43], v[156:159], v[192:195], v[40:43]
	v_mfma_f32_16x16x32_bf16 v[32:35], v[148:151], v[200:203], v[32:35]
	v_mfma_f32_16x16x32_bf16 v[24:27], v[156:159], v[200:203], v[24:27]
	v_mfma_f32_16x16x32_bf16 v[16:19], v[148:151], v[208:211], v[16:19]
	v_mfma_f32_16x16x32_bf16 v[8:11], v[156:159], v[208:211], v[8:11]
	s_setprio 0
	s_setprio 1
	v_mfma_f32_16x16x32_bf16 v[52:55], v[160:163], v[180:183], v[52:55]
	v_mfma_f32_16x16x32_bf16 v[44:47], v[168:171], v[180:183], v[44:47]
	v_mfma_f32_16x16x32_bf16 v[36:39], v[160:163], v[188:191], v[36:39]
	v_mfma_f32_16x16x32_bf16 v[28:31], v[168:171], v[188:191], v[28:31]
	v_mfma_f32_16x16x32_bf16 v[20:23], v[160:163], v[196:199], v[20:23]
	v_mfma_f32_16x16x32_bf16 v[12:15], v[168:171], v[196:199], v[12:15]
	v_mfma_f32_16x16x32_bf16 v[4:7], v[160:163], v[204:207], v[4:7]
	v_mfma_f32_16x16x32_bf16 v[0:3], v[168:171], v[204:207], v[0:3]
	v_mfma_f32_16x16x32_bf16 v[52:55], v[164:167], v[184:187], v[52:55]
	v_mfma_f32_16x16x32_bf16 v[44:47], v[172:175], v[184:187], v[44:47]
	v_mfma_f32_16x16x32_bf16 v[36:39], v[164:167], v[192:195], v[36:39]
	v_mfma_f32_16x16x32_bf16 v[28:31], v[172:175], v[192:195], v[28:31]
	v_mfma_f32_16x16x32_bf16 v[20:23], v[164:167], v[200:203], v[20:23]
	v_mfma_f32_16x16x32_bf16 v[12:15], v[172:175], v[200:203], v[12:15]
	v_mfma_f32_16x16x32_bf16 v[4:7], v[164:167], v[208:211], v[4:7]
	v_mfma_f32_16x16x32_bf16 v[0:3], v[172:175], v[208:211], v[0:3]
	s_setprio 0
	s_barrier
	s_add_i32 s3, 0, 0x18000
	v_add_u32_e32 v147, s3, v141
	s_add_i32 s33, 0, 0x1c000
	ds_read_b128 v[136:139], v147
	ds_read_b128 v[148:151], v147 offset:1024
	ds_read_b128 v[152:155], v147 offset:2048
	ds_read_b128 v[156:159], v147 offset:3072
	v_add_u32_e32 v147, s33, v141
	ds_read_b128 v[160:163], v147
	ds_read_b128 v[164:167], v147 offset:1024
	ds_read_b128 v[168:171], v147 offset:2048
	ds_read_b128 v[172:175], v147 offset:3072
	s_add_u32 s34, s34, 0x40000
	s_addc_u32 s35, s35, 0
	s_mov_b32 m0, s61
	v_lshl_add_u64 v[220:221], s[34:35], 0, v[128:129]
	ds_read_b128 v[180:183], v145 offset:32768
	ds_read_b128 v[184:187], v145 offset:33792
	ds_read_b128 v[188:191], v145 offset:34816
	ds_read_b128 v[192:195], v145 offset:35840
	ds_read_b128 v[196:199], v145 offset:36864
	ds_read_b128 v[200:203], v145 offset:37888
	ds_read_b128 v[204:207], v145 offset:38912
	ds_read_b128 v[208:211], v145 offset:39936
	global_load_lds_dwordx4 v[220:221], off
	v_lshl_add_u64 v[220:221], s[34:35], 0, v[130:131]
	s_mov_b32 m0, s62
	s_nop 0
	global_load_lds_dwordx4 v[220:221], off
	s_waitcnt vmcnt(8)
	s_waitcnt lgkmcnt(0)
	s_barrier
	s_setprio 1
	s_waitcnt lgkmcnt(0)
	v_mfma_f32_16x16x32_bf16 v[124:127], v[136:139], v[180:183], v[124:127]
	v_mfma_f32_16x16x32_bf16 v[120:123], v[152:155], v[180:183], v[120:123]
	v_mfma_f32_16x16x32_bf16 v[112:115], v[136:139], v[188:191], v[112:115]
	v_mfma_f32_16x16x32_bf16 v[104:107], v[152:155], v[188:191], v[104:107]
	v_mfma_f32_16x16x32_bf16 v[96:99], v[136:139], v[196:199], v[96:99]
	v_mfma_f32_16x16x32_bf16 v[88:91], v[152:155], v[196:199], v[88:91]
	v_mfma_f32_16x16x32_bf16 v[80:83], v[136:139], v[204:207], v[80:83]
	v_mfma_f32_16x16x32_bf16 v[72:75], v[152:155], v[204:207], v[72:75]
	v_mfma_f32_16x16x32_bf16 v[124:127], v[148:151], v[184:187], v[124:127]
	v_mfma_f32_16x16x32_bf16 v[120:123], v[156:159], v[184:187], v[120:123]
	v_mfma_f32_16x16x32_bf16 v[112:115], v[148:151], v[192:195], v[112:115]
	v_mfma_f32_16x16x32_bf16 v[104:107], v[156:159], v[192:195], v[104:107]
	v_mfma_f32_16x16x32_bf16 v[96:99], v[148:151], v[200:203], v[96:99]
	v_mfma_f32_16x16x32_bf16 v[88:91], v[156:159], v[200:203], v[88:91]
	v_mfma_f32_16x16x32_bf16 v[80:83], v[148:151], v[208:211], v[80:83]
	v_mfma_f32_16x16x32_bf16 v[72:75], v[156:159], v[208:211], v[72:75]
	s_setprio 0
	s_setprio 1
	v_mfma_f32_16x16x32_bf16 v[116:119], v[160:163], v[180:183], v[116:119]
	v_mfma_f32_16x16x32_bf16 v[108:111], v[168:171], v[180:183], v[108:111]
	v_mfma_f32_16x16x32_bf16 v[100:103], v[160:163], v[188:191], v[100:103]
	v_mfma_f32_16x16x32_bf16 v[92:95], v[168:171], v[188:191], v[92:95]
	v_mfma_f32_16x16x32_bf16 v[84:87], v[160:163], v[196:199], v[84:87]
	v_mfma_f32_16x16x32_bf16 v[76:79], v[168:171], v[196:199], v[76:79]
	v_mfma_f32_16x16x32_bf16 v[68:71], v[160:163], v[204:207], v[68:71]
	v_mfma_f32_16x16x32_bf16 v[64:67], v[168:171], v[204:207], v[64:67]
	v_mfma_f32_16x16x32_bf16 v[116:119], v[164:167], v[184:187], v[116:119]
	v_mfma_f32_16x16x32_bf16 v[108:111], v[172:175], v[184:187], v[108:111]
	v_mfma_f32_16x16x32_bf16 v[100:103], v[164:167], v[192:195], v[100:103]
	v_mfma_f32_16x16x32_bf16 v[92:95], v[172:175], v[192:195], v[92:95]
	v_mfma_f32_16x16x32_bf16 v[84:87], v[164:167], v[200:203], v[84:87]
	v_mfma_f32_16x16x32_bf16 v[76:79], v[172:175], v[200:203], v[76:79]
	v_mfma_f32_16x16x32_bf16 v[68:71], v[164:167], v[208:211], v[68:71]
	v_mfma_f32_16x16x32_bf16 v[64:67], v[172:175], v[208:211], v[64:67]
	s_setprio 0
	s_barrier
; #define PG8_STAGE(bufoff, gbase, voff) do { _Pragma("unroll") for (int _i = 0; _i < 2; ++_i) \
;         __builtin_amdgcn_global_load_lds((const unsigned*)((const char*)(gbase) + (voff)[_i]), (PG8_LAS unsigned*)(lds + (bufoff) + ldsw + _i * 8192), 16, 0, 0); } while (0)
; #define PG8_LDA(dst, b, h) do { _Pragma("unroll") for (int m = 0; m < 4; ++m) _Pragma("unroll") for (int k = 0; k < 2; ++k) dst[m][k] = *(const PG8_LAS bf16x8*)(lds + PG8_SA(b, h) + aoff + m * 2048 + k * 1024); } while (0)
; #define PG8_MMA(ai, bj, At, Bt) do { __builtin_amdgcn_s_setprio(1); _Pragma("unroll") for (int m = 0; m < 4; ++m) _Pragma("unroll") for (int n = 0; n < 2; ++n) _Pragma("unroll") for (int k = 0; k < 2; ++k) \
;         acc[ai][bj][m][n] = __builtin_amdgcn_mfma_f32_16x16x32_bf16(Bt[n][k], At[m][k], acc[ai][bj][m][n], 0, 0, 0); __builtin_amdgcn_s_setprio(0); } while (0)
; #define PG8_WAIT_V(n) asm volatile("s_waitcnt vmcnt(" #n ")" ::: "memory")
; template <class Epi, class Sched, bool ALIGN_EPI = false, bool SP2 = false>
; __device__ __forceinline__ void gemm_phase(PG8_LAS unsigned char* lds, const Gemm g, const Sched& S, const Epi& E) {
;     ...
;             PG8_LDA(At, 1, 1); PG8_STAGE(PG8_SB(1, 0), b3, voffB); PG8_STAGE(PG8_SB(1, 1), b3 + hstep, voffB); PG8_STAGE(PG8_SA(1, 0), a3, voffA);
;             PG8_WAIT_V(8); PG8_WAIT_L(0); PG8_BAR; PG8_MMA(1, 0, At, B0); PG8_MMA(1, 1, At, B1); PG8_BAR; PG8_SCHED;
;     __device__ __forceinline__ void operator()(const AccT& acc, const pg8::Unit& u, int wr, int wc, int fr, int fq) const {
;     ...
;             for (int m = 0; m < 4; ++m) { const int row = row0 + ai * 128 + m * 16; float ss = 0.f;
; #pragma unroll
;                 for (int bj = 0; bj < 2; ++bj)
; #pragma unroll
;                     for (int n = 0; n < 2; ++n) { f32x4 v = acc[ai][bj][m][n]; const size_t idx = (size_t)row * 1024 + col0 + bj * 128 + n * 16;
;                         if (MODE == 0) v = v * up4(*(const u32x2*)(io + idx));
;                         else if (MODE == 1) v = up4(*(const u32x2*)(io + idx)) + up4(*(const u32x2*)(g2 + idx)) * v;
;                         else ss += (v[0] * v[0] + v[1] * v[1]) + (v[2] * v[2] + v[3] * v[3]);
;                         if (!DRYE || v[0] == 123.456f) *(u32x2*)(io + idx) = pk4(v); }
;                 if (MODE == 2 && !DRYE) { ss += __shfl_xor(ss, 16); ss += __shfl_xor(ss, 32); if (fq == 0) atomicAdd(rowss + row, ss); } }
	s_add_i32 s3, s3, s46
	v_lshl_add_u64 v[212:213], v[212:213], 0, s[14:15]
	s_mov_b32 m0, s3
	ds_read_b128 v[180:183], v145 offset:49152
	ds_read_b128 v[184:187], v145 offset:50176
	ds_read_b128 v[188:191], v145 offset:51200
	ds_read_b128 v[192:195], v145 offset:52224
	ds_read_b128 v[196:199], v145 offset:53248
	ds_read_b128 v[200:203], v145 offset:54272
	ds_read_b128 v[204:207], v145 offset:55296
	ds_read_b128 v[208:211], v145 offset:56320
	global_load_lds_dwordx4 v[212:213], off
	s_add_i32 m0, s3, 0x2000
	s_add_u32 s30, s30, 0x40080
	v_lshl_add_u64 v[212:213], v[214:215], 0, s[14:15]
	s_addc_u32 s31, s31, 0
	s_add_i32 s3, s33, s46
	global_load_lds_dwordx4 v[212:213], off
	v_lshl_add_u64 v[212:213], s[30:31], 0, v[128:129]
	s_mov_b32 m0, s3
	s_nop 0
	global_load_lds_dwordx4 v[212:213], off
	v_lshl_add_u64 v[212:213], s[30:31], 0, v[130:131]
	s_add_i32 m0, s3, 0x2000
	s_nop 0
	global_load_lds_dwordx4 v[212:213], off
	v_lshl_add_u64 v[212:213], v[216:217], 0, s[14:15]
	s_mov_b32 m0, s63
	s_nop 0
	global_load_lds_dwordx4 v[212:213], off
	v_lshl_add_u64 v[212:213], v[218:219], 0, s[14:15]
	s_mov_b32 m0, s64
	s_nop 0
	global_load_lds_dwordx4 v[212:213], off
	s_waitcnt vmcnt(8)
	s_waitcnt lgkmcnt(0)
	s_barrier
	s_setprio 1
	s_waitcnt lgkmcnt(0)
	v_mfma_f32_16x16x32_bf16 v[60:63], v[136:139], v[180:183], v[60:63]
	v_mfma_f32_16x16x32_bf16 v[56:59], v[152:155], v[180:183], v[56:59]
	v_mfma_f32_16x16x32_bf16 v[48:51], v[136:139], v[188:191], v[48:51]
	v_mfma_f32_16x16x32_bf16 v[40:43], v[152:155], v[188:191], v[40:43]
	v_mfma_f32_16x16x32_bf16 v[32:35], v[136:139], v[196:199], v[32:35]
	v_mfma_f32_16x16x32_bf16 v[24:27], v[152:155], v[196:199], v[24:27]
	v_mfma_f32_16x16x32_bf16 v[16:19], v[136:139], v[204:207], v[16:19]
	v_mfma_f32_16x16x32_bf16 v[8:11], v[152:155], v[204:207], v[8:11]
	v_mfma_f32_16x16x32_bf16 v[60:63], v[148:151], v[184:187], v[60:63]
	v_mfma_f32_16x16x32_bf16 v[56:59], v[156:159], v[184:187], v[56:59]
	v_mfma_f32_16x16x32_bf16 v[48:51], v[148:151], v[192:195], v[48:51]
	v_mfma_f32_16x16x32_bf16 v[40:43], v[156:159], v[192:195], v[40:43]
	v_mfma_f32_16x16x32_bf16 v[32:35], v[148:151], v[200:203], v[32:35]
	v_mfma_f32_16x16x32_bf16 v[24:27], v[156:159], v[200:203], v[24:27]
	v_mfma_f32_16x16x32_bf16 v[16:19], v[148:151], v[208:211], v[16:19]
	v_mfma_f32_16x16x32_bf16 v[8:11], v[156:159], v[208:211], v[8:11]
	s_setprio 0
	s_setprio 1
	v_mfma_f32_16x16x32_bf16 v[52:55], v[160:163], v[180:183], v[52:55]
	v_mfma_f32_16x16x32_bf16 v[44:47], v[168:171], v[180:183], v[44:47]
	v_mfma_f32_16x16x32_bf16 v[36:39], v[160:163], v[188:191], v[36:39]
	v_mfma_f32_16x16x32_bf16 v[28:31], v[168:171], v[188:191], v[28:31]
	v_mfma_f32_16x16x32_bf16 v[20:23], v[160:163], v[196:199], v[20:23]
	s_add_i32 s71, s71, 2
	s_add_u32 s28, s28, 0x100
	s_addc_u32 s29, s29, 0
	s_add_u32 s69, s69, 0x100
	s_addc_u32 s70, s70, 0
	s_cmp_gt_u32 s71, 13
	v_mfma_f32_16x16x32_bf16 v[12:15], v[168:171], v[196:199], v[12:15]
	v_mfma_f32_16x16x32_bf16 v[4:7], v[160:163], v[204:207], v[4:7]
	v_mfma_f32_16x16x32_bf16 v[0:3], v[168:171], v[204:207], v[0:3]
	v_mfma_f32_16x16x32_bf16 v[52:55], v[164:167], v[184:187], v[52:55]
	v_mfma_f32_16x16x32_bf16 v[44:47], v[172:175], v[184:187], v[44:47]
	v_mfma_f32_16x16x32_bf16 v[36:39], v[164:167], v[192:195], v[36:39]
	v_mfma_f32_16x16x32_bf16 v[28:31], v[172:175], v[192:195], v[28:31]
	v_mfma_f32_16x16x32_bf16 v[20:23], v[164:167], v[200:203], v[20:23]
	v_mfma_f32_16x16x32_bf16 v[12:15], v[172:175], v[200:203], v[12:15]
	v_mfma_f32_16x16x32_bf16 v[4:7], v[164:167], v[208:211], v[4:7]
	v_mfma_f32_16x16x32_bf16 v[0:3], v[172:175], v[208:211], v[0:3]
	s_setprio 0
	s_barrier
	s_cbranch_scc0 .LBB0_1059
	v_and_b32_e32 v147, 64, v146
	v_xor_b32_e32 v139, 16, v146
	v_add_u32_e32 v147, 64, v147
	v_cmp_lt_i32_e32 vcc, v139, v147
	v_lshl_add_u32 v149, s26, 8, v140
	v_add_u32_e32 v138, 0x4000, v149
	v_cndmask_b32_e32 v139, v146, v139, vcc
	v_lshlrev_b32_e32 v148, 2, v139
	v_xor_b32_e32 v139, 32, v146
	v_cmp_lt_i32_e32 vcc, v139, v147
	v_lshl_or_b32 v136, s27, 8, v142
	v_mul_f32_e32 v152, v125, v125
	v_cndmask_b32_e32 v139, v146, v139, vcc
	v_lshlrev_b32_e32 v147, 2, v139
	v_ashrrev_i32_e32 v139, 31, v138
	v_lshlrev_b64 v[150:151], 11, v[138:139]
	v_mul_f32_e32 v153, v127, v127
	v_ashrrev_i32_e32 v137, 31, v136
	v_fmac_f32_e32 v152, v124, v124
	v_fmac_f32_e32 v153, v126, v126
	v_cvt_pk_bf16_f32 v124, v124, v125
	v_cvt_pk_bf16_f32 v125, v126, v127
	v_lshl_add_u64 v[126:127], s[8:9], 0, v[150:151]
	v_lshl_add_u64 v[126:127], v[136:137], 1, v[126:127]
	global_store_dwordx2 v[126:127], v[124:125], off
	v_mul_f32_e32 v124, v121, v121
	v_mul_f32_e32 v125, v123, v123
	v_fmac_f32_e32 v124, v120, v120
	v_fmac_f32_e32 v125, v122, v122
	v_add_f32_e32 v124, v124, v125
	v_cvt_pk_bf16_f32 v120, v120, v121
	v_mul_f32_e32 v121, v117, v117
	v_mul_f32_e32 v125, v119, v119
	v_add_f32_e32 v152, v152, v153
	v_fmac_f32_e32 v121, v116, v116
	v_fmac_f32_e32 v125, v118, v118
	v_add_f32_e32 v124, v152, v124
	v_add_f32_e32 v121, v121, v125
	v_add_f32_e32 v121, v124, v121
	v_mul_f32_e32 v124, v109, v109
	v_mul_f32_e32 v125, v111, v111
	v_fmac_f32_e32 v124, v108, v108
	v_fmac_f32_e32 v125, v110, v110
	v_add_f32_e32 v124, v124, v125
	v_add_f32_e32 v124, v121, v124
	ds_bpermute_b32 v125, v148, v124
	v_cvt_pk_bf16_f32 v121, v122, v123
	global_store_dwordx2 v[126:127], v[120:121], off offset:32
	v_cvt_pk_bf16_f32 v120, v116, v117
	v_cvt_pk_bf16_f32 v121, v118, v119
	s_waitcnt lgkmcnt(0)
	v_add_f32_e32 v116, v124, v125
	ds_bpermute_b32 v117, v147, v116
	v_cvt_pk_bf16_f32 v108, v108, v109
	v_cvt_pk_bf16_f32 v109, v110, v111
	global_store_dwordx2 v[126:127], v[120:121], off offset:256
	global_store_dwordx2 v[126:127], v[108:109], off offset:288
	s_and_saveexec_b64 s[26:27], s[0:1]
	s_cbranch_execz .LBB0_1062
	v_lshl_add_u64 v[108:109], v[138:139], 2, s[10:11]
	s_waitcnt lgkmcnt(0)
	v_add_f32_e32 v110, v116, v117
	global_atomic_add_f32 v[108:109], v110, off

; #define PG8_STAGE(bufoff, gbase, voff) do { _Pragma("unroll") for (int _i = 0; _i < 2; ++_i) \
;         __builtin_amdgcn_global_load_lds((const unsigned*)((const char*)(gbase) + (voff)[_i]), (PG8_LAS unsigned*)(lds + (bufoff) + ldsw + _i * 8192), 16, 0, 0); } while (0)
; #define PG8_LDA(dst, b, h) do { _Pragma("unroll") for (int m = 0; m < 4; ++m) _Pragma("unroll") for (int k = 0; k < 2; ++k) dst[m][k] = *(const PG8_LAS bf16x8*)(lds + PG8_SA(b, h) + aoff + m * 2048 + k * 1024); } while (0)
; #define PG8_LDB(dst, b, h) do { _Pragma("unroll") for (int n = 0; n < 2; ++n) _Pragma("unroll") for (int k = 0; k < 2; ++k) dst[n][k] = *(const PG8_LAS bf16x8*)(lds + PG8_SB(b, h) + boff + n * 2048 + k * 1024); } while (0)
; #define PG8_WAIT_V(n) asm volatile("s_waitcnt vmcnt(" #n ")" ::: "memory")
; #define PG8_WAIT_L(n) asm volatile("s_waitcnt lgkmcnt(" #n ")" ::: "memory")
; #define PG8_BAR __builtin_amdgcn_s_barrier()
; #define PG8_SCHED __builtin_amdgcn_sched_barrier(0)
; template <class Epi, class Sched, bool ALIGN_EPI = false, bool SP2 = false>
; __device__ __forceinline__ void gemm_phase(PG8_LAS unsigned char* lds, const Gemm g, const Sched& S, const Epi& E) {
;     ...
;         const bool has_next = S.next(ui + 1, nxt);
;         const char* nA = has_next ? (const char*)g.A + (size_t)nxt.pm * tstep : cA; const char* nB = has_next ? (const char*)g.Bt + (size_t)nxt.pn * tstep : cB;
;         for (int t = 0; t < nt; t += 2) {
;             const bool last = (t == nt - 2);
;             const char* a1 = cA + (size_t)(t + 1) * kstep;
;             const char* a2 = last ? nA : cA + (size_t)(t + 2) * kstep; const char* b2 = last ? nB : cB + (size_t)(t + 2) * kstep;
;             const char* a3 = a2 + kstep; const char* b3 = b2 + kstep;
;             if (last && has_next) S.a_ready(nxt);
;             if constexpr (SP2) {
;             PG8_LDB(B0, 0, 0); PG8_LDB(B1, 0, 1); PG8_SCHED; PG8_LDA(At, 0, 0); PG8_STAGE(PG8_SA(1, 1), a1 + hstep, voffA);
;             PG8_WAIT_V(8); PG8_WAIT_L(0); PG8_BAR; PG8_MMA(0, 0, At, B0); PG8_MMA(0, 1, At, B1); PG8_BAR; PG8_SCHED;
;             PG8_LDA(At, 0, 1); PG8_STAGE(PG8_SB(0, 0), b2, voffB); PG8_STAGE(PG8_SB(0, 1), b2 + hstep, voffB); PG8_STAGE(PG8_SA(0, 0), a2, voffA);
;             PG8_WAIT_V(8); PG8_WAIT_L(0); PG8_BAR; PG8_MMA(1, 0, At, B0); PG8_MMA(1, 1, At, B1); PG8_BAR; PG8_SCHED;
.LBB0_1203:
	ds_read_b128 v[150:153], v147
	ds_read_b128 v[154:157], v147 offset:1024
	ds_read_b128 v[158:161], v147 offset:2048
	ds_read_b128 v[162:165], v147 offset:3072
	ds_read_b128 v[166:169], v148
	ds_read_b128 v[170:173], v148 offset:1024
	ds_read_b128 v[180:183], v148 offset:2048
	ds_read_b128 v[184:187], v148 offset:3072
	s_add_u32 s3, s26, 0xfffc0080
	s_addc_u32 s28, s27, -1
	s_cmp_eq_u32 s65, 12
	s_cselect_b32 s31, s19, s28
	s_cselect_b32 s30, s61, s3
	s_cselect_b32 s29, s17, s64
	s_cselect_b32 s28, s62, s63
	v_lshl_add_u64 v[174:175], s[26:27], 0, v[136:137]
	s_add_i32 m0, s25, 0xc000
	ds_read_b128 v[188:191], v149
	ds_read_b128 v[192:195], v149 offset:1024
	ds_read_b128 v[196:199], v149 offset:2048
	ds_read_b128 v[200:203], v149 offset:3072
	ds_read_b128 v[204:207], v149 offset:4096
	ds_read_b128 v[208:211], v149 offset:5120
	ds_read_b128 v[212:215], v149 offset:6144
	ds_read_b128 v[216:219], v149 offset:7168
	global_load_lds_dwordx4 v[174:175], off
	v_lshl_add_u64 v[174:175], s[26:27], 0, v[138:139]
	s_add_i32 m0, s25, 0xe000
	s_nop 0
	global_load_lds_dwordx4 v[174:175], off
	s_waitcnt vmcnt(8)
	s_waitcnt lgkmcnt(0)
	s_barrier
	s_setprio 1
	s_waitcnt lgkmcnt(0)
	v_mfma_f32_16x16x32_bf16 v[124:127], v[150:153], v[188:191], v[124:127]
	v_mfma_f32_16x16x32_bf16 v[120:123], v[158:161], v[188:191], v[120:123]
	v_mfma_f32_16x16x32_bf16 v[108:111], v[150:153], v[196:199], v[108:111]
	v_mfma_f32_16x16x32_bf16 v[104:107], v[158:161], v[196:199], v[104:107]
	v_mfma_f32_16x16x32_bf16 v[92:95], v[150:153], v[204:207], v[92:95]
	v_mfma_f32_16x16x32_bf16 v[88:91], v[158:161], v[204:207], v[88:91]
	v_mfma_f32_16x16x32_bf16 v[76:79], v[150:153], v[212:215], v[76:79]
	v_mfma_f32_16x16x32_bf16 v[72:75], v[158:161], v[212:215], v[72:75]
	v_mfma_f32_16x16x32_bf16 v[124:127], v[154:157], v[192:195], v[124:127]
	v_mfma_f32_16x16x32_bf16 v[120:123], v[162:165], v[192:195], v[120:123]
	v_mfma_f32_16x16x32_bf16 v[108:111], v[154:157], v[200:203], v[108:111]
	v_mfma_f32_16x16x32_bf16 v[104:107], v[162:165], v[200:203], v[104:107]
	v_mfma_f32_16x16x32_bf16 v[92:95], v[154:157], v[208:211], v[92:95]
	v_mfma_f32_16x16x32_bf16 v[88:91], v[162:165], v[208:211], v[88:91]
	v_mfma_f32_16x16x32_bf16 v[76:79], v[154:157], v[216:219], v[76:79]
	v_mfma_f32_16x16x32_bf16 v[72:75], v[162:165], v[216:219], v[72:75]
	s_setprio 0
	s_setprio 1
	v_mfma_f32_16x16x32_bf16 v[116:119], v[166:169], v[188:191], v[116:119]
	v_mfma_f32_16x16x32_bf16 v[112:115], v[180:183], v[188:191], v[112:115]
	v_mfma_f32_16x16x32_bf16 v[100:103], v[166:169], v[196:199], v[100:103]
	v_mfma_f32_16x16x32_bf16 v[96:99], v[180:183], v[196:199], v[96:99]
	v_mfma_f32_16x16x32_bf16 v[84:87], v[166:169], v[204:207], v[84:87]
	v_mfma_f32_16x16x32_bf16 v[80:83], v[180:183], v[204:207], v[80:83]
	v_mfma_f32_16x16x32_bf16 v[68:71], v[166:169], v[212:215], v[68:71]
	v_mfma_f32_16x16x32_bf16 v[64:67], v[180:183], v[212:215], v[64:67]
	v_mfma_f32_16x16x32_bf16 v[116:119], v[170:173], v[192:195], v[116:119]
	v_mfma_f32_16x16x32_bf16 v[112:115], v[184:187], v[192:195], v[112:115]
	v_mfma_f32_16x16x32_bf16 v[100:103], v[170:173], v[200:203], v[100:103]
	v_mfma_f32_16x16x32_bf16 v[96:99], v[184:187], v[200:203], v[96:99]
	v_mfma_f32_16x16x32_bf16 v[84:87], v[170:173], v[208:211], v[84:87]
	v_mfma_f32_16x16x32_bf16 v[80:83], v[184:187], v[208:211], v[80:83]
	v_mfma_f32_16x16x32_bf16 v[68:71], v[170:173], v[216:219], v[68:71]
	v_mfma_f32_16x16x32_bf16 v[64:67], v[184:187], v[216:219], v[64:67]
	s_setprio 0
	s_barrier
	s_add_i32 s3, s49, s38
	v_lshl_add_u64 v[174:175], s[28:29], 0, v[132:133]
	s_mov_b32 m0, s3
	ds_read_b128 v[188:191], v149 offset:16384
	ds_read_b128 v[192:195], v149 offset:17408
	ds_read_b128 v[196:199], v149 offset:18432
	ds_read_b128 v[200:203], v149 offset:19456
	ds_read_b128 v[204:207], v149 offset:20480
	ds_read_b128 v[208:211], v149 offset:21504
	ds_read_b128 v[212:215], v149 offset:22528
	ds_read_b128 v[216:219], v149 offset:23552
	global_load_lds_dwordx4 v[174:175], off
	s_add_i32 m0, s3, 0x2000
	s_add_u32 s66, s28, 0x40000
	v_lshl_add_u64 v[220:221], s[28:29], 0, v[128:129]
	s_addc_u32 s67, s29, 0
	s_add_i32 s3, s50, s38
	global_load_lds_dwordx4 v[220:221], off
	v_lshl_add_u64 v[222:223], s[66:67], 0, v[132:133]
	s_mov_b32 m0, s3
	v_lshl_add_u64 v[224:225], s[30:31], 0, v[130:131]
	global_load_lds_dwordx4 v[222:223], off
	v_lshl_add_u64 v[222:223], s[66:67], 0, v[128:129]
	s_add_i32 m0, s3, 0x2000
	s_nop 0
	global_load_lds_dwordx4 v[222:223], off
	v_lshl_add_u64 v[222:223], s[30:31], 0, v[134:135]
	s_mov_b32 m0, s25
	s_nop 0
	global_load_lds_dwordx4 v[222:223], off
	s_mov_b32 m0, s41
	s_nop 0
	global_load_lds_dwordx4 v[224:225], off
	s_waitcnt vmcnt(8)
	s_waitcnt lgkmcnt(0)
	s_barrier
; #define PG8_STAGE(bufoff, gbase, voff) do { _Pragma("unroll") for (int _i = 0; _i < 2; ++_i) \
;         __builtin_amdgcn_global_load_lds((const unsigned*)((const char*)(gbase) + (voff)[_i]), (PG8_LAS unsigned*)(lds + (bufoff) + ldsw + _i * 8192), 16, 0, 0); } while (0)
; #define PG8_LDA(dst, b, h) do { _Pragma("unroll") for (int m = 0; m < 4; ++m) _Pragma("unroll") for (int k = 0; k < 2; ++k) dst[m][k] = *(const PG8_LAS bf16x8*)(lds + PG8_SA(b, h) + aoff + m * 2048 + k * 1024); } while (0)
; #define PG8_LDB(dst, b, h) do { _Pragma("unroll") for (int n = 0; n < 2; ++n) _Pragma("unroll") for (int k = 0; k < 2; ++k) dst[n][k] = *(const PG8_LAS bf16x8*)(lds + PG8_SB(b, h) + boff + n * 2048 + k * 1024); } while (0)
; #define PG8_MMA(ai, bj, At, Bt) do { __builtin_amdgcn_s_setprio(1); _Pragma("unroll") for (int m = 0; m < 4; ++m) _Pragma("unroll") for (int n = 0; n < 2; ++n) _Pragma("unroll") for (int k = 0; k < 2; ++k) \
;         acc[ai][bj][m][n] = __builtin_amdgcn_mfma_f32_16x16x32_bf16(Bt[n][k], At[m][k], acc[ai][bj][m][n], 0, 0, 0); __builtin_amdgcn_s_setprio(0); } while (0)
; #define PG8_WAIT_V(n) asm volatile("s_waitcnt vmcnt(" #n ")" ::: "memory")
; #define PG8_WAIT_L(n) asm volatile("s_waitcnt lgkmcnt(" #n ")" ::: "memory")
; #define PG8_BAR __builtin_amdgcn_s_barrier()
; #define PG8_SCHED __builtin_amdgcn_sched_barrier(0)
; template <class Epi, class Sched, bool ALIGN_EPI = false, bool SP2 = false>
; __device__ __forceinline__ void gemm_phase(PG8_LAS unsigned char* lds, const Gemm g, const Sched& S, const Epi& E) {
;     ...
;             PG8_WAIT_V(8); PG8_WAIT_L(0); PG8_BAR; PG8_MMA(1, 0, At, B0); PG8_MMA(1, 1, At, B1); PG8_BAR; PG8_SCHED;
;             PG8_LDB(B0, 1, 0); PG8_LDB(B1, 1, 1); PG8_SCHED; PG8_LDA(At, 1, 0); PG8_STAGE(PG8_SA(0, 1), a2 + hstep, voffA);
;             PG8_WAIT_V(8); PG8_WAIT_L(0); PG8_BAR; PG8_MMA(0, 0, At, B0); PG8_MMA(0, 1, At, B1); PG8_BAR; PG8_SCHED;
	s_setprio 1
	s_waitcnt lgkmcnt(0)
	v_mfma_f32_16x16x32_bf16 v[60:63], v[150:153], v[188:191], v[60:63]
	v_mfma_f32_16x16x32_bf16 v[56:59], v[158:161], v[188:191], v[56:59]
	v_mfma_f32_16x16x32_bf16 v[44:47], v[150:153], v[196:199], v[44:47]
	v_mfma_f32_16x16x32_bf16 v[40:43], v[158:161], v[196:199], v[40:43]
	v_mfma_f32_16x16x32_bf16 v[28:31], v[150:153], v[204:207], v[28:31]
	v_mfma_f32_16x16x32_bf16 v[24:27], v[158:161], v[204:207], v[24:27]
	v_mfma_f32_16x16x32_bf16 v[12:15], v[150:153], v[212:215], v[12:15]
	v_mfma_f32_16x16x32_bf16 v[8:11], v[158:161], v[212:215], v[8:11]
	v_mfma_f32_16x16x32_bf16 v[60:63], v[154:157], v[192:195], v[60:63]
	v_mfma_f32_16x16x32_bf16 v[56:59], v[162:165], v[192:195], v[56:59]
	v_mfma_f32_16x16x32_bf16 v[44:47], v[154:157], v[200:203], v[44:47]
	v_mfma_f32_16x16x32_bf16 v[40:43], v[162:165], v[200:203], v[40:43]
	v_mfma_f32_16x16x32_bf16 v[28:31], v[154:157], v[208:211], v[28:31]
	v_mfma_f32_16x16x32_bf16 v[24:27], v[162:165], v[208:211], v[24:27]
	v_mfma_f32_16x16x32_bf16 v[12:15], v[154:157], v[216:219], v[12:15]
	v_mfma_f32_16x16x32_bf16 v[8:11], v[162:165], v[216:219], v[8:11]
	s_setprio 0
	s_setprio 1
	v_mfma_f32_16x16x32_bf16 v[52:55], v[166:169], v[188:191], v[52:55]
	v_mfma_f32_16x16x32_bf16 v[48:51], v[180:183], v[188:191], v[48:51]
	v_mfma_f32_16x16x32_bf16 v[36:39], v[166:169], v[196:199], v[36:39]
	v_mfma_f32_16x16x32_bf16 v[32:35], v[180:183], v[196:199], v[32:35]
	v_mfma_f32_16x16x32_bf16 v[20:23], v[166:169], v[204:207], v[20:23]
	v_mfma_f32_16x16x32_bf16 v[16:19], v[180:183], v[204:207], v[16:19]
	v_mfma_f32_16x16x32_bf16 v[4:7], v[166:169], v[212:215], v[4:7]
	v_mfma_f32_16x16x32_bf16 v[0:3], v[180:183], v[212:215], v[0:3]
	v_mfma_f32_16x16x32_bf16 v[52:55], v[170:173], v[192:195], v[52:55]
	v_mfma_f32_16x16x32_bf16 v[48:51], v[184:187], v[192:195], v[48:51]
	v_mfma_f32_16x16x32_bf16 v[36:39], v[170:173], v[200:203], v[36:39]
	v_mfma_f32_16x16x32_bf16 v[32:35], v[184:187], v[200:203], v[32:35]
	v_mfma_f32_16x16x32_bf16 v[20:23], v[170:173], v[208:211], v[20:23]
	v_mfma_f32_16x16x32_bf16 v[16:19], v[184:187], v[208:211], v[16:19]
	v_mfma_f32_16x16x32_bf16 v[4:7], v[170:173], v[216:219], v[4:7]
	v_mfma_f32_16x16x32_bf16 v[0:3], v[184:187], v[216:219], v[0:3]
	s_setprio 0
	s_barrier
	s_add_i32 s3, 0, 0x18000
	s_add_i32 s33, 0, 0x1c000
	v_add_u32_e32 v162, s3, v145
	v_add_u32_e32 v177, s33, v145
	ds_read_b128 v[150:153], v162
	ds_read_b128 v[154:157], v162 offset:1024
	ds_read_b128 v[158:161], v162 offset:2048
	ds_read_b128 v[162:165], v162 offset:3072
	ds_read_b128 v[166:169], v177
	ds_read_b128 v[170:173], v177 offset:1024
	ds_read_b128 v[180:183], v177 offset:2048
	ds_read_b128 v[184:187], v177 offset:3072
	s_add_u32 s30, s30, 0x40000
	s_addc_u32 s31, s31, 0
	s_mov_b32 m0, s42
	v_lshl_add_u64 v[226:227], s[30:31], 0, v[134:135]
	ds_read_b128 v[188:191], v149 offset:32768
	ds_read_b128 v[192:195], v149 offset:33792
	ds_read_b128 v[196:199], v149 offset:34816
	ds_read_b128 v[200:203], v149 offset:35840
	ds_read_b128 v[204:207], v149 offset:36864
	ds_read_b128 v[208:211], v149 offset:37888
	ds_read_b128 v[212:215], v149 offset:38912
	ds_read_b128 v[216:219], v149 offset:39936
	global_load_lds_dwordx4 v[226:227], off
	v_lshl_add_u64 v[226:227], s[30:31], 0, v[130:131]
	s_mov_b32 m0, s43
	s_nop 0
	global_load_lds_dwordx4 v[226:227], off
	s_waitcnt vmcnt(8)
	s_waitcnt lgkmcnt(0)
	s_barrier
	s_setprio 1
	s_waitcnt lgkmcnt(0)
	v_mfma_f32_16x16x32_bf16 v[124:127], v[150:153], v[188:191], v[124:127]
	v_mfma_f32_16x16x32_bf16 v[120:123], v[158:161], v[188:191], v[120:123]
	v_mfma_f32_16x16x32_bf16 v[108:111], v[150:153], v[196:199], v[108:111]
	v_mfma_f32_16x16x32_bf16 v[104:107], v[158:161], v[196:199], v[104:107]
	v_mfma_f32_16x16x32_bf16 v[92:95], v[150:153], v[204:207], v[92:95]
	v_mfma_f32_16x16x32_bf16 v[88:91], v[158:161], v[204:207], v[88:91]
	v_mfma_f32_16x16x32_bf16 v[76:79], v[150:153], v[212:215], v[76:79]
	v_mfma_f32_16x16x32_bf16 v[72:75], v[158:161], v[212:215], v[72:75]
	v_mfma_f32_16x16x32_bf16 v[124:127], v[154:157], v[192:195], v[124:127]
	v_mfma_f32_16x16x32_bf16 v[120:123], v[162:165], v[192:195], v[120:123]
	v_mfma_f32_16x16x32_bf16 v[108:111], v[154:157], v[200:203], v[108:111]
	v_mfma_f32_16x16x32_bf16 v[104:107], v[162:165], v[200:203], v[104:107]
	v_mfma_f32_16x16x32_bf16 v[92:95], v[154:157], v[208:211], v[92:95]
	v_mfma_f32_16x16x32_bf16 v[88:91], v[162:165], v[208:211], v[88:91]
	v_mfma_f32_16x16x32_bf16 v[76:79], v[154:157], v[216:219], v[76:79]
	v_mfma_f32_16x16x32_bf16 v[72:75], v[162:165], v[216:219], v[72:75]
	s_setprio 0
	s_setprio 1
	v_mfma_f32_16x16x32_bf16 v[116:119], v[166:169], v[188:191], v[116:119]
	v_mfma_f32_16x16x32_bf16 v[112:115], v[180:183], v[188:191], v[112:115]
	v_mfma_f32_16x16x32_bf16 v[100:103], v[166:169], v[196:199], v[100:103]
	v_mfma_f32_16x16x32_bf16 v[96:99], v[180:183], v[196:199], v[96:99]
	v_mfma_f32_16x16x32_bf16 v[84:87], v[166:169], v[204:207], v[84:87]
	v_mfma_f32_16x16x32_bf16 v[80:83], v[180:183], v[204:207], v[80:83]
	v_mfma_f32_16x16x32_bf16 v[68:71], v[166:169], v[212:215], v[68:71]
	v_mfma_f32_16x16x32_bf16 v[64:67], v[180:183], v[212:215], v[64:67]
	v_mfma_f32_16x16x32_bf16 v[116:119], v[170:173], v[192:195], v[116:119]
	v_mfma_f32_16x16x32_bf16 v[112:115], v[184:187], v[192:195], v[112:115]
	v_mfma_f32_16x16x32_bf16 v[100:103], v[170:173], v[200:203], v[100:103]
	v_mfma_f32_16x16x32_bf16 v[96:99], v[184:187], v[200:203], v[96:99]
	v_mfma_f32_16x16x32_bf16 v[84:87], v[170:173], v[208:211], v[84:87]
	v_mfma_f32_16x16x32_bf16 v[80:83], v[184:187], v[208:211], v[80:83]
	v_mfma_f32_16x16x32_bf16 v[68:71], v[170:173], v[216:219], v[68:71]
	v_mfma_f32_16x16x32_bf16 v[64:67], v[184:187], v[216:219], v[64:67]
	s_setprio 0
	s_barrier
; #define PG8_STAGE(bufoff, gbase, voff) do { _Pragma("unroll") for (int _i = 0; _i < 2; ++_i) \
;         __builtin_amdgcn_global_load_lds((const unsigned*)((const char*)(gbase) + (voff)[_i]), (PG8_LAS unsigned*)(lds + (bufoff) + ldsw + _i * 8192), 16, 0, 0); } while (0)
; #define PG8_LDA(dst, b, h) do { _Pragma("unroll") for (int m = 0; m < 4; ++m) _Pragma("unroll") for (int k = 0; k < 2; ++k) dst[m][k] = *(const PG8_LAS bf16x8*)(lds + PG8_SA(b, h) + aoff + m * 2048 + k * 1024); } while (0)
; #define PG8_MMA(ai, bj, At, Bt) do { __builtin_amdgcn_s_setprio(1); _Pragma("unroll") for (int m = 0; m < 4; ++m) _Pragma("unroll") for (int n = 0; n < 2; ++n) _Pragma("unroll") for (int k = 0; k < 2; ++k) \
;         acc[ai][bj][m][n] = __builtin_amdgcn_mfma_f32_16x16x32_bf16(Bt[n][k], At[m][k], acc[ai][bj][m][n], 0, 0, 0); __builtin_amdgcn_s_setprio(0); } while (0)
; #define PG8_WAIT_V(n) asm volatile("s_waitcnt vmcnt(" #n ")" ::: "memory")
; #define PG8_WAIT_L(n) asm volatile("s_waitcnt lgkmcnt(" #n ")" ::: "memory")
; #define PG8_BAR __builtin_amdgcn_s_barrier()
; #define PG8_SCHED __builtin_amdgcn_sched_barrier(0)
; template <class Epi, class Sched, bool ALIGN_EPI = false, bool SP2 = false>
; __device__ __forceinline__ void gemm_phase(PG8_LAS unsigned char* lds, const Gemm g, const Sched& S, const Epi& E) {
;     ...
;             PG8_LDA(At, 1, 1); PG8_STAGE(PG8_SB(1, 0), b3, voffB); PG8_STAGE(PG8_SB(1, 1), b3 + hstep, voffB); PG8_STAGE(PG8_SA(1, 0), a3, voffA);
;             PG8_WAIT_V(8); PG8_WAIT_L(0); PG8_BAR; PG8_MMA(1, 0, At, B0); PG8_MMA(1, 1, At, B1); PG8_BAR; PG8_SCHED;
;     ...
;         if constexpr (ALIGN_EPI) { if (wr == 0) PG8_BAR; }
	s_add_i32 s3, s3, s38
	v_lshl_add_u64 v[174:175], v[174:175], 0, s[10:11]
	s_mov_b32 m0, s3
	ds_read_b128 v[188:191], v149 offset:49152
	ds_read_b128 v[192:195], v149 offset:50176
	ds_read_b128 v[196:199], v149 offset:51200
	ds_read_b128 v[200:203], v149 offset:52224
	ds_read_b128 v[204:207], v149 offset:53248
	ds_read_b128 v[208:211], v149 offset:54272
	ds_read_b128 v[212:215], v149 offset:55296
	ds_read_b128 v[216:219], v149 offset:56320
	global_load_lds_dwordx4 v[174:175], off
	s_add_i32 m0, s3, 0x2000
	s_add_u32 s28, s28, 0x40080
	v_lshl_add_u64 v[174:175], v[220:221], 0, s[10:11]
	s_addc_u32 s29, s29, 0
	s_add_i32 s3, s33, s38
	global_load_lds_dwordx4 v[174:175], off
	v_lshl_add_u64 v[174:175], s[28:29], 0, v[132:133]
	s_mov_b32 m0, s3
	s_nop 0
	global_load_lds_dwordx4 v[174:175], off
	v_lshl_add_u64 v[174:175], s[28:29], 0, v[128:129]
	s_add_i32 m0, s3, 0x2000
	s_nop 0
	global_load_lds_dwordx4 v[174:175], off
	v_lshl_add_u64 v[174:175], v[222:223], 0, s[10:11]
	s_mov_b32 m0, s45
	s_nop 0
	global_load_lds_dwordx4 v[174:175], off
	v_lshl_add_u64 v[174:175], v[224:225], 0, s[10:11]
	s_mov_b32 m0, s46
	s_nop 0
	global_load_lds_dwordx4 v[174:175], off
	s_waitcnt vmcnt(8)
	s_waitcnt lgkmcnt(0)
	s_barrier
	s_setprio 1
	s_waitcnt lgkmcnt(0)
	v_mfma_f32_16x16x32_bf16 v[60:63], v[150:153], v[188:191], v[60:63]
	v_mfma_f32_16x16x32_bf16 v[56:59], v[158:161], v[188:191], v[56:59]
	v_mfma_f32_16x16x32_bf16 v[44:47], v[150:153], v[196:199], v[44:47]
	v_mfma_f32_16x16x32_bf16 v[40:43], v[158:161], v[196:199], v[40:43]
	v_mfma_f32_16x16x32_bf16 v[28:31], v[150:153], v[204:207], v[28:31]
	v_mfma_f32_16x16x32_bf16 v[24:27], v[158:161], v[204:207], v[24:27]
	v_mfma_f32_16x16x32_bf16 v[12:15], v[150:153], v[212:215], v[12:15]
	v_mfma_f32_16x16x32_bf16 v[8:11], v[158:161], v[212:215], v[8:11]
	v_mfma_f32_16x16x32_bf16 v[60:63], v[154:157], v[192:195], v[60:63]
	v_mfma_f32_16x16x32_bf16 v[56:59], v[162:165], v[192:195], v[56:59]
	v_mfma_f32_16x16x32_bf16 v[44:47], v[154:157], v[200:203], v[44:47]
	v_mfma_f32_16x16x32_bf16 v[40:43], v[162:165], v[200:203], v[40:43]
	v_mfma_f32_16x16x32_bf16 v[28:31], v[154:157], v[208:211], v[28:31]
	v_mfma_f32_16x16x32_bf16 v[24:27], v[162:165], v[208:211], v[24:27]
	v_mfma_f32_16x16x32_bf16 v[12:15], v[154:157], v[216:219], v[12:15]
	v_mfma_f32_16x16x32_bf16 v[8:11], v[162:165], v[216:219], v[8:11]
	s_setprio 0
	s_setprio 1
	v_mfma_f32_16x16x32_bf16 v[52:55], v[166:169], v[188:191], v[52:55]
	v_mfma_f32_16x16x32_bf16 v[48:51], v[180:183], v[188:191], v[48:51]
	v_mfma_f32_16x16x32_bf16 v[36:39], v[166:169], v[196:199], v[36:39]
	v_mfma_f32_16x16x32_bf16 v[32:35], v[180:183], v[196:199], v[32:35]
	v_mfma_f32_16x16x32_bf16 v[20:23], v[166:169], v[204:207], v[20:23]
	s_add_i32 s65, s65, 2
	s_add_u32 s26, s26, 0x100
	s_addc_u32 s27, s27, 0
	s_add_u32 s63, s63, 0x100
	s_addc_u32 s64, s64, 0
	s_cmp_gt_u32 s65, 13
	v_mfma_f32_16x16x32_bf16 v[16:19], v[180:183], v[204:207], v[16:19]
	v_mfma_f32_16x16x32_bf16 v[4:7], v[166:169], v[212:215], v[4:7]
	v_mfma_f32_16x16x32_bf16 v[0:3], v[180:183], v[212:215], v[0:3]
	v_mfma_f32_16x16x32_bf16 v[52:55], v[170:173], v[192:195], v[52:55]
	v_mfma_f32_16x16x32_bf16 v[48:51], v[184:187], v[192:195], v[48:51]
	v_mfma_f32_16x16x32_bf16 v[36:39], v[170:173], v[200:203], v[36:39]
	v_mfma_f32_16x16x32_bf16 v[32:35], v[184:187], v[200:203], v[32:35]
	v_mfma_f32_16x16x32_bf16 v[20:23], v[170:173], v[208:211], v[20:23]
	v_mfma_f32_16x16x32_bf16 v[16:19], v[184:187], v[208:211], v[16:19]
	v_mfma_f32_16x16x32_bf16 v[4:7], v[170:173], v[216:219], v[4:7]
	v_mfma_f32_16x16x32_bf16 v[0:3], v[184:187], v[216:219], v[0:3]
	s_setprio 0
	s_barrier
	s_cbranch_scc0 .LBB0_1203
	s_and_b64 vcc, exec, s[14:15]
	s_cbranch_vccz .LBB0_1206
	s_barrier

; #define PG8_STAGE(bufoff, gbase, voff) do { _Pragma("unroll") for (int _i = 0; _i < 2; ++_i) \
;         __builtin_amdgcn_global_load_lds((const unsigned*)((const char*)(gbase) + (voff)[_i]), (PG8_LAS unsigned*)(lds + (bufoff) + ldsw + _i * 8192), 16, 0, 0); } while (0)
; #define PG8_LDA(dst, b, h) do { _Pragma("unroll") for (int m = 0; m < 4; ++m) _Pragma("unroll") for (int k = 0; k < 2; ++k) dst[m][k] = *(const PG8_LAS bf16x8*)(lds + PG8_SA(b, h) + aoff + m * 2048 + k * 1024); } while (0)
; #define PG8_LDB(dst, b, h) do { _Pragma("unroll") for (int n = 0; n < 2; ++n) _Pragma("unroll") for (int k = 0; k < 2; ++k) dst[n][k] = *(const PG8_LAS bf16x8*)(lds + PG8_SB(b, h) + boff + n * 2048 + k * 1024); } while (0)
; #define PG8_WAIT_V(n) asm volatile("s_waitcnt vmcnt(" #n ")" ::: "memory")
; #define PG8_WAIT_L(n) asm volatile("s_waitcnt lgkmcnt(" #n ")" ::: "memory")
; #define PG8_BAR __builtin_amdgcn_s_barrier()
; #define PG8_SCHED __builtin_amdgcn_sched_barrier(0)
; template <class Epi, class Sched, bool ALIGN_EPI = false, bool SP2 = false>
; __device__ __forceinline__ void gemm_phase(PG8_LAS unsigned char* lds, const Gemm g, const Sched& S, const Epi& E) {
;     ...
;         const bool has_next = S.next(ui + 1, nxt);
;         const char* nA = has_next ? (const char*)g.A + (size_t)nxt.pm * tstep : cA; const char* nB = has_next ? (const char*)g.Bt + (size_t)nxt.pn * tstep : cB;
;         for (int t = 0; t < nt; t += 2) {
;             const bool last = (t == nt - 2);
;             const char* a1 = cA + (size_t)(t + 1) * kstep;
;             const char* a2 = last ? nA : cA + (size_t)(t + 2) * kstep; const char* b2 = last ? nB : cB + (size_t)(t + 2) * kstep;
;             const char* a3 = a2 + kstep; const char* b3 = b2 + kstep;
;             if (last && has_next) S.a_ready(nxt);
;             if constexpr (SP2) {
;             PG8_LDB(B0, 0, 0); PG8_LDB(B1, 0, 1); PG8_SCHED; PG8_LDA(At, 0, 0); PG8_STAGE(PG8_SA(1, 1), a1 + hstep, voffA);
;             PG8_WAIT_V(8); PG8_WAIT_L(0); PG8_BAR; PG8_MMA(0, 0, At, B0); PG8_MMA(0, 1, At, B1); PG8_BAR; PG8_SCHED;
;             PG8_LDA(At, 0, 1); PG8_STAGE(PG8_SB(0, 0), b2, voffB); PG8_STAGE(PG8_SB(0, 1), b2 + hstep, voffB); PG8_STAGE(PG8_SA(0, 0), a2, voffA);
;             PG8_WAIT_V(8); PG8_WAIT_L(0); PG8_BAR; PG8_MMA(1, 0, At, B0); PG8_MMA(1, 1, At, B1); PG8_BAR; PG8_SCHED;
.LBB0_1287:
	ds_read_b128 v[140:143], v147
	ds_read_b128 v[152:155], v147 offset:1024
	ds_read_b128 v[156:159], v147 offset:2048
	ds_read_b128 v[160:163], v147 offset:3072
	ds_read_b128 v[164:167], v148
	ds_read_b128 v[168:171], v148 offset:1024
	ds_read_b128 v[172:175], v148 offset:2048
	ds_read_b128 v[180:183], v148 offset:3072
	s_add_u32 s3, s20, 0xfff50080
	s_addc_u32 s22, s21, -1
	s_cmp_eq_u32 s60, 40
	s_cselect_b32 s25, s5, s22
	s_cselect_b32 s24, s4, s3
	s_cselect_b32 s23, s7, s51
	s_cselect_b32 s22, s6, s50
	v_lshl_add_u64 v[216:217], s[20:21], 0, v[132:133]
	s_add_i32 m0, s34, 0xc000
	ds_read_b128 v[184:187], v149
	ds_read_b128 v[188:191], v149 offset:1024
	ds_read_b128 v[192:195], v149 offset:2048
	ds_read_b128 v[196:199], v149 offset:3072
	ds_read_b128 v[200:203], v149 offset:4096
	ds_read_b128 v[204:207], v149 offset:5120
	ds_read_b128 v[208:211], v149 offset:6144
	ds_read_b128 v[212:215], v149 offset:7168
	global_load_lds_dwordx4 v[216:217], off
	v_lshl_add_u64 v[216:217], s[20:21], 0, v[134:135]
	s_add_i32 m0, s34, 0xe000
	s_nop 0
	global_load_lds_dwordx4 v[216:217], off
	s_waitcnt vmcnt(8)
	s_waitcnt lgkmcnt(0)
	s_barrier
	s_setprio 1
	s_waitcnt lgkmcnt(0)
	v_mfma_f32_16x16x32_bf16 v[124:127], v[140:143], v[184:187], v[124:127]
	v_mfma_f32_16x16x32_bf16 v[120:123], v[156:159], v[184:187], v[120:123]
	v_mfma_f32_16x16x32_bf16 v[112:115], v[140:143], v[192:195], v[112:115]
	v_mfma_f32_16x16x32_bf16 v[104:107], v[156:159], v[192:195], v[104:107]
	v_mfma_f32_16x16x32_bf16 v[96:99], v[140:143], v[200:203], v[96:99]
	v_mfma_f32_16x16x32_bf16 v[88:91], v[156:159], v[200:203], v[88:91]
	v_mfma_f32_16x16x32_bf16 v[80:83], v[140:143], v[208:211], v[80:83]
	v_mfma_f32_16x16x32_bf16 v[72:75], v[156:159], v[208:211], v[72:75]
	v_mfma_f32_16x16x32_bf16 v[124:127], v[152:155], v[188:191], v[124:127]
	v_mfma_f32_16x16x32_bf16 v[120:123], v[160:163], v[188:191], v[120:123]
	v_mfma_f32_16x16x32_bf16 v[112:115], v[152:155], v[196:199], v[112:115]
	v_mfma_f32_16x16x32_bf16 v[104:107], v[160:163], v[196:199], v[104:107]
	v_mfma_f32_16x16x32_bf16 v[96:99], v[152:155], v[204:207], v[96:99]
	v_mfma_f32_16x16x32_bf16 v[88:91], v[160:163], v[204:207], v[88:91]
	v_mfma_f32_16x16x32_bf16 v[80:83], v[152:155], v[212:215], v[80:83]
	v_mfma_f32_16x16x32_bf16 v[72:75], v[160:163], v[212:215], v[72:75]
	s_setprio 0
	s_setprio 1
	v_mfma_f32_16x16x32_bf16 v[116:119], v[164:167], v[184:187], v[116:119]
	v_mfma_f32_16x16x32_bf16 v[108:111], v[172:175], v[184:187], v[108:111]
	v_mfma_f32_16x16x32_bf16 v[100:103], v[164:167], v[192:195], v[100:103]
	v_mfma_f32_16x16x32_bf16 v[92:95], v[172:175], v[192:195], v[92:95]
	v_mfma_f32_16x16x32_bf16 v[84:87], v[164:167], v[200:203], v[84:87]
	v_mfma_f32_16x16x32_bf16 v[76:79], v[172:175], v[200:203], v[76:79]
	v_mfma_f32_16x16x32_bf16 v[68:71], v[164:167], v[208:211], v[68:71]
	v_mfma_f32_16x16x32_bf16 v[64:67], v[172:175], v[208:211], v[64:67]
	v_mfma_f32_16x16x32_bf16 v[116:119], v[168:171], v[188:191], v[116:119]
	v_mfma_f32_16x16x32_bf16 v[108:111], v[180:183], v[188:191], v[108:111]
	v_mfma_f32_16x16x32_bf16 v[100:103], v[168:171], v[196:199], v[100:103]
	v_mfma_f32_16x16x32_bf16 v[92:95], v[180:183], v[196:199], v[92:95]
	v_mfma_f32_16x16x32_bf16 v[84:87], v[168:171], v[204:207], v[84:87]
	v_mfma_f32_16x16x32_bf16 v[76:79], v[180:183], v[204:207], v[76:79]
	v_mfma_f32_16x16x32_bf16 v[68:71], v[168:171], v[212:215], v[68:71]
	v_mfma_f32_16x16x32_bf16 v[64:67], v[180:183], v[212:215], v[64:67]
	s_setprio 0
	s_barrier
	s_add_i32 s3, s44, s31
	v_lshl_add_u64 v[216:217], s[22:23], 0, v[128:129]
	s_mov_b32 m0, s3
	ds_read_b128 v[184:187], v149 offset:16384
	ds_read_b128 v[188:191], v149 offset:17408
	ds_read_b128 v[192:195], v149 offset:18432
	ds_read_b128 v[196:199], v149 offset:19456
	ds_read_b128 v[200:203], v149 offset:20480
	ds_read_b128 v[204:207], v149 offset:21504
	ds_read_b128 v[208:211], v149 offset:22528
	ds_read_b128 v[212:215], v149 offset:23552
	global_load_lds_dwordx4 v[216:217], off
	s_add_i32 m0, s3, 0x2000
	s_add_u32 s62, s22, 0xb0000
	v_lshl_add_u64 v[218:219], s[22:23], 0, v[130:131]
	s_addc_u32 s63, s23, 0
	s_add_i32 s3, s45, s31
	global_load_lds_dwordx4 v[218:219], off
	v_lshl_add_u64 v[220:221], s[62:63], 0, v[128:129]
	s_mov_b32 m0, s3
	v_lshl_add_u64 v[222:223], s[24:25], 0, v[130:131]
	global_load_lds_dwordx4 v[220:221], off
	v_lshl_add_u64 v[220:221], s[62:63], 0, v[130:131]
	s_add_i32 m0, s3, 0x2000
	s_nop 0
	global_load_lds_dwordx4 v[220:221], off
	v_lshl_add_u64 v[220:221], s[24:25], 0, v[128:129]
	s_mov_b32 m0, s34
	s_nop 0
	global_load_lds_dwordx4 v[220:221], off
	s_mov_b32 m0, s35
	s_nop 0
	global_load_lds_dwordx4 v[222:223], off
	s_waitcnt vmcnt(8)
	s_waitcnt lgkmcnt(0)
	s_barrier
; #define PG8_STAGE(bufoff, gbase, voff) do { _Pragma("unroll") for (int _i = 0; _i < 2; ++_i) \
;         __builtin_amdgcn_global_load_lds((const unsigned*)((const char*)(gbase) + (voff)[_i]), (PG8_LAS unsigned*)(lds + (bufoff) + ldsw + _i * 8192), 16, 0, 0); } while (0)
; #define PG8_LDA(dst, b, h) do { _Pragma("unroll") for (int m = 0; m < 4; ++m) _Pragma("unroll") for (int k = 0; k < 2; ++k) dst[m][k] = *(const PG8_LAS bf16x8*)(lds + PG8_SA(b, h) + aoff + m * 2048 + k * 1024); } while (0)
; #define PG8_LDB(dst, b, h) do { _Pragma("unroll") for (int n = 0; n < 2; ++n) _Pragma("unroll") for (int k = 0; k < 2; ++k) dst[n][k] = *(const PG8_LAS bf16x8*)(lds + PG8_SB(b, h) + boff + n * 2048 + k * 1024); } while (0)
; #define PG8_MMA(ai, bj, At, Bt) do { __builtin_amdgcn_s_setprio(1); _Pragma("unroll") for (int m = 0; m < 4; ++m) _Pragma("unroll") for (int n = 0; n < 2; ++n) _Pragma("unroll") for (int k = 0; k < 2; ++k) \
;         acc[ai][bj][m][n] = __builtin_amdgcn_mfma_f32_16x16x32_bf16(Bt[n][k], At[m][k], acc[ai][bj][m][n], 0, 0, 0); __builtin_amdgcn_s_setprio(0); } while (0)
; #define PG8_WAIT_V(n) asm volatile("s_waitcnt vmcnt(" #n ")" ::: "memory")
; #define PG8_WAIT_L(n) asm volatile("s_waitcnt lgkmcnt(" #n ")" ::: "memory")
; #define PG8_BAR __builtin_amdgcn_s_barrier()
; #define PG8_SCHED __builtin_amdgcn_sched_barrier(0)
; template <class Epi, class Sched, bool ALIGN_EPI = false, bool SP2 = false>
; __device__ __forceinline__ void gemm_phase(PG8_LAS unsigned char* lds, const Gemm g, const Sched& S, const Epi& E) {
;     ...
;             PG8_WAIT_V(8); PG8_WAIT_L(0); PG8_BAR; PG8_MMA(1, 0, At, B0); PG8_MMA(1, 1, At, B1); PG8_BAR; PG8_SCHED;
;             PG8_LDB(B0, 1, 0); PG8_LDB(B1, 1, 1); PG8_SCHED; PG8_LDA(At, 1, 0); PG8_STAGE(PG8_SA(0, 1), a2 + hstep, voffA);
;             PG8_WAIT_V(8); PG8_WAIT_L(0); PG8_BAR; PG8_MMA(0, 0, At, B0); PG8_MMA(0, 1, At, B1); PG8_BAR; PG8_SCHED;
	s_setprio 1
	s_waitcnt lgkmcnt(0)
	v_mfma_f32_16x16x32_bf16 v[60:63], v[140:143], v[184:187], v[60:63]
	v_mfma_f32_16x16x32_bf16 v[56:59], v[156:159], v[184:187], v[56:59]
	v_mfma_f32_16x16x32_bf16 v[48:51], v[140:143], v[192:195], v[48:51]
	v_mfma_f32_16x16x32_bf16 v[40:43], v[156:159], v[192:195], v[40:43]
	v_mfma_f32_16x16x32_bf16 v[32:35], v[140:143], v[200:203], v[32:35]
	v_mfma_f32_16x16x32_bf16 v[24:27], v[156:159], v[200:203], v[24:27]
	v_mfma_f32_16x16x32_bf16 v[16:19], v[140:143], v[208:211], v[16:19]
	v_mfma_f32_16x16x32_bf16 v[8:11], v[156:159], v[208:211], v[8:11]
	v_mfma_f32_16x16x32_bf16 v[60:63], v[152:155], v[188:191], v[60:63]
	v_mfma_f32_16x16x32_bf16 v[56:59], v[160:163], v[188:191], v[56:59]
	v_mfma_f32_16x16x32_bf16 v[48:51], v[152:155], v[196:199], v[48:51]
	v_mfma_f32_16x16x32_bf16 v[40:43], v[160:163], v[196:199], v[40:43]
	v_mfma_f32_16x16x32_bf16 v[32:35], v[152:155], v[204:207], v[32:35]
	v_mfma_f32_16x16x32_bf16 v[24:27], v[160:163], v[204:207], v[24:27]
	v_mfma_f32_16x16x32_bf16 v[16:19], v[152:155], v[212:215], v[16:19]
	v_mfma_f32_16x16x32_bf16 v[8:11], v[160:163], v[212:215], v[8:11]
	s_setprio 0
	s_setprio 1
	v_mfma_f32_16x16x32_bf16 v[52:55], v[164:167], v[184:187], v[52:55]
	v_mfma_f32_16x16x32_bf16 v[44:47], v[172:175], v[184:187], v[44:47]
	v_mfma_f32_16x16x32_bf16 v[36:39], v[164:167], v[192:195], v[36:39]
	v_mfma_f32_16x16x32_bf16 v[28:31], v[172:175], v[192:195], v[28:31]
	v_mfma_f32_16x16x32_bf16 v[20:23], v[164:167], v[200:203], v[20:23]
	v_mfma_f32_16x16x32_bf16 v[12:15], v[172:175], v[200:203], v[12:15]
	v_mfma_f32_16x16x32_bf16 v[4:7], v[164:167], v[208:211], v[4:7]
	v_mfma_f32_16x16x32_bf16 v[0:3], v[172:175], v[208:211], v[0:3]
	v_mfma_f32_16x16x32_bf16 v[52:55], v[168:171], v[188:191], v[52:55]
	v_mfma_f32_16x16x32_bf16 v[44:47], v[180:183], v[188:191], v[44:47]
	v_mfma_f32_16x16x32_bf16 v[36:39], v[168:171], v[196:199], v[36:39]
	v_mfma_f32_16x16x32_bf16 v[28:31], v[180:183], v[196:199], v[28:31]
	v_mfma_f32_16x16x32_bf16 v[20:23], v[168:171], v[204:207], v[20:23]
	v_mfma_f32_16x16x32_bf16 v[12:15], v[180:183], v[204:207], v[12:15]
	v_mfma_f32_16x16x32_bf16 v[4:7], v[168:171], v[212:215], v[4:7]
	v_mfma_f32_16x16x32_bf16 v[0:3], v[180:183], v[212:215], v[0:3]
	s_setprio 0
	s_barrier
	s_add_i32 s3, 0, 0x18000
	v_add_u32_e32 v151, s3, v145
	s_add_i32 s33, 0, 0x1c000
	ds_read_b128 v[140:143], v151
	ds_read_b128 v[152:155], v151 offset:1024
	ds_read_b128 v[156:159], v151 offset:2048
	ds_read_b128 v[160:163], v151 offset:3072
	v_add_u32_e32 v151, s33, v145
	ds_read_b128 v[164:167], v151
	ds_read_b128 v[168:171], v151 offset:1024
	ds_read_b128 v[172:175], v151 offset:2048
	ds_read_b128 v[180:183], v151 offset:3072
	s_add_u32 s24, s24, 0xb0000
	s_addc_u32 s25, s25, 0
	s_mov_b32 m0, s36
	v_lshl_add_u64 v[224:225], s[24:25], 0, v[128:129]
	ds_read_b128 v[184:187], v149 offset:32768
	ds_read_b128 v[188:191], v149 offset:33792
	ds_read_b128 v[192:195], v149 offset:34816
	ds_read_b128 v[196:199], v149 offset:35840
	ds_read_b128 v[200:203], v149 offset:36864
	ds_read_b128 v[204:207], v149 offset:37888
	ds_read_b128 v[208:211], v149 offset:38912
	ds_read_b128 v[212:215], v149 offset:39936
	global_load_lds_dwordx4 v[224:225], off
	v_lshl_add_u64 v[224:225], s[24:25], 0, v[130:131]
	s_mov_b32 m0, s37
	s_nop 0
	global_load_lds_dwordx4 v[224:225], off
	s_waitcnt vmcnt(8)
	s_waitcnt lgkmcnt(0)
	s_barrier
	s_setprio 1
	s_waitcnt lgkmcnt(0)
	v_mfma_f32_16x16x32_bf16 v[124:127], v[140:143], v[184:187], v[124:127]
	v_mfma_f32_16x16x32_bf16 v[120:123], v[156:159], v[184:187], v[120:123]
	v_mfma_f32_16x16x32_bf16 v[112:115], v[140:143], v[192:195], v[112:115]
	v_mfma_f32_16x16x32_bf16 v[104:107], v[156:159], v[192:195], v[104:107]
	v_mfma_f32_16x16x32_bf16 v[96:99], v[140:143], v[200:203], v[96:99]
	v_mfma_f32_16x16x32_bf16 v[88:91], v[156:159], v[200:203], v[88:91]
	v_mfma_f32_16x16x32_bf16 v[80:83], v[140:143], v[208:211], v[80:83]
	v_mfma_f32_16x16x32_bf16 v[72:75], v[156:159], v[208:211], v[72:75]
	v_mfma_f32_16x16x32_bf16 v[124:127], v[152:155], v[188:191], v[124:127]
	v_mfma_f32_16x16x32_bf16 v[120:123], v[160:163], v[188:191], v[120:123]
	v_mfma_f32_16x16x32_bf16 v[112:115], v[152:155], v[196:199], v[112:115]
	v_mfma_f32_16x16x32_bf16 v[104:107], v[160:163], v[196:199], v[104:107]
	v_mfma_f32_16x16x32_bf16 v[96:99], v[152:155], v[204:207], v[96:99]
	v_mfma_f32_16x16x32_bf16 v[88:91], v[160:163], v[204:207], v[88:91]
	v_mfma_f32_16x16x32_bf16 v[80:83], v[152:155], v[212:215], v[80:83]
	v_mfma_f32_16x16x32_bf16 v[72:75], v[160:163], v[212:215], v[72:75]
	s_setprio 0
	s_setprio 1
	v_mfma_f32_16x16x32_bf16 v[116:119], v[164:167], v[184:187], v[116:119]
	v_mfma_f32_16x16x32_bf16 v[108:111], v[172:175], v[184:187], v[108:111]
	v_mfma_f32_16x16x32_bf16 v[100:103], v[164:167], v[192:195], v[100:103]
	v_mfma_f32_16x16x32_bf16 v[92:95], v[172:175], v[192:195], v[92:95]
	v_mfma_f32_16x16x32_bf16 v[84:87], v[164:167], v[200:203], v[84:87]
	v_mfma_f32_16x16x32_bf16 v[76:79], v[172:175], v[200:203], v[76:79]
	v_mfma_f32_16x16x32_bf16 v[68:71], v[164:167], v[208:211], v[68:71]
	v_mfma_f32_16x16x32_bf16 v[64:67], v[172:175], v[208:211], v[64:67]
	v_mfma_f32_16x16x32_bf16 v[116:119], v[168:171], v[188:191], v[116:119]
	v_mfma_f32_16x16x32_bf16 v[108:111], v[180:183], v[188:191], v[108:111]
	v_mfma_f32_16x16x32_bf16 v[100:103], v[168:171], v[196:199], v[100:103]
	v_mfma_f32_16x16x32_bf16 v[92:95], v[180:183], v[196:199], v[92:95]
	v_mfma_f32_16x16x32_bf16 v[84:87], v[168:171], v[204:207], v[84:87]
	v_mfma_f32_16x16x32_bf16 v[76:79], v[180:183], v[204:207], v[76:79]
	v_mfma_f32_16x16x32_bf16 v[68:71], v[168:171], v[212:215], v[68:71]
	v_mfma_f32_16x16x32_bf16 v[64:67], v[180:183], v[212:215], v[64:67]
	s_setprio 0
	s_barrier
; #define PG8_STAGE(bufoff, gbase, voff) do { _Pragma("unroll") for (int _i = 0; _i < 2; ++_i) \
;         __builtin_amdgcn_global_load_lds((const unsigned*)((const char*)(gbase) + (voff)[_i]), (PG8_LAS unsigned*)(lds + (bufoff) + ldsw + _i * 8192), 16, 0, 0); } while (0)
; #define PG8_LDA(dst, b, h) do { _Pragma("unroll") for (int m = 0; m < 4; ++m) _Pragma("unroll") for (int k = 0; k < 2; ++k) dst[m][k] = *(const PG8_LAS bf16x8*)(lds + PG8_SA(b, h) + aoff + m * 2048 + k * 1024); } while (0)
; #define PG8_MMA(ai, bj, At, Bt) do { __builtin_amdgcn_s_setprio(1); _Pragma("unroll") for (int m = 0; m < 4; ++m) _Pragma("unroll") for (int n = 0; n < 2; ++n) _Pragma("unroll") for (int k = 0; k < 2; ++k) \
;         acc[ai][bj][m][n] = __builtin_amdgcn_mfma_f32_16x16x32_bf16(Bt[n][k], At[m][k], acc[ai][bj][m][n], 0, 0, 0); __builtin_amdgcn_s_setprio(0); } while (0)
; #define PG8_WAIT_V(n) asm volatile("s_waitcnt vmcnt(" #n ")" ::: "memory")
; template <class Epi, class Sched, bool ALIGN_EPI = false, bool SP2 = false>
; __device__ __forceinline__ void gemm_phase(PG8_LAS unsigned char* lds, const Gemm g, const Sched& S, const Epi& E) {
;     ...
;             PG8_LDA(At, 1, 1); PG8_STAGE(PG8_SB(1, 0), b3, voffB); PG8_STAGE(PG8_SB(1, 1), b3 + hstep, voffB); PG8_STAGE(PG8_SA(1, 0), a3, voffA);
;             PG8_WAIT_V(8); PG8_WAIT_L(0); PG8_BAR; PG8_MMA(1, 0, At, B0); PG8_MMA(1, 1, At, B1); PG8_BAR; PG8_SCHED;
;     __device__ __forceinline__ void operator()(const AccT& acc, const pg8::Unit& u, int wr, int wc, int fr, int fq) const {
;     ...
;             for (int m = 0; m < 4; ++m) { const int row = row0 + ai * 128 + m * 16; float ss = 0.f;
; #pragma unroll
;                 for (int bj = 0; bj < 2; ++bj)
; #pragma unroll
;                     for (int n = 0; n < 2; ++n) { f32x4 v = acc[ai][bj][m][n]; const size_t idx = (size_t)row * 1024 + col0 + bj * 128 + n * 16;
;                         if (MODE == 0) v = v * up4(*(const u32x2*)(io + idx));
;                         else if (MODE == 1) v = up4(*(const u32x2*)(io + idx)) + up4(*(const u32x2*)(g2 + idx)) * v;
;                         else ss += (v[0] * v[0] + v[1] * v[1]) + (v[2] * v[2] + v[3] * v[3]);
;                         if (!DRYE || v[0] == 123.456f) *(u32x2*)(io + idx) = pk4(v); }
;                 if (MODE == 2 && !DRYE) { ss += __shfl_xor(ss, 16); ss += __shfl_xor(ss, 32); if (fq == 0) atomicAdd(rowss + row, ss); } }
	s_add_i32 s3, s3, s31
	v_lshl_add_u64 v[216:217], v[216:217], 0, s[18:19]
	s_mov_b32 m0, s3
	ds_read_b128 v[184:187], v149 offset:49152
	ds_read_b128 v[188:191], v149 offset:50176
	ds_read_b128 v[192:195], v149 offset:51200
	ds_read_b128 v[196:199], v149 offset:52224
	ds_read_b128 v[200:203], v149 offset:53248
	ds_read_b128 v[204:207], v149 offset:54272
	ds_read_b128 v[208:211], v149 offset:55296
	ds_read_b128 v[212:215], v149 offset:56320
	global_load_lds_dwordx4 v[216:217], off
	s_add_i32 m0, s3, 0x2000
	s_add_u32 s22, s22, 0xb0080
	v_lshl_add_u64 v[216:217], v[218:219], 0, s[18:19]
	s_addc_u32 s23, s23, 0
	s_add_i32 s3, s33, s31
	global_load_lds_dwordx4 v[216:217], off
	v_lshl_add_u64 v[216:217], s[22:23], 0, v[128:129]
	s_mov_b32 m0, s3
	s_nop 0
	global_load_lds_dwordx4 v[216:217], off
	v_lshl_add_u64 v[216:217], s[22:23], 0, v[130:131]
	s_add_i32 m0, s3, 0x2000
	s_nop 0
	global_load_lds_dwordx4 v[216:217], off
	v_lshl_add_u64 v[216:217], v[220:221], 0, s[18:19]
	s_mov_b32 m0, s39
	s_nop 0
	global_load_lds_dwordx4 v[216:217], off
	v_lshl_add_u64 v[216:217], v[222:223], 0, s[18:19]
	s_mov_b32 m0, s40
	s_nop 0
	global_load_lds_dwordx4 v[216:217], off
	s_waitcnt vmcnt(8)
	s_waitcnt lgkmcnt(0)
	s_barrier
	s_setprio 1
	s_waitcnt lgkmcnt(0)
	v_mfma_f32_16x16x32_bf16 v[60:63], v[140:143], v[184:187], v[60:63]
	v_mfma_f32_16x16x32_bf16 v[56:59], v[156:159], v[184:187], v[56:59]
	v_mfma_f32_16x16x32_bf16 v[48:51], v[140:143], v[192:195], v[48:51]
	v_mfma_f32_16x16x32_bf16 v[40:43], v[156:159], v[192:195], v[40:43]
	v_mfma_f32_16x16x32_bf16 v[32:35], v[140:143], v[200:203], v[32:35]
	v_mfma_f32_16x16x32_bf16 v[24:27], v[156:159], v[200:203], v[24:27]
	v_mfma_f32_16x16x32_bf16 v[16:19], v[140:143], v[208:211], v[16:19]
	v_mfma_f32_16x16x32_bf16 v[8:11], v[156:159], v[208:211], v[8:11]
	v_mfma_f32_16x16x32_bf16 v[60:63], v[152:155], v[188:191], v[60:63]
	v_mfma_f32_16x16x32_bf16 v[56:59], v[160:163], v[188:191], v[56:59]
	v_mfma_f32_16x16x32_bf16 v[48:51], v[152:155], v[196:199], v[48:51]
	v_mfma_f32_16x16x32_bf16 v[40:43], v[160:163], v[196:199], v[40:43]
	v_mfma_f32_16x16x32_bf16 v[32:35], v[152:155], v[204:207], v[32:35]
	v_mfma_f32_16x16x32_bf16 v[24:27], v[160:163], v[204:207], v[24:27]
	v_mfma_f32_16x16x32_bf16 v[16:19], v[152:155], v[212:215], v[16:19]
	v_mfma_f32_16x16x32_bf16 v[8:11], v[160:163], v[212:215], v[8:11]
	s_setprio 0
	s_setprio 1
	v_mfma_f32_16x16x32_bf16 v[52:55], v[164:167], v[184:187], v[52:55]
	v_mfma_f32_16x16x32_bf16 v[44:47], v[172:175], v[184:187], v[44:47]
	v_mfma_f32_16x16x32_bf16 v[36:39], v[164:167], v[192:195], v[36:39]
	v_mfma_f32_16x16x32_bf16 v[28:31], v[172:175], v[192:195], v[28:31]
	v_mfma_f32_16x16x32_bf16 v[20:23], v[164:167], v[200:203], v[20:23]
	s_add_i32 s60, s60, 2
	s_add_u32 s20, s20, 0x100
	s_addc_u32 s21, s21, 0
	s_add_u32 s50, s50, 0x100
	s_addc_u32 s51, s51, 0
	s_cmp_gt_u32 s60, 41
	v_mfma_f32_16x16x32_bf16 v[12:15], v[172:175], v[200:203], v[12:15]
	v_mfma_f32_16x16x32_bf16 v[4:7], v[164:167], v[208:211], v[4:7]
	v_mfma_f32_16x16x32_bf16 v[0:3], v[172:175], v[208:211], v[0:3]
	v_mfma_f32_16x16x32_bf16 v[52:55], v[168:171], v[188:191], v[52:55]
	v_mfma_f32_16x16x32_bf16 v[44:47], v[180:183], v[188:191], v[44:47]
	v_mfma_f32_16x16x32_bf16 v[36:39], v[168:171], v[196:199], v[36:39]
	v_mfma_f32_16x16x32_bf16 v[28:31], v[180:183], v[196:199], v[28:31]
	v_mfma_f32_16x16x32_bf16 v[20:23], v[168:171], v[204:207], v[20:23]
	v_mfma_f32_16x16x32_bf16 v[12:15], v[180:183], v[204:207], v[12:15]
	v_mfma_f32_16x16x32_bf16 v[4:7], v[168:171], v[212:215], v[4:7]
	v_mfma_f32_16x16x32_bf16 v[0:3], v[180:183], v[212:215], v[0:3]
	s_setprio 0
	s_barrier
	s_cbranch_scc0 .LBB0_1287
	v_and_b32_e32 v151, 64, v150
	v_xor_b32_e32 v143, 16, v150
	v_add_u32_e32 v151, 64, v151
	v_cmp_lt_i32_e32 vcc, v143, v151
	v_lshl_add_u32 v142, s48, 8, v144
	v_lshl_or_b32 v140, s49, 8, v146
	v_cndmask_b32_e32 v143, v150, v143, vcc
	v_lshlrev_b32_e32 v152, 2, v143
	v_xor_b32_e32 v143, 32, v150
	v_cmp_lt_i32_e32 vcc, v143, v151
	v_mul_f32_e32 v153, v125, v125
	v_mul_f32_e32 v156, v127, v127
	v_cndmask_b32_e32 v143, v150, v143, vcc
	v_lshlrev_b32_e32 v151, 2, v143
	v_ashrrev_i32_e32 v143, 31, v142
	v_lshlrev_b64 v[154:155], 11, v[142:143]
	v_ashrrev_i32_e32 v141, 31, v140
	v_fmac_f32_e32 v153, v124, v124
	v_fmac_f32_e32 v156, v126, v126
	v_cvt_pk_bf16_f32 v124, v124, v125
	v_cvt_pk_bf16_f32 v125, v126, v127
	v_lshl_add_u64 v[126:127], s[14:15], 0, v[154:155]
	v_lshl_add_u64 v[126:127], v[140:141], 1, v[126:127]
	global_store_dwordx2 v[126:127], v[124:125], off
	v_mul_f32_e32 v124, v121, v121
	v_mul_f32_e32 v125, v123, v123
	v_fmac_f32_e32 v124, v120, v120
	v_fmac_f32_e32 v125, v122, v122
	v_add_f32_e32 v124, v124, v125
	v_cvt_pk_bf16_f32 v120, v120, v121
	v_mul_f32_e32 v121, v117, v117
	v_mul_f32_e32 v125, v119, v119
	v_add_f32_e32 v153, v153, v156
	v_fmac_f32_e32 v121, v116, v116
	v_fmac_f32_e32 v125, v118, v118
	v_add_f32_e32 v124, v153, v124
	v_add_f32_e32 v121, v121, v125
	v_add_f32_e32 v121, v124, v121
	v_mul_f32_e32 v124, v109, v109
	v_mul_f32_e32 v125, v111, v111
	v_fmac_f32_e32 v124, v108, v108
	v_fmac_f32_e32 v125, v110, v110
	v_add_f32_e32 v124, v124, v125
	v_add_f32_e32 v124, v121, v124
	ds_bpermute_b32 v125, v152, v124
	v_cvt_pk_bf16_f32 v121, v122, v123
	global_store_dwordx2 v[126:127], v[120:121], off offset:32
	v_cvt_pk_bf16_f32 v120, v116, v117
	v_cvt_pk_bf16_f32 v121, v118, v119
	s_waitcnt lgkmcnt(0)
	v_add_f32_e32 v116, v124, v125
	ds_bpermute_b32 v117, v151, v116
	v_cvt_pk_bf16_f32 v108, v108, v109
	v_cvt_pk_bf16_f32 v109, v110, v111
	global_store_dwordx2 v[126:127], v[120:121], off offset:256
	global_store_dwordx2 v[126:127], v[108:109], off offset:288
	s_and_saveexec_b64 s[20:21], s[0:1]
	s_cbranch_execz .LBB0_1290
	v_lshl_add_u64 v[108:109], v[142:143], 2, s[16:17]
	s_waitcnt lgkmcnt(0)
	v_add_f32_e32 v110, v116, v117
	global_atomic_add_f32 v[108:109], v110, off
